# weight-conversion items: wait only for LDS (not for the item's global stores) before reusing the per-wave LDS tile
# speedup vs baseline: 1.0008x; 1.0008x over previous
; DI void transpose_item(const float* W, int K, int N, bf16_t* WT, int mode, float* scr, int item, int lane) {
;     const int nblk = N / 64, kb = item / nblk, nb = item % nblk, k0 = 64 * kb, n0 = 64 * nb;
;     int drow0 = n0;
;     if (mode == 1) { const int seg = n0 >> 10; const int dst = seg < 2 ? seg : (seg == 2 ? 6 : seg - 1); drow0 = dst * 1024 + (n0 & 1023); }
; DI void convert_item(const Args& a, float* scr, int it, int lane) {
;     unsigned char* ws = a.ws; int r = it;
;     if (r < I_INE) { transpose_item(a.in[7], D_, NINE, (bf16_t*)(ws + WS_WINE), 1, scr, r, lane); return; } r -= I_INE;
;     if (r < I_OUTE) { transpose_item(a.in[8], D_, D_, (bf16_t*)(ws + WS_WOUTE), 0, scr, r, lane); return; } r -= I_OUTE;
;     if (r < I_GU) { transpose_item(a.in[20], D_, 2 * DFF, (bf16_t*)(ws + WS_WGU), 2, scr, r, lane); return; } r -= I_GU;
;     if (r < I_DN) { transpose_item(a.in[21], DFF, D_, (bf16_t*)(ws + WS_WDN), 0, scr, r, lane); return; } r -= I_DN;
;     if (r < I_PU) { transpose_item(a.in[22], PLE, D_, (bf16_t*)(ws + WS_WPU), 0, scr, r, lane); return; } r -= I_PU;
;     if (r < I_PG) { transpose_item(a.in[23], D_, D_, (bf16_t*)(ws + WS_WPG), 0, scr, r, lane); return; } r -= I_PG;
;     if (r < I_INO) { transpose_item(a.in[11], D_, 2 * LRU, (bf16_t*)(ws + WS_WINO), 0, scr, r, lane); return; } r -= I_INO;
;     if (r < I_OUTO) { transpose_item(a.in[19], LRU, D_, (bf16_t*)(ws + WS_WOUTO), 0, scr, r, lane); return; } r -= I_OUTO;
;     if (r < I_GU) { transpose_item(a.in[20] + (size_t)D_ * 2 * DFF, D_, 2 * DFF, (bf16_t*)(ws + WS_WGU) + (size_t)2 * DFF * D_, 2, scr, r, lane); return; } r -= I_GU;
;     if (r < I_DN) { transpose_item(a.in[21] + (size_t)DFF * D_, DFF, D_, (bf16_t*)(ws + WS_WDN) + (size_t)D_ * DFF, 0, scr, r, lane); return; } r -= I_DN;
;     if (r < I_PU) { transpose_item(a.in[22] + (size_t)PLE * D_, PLE, D_, (bf16_t*)(ws + WS_WPU) + (size_t)D_ * PLE, 0, scr, r, lane); return; } r -= I_PU;
;     if (r < I_PG) { transpose_item(a.in[23] + (size_t)D_ * D_, D_, D_, (bf16_t*)(ws + WS_WPG) + (size_t)D_ * D_, 0, scr, r, lane); return; } r -= I_PG;
;     { const int mtx = r / I_RG, blk = mtx >> 1, which = mtx & 1;
;       transpose_item((which ? a.in[16] : a.in[14]) + (size_t)blk * 65536, 256, 256, (bf16_t*)(ws + WS_WRG) + (size_t)blk * 512 * 256, 3 + which, scr, r % I_RG, lane); }
.LBB0_9:
	s_cmpk_gt_i32 s81, 0xdff
	s_mov_b64 s[8:9], -1
	s_cbranch_scc0 .LBB0_63
	s_cmpk_gt_u32 s81, 0x11ff
	s_cbranch_scc0 .LBB0_60
	s_cmpk_gt_u32 s81, 0x27ff
	s_cbranch_scc0 .LBB0_53
	s_cmpk_gt_u32 s81, 0x32ff
	s_cbranch_scc0 .LBB0_50
	s_cmpk_gt_u32 s81, 0x337f
	s_cbranch_scc0 .LBB0_47
	s_cmpk_gt_u32 s81, 0x377f
	s_cbranch_scc0 .LBB0_44
	s_cmpk_gt_u32 s81, 0x427f
	s_cbranch_scc0 .LBB0_41
	s_cmpk_gt_u32 s81, 0x47ff
	s_cbranch_scc0 .LBB0_38
	s_cmpk_gt_u32 s81, 0x5dff
	s_cbranch_scc0 .LBB0_31
	s_cmpk_gt_u32 s81, 0x68ff
	s_cbranch_scc0 .LBB0_28
	s_cmpk_gt_u32 s81, 0x697f
	s_cbranch_scc0 .LBB0_25
	s_cmpk_gt_u32 s81, 0x6d7f
	s_cbranch_scc0 .LBB0_22
	s_add_i32 s8, s81, 0xffff9280
	s_and_b32 s9, s21, 0x100
	s_lshr_b32 s40, s8, 5
	s_add_i32 s9, s14, s9
	s_and_b32 s8, s81, 16
	s_lshl_b64 s[10:11], s[40:41], 18
	s_add_i32 s40, s9, 0x80
	s_cmp_eq_u32 s8, 0
	s_cselect_b32 s73, s36, s38
	s_cselect_b32 s72, s37, s39
	s_cselect_b32 s8, s9, s40
	s_add_u32 s9, s73, s10
	s_addc_u32 s40, s72, s11
	s_add_u32 s72, s12, s10
	s_addc_u32 s73, s13, s11
	s_and_b32 s82, s23, 0xc0
	s_add_u32 s10, s9, s44
	v_or_b32_e32 v2, s82, v59
	s_addc_u32 s11, s40, 0
	v_mov_b32_e32 v45, v3
	v_lshl_add_u64 v[56:57], s[10:11], 0, v[44:45]
	v_lshlrev_b32_e32 v2, 10, v2
	v_lshl_add_u64 v[56:57], v[56:57], 0, v[2:3]
	v_add_co_u32_e32 v80, vcc, s45, v56
	global_load_dwordx4 v[72:75], v[56:57], off nt
	s_nop 0
	v_addc_co_u32_e32 v81, vcc, 0, v57, vcc
	v_add_co_u32_e32 v88, vcc, s46, v56
	global_load_dwordx4 v[76:79], v[80:81], off offset:-4096 nt
	s_nop 0
	global_load_dwordx4 v[80:83], v[80:81], off nt
	v_addc_co_u32_e32 v89, vcc, 0, v57, vcc
	v_add_co_u32_e32 v96, vcc, s47, v56
	global_load_dwordx4 v[84:87], v[88:89], off offset:-4096 nt
	s_nop 0
	global_load_dwordx4 v[88:91], v[88:89], off nt
	v_addc_co_u32_e32 v97, vcc, 0, v57, vcc
	global_load_dwordx4 v[92:95], v[96:97], off offset:-4096 nt
	s_nop 0
	global_load_dwordx4 v[96:99], v[96:97], off nt
	v_add_co_u32_e32 v104, vcc, s49, v56
	v_add_u32_e32 v2, 0x410, v60
	s_nop 0
	v_addc_co_u32_e32 v105, vcc, 0, v57, vcc
	global_load_dwordx4 v[100:103], v[104:105], off offset:-4096 nt
	s_nop 0
	global_load_dwordx4 v[104:107], v[104:105], off nt
	v_add_co_u32_e32 v112, vcc, s50, v56
	v_add_u32_e32 v45, 0x418, v60
	s_nop 0
	v_addc_co_u32_e32 v113, vcc, 0, v57, vcc
	global_load_dwordx4 v[108:111], v[112:113], off offset:-4096 nt
	s_nop 0
	global_load_dwordx4 v[112:115], v[112:113], off nt
	v_add_co_u32_e32 v120, vcc, s51, v56
	v_add_u32_e32 v47, 0x820, v60
	s_nop 0
	v_addc_co_u32_e32 v121, vcc, 0, v57, vcc
	global_load_dwordx4 v[116:119], v[120:121], off offset:-4096 nt
	s_nop 0
	global_load_dwordx4 v[120:123], v[120:121], off nt
	v_add_co_u32_e32 v128, vcc, s52, v56
	v_add_u32_e32 v71, 0xc38, v60
	s_nop 0
	v_addc_co_u32_e32 v129, vcc, 0, v57, vcc
	global_load_dwordx4 v[124:127], v[128:129], off offset:-4096 nt
	s_nop 0
	global_load_dwordx4 v[128:131], v[128:129], off nt
	v_add_co_u32_e32 v56, vcc, s53, v56
	v_add_u32_e32 v136, 0x1040, v60
	s_nop 0
	v_addc_co_u32_e32 v57, vcc, 0, v57, vcc
	global_load_dwordx4 v[132:135], v[56:57], off nt
	v_add_u32_e32 v56, 0x828, v60
	v_add_u32_e32 v57, 0xc30, v60
	v_add_u32_e32 v137, 0x1048, v60
	v_add_u32_e32 v138, 0x1450, v60
	v_add_u32_e32 v139, 0x1458, v60
	v_add_u32_e32 v140, 0x1860, v60
	s_lshl_b32 s9, s82, 1
	s_add_u32 s10, s72, s9
	s_addc_u32 s11, s73, 0
	s_waitcnt vmcnt(15)
	ds_write2_b32 v60, v72, v73 offset1:1
	ds_write2_b32 v60, v74, v75 offset0:2 offset1:3
	s_waitcnt vmcnt(14)
	ds_write2_b32 v2, v76, v77 offset1:1
	ds_write2_b32 v45, v78, v79 offset1:1
	s_waitcnt vmcnt(13)
	ds_write2_b32 v47, v80, v81 offset1:1
	ds_write2_b32 v56, v82, v83 offset1:1
	s_waitcnt vmcnt(12)
	ds_write2_b32 v57, v84, v85 offset1:1
	ds_write2_b32 v71, v86, v87 offset1:1
	s_waitcnt vmcnt(11)
	ds_write2_b32 v136, v88, v89 offset1:1
	ds_write2_b32 v137, v90, v91 offset1:1
	s_waitcnt vmcnt(10)
	ds_write2_b32 v138, v92, v93 offset1:1
	ds_write2_b32 v139, v94, v95 offset1:1
	s_waitcnt vmcnt(9)
	ds_write2_b32 v140, v96, v97 offset1:1
	v_add_u32_e32 v2, 0x1868, v60
	ds_write2_b32 v2, v98, v99 offset1:1
	v_add_u32_e32 v2, 0x1c70, v60
	v_mov_b32_e32 v47, v3
	s_waitcnt vmcnt(8)
	ds_write2_b32 v2, v100, v101 offset1:1
	v_add_u32_e32 v2, 0x1c78, v60
	ds_write2_b32 v2, v102, v103 offset1:1
	v_add_u32_e32 v2, 0x2080, v60
	s_waitcnt vmcnt(7)
	ds_write2_b32 v2, v104, v105 offset1:1
	v_add_u32_e32 v2, 0x2088, v60
	ds_write2_b32 v2, v106, v107 offset1:1
	v_add_u32_e32 v2, 0x2490, v60
	s_waitcnt vmcnt(6)
	ds_write2_b32 v2, v108, v109 offset1:1
	v_add_u32_e32 v2, 0x2498, v60
	ds_write2_b32 v2, v110, v111 offset1:1
	v_add_u32_e32 v2, 0x28a0, v60
	s_waitcnt vmcnt(5)
	ds_write2_b32 v2, v112, v113 offset1:1
	v_add_u32_e32 v2, 0x28a8, v60
	ds_write2_b32 v2, v114, v115 offset1:1
	v_add_u32_e32 v2, 0x2cb0, v60
	s_waitcnt vmcnt(4)
	ds_write2_b32 v2, v116, v117 offset1:1
	v_add_u32_e32 v2, 0x2cb8, v60
	ds_write2_b32 v2, v118, v119 offset1:1
	v_add_u32_e32 v2, 0x30c0, v60
	s_waitcnt vmcnt(3)
	ds_write2_b32 v2, v120, v121 offset1:1
	v_add_u32_e32 v2, 0x30c8, v60
	ds_write2_b32 v2, v122, v123 offset1:1
	v_add_u32_e32 v2, 0x34d0, v60
	s_waitcnt vmcnt(2)
	ds_write2_b32 v2, v124, v125 offset1:1
	v_add_u32_e32 v2, 0x34d8, v60
	ds_write2_b32 v2, v126, v127 offset1:1
	v_add_u32_e32 v2, 0x38e0, v60
	s_waitcnt vmcnt(1)
	ds_write2_b32 v2, v128, v129 offset1:1
	v_add_u32_e32 v2, 0x38e8, v60
	ds_write2_b32 v2, v130, v131 offset1:1
	v_add_u32_e32 v2, 0x3cf0, v60
	s_waitcnt vmcnt(0)
	ds_write2_b32 v2, v132, v133 offset1:1
	v_add_u32_e32 v2, 0x3cf8, v60
	ds_write2_b32 v2, v134, v135 offset1:1
	s_waitcnt vmcnt(0) expcnt(0) lgkmcnt(0)
; DI unsigned pk2w(float lo, float hi) { return f2bfw(lo) | (f2bfw(hi) << 16); }
; DI void transpose_item(const float* W, int K, int N, bf16_t* WT, int mode, float* scr, int item, int lane) {
;     ...
;     const int c = lane & 7;
; #pragma unroll
;     for (int j = 0; j < 8; ++j) { const int n = (lane >> 3) + 8 * j; const float* sp = scr + (8 * c) * 65 + n;
;         u32x4 o; o.x = pk2w(sp[0 * 65], sp[1 * 65]); o.y = pk2w(sp[2 * 65], sp[3 * 65]); o.z = pk2w(sp[4 * 65], sp[5 * 65]); o.w = pk2w(sp[6 * 65], sp[7 * 65]);
;         *(u32x4*)(WT + (size_t)(drow0 + n) * K + k0 + 8 * c) = o; }
	ds_read2_b32 v[76:77], v62 offset1:8
	ds_read2_b32 v[78:79], v62 offset0:65 offset1:73
	ds_read2_b32 v[80:81], v62 offset0:130 offset1:138
	ds_read2_b32 v[82:83], v62 offset0:195 offset1:203
	v_lshl_add_u64 v[56:57], s[10:11], 0, v[46:47]
	s_waitcnt lgkmcnt(3)
	v_bfe_u32 v2, v76, 16, 1
	v_add3_u32 v2, v76, v2, s54
	s_waitcnt lgkmcnt(2)
	v_bfe_u32 v45, v78, 16, 1
	v_lshrrev_b32_e32 v2, 16, v2
	v_add3_u32 v45, v78, v45, s54
	v_and_or_b32 v72, v45, s55, v2
	v_add_u32_e32 v45, 0x400, v62
	ds_read2_b32 v[84:85], v45 offset0:4 offset1:12
	ds_read2_b32 v[86:87], v45 offset0:69 offset1:77
	s_waitcnt lgkmcnt(3)
	v_bfe_u32 v2, v80, 16, 1
	v_add3_u32 v2, v80, v2, s54
	s_waitcnt lgkmcnt(2)
	v_bfe_u32 v47, v82, 16, 1
	ds_read2_b32 v[88:89], v45 offset0:134 offset1:142
	v_lshrrev_b32_e32 v2, 16, v2
	v_add3_u32 v47, v82, v47, s54
	ds_read2_b32 v[90:91], v45 offset0:199 offset1:207
	v_and_or_b32 v73, v47, s55, v2
	s_waitcnt lgkmcnt(3)
	v_bfe_u32 v2, v84, 16, 1
	v_add3_u32 v2, v84, v2, s54
	s_waitcnt lgkmcnt(2)
	v_bfe_u32 v47, v86, 16, 1
	v_lshrrev_b32_e32 v2, 16, v2
	v_add3_u32 v47, v86, v47, s54
	v_and_or_b32 v74, v47, s55, v2
	s_waitcnt lgkmcnt(1)
	v_bfe_u32 v2, v88, 16, 1
	v_add3_u32 v2, v88, v2, s54
	s_waitcnt lgkmcnt(0)
	v_bfe_u32 v47, v90, 16, 1
	v_lshrrev_b32_e32 v2, 16, v2
	v_add3_u32 v47, v90, v47, s54
	v_or_b32_e32 v92, s8, v61
	v_and_or_b32 v75, v47, s55, v2
	v_ashrrev_i32_e32 v93, 31, v92
	v_bfe_u32 v2, v77, 16, 1
	v_lshlrev_b64 v[92:93], 9, v[92:93]
	v_add3_u32 v2, v77, v2, s54
	v_bfe_u32 v47, v79, 16, 1
	v_lshl_add_u64 v[92:93], v[56:57], 0, v[92:93]
	v_lshrrev_b32_e32 v2, 16, v2
	v_add3_u32 v47, v79, v47, s54
	global_store_dwordx4 v[92:93], v[72:75], off
	v_or_b32_e32 v76, s8, v63
	v_ashrrev_i32_e32 v77, 31, v76
	v_and_or_b32 v72, v47, s55, v2
	v_bfe_u32 v2, v81, 16, 1
	v_add3_u32 v2, v81, v2, s54
	v_bfe_u32 v47, v83, 16, 1
	v_lshrrev_b32_e32 v2, 16, v2
	v_add3_u32 v47, v83, v47, s54
	v_and_or_b32 v73, v47, s55, v2
	v_bfe_u32 v2, v85, 16, 1
	v_add3_u32 v2, v85, v2, s54
	v_bfe_u32 v47, v87, 16, 1
	v_lshrrev_b32_e32 v2, 16, v2
	v_add3_u32 v47, v87, v47, s54
	v_and_or_b32 v74, v47, s55, v2
	v_bfe_u32 v2, v89, 16, 1
	v_add3_u32 v2, v89, v2, s54
	v_bfe_u32 v47, v91, 16, 1
	v_lshrrev_b32_e32 v2, 16, v2
	v_add3_u32 v47, v91, v47, s54
	v_lshlrev_b64 v[76:77], 9, v[76:77]
	v_and_or_b32 v75, v47, s55, v2
	ds_read2_b32 v[78:79], v62 offset0:16 offset1:24
	v_lshl_add_u64 v[76:77], v[56:57], 0, v[76:77]
	global_store_dwordx4 v[76:77], v[72:75], off
	ds_read2_b32 v[76:77], v62 offset0:81 offset1:89
	ds_read2_b32 v[80:81], v62 offset0:146 offset1:154
	ds_read2_b32 v[82:83], v62 offset0:211 offset1:219
	s_waitcnt lgkmcnt(3)
	v_bfe_u32 v2, v78, 16, 1
	v_add3_u32 v2, v78, v2, s54
	s_waitcnt lgkmcnt(2)
	v_bfe_u32 v47, v76, 16, 1
	ds_read2_b32 v[84:85], v45 offset0:20 offset1:28
	v_lshrrev_b32_e32 v2, 16, v2
	v_add3_u32 v47, v76, v47, s54
	ds_read2_b32 v[86:87], v45 offset0:85 offset1:93
	v_and_or_b32 v72, v47, s55, v2
	s_waitcnt lgkmcnt(3)
	v_bfe_u32 v2, v80, 16, 1
	v_add3_u32 v2, v80, v2, s54
	s_waitcnt lgkmcnt(2)
	v_bfe_u32 v47, v82, 16, 1
	ds_read2_b32 v[88:89], v45 offset0:150 offset1:158
	v_lshrrev_b32_e32 v2, 16, v2
	v_add3_u32 v47, v82, v47, s54
	ds_read2_b32 v[90:91], v45 offset0:215 offset1:223
	v_and_or_b32 v73, v47, s55, v2
	s_waitcnt lgkmcnt(3)
	v_bfe_u32 v2, v84, 16, 1
	v_add3_u32 v2, v84, v2, s54
	s_waitcnt lgkmcnt(2)
	v_bfe_u32 v47, v86, 16, 1
	v_lshrrev_b32_e32 v2, 16, v2
	v_add3_u32 v47, v86, v47, s54
	v_and_or_b32 v74, v47, s55, v2
	s_waitcnt lgkmcnt(1)
	v_bfe_u32 v2, v88, 16, 1
	v_add3_u32 v2, v88, v2, s54
	s_waitcnt lgkmcnt(0)
	v_bfe_u32 v47, v90, 16, 1
	v_lshrrev_b32_e32 v2, 16, v2
	v_add3_u32 v47, v90, v47, s54
	v_or_b32_e32 v92, s8, v64
	v_and_or_b32 v75, v47, s55, v2
	v_ashrrev_i32_e32 v93, 31, v92
	v_bfe_u32 v2, v79, 16, 1
	v_lshlrev_b64 v[92:93], 9, v[92:93]
	v_add3_u32 v2, v79, v2, s54
	v_bfe_u32 v47, v77, 16, 1
	v_lshl_add_u64 v[92:93], v[56:57], 0, v[92:93]
	v_lshrrev_b32_e32 v2, 16, v2
	v_add3_u32 v47, v77, v47, s54
	global_store_dwordx4 v[92:93], v[72:75], off
	v_or_b32_e32 v76, s8, v65
	v_ashrrev_i32_e32 v77, 31, v76
	v_and_or_b32 v72, v47, s55, v2
	v_bfe_u32 v2, v81, 16, 1
	v_add3_u32 v2, v81, v2, s54
	v_bfe_u32 v47, v83, 16, 1
	v_lshrrev_b32_e32 v2, 16, v2
	v_add3_u32 v47, v83, v47, s54
	v_and_or_b32 v73, v47, s55, v2
	v_bfe_u32 v2, v85, 16, 1
	v_add3_u32 v2, v85, v2, s54
	v_bfe_u32 v47, v87, 16, 1
	v_lshrrev_b32_e32 v2, 16, v2
	v_add3_u32 v47, v87, v47, s54
	v_and_or_b32 v74, v47, s55, v2
	v_bfe_u32 v2, v89, 16, 1
	v_add3_u32 v2, v89, v2, s54
	v_bfe_u32 v47, v91, 16, 1
	v_lshrrev_b32_e32 v2, 16, v2
	v_add3_u32 v47, v91, v47, s54
	v_lshlrev_b64 v[76:77], 9, v[76:77]
	v_and_or_b32 v75, v47, s55, v2
	ds_read2_b32 v[78:79], v62 offset0:32 offset1:40
	v_lshl_add_u64 v[76:77], v[56:57], 0, v[76:77]
	global_store_dwordx4 v[76:77], v[72:75], off
	ds_read2_b32 v[76:77], v62 offset0:97 offset1:105
	ds_read2_b32 v[80:81], v62 offset0:162 offset1:170
	ds_read2_b32 v[82:83], v62 offset0:227 offset1:235
	s_waitcnt lgkmcnt(3)
	v_bfe_u32 v2, v78, 16, 1
	v_add3_u32 v2, v78, v2, s54
	s_waitcnt lgkmcnt(2)
	v_bfe_u32 v47, v76, 16, 1
	ds_read2_b32 v[84:85], v45 offset0:36 offset1:44
	v_lshrrev_b32_e32 v2, 16, v2
	v_add3_u32 v47, v76, v47, s54
	ds_read2_b32 v[86:87], v45 offset0:101 offset1:109
	v_and_or_b32 v72, v47, s55, v2
	s_waitcnt lgkmcnt(3)
	v_bfe_u32 v2, v80, 16, 1
	v_add3_u32 v2, v80, v2, s54
	s_waitcnt lgkmcnt(2)
	v_bfe_u32 v47, v82, 16, 1
	ds_read2_b32 v[88:89], v45 offset0:166 offset1:174
	v_lshrrev_b32_e32 v2, 16, v2
	v_add3_u32 v47, v82, v47, s54
	ds_read2_b32 v[90:91], v45 offset0:231 offset1:239
	v_and_or_b32 v73, v47, s55, v2
	s_waitcnt lgkmcnt(3)
; DI unsigned pk2w(float lo, float hi) { return f2bfw(lo) | (f2bfw(hi) << 16); }
; DI void transpose_item(const float* W, int K, int N, bf16_t* WT, int mode, float* scr, int item, int lane) {
;     const int nblk = N / 64, kb = item / nblk, nb = item % nblk, k0 = 64 * kb, n0 = 64 * nb;
;     int drow0 = n0;
;     if (mode == 1) { const int seg = n0 >> 10; const int dst = seg < 2 ? seg : (seg == 2 ? 6 : seg - 1); drow0 = dst * 1024 + (n0 & 1023); }
;     else if (mode == 2) { drow0 = n0 < DFF ? (n0 / 128) * 256 + (n0 % 128) : ((n0 - DFF) / 128) * 256 + 128 + ((n0 - DFF) % 128); }
;     else if (mode == 3) { drow0 = (n0 / 128) * 256 + (n0 % 128); }
;     else if (mode == 4) { drow0 = (n0 / 128) * 256 + 128 + (n0 % 128); }
;     f32x4 v[16];
; #pragma unroll
;     for (int i = 0; i < 16; ++i) v[i] = __builtin_nontemporal_load((const f32x4*)(W + (size_t)(k0 + 4 * i + (lane >> 4)) * N + n0 + 4 * (lane & 15)));
;     ...
;     const int c = lane & 7;
; #pragma unroll
;     for (int j = 0; j < 8; ++j) { const int n = (lane >> 3) + 8 * j; const float* sp = scr + (8 * c) * 65 + n;
;         u32x4 o; o.x = pk2w(sp[0 * 65], sp[1 * 65]); o.y = pk2w(sp[2 * 65], sp[3 * 65]); o.z = pk2w(sp[4 * 65], sp[5 * 65]); o.w = pk2w(sp[6 * 65], sp[7 * 65]);
;         *(u32x4*)(WT + (size_t)(drow0 + n) * K + k0 + 8 * c) = o; }
;     __builtin_amdgcn_s_waitcnt(0); __builtin_amdgcn_wave_barrier();
	v_bfe_u32 v2, v84, 16, 1
	v_add3_u32 v2, v84, v2, s54
	s_waitcnt lgkmcnt(2)
	v_bfe_u32 v47, v86, 16, 1
	v_lshrrev_b32_e32 v2, 16, v2
	v_add3_u32 v47, v86, v47, s54
	v_and_or_b32 v74, v47, s55, v2
	s_waitcnt lgkmcnt(1)
	v_bfe_u32 v2, v88, 16, 1
	v_add3_u32 v2, v88, v2, s54
	s_waitcnt lgkmcnt(0)
	v_bfe_u32 v47, v90, 16, 1
	v_lshrrev_b32_e32 v2, 16, v2
	v_add3_u32 v47, v90, v47, s54
	v_or_b32_e32 v92, s8, v67
	v_and_or_b32 v75, v47, s55, v2
	v_ashrrev_i32_e32 v93, 31, v92
	v_bfe_u32 v2, v79, 16, 1
	v_lshlrev_b64 v[92:93], 9, v[92:93]
	v_add3_u32 v2, v79, v2, s54
	v_bfe_u32 v47, v77, 16, 1
	v_lshl_add_u64 v[92:93], v[56:57], 0, v[92:93]
	v_lshrrev_b32_e32 v2, 16, v2
	v_add3_u32 v47, v77, v47, s54
	global_store_dwordx4 v[92:93], v[72:75], off
	v_or_b32_e32 v76, s8, v68
	v_ashrrev_i32_e32 v77, 31, v76
	v_and_or_b32 v72, v47, s55, v2
	v_bfe_u32 v2, v81, 16, 1
	v_add3_u32 v2, v81, v2, s54
	v_bfe_u32 v47, v83, 16, 1
	v_lshrrev_b32_e32 v2, 16, v2
	v_add3_u32 v47, v83, v47, s54
	v_and_or_b32 v73, v47, s55, v2
	v_bfe_u32 v2, v85, 16, 1
	v_add3_u32 v2, v85, v2, s54
	v_bfe_u32 v47, v87, 16, 1
	v_lshrrev_b32_e32 v2, 16, v2
	v_add3_u32 v47, v87, v47, s54
	v_and_or_b32 v74, v47, s55, v2
	v_bfe_u32 v2, v89, 16, 1
	v_add3_u32 v2, v89, v2, s54
	v_bfe_u32 v47, v91, 16, 1
	v_lshrrev_b32_e32 v2, 16, v2
	v_add3_u32 v47, v91, v47, s54
	v_lshlrev_b64 v[76:77], 9, v[76:77]
	v_and_or_b32 v75, v47, s55, v2
	ds_read2_b32 v[78:79], v62 offset0:48 offset1:56
	v_lshl_add_u64 v[76:77], v[56:57], 0, v[76:77]
	global_store_dwordx4 v[76:77], v[72:75], off
	ds_read2_b32 v[76:77], v62 offset0:113 offset1:121
	ds_read2_b32 v[80:81], v62 offset0:178 offset1:186
	ds_read2_b32 v[82:83], v62 offset0:243 offset1:251
	s_waitcnt lgkmcnt(3)
	v_bfe_u32 v2, v78, 16, 1
	v_add3_u32 v2, v78, v2, s54
	s_waitcnt lgkmcnt(2)
	v_bfe_u32 v47, v76, 16, 1
	ds_read2_b32 v[84:85], v45 offset0:52 offset1:60
	v_lshrrev_b32_e32 v2, 16, v2
	v_add3_u32 v47, v76, v47, s54
	ds_read2_b32 v[86:87], v45 offset0:117 offset1:125
	v_and_or_b32 v72, v47, s55, v2
	s_waitcnt lgkmcnt(3)
	v_bfe_u32 v2, v80, 16, 1
	v_add3_u32 v2, v80, v2, s54
	s_waitcnt lgkmcnt(2)
	v_bfe_u32 v47, v82, 16, 1
	ds_read2_b32 v[88:89], v45 offset0:182 offset1:190
	v_lshrrev_b32_e32 v2, 16, v2
	v_add3_u32 v47, v82, v47, s54
	ds_read2_b32 v[90:91], v45 offset0:247 offset1:255
	v_and_or_b32 v73, v47, s55, v2
	s_waitcnt lgkmcnt(3)
	v_bfe_u32 v2, v84, 16, 1
	v_add3_u32 v2, v84, v2, s54
	s_waitcnt lgkmcnt(2)
	v_bfe_u32 v47, v86, 16, 1
	v_lshrrev_b32_e32 v2, 16, v2
	v_add3_u32 v47, v86, v47, s54
	v_and_or_b32 v74, v47, s55, v2
	s_waitcnt lgkmcnt(1)
	v_bfe_u32 v2, v88, 16, 1
	v_add3_u32 v2, v88, v2, s54
	s_waitcnt lgkmcnt(0)
	v_bfe_u32 v45, v90, 16, 1
	v_lshrrev_b32_e32 v2, 16, v2
	v_add3_u32 v45, v90, v45, s54
	v_or_b32_e32 v92, s8, v69
	v_and_or_b32 v75, v45, s55, v2
	v_ashrrev_i32_e32 v93, 31, v92
	v_bfe_u32 v2, v79, 16, 1
	v_lshlrev_b64 v[92:93], 9, v[92:93]
	v_add3_u32 v2, v79, v2, s54
	v_bfe_u32 v45, v77, 16, 1
	v_lshl_add_u64 v[92:93], v[56:57], 0, v[92:93]
	v_lshrrev_b32_e32 v2, 16, v2
	v_add3_u32 v45, v77, v45, s54
	global_store_dwordx4 v[92:93], v[72:75], off
	v_or_b32_e32 v76, s8, v70
	v_ashrrev_i32_e32 v77, 31, v76
	v_and_or_b32 v72, v45, s55, v2
	v_bfe_u32 v2, v81, 16, 1
	v_add3_u32 v2, v81, v2, s54
	v_bfe_u32 v45, v83, 16, 1
	v_lshrrev_b32_e32 v2, 16, v2
	v_add3_u32 v45, v83, v45, s54
	v_and_or_b32 v73, v45, s55, v2
	v_bfe_u32 v2, v85, 16, 1
	v_add3_u32 v2, v85, v2, s54
	v_bfe_u32 v45, v87, 16, 1
	v_lshrrev_b32_e32 v2, 16, v2
	v_add3_u32 v45, v87, v45, s54
	v_and_or_b32 v74, v45, s55, v2
	v_bfe_u32 v2, v89, 16, 1
	v_add3_u32 v2, v89, v2, s54
	v_bfe_u32 v45, v91, 16, 1
	v_lshrrev_b32_e32 v2, 16, v2
	v_add3_u32 v45, v91, v45, s54
	v_lshlrev_b64 v[76:77], 9, v[76:77]
	v_and_or_b32 v75, v45, s55, v2
	v_lshl_add_u64 v[56:57], v[56:57], 0, v[76:77]
	global_store_dwordx4 v[56:57], v[72:75], off
	s_waitcnt lgkmcnt(0)
	s_mov_b64 s[8:9], 0
.LBB0_22:
	s_andn2_b64 vcc, exec, s[8:9]
	s_cbranch_vccnz .LBB0_24
	s_and_b32 s8, s15, 0x7c0
	s_and_b32 s9, s42, 0x1ffc0
	v_or_b32_e32 v2, s9, v59
	s_lshl_b32 s40, s8, 2
	v_lshl_add_u64 v[56:57], v[48:49], 0, s[40:41]
	v_lshlrev_b32_e32 v2, 13, v2
	v_lshl_add_u64 v[56:57], v[56:57], 0, v[2:3]
	v_add_co_u32_e32 v76, vcc, 0x8000, v56
	v_add_u32_e32 v2, 0x410, v60
	s_nop 0
	v_addc_co_u32_e32 v77, vcc, 0, v57, vcc
	v_add_co_u32_e32 v80, vcc, 0x10000, v56
	global_load_dwordx4 v[72:75], v[56:57], off nt
	s_nop 0
	global_load_dwordx4 v[76:79], v[76:77], off nt
	v_addc_co_u32_e32 v81, vcc, 0, v57, vcc
	v_add_co_u32_e32 v84, vcc, 0x18000, v56
	s_lshl_b32 s40, s9, 1
	s_nop 0
	v_addc_co_u32_e32 v85, vcc, 0, v57, vcc
	global_load_dwordx4 v[80:83], v[80:81], off nt
	s_nop 0
	global_load_dwordx4 v[84:87], v[84:85], off nt
	v_add_co_u32_e32 v88, vcc, 0x20000, v56
	s_nop 1
	v_addc_co_u32_e32 v89, vcc, 0, v57, vcc
	v_add_co_u32_e32 v92, vcc, 0x28000, v56
	s_nop 1
	v_addc_co_u32_e32 v93, vcc, 0, v57, vcc
	global_load_dwordx4 v[88:91], v[88:89], off nt
	s_nop 0
	global_load_dwordx4 v[92:95], v[92:93], off nt
	v_add_co_u32_e32 v96, vcc, 0x30000, v56
	s_nop 1
	v_addc_co_u32_e32 v97, vcc, 0, v57, vcc
	v_add_co_u32_e32 v100, vcc, 0x38000, v56
	s_nop 1
	v_addc_co_u32_e32 v101, vcc, 0, v57, vcc
	global_load_dwordx4 v[96:99], v[96:97], off nt
	s_nop 0
	global_load_dwordx4 v[100:103], v[100:101], off nt
	v_add_co_u32_e32 v104, vcc, 0x40000, v56
	s_nop 1
	v_addc_co_u32_e32 v105, vcc, 0, v57, vcc
	v_add_co_u32_e32 v108, vcc, 0x48000, v56
	s_nop 1
	v_addc_co_u32_e32 v109, vcc, 0, v57, vcc
	global_load_dwordx4 v[104:107], v[104:105], off nt
	s_nop 0
	global_load_dwordx4 v[108:111], v[108:109], off nt
	v_add_co_u32_e32 v112, vcc, 0x50000, v56
	s_nop 1
	v_addc_co_u32_e32 v113, vcc, 0, v57, vcc
	v_add_co_u32_e32 v116, vcc, 0x58000, v56
	s_nop 1
	v_addc_co_u32_e32 v117, vcc, 0, v57, vcc
	global_load_dwordx4 v[112:115], v[112:113], off nt
	s_nop 0
	global_load_dwordx4 v[116:119], v[116:117], off nt
	v_add_co_u32_e32 v120, vcc, 0x60000, v56
	s_nop 1
	v_addc_co_u32_e32 v121, vcc, 0, v57, vcc
	v_add_co_u32_e32 v124, vcc, 0x68000, v56
	s_nop 1
	v_addc_co_u32_e32 v125, vcc, 0, v57, vcc
	global_load_dwordx4 v[120:123], v[120:121], off nt
	s_nop 0
	global_load_dwordx4 v[124:127], v[124:125], off nt
	v_add_co_u32_e32 v128, vcc, 0x70000, v56
	s_nop 1
	v_addc_co_u32_e32 v129, vcc, 0, v57, vcc
	global_load_dwordx4 v[128:131], v[128:129], off nt
	v_add_co_u32_e32 v56, vcc, 0x78000, v56
	s_nop 1
	v_addc_co_u32_e32 v57, vcc, 0, v57, vcc
	global_load_dwordx4 v[132:135], v[56:57], off nt
	s_waitcnt vmcnt(15)
; DI unsigned pk2w(float lo, float hi) { return f2bfw(lo) | (f2bfw(hi) << 16); }
; DI void transpose_item(const float* W, int K, int N, bf16_t* WT, int mode, float* scr, int item, int lane) {
;     ...
;     for (int i = 0; i < 16; ++i) v[i] = __builtin_nontemporal_load((const f32x4*)(W + (size_t)(k0 + 4 * i + (lane >> 4)) * N + n0 + 4 * (lane & 15)));
; #pragma unroll
;     for (int i = 0; i < 16; ++i) { float* d = scr + (4 * i + (lane >> 4)) * 65 + 4 * (lane & 15); d[0] = v[i][0]; d[1] = v[i][1]; d[2] = v[i][2]; d[3] = v[i][3]; }
;     __builtin_amdgcn_s_waitcnt(0); __builtin_amdgcn_wave_barrier();
;     const int c = lane & 7;
; #pragma unroll
;     for (int j = 0; j < 8; ++j) { const int n = (lane >> 3) + 8 * j; const float* sp = scr + (8 * c) * 65 + n;
;         u32x4 o; o.x = pk2w(sp[0 * 65], sp[1 * 65]); o.y = pk2w(sp[2 * 65], sp[3 * 65]); o.z = pk2w(sp[4 * 65], sp[5 * 65]); o.w = pk2w(sp[6 * 65], sp[7 * 65]);
;         *(u32x4*)(WT + (size_t)(drow0 + n) * K + k0 + 8 * c) = o; }
	ds_write2_b32 v60, v72, v73 offset1:1
	ds_write2_b32 v60, v74, v75 offset0:2 offset1:3
	s_waitcnt vmcnt(14)
	ds_write2_b32 v2, v76, v77 offset1:1
	v_add_u32_e32 v2, 0x418, v60
	ds_write2_b32 v2, v78, v79 offset1:1
	v_add_u32_e32 v2, 0x820, v60
	v_lshl_add_u64 v[56:57], v[20:21], 0, s[40:41]
	s_waitcnt vmcnt(13)
	ds_write2_b32 v2, v80, v81 offset1:1
	v_add_u32_e32 v2, 0x828, v60
	ds_write2_b32 v2, v82, v83 offset1:1
	v_add_u32_e32 v2, 0xc30, v60
	s_waitcnt vmcnt(12)
	ds_write2_b32 v2, v84, v85 offset1:1
	v_add_u32_e32 v2, 0xc38, v60
	ds_write2_b32 v2, v86, v87 offset1:1
	v_add_u32_e32 v2, 0x1040, v60
	s_waitcnt vmcnt(11)
	ds_write2_b32 v2, v88, v89 offset1:1
	v_add_u32_e32 v2, 0x1048, v60
	ds_write2_b32 v2, v90, v91 offset1:1
	v_add_u32_e32 v2, 0x1450, v60
	s_waitcnt vmcnt(10)
	ds_write2_b32 v2, v92, v93 offset1:1
	v_add_u32_e32 v2, 0x1458, v60
	ds_write2_b32 v2, v94, v95 offset1:1
	v_add_u32_e32 v2, 0x1860, v60
	s_waitcnt vmcnt(9)
	ds_write2_b32 v2, v96, v97 offset1:1
	v_add_u32_e32 v2, 0x1868, v60
	ds_write2_b32 v2, v98, v99 offset1:1
	v_add_u32_e32 v2, 0x1c70, v60
	s_waitcnt vmcnt(8)
	ds_write2_b32 v2, v100, v101 offset1:1
	v_add_u32_e32 v2, 0x1c78, v60
	ds_write2_b32 v2, v102, v103 offset1:1
	v_add_u32_e32 v2, 0x2080, v60
	s_waitcnt vmcnt(7)
	ds_write2_b32 v2, v104, v105 offset1:1
	v_add_u32_e32 v2, 0x2088, v60
	ds_write2_b32 v2, v106, v107 offset1:1
	v_add_u32_e32 v2, 0x2490, v60
	s_waitcnt vmcnt(6)
	ds_write2_b32 v2, v108, v109 offset1:1
	v_add_u32_e32 v2, 0x2498, v60
	ds_write2_b32 v2, v110, v111 offset1:1
	v_add_u32_e32 v2, 0x28a0, v60
	s_waitcnt vmcnt(5)
	ds_write2_b32 v2, v112, v113 offset1:1
	v_add_u32_e32 v2, 0x28a8, v60
	ds_write2_b32 v2, v114, v115 offset1:1
	v_add_u32_e32 v2, 0x2cb0, v60
	s_waitcnt vmcnt(4)
	ds_write2_b32 v2, v116, v117 offset1:1
	v_add_u32_e32 v2, 0x2cb8, v60
	ds_write2_b32 v2, v118, v119 offset1:1
	v_add_u32_e32 v2, 0x30c0, v60
	s_waitcnt vmcnt(3)
	ds_write2_b32 v2, v120, v121 offset1:1
	v_add_u32_e32 v2, 0x30c8, v60
	ds_write2_b32 v2, v122, v123 offset1:1
	v_add_u32_e32 v2, 0x34d0, v60
	s_waitcnt vmcnt(2)
	ds_write2_b32 v2, v124, v125 offset1:1
	v_add_u32_e32 v2, 0x34d8, v60
	ds_write2_b32 v2, v126, v127 offset1:1
	v_add_u32_e32 v2, 0x38e0, v60
	s_waitcnt vmcnt(1)
	ds_write2_b32 v2, v128, v129 offset1:1
	v_add_u32_e32 v2, 0x38e8, v60
	ds_write2_b32 v2, v130, v131 offset1:1
	v_add_u32_e32 v2, 0x3cf0, v60
	s_waitcnt vmcnt(0)
	ds_write2_b32 v2, v132, v133 offset1:1
	v_add_u32_e32 v2, 0x3cf8, v60
	ds_write2_b32 v2, v134, v135 offset1:1
	s_waitcnt vmcnt(0) expcnt(0) lgkmcnt(0)
	ds_read2_b32 v[76:77], v62 offset1:8
	ds_read2_b32 v[78:79], v62 offset0:65 offset1:73
	ds_read2_b32 v[80:81], v62 offset0:130 offset1:138
	ds_read2_b32 v[82:83], v62 offset0:195 offset1:203
	s_waitcnt lgkmcnt(3)
	v_bfe_u32 v2, v76, 16, 1
	v_add3_u32 v2, v76, v2, s54
	s_waitcnt lgkmcnt(2)
	v_bfe_u32 v45, v78, 16, 1
	v_lshrrev_b32_e32 v2, 16, v2
	v_add3_u32 v45, v78, v45, s54
	v_and_or_b32 v72, v45, s55, v2
	v_add_u32_e32 v45, 0x400, v62
	ds_read2_b32 v[84:85], v45 offset0:4 offset1:12
	ds_read2_b32 v[86:87], v45 offset0:69 offset1:77
	s_waitcnt lgkmcnt(3)
	v_bfe_u32 v2, v80, 16, 1
	v_add3_u32 v2, v80, v2, s54
	s_waitcnt lgkmcnt(2)
	v_bfe_u32 v47, v82, 16, 1
	ds_read2_b32 v[88:89], v45 offset0:134 offset1:142
	v_lshrrev_b32_e32 v2, 16, v2
	v_add3_u32 v47, v82, v47, s54
	ds_read2_b32 v[90:91], v45 offset0:199 offset1:207
	v_and_or_b32 v73, v47, s55, v2
	s_waitcnt lgkmcnt(3)
	v_bfe_u32 v2, v84, 16, 1
	v_add3_u32 v2, v84, v2, s54
	s_waitcnt lgkmcnt(2)
	v_bfe_u32 v47, v86, 16, 1
	v_lshrrev_b32_e32 v2, 16, v2
	v_add3_u32 v47, v86, v47, s54
	v_and_or_b32 v74, v47, s55, v2
	s_waitcnt lgkmcnt(1)
	v_bfe_u32 v2, v88, 16, 1
	v_add3_u32 v2, v88, v2, s54
	s_waitcnt lgkmcnt(0)
	v_bfe_u32 v47, v90, 16, 1
	v_lshrrev_b32_e32 v2, 16, v2
	v_add3_u32 v47, v90, v47, s54
	v_and_or_b32 v75, v47, s55, v2
	v_or_b32_e32 v2, s8, v61
	v_lshlrev_b32_e32 v2, 12, v2
	v_lshl_add_u64 v[92:93], v[56:57], 0, v[2:3]
	v_bfe_u32 v2, v77, 16, 1
	v_add3_u32 v2, v77, v2, s54
	v_bfe_u32 v47, v79, 16, 1
	v_lshrrev_b32_e32 v2, 16, v2
	v_add3_u32 v47, v79, v47, s54
	global_store_dwordx4 v[92:93], v[72:75], off
	ds_read2_b32 v[76:77], v62 offset0:16 offset1:24
	s_nop 0
	v_and_or_b32 v72, v47, s55, v2
	v_bfe_u32 v2, v81, 16, 1
	v_add3_u32 v2, v81, v2, s54
	v_bfe_u32 v47, v83, 16, 1
	v_lshrrev_b32_e32 v2, 16, v2
	v_add3_u32 v47, v83, v47, s54
	v_and_or_b32 v73, v47, s55, v2
	v_bfe_u32 v2, v85, 16, 1
	v_add3_u32 v2, v85, v2, s54
	v_bfe_u32 v47, v87, 16, 1
	v_lshrrev_b32_e32 v2, 16, v2
	v_add3_u32 v47, v87, v47, s54
	v_and_or_b32 v74, v47, s55, v2
	v_bfe_u32 v2, v89, 16, 1
	v_add3_u32 v2, v89, v2, s54
	v_bfe_u32 v47, v91, 16, 1
	v_lshrrev_b32_e32 v2, 16, v2
	v_add3_u32 v47, v91, v47, s54
	v_and_or_b32 v75, v47, s55, v2
	v_or_b32_e32 v2, s8, v63
	v_lshlrev_b32_e32 v2, 12, v2
	v_lshl_add_u64 v[78:79], v[56:57], 0, v[2:3]
	global_store_dwordx4 v[78:79], v[72:75], off
	ds_read2_b32 v[78:79], v62 offset0:81 offset1:89
	ds_read2_b32 v[80:81], v62 offset0:146 offset1:154
	ds_read2_b32 v[82:83], v62 offset0:211 offset1:219
	s_waitcnt lgkmcnt(3)
	v_bfe_u32 v2, v76, 16, 1
	v_add3_u32 v2, v76, v2, s54
	s_waitcnt lgkmcnt(2)
	v_bfe_u32 v47, v78, 16, 1
	ds_read2_b32 v[84:85], v45 offset0:20 offset1:28
	v_lshrrev_b32_e32 v2, 16, v2
	v_add3_u32 v47, v78, v47, s54
	ds_read2_b32 v[86:87], v45 offset0:85 offset1:93
	v_and_or_b32 v72, v47, s55, v2
	s_waitcnt lgkmcnt(3)
	v_bfe_u32 v2, v80, 16, 1
	v_add3_u32 v2, v80, v2, s54
	s_waitcnt lgkmcnt(2)
	v_bfe_u32 v47, v82, 16, 1
	ds_read2_b32 v[88:89], v45 offset0:150 offset1:158
	v_lshrrev_b32_e32 v2, 16, v2
	v_add3_u32 v47, v82, v47, s54
	ds_read2_b32 v[90:91], v45 offset0:215 offset1:223
	v_and_or_b32 v73, v47, s55, v2
	s_waitcnt lgkmcnt(3)
; DI unsigned pk2w(float lo, float hi) { return f2bfw(lo) | (f2bfw(hi) << 16); }
; DI void transpose_item(const float* W, int K, int N, bf16_t* WT, int mode, float* scr, int item, int lane) {
;     ...
;     const int c = lane & 7;
; #pragma unroll
;     for (int j = 0; j < 8; ++j) { const int n = (lane >> 3) + 8 * j; const float* sp = scr + (8 * c) * 65 + n;
;         u32x4 o; o.x = pk2w(sp[0 * 65], sp[1 * 65]); o.y = pk2w(sp[2 * 65], sp[3 * 65]); o.z = pk2w(sp[4 * 65], sp[5 * 65]); o.w = pk2w(sp[6 * 65], sp[7 * 65]);
;         *(u32x4*)(WT + (size_t)(drow0 + n) * K + k0 + 8 * c) = o; }
;     __builtin_amdgcn_s_waitcnt(0); __builtin_amdgcn_wave_barrier();
	v_bfe_u32 v2, v84, 16, 1
	v_add3_u32 v2, v84, v2, s54
	s_waitcnt lgkmcnt(2)
	v_bfe_u32 v47, v86, 16, 1
	v_lshrrev_b32_e32 v2, 16, v2
	v_add3_u32 v47, v86, v47, s54
	v_and_or_b32 v74, v47, s55, v2
	s_waitcnt lgkmcnt(1)
	v_bfe_u32 v2, v88, 16, 1
	v_add3_u32 v2, v88, v2, s54
	s_waitcnt lgkmcnt(0)
	v_bfe_u32 v47, v90, 16, 1
	v_lshrrev_b32_e32 v2, 16, v2
	v_add3_u32 v47, v90, v47, s54
	v_and_or_b32 v75, v47, s55, v2
	v_or_b32_e32 v2, s8, v64
	v_lshlrev_b32_e32 v2, 12, v2
	v_lshl_add_u64 v[92:93], v[56:57], 0, v[2:3]
	v_bfe_u32 v2, v77, 16, 1
	v_add3_u32 v2, v77, v2, s54
	v_bfe_u32 v47, v79, 16, 1
	v_lshrrev_b32_e32 v2, 16, v2
	v_add3_u32 v47, v79, v47, s54
	global_store_dwordx4 v[92:93], v[72:75], off
	ds_read2_b32 v[76:77], v62 offset0:32 offset1:40
	s_nop 0
	v_and_or_b32 v72, v47, s55, v2
	v_bfe_u32 v2, v81, 16, 1
	v_add3_u32 v2, v81, v2, s54
	v_bfe_u32 v47, v83, 16, 1
	v_lshrrev_b32_e32 v2, 16, v2
	v_add3_u32 v47, v83, v47, s54
	v_and_or_b32 v73, v47, s55, v2
	v_bfe_u32 v2, v85, 16, 1
	v_add3_u32 v2, v85, v2, s54
	v_bfe_u32 v47, v87, 16, 1
	v_lshrrev_b32_e32 v2, 16, v2
	v_add3_u32 v47, v87, v47, s54
	v_and_or_b32 v74, v47, s55, v2
	v_bfe_u32 v2, v89, 16, 1
	v_add3_u32 v2, v89, v2, s54
	v_bfe_u32 v47, v91, 16, 1
	v_lshrrev_b32_e32 v2, 16, v2
	v_add3_u32 v47, v91, v47, s54
	v_and_or_b32 v75, v47, s55, v2
	v_or_b32_e32 v2, s8, v65
	v_lshlrev_b32_e32 v2, 12, v2
	v_lshl_add_u64 v[78:79], v[56:57], 0, v[2:3]
	global_store_dwordx4 v[78:79], v[72:75], off
	ds_read2_b32 v[78:79], v62 offset0:97 offset1:105
	ds_read2_b32 v[80:81], v62 offset0:162 offset1:170
	ds_read2_b32 v[82:83], v62 offset0:227 offset1:235
	s_waitcnt lgkmcnt(3)
	v_bfe_u32 v2, v76, 16, 1
	v_add3_u32 v2, v76, v2, s54
	s_waitcnt lgkmcnt(2)
	v_bfe_u32 v47, v78, 16, 1
	ds_read2_b32 v[84:85], v45 offset0:36 offset1:44
	v_lshrrev_b32_e32 v2, 16, v2
	v_add3_u32 v47, v78, v47, s54
	ds_read2_b32 v[86:87], v45 offset0:101 offset1:109
	v_and_or_b32 v72, v47, s55, v2
	s_waitcnt lgkmcnt(3)
	v_bfe_u32 v2, v80, 16, 1
	v_add3_u32 v2, v80, v2, s54
	s_waitcnt lgkmcnt(2)
	v_bfe_u32 v47, v82, 16, 1
	ds_read2_b32 v[88:89], v45 offset0:166 offset1:174
	v_lshrrev_b32_e32 v2, 16, v2
	v_add3_u32 v47, v82, v47, s54
	ds_read2_b32 v[90:91], v45 offset0:231 offset1:239
	v_and_or_b32 v73, v47, s55, v2
	s_waitcnt lgkmcnt(3)
	v_bfe_u32 v2, v84, 16, 1
	v_add3_u32 v2, v84, v2, s54
	s_waitcnt lgkmcnt(2)
	v_bfe_u32 v47, v86, 16, 1
	v_lshrrev_b32_e32 v2, 16, v2
	v_add3_u32 v47, v86, v47, s54
	v_and_or_b32 v74, v47, s55, v2
	s_waitcnt lgkmcnt(1)
	v_bfe_u32 v2, v88, 16, 1
	v_add3_u32 v2, v88, v2, s54
	s_waitcnt lgkmcnt(0)
	v_bfe_u32 v47, v90, 16, 1
	v_lshrrev_b32_e32 v2, 16, v2
	v_add3_u32 v47, v90, v47, s54
	v_and_or_b32 v75, v47, s55, v2
	v_or_b32_e32 v2, s8, v67
	v_lshlrev_b32_e32 v2, 12, v2
	v_lshl_add_u64 v[92:93], v[56:57], 0, v[2:3]
	v_bfe_u32 v2, v77, 16, 1
	v_add3_u32 v2, v77, v2, s54
	v_bfe_u32 v47, v79, 16, 1
	v_lshrrev_b32_e32 v2, 16, v2
	v_add3_u32 v47, v79, v47, s54
	global_store_dwordx4 v[92:93], v[72:75], off
	ds_read2_b32 v[76:77], v62 offset0:48 offset1:56
	s_nop 0
	v_and_or_b32 v72, v47, s55, v2
	v_bfe_u32 v2, v81, 16, 1
	v_add3_u32 v2, v81, v2, s54
	v_bfe_u32 v47, v83, 16, 1
	v_lshrrev_b32_e32 v2, 16, v2
	v_add3_u32 v47, v83, v47, s54
	v_and_or_b32 v73, v47, s55, v2
	v_bfe_u32 v2, v85, 16, 1
	v_add3_u32 v2, v85, v2, s54
	v_bfe_u32 v47, v87, 16, 1
	v_lshrrev_b32_e32 v2, 16, v2
	v_add3_u32 v47, v87, v47, s54
	v_and_or_b32 v74, v47, s55, v2
	v_bfe_u32 v2, v89, 16, 1
	v_add3_u32 v2, v89, v2, s54
	v_bfe_u32 v47, v91, 16, 1
	v_lshrrev_b32_e32 v2, 16, v2
	v_add3_u32 v47, v91, v47, s54
	v_and_or_b32 v75, v47, s55, v2
	v_or_b32_e32 v2, s8, v68
	v_lshlrev_b32_e32 v2, 12, v2
	v_lshl_add_u64 v[78:79], v[56:57], 0, v[2:3]
	global_store_dwordx4 v[78:79], v[72:75], off
	ds_read2_b32 v[78:79], v62 offset0:113 offset1:121
	ds_read2_b32 v[80:81], v62 offset0:178 offset1:186
	ds_read2_b32 v[82:83], v62 offset0:243 offset1:251
	s_waitcnt lgkmcnt(3)
	v_bfe_u32 v2, v76, 16, 1
	v_add3_u32 v2, v76, v2, s54
	s_waitcnt lgkmcnt(2)
	v_bfe_u32 v47, v78, 16, 1
	ds_read2_b32 v[84:85], v45 offset0:52 offset1:60
	v_lshrrev_b32_e32 v2, 16, v2
	v_add3_u32 v47, v78, v47, s54
	ds_read2_b32 v[86:87], v45 offset0:117 offset1:125
	v_and_or_b32 v72, v47, s55, v2
	s_waitcnt lgkmcnt(3)
	v_bfe_u32 v2, v80, 16, 1
	v_add3_u32 v2, v80, v2, s54
	s_waitcnt lgkmcnt(2)
	v_bfe_u32 v47, v82, 16, 1
	ds_read2_b32 v[88:89], v45 offset0:182 offset1:190
	v_lshrrev_b32_e32 v2, 16, v2
	v_add3_u32 v47, v82, v47, s54
	ds_read2_b32 v[90:91], v45 offset0:247 offset1:255
	v_and_or_b32 v73, v47, s55, v2
	s_waitcnt lgkmcnt(3)
	v_bfe_u32 v2, v84, 16, 1
	v_add3_u32 v2, v84, v2, s54
	s_waitcnt lgkmcnt(2)
	v_bfe_u32 v47, v86, 16, 1
	v_lshrrev_b32_e32 v2, 16, v2
	v_add3_u32 v47, v86, v47, s54
	v_and_or_b32 v74, v47, s55, v2
	s_waitcnt lgkmcnt(1)
	v_bfe_u32 v2, v88, 16, 1
	v_add3_u32 v2, v88, v2, s54
	s_waitcnt lgkmcnt(0)
	v_bfe_u32 v45, v90, 16, 1
	v_lshrrev_b32_e32 v2, 16, v2
	v_add3_u32 v45, v90, v45, s54
	v_and_or_b32 v75, v45, s55, v2
	v_or_b32_e32 v2, s8, v69
	v_lshlrev_b32_e32 v2, 12, v2
	v_lshl_add_u64 v[92:93], v[56:57], 0, v[2:3]
	v_bfe_u32 v2, v77, 16, 1
	v_add3_u32 v2, v77, v2, s54
	v_bfe_u32 v45, v79, 16, 1
	v_lshrrev_b32_e32 v2, 16, v2
	v_add3_u32 v45, v79, v45, s54
	global_store_dwordx4 v[92:93], v[72:75], off
	s_nop 1
	v_and_or_b32 v72, v45, s55, v2
	v_bfe_u32 v2, v81, 16, 1
	v_add3_u32 v2, v81, v2, s54
	v_bfe_u32 v45, v83, 16, 1
	v_lshrrev_b32_e32 v2, 16, v2
	v_add3_u32 v45, v83, v45, s54
	v_and_or_b32 v73, v45, s55, v2
	v_bfe_u32 v2, v85, 16, 1
	v_add3_u32 v2, v85, v2, s54
	v_bfe_u32 v45, v87, 16, 1
	v_lshrrev_b32_e32 v2, 16, v2
	v_add3_u32 v45, v87, v45, s54
	v_and_or_b32 v74, v45, s55, v2
	v_bfe_u32 v2, v89, 16, 1
	v_add3_u32 v2, v89, v2, s54
	v_bfe_u32 v45, v91, 16, 1
	v_lshrrev_b32_e32 v2, 16, v2
	v_add3_u32 v45, v91, v45, s54
	v_and_or_b32 v75, v45, s55, v2
	v_or_b32_e32 v2, s8, v70
	v_lshlrev_b32_e32 v2, 12, v2
	v_lshl_add_u64 v[56:57], v[56:57], 0, v[2:3]
	global_store_dwordx4 v[56:57], v[72:75], off
	s_waitcnt lgkmcnt(0)

; DI void transpose_item(const float* W, int K, int N, bf16_t* WT, int mode, float* scr, int item, int lane) {
;     const int nblk = N / 64, kb = item / nblk, nb = item % nblk, k0 = 64 * kb, n0 = 64 * nb;
;     int drow0 = n0;
;     if (mode == 1) { const int seg = n0 >> 10; const int dst = seg < 2 ? seg : (seg == 2 ? 6 : seg - 1); drow0 = dst * 1024 + (n0 & 1023); }
;     else if (mode == 2) { drow0 = n0 < DFF ? (n0 / 128) * 256 + (n0 % 128) : ((n0 - DFF) / 128) * 256 + 128 + ((n0 - DFF) % 128); }
;     else if (mode == 3) { drow0 = (n0 / 128) * 256 + (n0 % 128); }
;     else if (mode == 4) { drow0 = (n0 / 128) * 256 + 128 + (n0 % 128); }
;     f32x4 v[16];
; #pragma unroll
;     for (int i = 0; i < 16; ++i) v[i] = __builtin_nontemporal_load((const f32x4*)(W + (size_t)(k0 + 4 * i + (lane >> 4)) * N + n0 + 4 * (lane & 15)));
; #pragma unroll
;     for (int i = 0; i < 16; ++i) { float* d = scr + (4 * i + (lane >> 4)) * 65 + 4 * (lane & 15); d[0] = v[i][0]; d[1] = v[i][1]; d[2] = v[i][2]; d[3] = v[i][3]; }
;     __builtin_amdgcn_s_waitcnt(0); __builtin_amdgcn_wave_barrier();
.LBB0_25:
	s_andn2_b64 vcc, exec, s[8:9]
	s_cbranch_vccnz .LBB0_27
	s_add_i32 s9, s42, 0xfffed300
	s_and_b32 s8, s15, 0x7c0
	s_and_b32 s9, s9, 0x1c0
	v_or_b32_e32 v2, s9, v59
	s_lshl_b32 s40, s8, 2
	v_lshl_add_u64 v[56:57], v[50:51], 0, s[40:41]
	v_lshlrev_b32_e32 v2, 13, v2
	v_lshl_add_u64 v[56:57], v[56:57], 0, v[2:3]
	v_add_co_u32_e32 v76, vcc, 0x8000, v56
	v_add_u32_e32 v2, 0x410, v60
	s_nop 0
	v_addc_co_u32_e32 v77, vcc, 0, v57, vcc
	v_add_co_u32_e32 v80, vcc, 0x10000, v56
	global_load_dwordx4 v[72:75], v[56:57], off nt
	s_nop 0
	global_load_dwordx4 v[76:79], v[76:77], off nt
	v_addc_co_u32_e32 v81, vcc, 0, v57, vcc
	v_add_co_u32_e32 v84, vcc, 0x18000, v56
	s_lshl_b32 s40, s9, 1
	s_nop 0
	v_addc_co_u32_e32 v85, vcc, 0, v57, vcc
	global_load_dwordx4 v[80:83], v[80:81], off nt
	s_nop 0
	global_load_dwordx4 v[84:87], v[84:85], off nt
	v_add_co_u32_e32 v88, vcc, 0x20000, v56
	s_nop 1
	v_addc_co_u32_e32 v89, vcc, 0, v57, vcc
	v_add_co_u32_e32 v92, vcc, 0x28000, v56
	s_nop 1
	v_addc_co_u32_e32 v93, vcc, 0, v57, vcc
	global_load_dwordx4 v[88:91], v[88:89], off nt
	s_nop 0
	global_load_dwordx4 v[92:95], v[92:93], off nt
	v_add_co_u32_e32 v96, vcc, 0x30000, v56
	s_nop 1
	v_addc_co_u32_e32 v97, vcc, 0, v57, vcc
	v_add_co_u32_e32 v100, vcc, 0x38000, v56
	s_nop 1
	v_addc_co_u32_e32 v101, vcc, 0, v57, vcc
	global_load_dwordx4 v[96:99], v[96:97], off nt
	s_nop 0
	global_load_dwordx4 v[100:103], v[100:101], off nt
	v_add_co_u32_e32 v104, vcc, 0x40000, v56
	s_nop 1
	v_addc_co_u32_e32 v105, vcc, 0, v57, vcc
	v_add_co_u32_e32 v108, vcc, 0x48000, v56
	s_nop 1
	v_addc_co_u32_e32 v109, vcc, 0, v57, vcc
	global_load_dwordx4 v[104:107], v[104:105], off nt
	s_nop 0
	global_load_dwordx4 v[108:111], v[108:109], off nt
	v_add_co_u32_e32 v112, vcc, 0x50000, v56
	s_nop 1
	v_addc_co_u32_e32 v113, vcc, 0, v57, vcc
	v_add_co_u32_e32 v116, vcc, 0x58000, v56
	s_nop 1
	v_addc_co_u32_e32 v117, vcc, 0, v57, vcc
	global_load_dwordx4 v[112:115], v[112:113], off nt
	s_nop 0
	global_load_dwordx4 v[116:119], v[116:117], off nt
	v_add_co_u32_e32 v120, vcc, 0x60000, v56
	s_nop 1
	v_addc_co_u32_e32 v121, vcc, 0, v57, vcc
	v_add_co_u32_e32 v124, vcc, 0x68000, v56
	s_nop 1
	v_addc_co_u32_e32 v125, vcc, 0, v57, vcc
	global_load_dwordx4 v[120:123], v[120:121], off nt
	s_nop 0
	global_load_dwordx4 v[124:127], v[124:125], off nt
	v_add_co_u32_e32 v128, vcc, 0x70000, v56
	s_nop 1
	v_addc_co_u32_e32 v129, vcc, 0, v57, vcc
	global_load_dwordx4 v[128:131], v[128:129], off nt
	v_add_co_u32_e32 v56, vcc, 0x78000, v56
	s_nop 1
	v_addc_co_u32_e32 v57, vcc, 0, v57, vcc
	global_load_dwordx4 v[132:135], v[56:57], off nt
	s_waitcnt vmcnt(15)
	ds_write2_b32 v60, v72, v73 offset1:1
	ds_write2_b32 v60, v74, v75 offset0:2 offset1:3
	s_waitcnt vmcnt(14)
	ds_write2_b32 v2, v76, v77 offset1:1
	v_add_u32_e32 v2, 0x418, v60
	ds_write2_b32 v2, v78, v79 offset1:1
	v_add_u32_e32 v2, 0x820, v60
	v_lshl_add_u64 v[56:57], v[22:23], 0, s[40:41]
	s_waitcnt vmcnt(13)
	ds_write2_b32 v2, v80, v81 offset1:1
	v_add_u32_e32 v2, 0x828, v60
	ds_write2_b32 v2, v82, v83 offset1:1
	v_add_u32_e32 v2, 0xc30, v60
	s_waitcnt vmcnt(12)
	ds_write2_b32 v2, v84, v85 offset1:1
	v_add_u32_e32 v2, 0xc38, v60
	ds_write2_b32 v2, v86, v87 offset1:1
	v_add_u32_e32 v2, 0x1040, v60
	s_waitcnt vmcnt(11)
	ds_write2_b32 v2, v88, v89 offset1:1
	v_add_u32_e32 v2, 0x1048, v60
	ds_write2_b32 v2, v90, v91 offset1:1
	v_add_u32_e32 v2, 0x1450, v60
	s_waitcnt vmcnt(10)
	ds_write2_b32 v2, v92, v93 offset1:1
	v_add_u32_e32 v2, 0x1458, v60
	ds_write2_b32 v2, v94, v95 offset1:1
	v_add_u32_e32 v2, 0x1860, v60
	s_waitcnt vmcnt(9)
	ds_write2_b32 v2, v96, v97 offset1:1
	v_add_u32_e32 v2, 0x1868, v60
	ds_write2_b32 v2, v98, v99 offset1:1
	v_add_u32_e32 v2, 0x1c70, v60
	s_waitcnt vmcnt(8)
	ds_write2_b32 v2, v100, v101 offset1:1
	v_add_u32_e32 v2, 0x1c78, v60
	ds_write2_b32 v2, v102, v103 offset1:1
	v_add_u32_e32 v2, 0x2080, v60
	s_waitcnt vmcnt(7)
	ds_write2_b32 v2, v104, v105 offset1:1
	v_add_u32_e32 v2, 0x2088, v60
	ds_write2_b32 v2, v106, v107 offset1:1
	v_add_u32_e32 v2, 0x2490, v60
	s_waitcnt vmcnt(6)
	ds_write2_b32 v2, v108, v109 offset1:1
	v_add_u32_e32 v2, 0x2498, v60
	ds_write2_b32 v2, v110, v111 offset1:1
	v_add_u32_e32 v2, 0x28a0, v60
	s_waitcnt vmcnt(5)
	ds_write2_b32 v2, v112, v113 offset1:1
	v_add_u32_e32 v2, 0x28a8, v60
	ds_write2_b32 v2, v114, v115 offset1:1
	v_add_u32_e32 v2, 0x2cb0, v60
	s_waitcnt vmcnt(4)
	ds_write2_b32 v2, v116, v117 offset1:1
	v_add_u32_e32 v2, 0x2cb8, v60
	ds_write2_b32 v2, v118, v119 offset1:1
	v_add_u32_e32 v2, 0x30c0, v60
	s_waitcnt vmcnt(3)
	ds_write2_b32 v2, v120, v121 offset1:1
	v_add_u32_e32 v2, 0x30c8, v60
	ds_write2_b32 v2, v122, v123 offset1:1
	v_add_u32_e32 v2, 0x34d0, v60
	s_waitcnt vmcnt(2)
	ds_write2_b32 v2, v124, v125 offset1:1
	v_add_u32_e32 v2, 0x34d8, v60
	ds_write2_b32 v2, v126, v127 offset1:1
	v_add_u32_e32 v2, 0x38e0, v60
	s_waitcnt vmcnt(1)
	ds_write2_b32 v2, v128, v129 offset1:1
	v_add_u32_e32 v2, 0x38e8, v60
	ds_write2_b32 v2, v130, v131 offset1:1
	v_add_u32_e32 v2, 0x3cf0, v60
	s_waitcnt vmcnt(0)
	ds_write2_b32 v2, v132, v133 offset1:1
	v_add_u32_e32 v2, 0x3cf8, v60
	ds_write2_b32 v2, v134, v135 offset1:1
	s_waitcnt vmcnt(0) expcnt(0) lgkmcnt(0)
	ds_read2_b32 v[76:77], v62 offset1:8
	ds_read2_b32 v[78:79], v62 offset0:65 offset1:73
	ds_read2_b32 v[80:81], v62 offset0:130 offset1:138
	ds_read2_b32 v[82:83], v62 offset0:195 offset1:203
	s_waitcnt lgkmcnt(3)
	v_bfe_u32 v2, v76, 16, 1
	v_add3_u32 v2, v76, v2, s54
	s_waitcnt lgkmcnt(2)
	v_bfe_u32 v45, v78, 16, 1
	v_lshrrev_b32_e32 v2, 16, v2
	v_add3_u32 v45, v78, v45, s54
	v_and_or_b32 v72, v45, s55, v2
	v_add_u32_e32 v45, 0x400, v62
	ds_read2_b32 v[84:85], v45 offset0:4 offset1:12
	ds_read2_b32 v[86:87], v45 offset0:69 offset1:77
	s_waitcnt lgkmcnt(3)
; DI unsigned pk2w(float lo, float hi) { return f2bfw(lo) | (f2bfw(hi) << 16); }
; DI void transpose_item(const float* W, int K, int N, bf16_t* WT, int mode, float* scr, int item, int lane) {
;     ...
;     const int c = lane & 7;
; #pragma unroll
;     for (int j = 0; j < 8; ++j) { const int n = (lane >> 3) + 8 * j; const float* sp = scr + (8 * c) * 65 + n;
;         u32x4 o; o.x = pk2w(sp[0 * 65], sp[1 * 65]); o.y = pk2w(sp[2 * 65], sp[3 * 65]); o.z = pk2w(sp[4 * 65], sp[5 * 65]); o.w = pk2w(sp[6 * 65], sp[7 * 65]);
;         *(u32x4*)(WT + (size_t)(drow0 + n) * K + k0 + 8 * c) = o; }
	v_bfe_u32 v2, v80, 16, 1
	v_add3_u32 v2, v80, v2, s54
	s_waitcnt lgkmcnt(2)
	v_bfe_u32 v47, v82, 16, 1
	ds_read2_b32 v[88:89], v45 offset0:134 offset1:142
	v_lshrrev_b32_e32 v2, 16, v2
	v_add3_u32 v47, v82, v47, s54
	ds_read2_b32 v[90:91], v45 offset0:199 offset1:207
	v_and_or_b32 v73, v47, s55, v2
	s_waitcnt lgkmcnt(3)
	v_bfe_u32 v2, v84, 16, 1
	v_add3_u32 v2, v84, v2, s54
	s_waitcnt lgkmcnt(2)
	v_bfe_u32 v47, v86, 16, 1
	v_lshrrev_b32_e32 v2, 16, v2
	v_add3_u32 v47, v86, v47, s54
	v_and_or_b32 v74, v47, s55, v2
	s_waitcnt lgkmcnt(1)
	v_bfe_u32 v2, v88, 16, 1
	v_add3_u32 v2, v88, v2, s54
	s_waitcnt lgkmcnt(0)
	v_bfe_u32 v47, v90, 16, 1
	v_lshrrev_b32_e32 v2, 16, v2
	v_add3_u32 v47, v90, v47, s54
	v_and_or_b32 v75, v47, s55, v2
	v_or_b32_e32 v2, s8, v61
	v_lshlrev_b32_e32 v2, 9, v2
	v_lshl_add_u64 v[92:93], v[56:57], 0, v[2:3]
	v_bfe_u32 v2, v77, 16, 1
	v_add3_u32 v2, v77, v2, s54
	v_bfe_u32 v47, v79, 16, 1
	v_lshrrev_b32_e32 v2, 16, v2
	v_add3_u32 v47, v79, v47, s54
	global_store_dwordx4 v[92:93], v[72:75], off
	ds_read2_b32 v[76:77], v62 offset0:16 offset1:24
	s_nop 0
	v_and_or_b32 v72, v47, s55, v2
	v_bfe_u32 v2, v81, 16, 1
	v_add3_u32 v2, v81, v2, s54
	v_bfe_u32 v47, v83, 16, 1
	v_lshrrev_b32_e32 v2, 16, v2
	v_add3_u32 v47, v83, v47, s54
	v_and_or_b32 v73, v47, s55, v2
	v_bfe_u32 v2, v85, 16, 1
	v_add3_u32 v2, v85, v2, s54
	v_bfe_u32 v47, v87, 16, 1
	v_lshrrev_b32_e32 v2, 16, v2
	v_add3_u32 v47, v87, v47, s54
	v_and_or_b32 v74, v47, s55, v2
	v_bfe_u32 v2, v89, 16, 1
	v_add3_u32 v2, v89, v2, s54
	v_bfe_u32 v47, v91, 16, 1
	v_lshrrev_b32_e32 v2, 16, v2
	v_add3_u32 v47, v91, v47, s54
	v_and_or_b32 v75, v47, s55, v2
	v_or_b32_e32 v2, s8, v63
	v_lshlrev_b32_e32 v2, 9, v2
	v_lshl_add_u64 v[78:79], v[56:57], 0, v[2:3]
	global_store_dwordx4 v[78:79], v[72:75], off
	ds_read2_b32 v[78:79], v62 offset0:81 offset1:89
	ds_read2_b32 v[80:81], v62 offset0:146 offset1:154
	ds_read2_b32 v[82:83], v62 offset0:211 offset1:219
	s_waitcnt lgkmcnt(3)
	v_bfe_u32 v2, v76, 16, 1
	v_add3_u32 v2, v76, v2, s54
	s_waitcnt lgkmcnt(2)
	v_bfe_u32 v47, v78, 16, 1
	ds_read2_b32 v[84:85], v45 offset0:20 offset1:28
	v_lshrrev_b32_e32 v2, 16, v2
	v_add3_u32 v47, v78, v47, s54
	ds_read2_b32 v[86:87], v45 offset0:85 offset1:93
	v_and_or_b32 v72, v47, s55, v2
	s_waitcnt lgkmcnt(3)
	v_bfe_u32 v2, v80, 16, 1
	v_add3_u32 v2, v80, v2, s54
	s_waitcnt lgkmcnt(2)
	v_bfe_u32 v47, v82, 16, 1
	ds_read2_b32 v[88:89], v45 offset0:150 offset1:158
	v_lshrrev_b32_e32 v2, 16, v2
	v_add3_u32 v47, v82, v47, s54
	ds_read2_b32 v[90:91], v45 offset0:215 offset1:223
	v_and_or_b32 v73, v47, s55, v2
	s_waitcnt lgkmcnt(3)
	v_bfe_u32 v2, v84, 16, 1
	v_add3_u32 v2, v84, v2, s54
	s_waitcnt lgkmcnt(2)
	v_bfe_u32 v47, v86, 16, 1
	v_lshrrev_b32_e32 v2, 16, v2
	v_add3_u32 v47, v86, v47, s54
	v_and_or_b32 v74, v47, s55, v2
	s_waitcnt lgkmcnt(1)
	v_bfe_u32 v2, v88, 16, 1
	v_add3_u32 v2, v88, v2, s54
	s_waitcnt lgkmcnt(0)
	v_bfe_u32 v47, v90, 16, 1
	v_lshrrev_b32_e32 v2, 16, v2
	v_add3_u32 v47, v90, v47, s54
	v_and_or_b32 v75, v47, s55, v2
	v_or_b32_e32 v2, s8, v64
	v_lshlrev_b32_e32 v2, 9, v2
	v_lshl_add_u64 v[92:93], v[56:57], 0, v[2:3]
	v_bfe_u32 v2, v77, 16, 1
	v_add3_u32 v2, v77, v2, s54
	v_bfe_u32 v47, v79, 16, 1
	v_lshrrev_b32_e32 v2, 16, v2
	v_add3_u32 v47, v79, v47, s54
	global_store_dwordx4 v[92:93], v[72:75], off
	ds_read2_b32 v[76:77], v62 offset0:32 offset1:40
	s_nop 0
	v_and_or_b32 v72, v47, s55, v2
	v_bfe_u32 v2, v81, 16, 1
	v_add3_u32 v2, v81, v2, s54
	v_bfe_u32 v47, v83, 16, 1
	v_lshrrev_b32_e32 v2, 16, v2
	v_add3_u32 v47, v83, v47, s54
	v_and_or_b32 v73, v47, s55, v2
	v_bfe_u32 v2, v85, 16, 1
	v_add3_u32 v2, v85, v2, s54
	v_bfe_u32 v47, v87, 16, 1
	v_lshrrev_b32_e32 v2, 16, v2
	v_add3_u32 v47, v87, v47, s54
	v_and_or_b32 v74, v47, s55, v2
	v_bfe_u32 v2, v89, 16, 1
	v_add3_u32 v2, v89, v2, s54
	v_bfe_u32 v47, v91, 16, 1
	v_lshrrev_b32_e32 v2, 16, v2
	v_add3_u32 v47, v91, v47, s54
	v_and_or_b32 v75, v47, s55, v2
	v_or_b32_e32 v2, s8, v65
	v_lshlrev_b32_e32 v2, 9, v2
	v_lshl_add_u64 v[78:79], v[56:57], 0, v[2:3]
	global_store_dwordx4 v[78:79], v[72:75], off
	ds_read2_b32 v[78:79], v62 offset0:97 offset1:105
	ds_read2_b32 v[80:81], v62 offset0:162 offset1:170
	ds_read2_b32 v[82:83], v62 offset0:227 offset1:235
	s_waitcnt lgkmcnt(3)
	v_bfe_u32 v2, v76, 16, 1
	v_add3_u32 v2, v76, v2, s54
	s_waitcnt lgkmcnt(2)
; DI unsigned pk2w(float lo, float hi) { return f2bfw(lo) | (f2bfw(hi) << 16); }
; DI void transpose_item(const float* W, int K, int N, bf16_t* WT, int mode, float* scr, int item, int lane) {
;     ...
;     const int c = lane & 7;
; #pragma unroll
;     for (int j = 0; j < 8; ++j) { const int n = (lane >> 3) + 8 * j; const float* sp = scr + (8 * c) * 65 + n;
;         u32x4 o; o.x = pk2w(sp[0 * 65], sp[1 * 65]); o.y = pk2w(sp[2 * 65], sp[3 * 65]); o.z = pk2w(sp[4 * 65], sp[5 * 65]); o.w = pk2w(sp[6 * 65], sp[7 * 65]);
;         *(u32x4*)(WT + (size_t)(drow0 + n) * K + k0 + 8 * c) = o; }
;     __builtin_amdgcn_s_waitcnt(0); __builtin_amdgcn_wave_barrier();
	v_bfe_u32 v47, v78, 16, 1
	ds_read2_b32 v[84:85], v45 offset0:36 offset1:44
	v_lshrrev_b32_e32 v2, 16, v2
	v_add3_u32 v47, v78, v47, s54
	ds_read2_b32 v[86:87], v45 offset0:101 offset1:109
	v_and_or_b32 v72, v47, s55, v2
	s_waitcnt lgkmcnt(3)
	v_bfe_u32 v2, v80, 16, 1
	v_add3_u32 v2, v80, v2, s54
	s_waitcnt lgkmcnt(2)
	v_bfe_u32 v47, v82, 16, 1
	ds_read2_b32 v[88:89], v45 offset0:166 offset1:174
	v_lshrrev_b32_e32 v2, 16, v2
	v_add3_u32 v47, v82, v47, s54
	ds_read2_b32 v[90:91], v45 offset0:231 offset1:239
	v_and_or_b32 v73, v47, s55, v2
	s_waitcnt lgkmcnt(3)
	v_bfe_u32 v2, v84, 16, 1
	v_add3_u32 v2, v84, v2, s54
	s_waitcnt lgkmcnt(2)
	v_bfe_u32 v47, v86, 16, 1
	v_lshrrev_b32_e32 v2, 16, v2
	v_add3_u32 v47, v86, v47, s54
	v_and_or_b32 v74, v47, s55, v2
	s_waitcnt lgkmcnt(1)
	v_bfe_u32 v2, v88, 16, 1
	v_add3_u32 v2, v88, v2, s54
	s_waitcnt lgkmcnt(0)
	v_bfe_u32 v47, v90, 16, 1
	v_lshrrev_b32_e32 v2, 16, v2
	v_add3_u32 v47, v90, v47, s54
	v_and_or_b32 v75, v47, s55, v2
	v_or_b32_e32 v2, s8, v67
	v_lshlrev_b32_e32 v2, 9, v2
	v_lshl_add_u64 v[92:93], v[56:57], 0, v[2:3]
	v_bfe_u32 v2, v77, 16, 1
	v_add3_u32 v2, v77, v2, s54
	v_bfe_u32 v47, v79, 16, 1
	v_lshrrev_b32_e32 v2, 16, v2
	v_add3_u32 v47, v79, v47, s54
	global_store_dwordx4 v[92:93], v[72:75], off
	ds_read2_b32 v[76:77], v62 offset0:48 offset1:56
	s_nop 0
	v_and_or_b32 v72, v47, s55, v2
	v_bfe_u32 v2, v81, 16, 1
	v_add3_u32 v2, v81, v2, s54
	v_bfe_u32 v47, v83, 16, 1
	v_lshrrev_b32_e32 v2, 16, v2
	v_add3_u32 v47, v83, v47, s54
	v_and_or_b32 v73, v47, s55, v2
	v_bfe_u32 v2, v85, 16, 1
	v_add3_u32 v2, v85, v2, s54
	v_bfe_u32 v47, v87, 16, 1
	v_lshrrev_b32_e32 v2, 16, v2
	v_add3_u32 v47, v87, v47, s54
	v_and_or_b32 v74, v47, s55, v2
	v_bfe_u32 v2, v89, 16, 1
	v_add3_u32 v2, v89, v2, s54
	v_bfe_u32 v47, v91, 16, 1
	v_lshrrev_b32_e32 v2, 16, v2
	v_add3_u32 v47, v91, v47, s54
	v_and_or_b32 v75, v47, s55, v2
	v_or_b32_e32 v2, s8, v68
	v_lshlrev_b32_e32 v2, 9, v2
	v_lshl_add_u64 v[78:79], v[56:57], 0, v[2:3]
	global_store_dwordx4 v[78:79], v[72:75], off
	ds_read2_b32 v[78:79], v62 offset0:113 offset1:121
	ds_read2_b32 v[80:81], v62 offset0:178 offset1:186
	ds_read2_b32 v[82:83], v62 offset0:243 offset1:251
	s_waitcnt lgkmcnt(3)
	v_bfe_u32 v2, v76, 16, 1
	v_add3_u32 v2, v76, v2, s54
	s_waitcnt lgkmcnt(2)
	v_bfe_u32 v47, v78, 16, 1
	ds_read2_b32 v[84:85], v45 offset0:52 offset1:60
	v_lshrrev_b32_e32 v2, 16, v2
	v_add3_u32 v47, v78, v47, s54
	ds_read2_b32 v[86:87], v45 offset0:117 offset1:125
	v_and_or_b32 v72, v47, s55, v2
	s_waitcnt lgkmcnt(3)
	v_bfe_u32 v2, v80, 16, 1
	v_add3_u32 v2, v80, v2, s54
	s_waitcnt lgkmcnt(2)
	v_bfe_u32 v47, v82, 16, 1
	ds_read2_b32 v[88:89], v45 offset0:182 offset1:190
	v_lshrrev_b32_e32 v2, 16, v2
	v_add3_u32 v47, v82, v47, s54
	ds_read2_b32 v[90:91], v45 offset0:247 offset1:255
	v_and_or_b32 v73, v47, s55, v2
	s_waitcnt lgkmcnt(3)
	v_bfe_u32 v2, v84, 16, 1
	v_add3_u32 v2, v84, v2, s54
	s_waitcnt lgkmcnt(2)
	v_bfe_u32 v47, v86, 16, 1
	v_lshrrev_b32_e32 v2, 16, v2
	v_add3_u32 v47, v86, v47, s54
	v_and_or_b32 v74, v47, s55, v2
	s_waitcnt lgkmcnt(1)
	v_bfe_u32 v2, v88, 16, 1
	v_add3_u32 v2, v88, v2, s54
	s_waitcnt lgkmcnt(0)
	v_bfe_u32 v45, v90, 16, 1
	v_lshrrev_b32_e32 v2, 16, v2
	v_add3_u32 v45, v90, v45, s54
	v_and_or_b32 v75, v45, s55, v2
	v_or_b32_e32 v2, s8, v69
	v_lshlrev_b32_e32 v2, 9, v2
	v_lshl_add_u64 v[92:93], v[56:57], 0, v[2:3]
	v_bfe_u32 v2, v77, 16, 1
	v_add3_u32 v2, v77, v2, s54
	v_bfe_u32 v45, v79, 16, 1
	v_lshrrev_b32_e32 v2, 16, v2
	v_add3_u32 v45, v79, v45, s54
	global_store_dwordx4 v[92:93], v[72:75], off
	s_nop 1
	v_and_or_b32 v72, v45, s55, v2
	v_bfe_u32 v2, v81, 16, 1
	v_add3_u32 v2, v81, v2, s54
	v_bfe_u32 v45, v83, 16, 1
	v_lshrrev_b32_e32 v2, 16, v2
	v_add3_u32 v45, v83, v45, s54
	v_and_or_b32 v73, v45, s55, v2
	v_bfe_u32 v2, v85, 16, 1
	v_add3_u32 v2, v85, v2, s54
	v_bfe_u32 v45, v87, 16, 1
	v_lshrrev_b32_e32 v2, 16, v2
	v_add3_u32 v45, v87, v45, s54
	v_and_or_b32 v74, v45, s55, v2
	v_bfe_u32 v2, v89, 16, 1
	v_add3_u32 v2, v89, v2, s54
	v_bfe_u32 v45, v91, 16, 1
	v_lshrrev_b32_e32 v2, 16, v2
	v_add3_u32 v45, v91, v45, s54
	v_and_or_b32 v75, v45, s55, v2
	v_or_b32_e32 v2, s8, v70
	v_lshlrev_b32_e32 v2, 9, v2
	v_lshl_add_u64 v[56:57], v[56:57], 0, v[2:3]
	global_store_dwordx4 v[56:57], v[72:75], off
	s_waitcnt lgkmcnt(0)

; DI unsigned pk2w(float lo, float hi) { return f2bfw(lo) | (f2bfw(hi) << 16); }
; DI void transpose_item(const float* W, int K, int N, bf16_t* WT, int mode, float* scr, int item, int lane) {
;     const int nblk = N / 64, kb = item / nblk, nb = item % nblk, k0 = 64 * kb, n0 = 64 * nb;
;     int drow0 = n0;
;     if (mode == 1) { const int seg = n0 >> 10; const int dst = seg < 2 ? seg : (seg == 2 ? 6 : seg - 1); drow0 = dst * 1024 + (n0 & 1023); }
;     else if (mode == 2) { drow0 = n0 < DFF ? (n0 / 128) * 256 + (n0 % 128) : ((n0 - DFF) / 128) * 256 + 128 + ((n0 - DFF) % 128); }
;     else if (mode == 3) { drow0 = (n0 / 128) * 256 + (n0 % 128); }
;     else if (mode == 4) { drow0 = (n0 / 128) * 256 + 128 + (n0 % 128); }
;     f32x4 v[16];
; #pragma unroll
;     for (int i = 0; i < 16; ++i) v[i] = __builtin_nontemporal_load((const f32x4*)(W + (size_t)(k0 + 4 * i + (lane >> 4)) * N + n0 + 4 * (lane & 15)));
; #pragma unroll
;     for (int i = 0; i < 16; ++i) { float* d = scr + (4 * i + (lane >> 4)) * 65 + 4 * (lane & 15); d[0] = v[i][0]; d[1] = v[i][1]; d[2] = v[i][2]; d[3] = v[i][3]; }
;     __builtin_amdgcn_s_waitcnt(0); __builtin_amdgcn_wave_barrier();
;     const int c = lane & 7;
; #pragma unroll
;     for (int j = 0; j < 8; ++j) { const int n = (lane >> 3) + 8 * j; const float* sp = scr + (8 * c) * 65 + n;
;         u32x4 o; o.x = pk2w(sp[0 * 65], sp[1 * 65]); o.y = pk2w(sp[2 * 65], sp[3 * 65]); o.z = pk2w(sp[4 * 65], sp[5 * 65]); o.w = pk2w(sp[6 * 65], sp[7 * 65]);
.LBB0_28:
	s_andn2_b64 vcc, exec, s[8:9]
	s_cbranch_vccnz .LBB0_30
	s_add_i32 s9, s42, 0x1700
	s_and_b32 s8, s15, 0x7c0
	s_and_b32 s9, s9, 0x1ffc0
	v_or_b32_e32 v2, s9, v59
	s_lshl_b32 s40, s8, 2
	v_lshl_add_u64 v[56:57], v[52:53], 0, s[40:41]
	v_lshlrev_b32_e32 v2, 13, v2
	v_lshl_add_u64 v[56:57], v[56:57], 0, v[2:3]
	v_add_co_u32_e32 v76, vcc, 0x8000, v56
	v_add_u32_e32 v2, 0x410, v60
	s_nop 0
	v_addc_co_u32_e32 v77, vcc, 0, v57, vcc
	v_add_co_u32_e32 v80, vcc, 0x10000, v56
	global_load_dwordx4 v[72:75], v[56:57], off nt
	s_nop 0
	global_load_dwordx4 v[76:79], v[76:77], off nt
	v_addc_co_u32_e32 v81, vcc, 0, v57, vcc
	v_add_co_u32_e32 v84, vcc, 0x18000, v56
	s_lshl_b32 s40, s9, 1
	s_nop 0
	v_addc_co_u32_e32 v85, vcc, 0, v57, vcc
	global_load_dwordx4 v[80:83], v[80:81], off nt
	s_nop 0
	global_load_dwordx4 v[84:87], v[84:85], off nt
	v_add_co_u32_e32 v88, vcc, 0x20000, v56
	s_nop 1
	v_addc_co_u32_e32 v89, vcc, 0, v57, vcc
	v_add_co_u32_e32 v92, vcc, 0x28000, v56
	s_nop 1
	v_addc_co_u32_e32 v93, vcc, 0, v57, vcc
	global_load_dwordx4 v[88:91], v[88:89], off nt
	s_nop 0
	global_load_dwordx4 v[92:95], v[92:93], off nt
	v_add_co_u32_e32 v96, vcc, 0x30000, v56
	s_nop 1
	v_addc_co_u32_e32 v97, vcc, 0, v57, vcc
	v_add_co_u32_e32 v100, vcc, 0x38000, v56
	s_nop 1
	v_addc_co_u32_e32 v101, vcc, 0, v57, vcc
	global_load_dwordx4 v[96:99], v[96:97], off nt
	s_nop 0
	global_load_dwordx4 v[100:103], v[100:101], off nt
	v_add_co_u32_e32 v104, vcc, 0x40000, v56
	s_nop 1
	v_addc_co_u32_e32 v105, vcc, 0, v57, vcc
	v_add_co_u32_e32 v108, vcc, 0x48000, v56
	s_nop 1
	v_addc_co_u32_e32 v109, vcc, 0, v57, vcc
	global_load_dwordx4 v[104:107], v[104:105], off nt
	s_nop 0
	global_load_dwordx4 v[108:111], v[108:109], off nt
	v_add_co_u32_e32 v112, vcc, 0x50000, v56
	s_nop 1
	v_addc_co_u32_e32 v113, vcc, 0, v57, vcc
	v_add_co_u32_e32 v116, vcc, 0x58000, v56
	s_nop 1
	v_addc_co_u32_e32 v117, vcc, 0, v57, vcc
	global_load_dwordx4 v[112:115], v[112:113], off nt
	s_nop 0
	global_load_dwordx4 v[116:119], v[116:117], off nt
	v_add_co_u32_e32 v120, vcc, 0x60000, v56
	s_nop 1
	v_addc_co_u32_e32 v121, vcc, 0, v57, vcc
	v_add_co_u32_e32 v124, vcc, 0x68000, v56
	s_nop 1
	v_addc_co_u32_e32 v125, vcc, 0, v57, vcc
	global_load_dwordx4 v[120:123], v[120:121], off nt
	s_nop 0
	global_load_dwordx4 v[124:127], v[124:125], off nt
	v_add_co_u32_e32 v128, vcc, 0x70000, v56
	s_nop 1
	v_addc_co_u32_e32 v129, vcc, 0, v57, vcc
	global_load_dwordx4 v[128:131], v[128:129], off nt
	v_add_co_u32_e32 v56, vcc, 0x78000, v56
	s_nop 1
	v_addc_co_u32_e32 v57, vcc, 0, v57, vcc
	global_load_dwordx4 v[132:135], v[56:57], off nt
	s_waitcnt vmcnt(15)
	ds_write2_b32 v60, v72, v73 offset1:1
	ds_write2_b32 v60, v74, v75 offset0:2 offset1:3
	s_waitcnt vmcnt(14)
	ds_write2_b32 v2, v76, v77 offset1:1
	v_add_u32_e32 v2, 0x418, v60
	ds_write2_b32 v2, v78, v79 offset1:1
	v_add_u32_e32 v2, 0x820, v60
	v_lshl_add_u64 v[56:57], v[24:25], 0, s[40:41]
	s_waitcnt vmcnt(13)
	ds_write2_b32 v2, v80, v81 offset1:1
	v_add_u32_e32 v2, 0x828, v60
	ds_write2_b32 v2, v82, v83 offset1:1
	v_add_u32_e32 v2, 0xc30, v60
	s_waitcnt vmcnt(12)
	ds_write2_b32 v2, v84, v85 offset1:1
	v_add_u32_e32 v2, 0xc38, v60
	ds_write2_b32 v2, v86, v87 offset1:1
	v_add_u32_e32 v2, 0x1040, v60
	s_waitcnt vmcnt(11)
	ds_write2_b32 v2, v88, v89 offset1:1
	v_add_u32_e32 v2, 0x1048, v60
	ds_write2_b32 v2, v90, v91 offset1:1
	v_add_u32_e32 v2, 0x1450, v60
	s_waitcnt vmcnt(10)
	ds_write2_b32 v2, v92, v93 offset1:1
	v_add_u32_e32 v2, 0x1458, v60
	ds_write2_b32 v2, v94, v95 offset1:1
	v_add_u32_e32 v2, 0x1860, v60
	s_waitcnt vmcnt(9)
	ds_write2_b32 v2, v96, v97 offset1:1
	v_add_u32_e32 v2, 0x1868, v60
	ds_write2_b32 v2, v98, v99 offset1:1
	v_add_u32_e32 v2, 0x1c70, v60
	s_waitcnt vmcnt(8)
	ds_write2_b32 v2, v100, v101 offset1:1
	v_add_u32_e32 v2, 0x1c78, v60
	ds_write2_b32 v2, v102, v103 offset1:1
	v_add_u32_e32 v2, 0x2080, v60
	s_waitcnt vmcnt(7)
	ds_write2_b32 v2, v104, v105 offset1:1
	v_add_u32_e32 v2, 0x2088, v60
	ds_write2_b32 v2, v106, v107 offset1:1
	v_add_u32_e32 v2, 0x2490, v60
	s_waitcnt vmcnt(6)
	ds_write2_b32 v2, v108, v109 offset1:1
	v_add_u32_e32 v2, 0x2498, v60
	ds_write2_b32 v2, v110, v111 offset1:1
	v_add_u32_e32 v2, 0x28a0, v60
	s_waitcnt vmcnt(5)
	ds_write2_b32 v2, v112, v113 offset1:1
	v_add_u32_e32 v2, 0x28a8, v60
	ds_write2_b32 v2, v114, v115 offset1:1
	v_add_u32_e32 v2, 0x2cb0, v60
	s_waitcnt vmcnt(4)
	ds_write2_b32 v2, v116, v117 offset1:1
	v_add_u32_e32 v2, 0x2cb8, v60
	ds_write2_b32 v2, v118, v119 offset1:1
	v_add_u32_e32 v2, 0x30c0, v60
	s_waitcnt vmcnt(3)
	ds_write2_b32 v2, v120, v121 offset1:1
	v_add_u32_e32 v2, 0x30c8, v60
	ds_write2_b32 v2, v122, v123 offset1:1
	v_add_u32_e32 v2, 0x34d0, v60
	s_waitcnt vmcnt(2)
	ds_write2_b32 v2, v124, v125 offset1:1
	v_add_u32_e32 v2, 0x34d8, v60
	ds_write2_b32 v2, v126, v127 offset1:1
	v_add_u32_e32 v2, 0x38e0, v60
	s_waitcnt vmcnt(1)
	ds_write2_b32 v2, v128, v129 offset1:1
	v_add_u32_e32 v2, 0x38e8, v60
	ds_write2_b32 v2, v130, v131 offset1:1
	v_add_u32_e32 v2, 0x3cf0, v60
	s_waitcnt vmcnt(0)
	ds_write2_b32 v2, v132, v133 offset1:1
	v_add_u32_e32 v2, 0x3cf8, v60
	ds_write2_b32 v2, v134, v135 offset1:1
	s_waitcnt vmcnt(0) expcnt(0) lgkmcnt(0)
	ds_read2_b32 v[76:77], v62 offset1:8
	ds_read2_b32 v[78:79], v62 offset0:65 offset1:73
	ds_read2_b32 v[80:81], v62 offset0:130 offset1:138
	ds_read2_b32 v[82:83], v62 offset0:195 offset1:203
	s_waitcnt lgkmcnt(3)
	v_bfe_u32 v2, v76, 16, 1
	v_add3_u32 v2, v76, v2, s54
	s_waitcnt lgkmcnt(2)
	v_bfe_u32 v45, v78, 16, 1
	v_lshrrev_b32_e32 v2, 16, v2
	v_add3_u32 v45, v78, v45, s54
	v_and_or_b32 v72, v45, s55, v2
	v_add_u32_e32 v45, 0x400, v62
	ds_read2_b32 v[84:85], v45 offset0:4 offset1:12
	ds_read2_b32 v[86:87], v45 offset0:69 offset1:77
	s_waitcnt lgkmcnt(3)
; DI unsigned pk2w(float lo, float hi) { return f2bfw(lo) | (f2bfw(hi) << 16); }
; DI void transpose_item(const float* W, int K, int N, bf16_t* WT, int mode, float* scr, int item, int lane) {
;     ...
;     const int c = lane & 7;
; #pragma unroll
;     for (int j = 0; j < 8; ++j) { const int n = (lane >> 3) + 8 * j; const float* sp = scr + (8 * c) * 65 + n;
;         u32x4 o; o.x = pk2w(sp[0 * 65], sp[1 * 65]); o.y = pk2w(sp[2 * 65], sp[3 * 65]); o.z = pk2w(sp[4 * 65], sp[5 * 65]); o.w = pk2w(sp[6 * 65], sp[7 * 65]);
;         *(u32x4*)(WT + (size_t)(drow0 + n) * K + k0 + 8 * c) = o; }
	v_bfe_u32 v2, v80, 16, 1
	v_add3_u32 v2, v80, v2, s54
	s_waitcnt lgkmcnt(2)
	v_bfe_u32 v47, v82, 16, 1
	ds_read2_b32 v[88:89], v45 offset0:134 offset1:142
	v_lshrrev_b32_e32 v2, 16, v2
	v_add3_u32 v47, v82, v47, s54
	ds_read2_b32 v[90:91], v45 offset0:199 offset1:207
	v_and_or_b32 v73, v47, s55, v2
	s_waitcnt lgkmcnt(3)
	v_bfe_u32 v2, v84, 16, 1
	v_add3_u32 v2, v84, v2, s54
	s_waitcnt lgkmcnt(2)
	v_bfe_u32 v47, v86, 16, 1
	v_lshrrev_b32_e32 v2, 16, v2
	v_add3_u32 v47, v86, v47, s54
	v_and_or_b32 v74, v47, s55, v2
	s_waitcnt lgkmcnt(1)
	v_bfe_u32 v2, v88, 16, 1
	v_add3_u32 v2, v88, v2, s54
	s_waitcnt lgkmcnt(0)
	v_bfe_u32 v47, v90, 16, 1
	v_lshrrev_b32_e32 v2, 16, v2
	v_add3_u32 v47, v90, v47, s54
	v_and_or_b32 v75, v47, s55, v2
	v_or_b32_e32 v2, s8, v61
	v_mul_u32_u24_e32 v2, 0x1600, v2
	v_lshlrev_b32_e32 v2, 1, v2
	v_lshl_add_u64 v[92:93], v[56:57], 0, v[2:3]
	v_bfe_u32 v2, v77, 16, 1
	v_add3_u32 v2, v77, v2, s54
	v_bfe_u32 v47, v79, 16, 1
	v_lshrrev_b32_e32 v2, 16, v2
	v_add3_u32 v47, v79, v47, s54
	global_store_dwordx4 v[92:93], v[72:75], off
	ds_read2_b32 v[76:77], v62 offset0:16 offset1:24
	s_nop 0
	v_and_or_b32 v72, v47, s55, v2
	v_bfe_u32 v2, v81, 16, 1
	v_add3_u32 v2, v81, v2, s54
	v_bfe_u32 v47, v83, 16, 1
	v_lshrrev_b32_e32 v2, 16, v2
	v_add3_u32 v47, v83, v47, s54
	v_and_or_b32 v73, v47, s55, v2
	v_bfe_u32 v2, v85, 16, 1
	v_add3_u32 v2, v85, v2, s54
	v_bfe_u32 v47, v87, 16, 1
	v_lshrrev_b32_e32 v2, 16, v2
	v_add3_u32 v47, v87, v47, s54
	v_and_or_b32 v74, v47, s55, v2
	v_bfe_u32 v2, v89, 16, 1
	v_add3_u32 v2, v89, v2, s54
	v_bfe_u32 v47, v91, 16, 1
	v_lshrrev_b32_e32 v2, 16, v2
	v_add3_u32 v47, v91, v47, s54
	v_and_or_b32 v75, v47, s55, v2
	v_or_b32_e32 v2, s8, v63
	v_mul_u32_u24_e32 v2, 0x1600, v2
	v_lshlrev_b32_e32 v2, 1, v2
	v_lshl_add_u64 v[78:79], v[56:57], 0, v[2:3]
	global_store_dwordx4 v[78:79], v[72:75], off
	ds_read2_b32 v[78:79], v62 offset0:81 offset1:89
	ds_read2_b32 v[80:81], v62 offset0:146 offset1:154
	ds_read2_b32 v[82:83], v62 offset0:211 offset1:219
	s_waitcnt lgkmcnt(3)
	v_bfe_u32 v2, v76, 16, 1
	v_add3_u32 v2, v76, v2, s54
	s_waitcnt lgkmcnt(2)
	v_bfe_u32 v47, v78, 16, 1
	ds_read2_b32 v[84:85], v45 offset0:20 offset1:28
	v_lshrrev_b32_e32 v2, 16, v2
	v_add3_u32 v47, v78, v47, s54
	ds_read2_b32 v[86:87], v45 offset0:85 offset1:93
	v_and_or_b32 v72, v47, s55, v2
	s_waitcnt lgkmcnt(3)
	v_bfe_u32 v2, v80, 16, 1
	v_add3_u32 v2, v80, v2, s54
	s_waitcnt lgkmcnt(2)
	v_bfe_u32 v47, v82, 16, 1
	ds_read2_b32 v[88:89], v45 offset0:150 offset1:158
	v_lshrrev_b32_e32 v2, 16, v2
	v_add3_u32 v47, v82, v47, s54
	ds_read2_b32 v[90:91], v45 offset0:215 offset1:223
	v_and_or_b32 v73, v47, s55, v2
	s_waitcnt lgkmcnt(3)
	v_bfe_u32 v2, v84, 16, 1
	v_add3_u32 v2, v84, v2, s54
	s_waitcnt lgkmcnt(2)
	v_bfe_u32 v47, v86, 16, 1
	v_lshrrev_b32_e32 v2, 16, v2
	v_add3_u32 v47, v86, v47, s54
	v_and_or_b32 v74, v47, s55, v2
	s_waitcnt lgkmcnt(1)
	v_bfe_u32 v2, v88, 16, 1
	v_add3_u32 v2, v88, v2, s54
	s_waitcnt lgkmcnt(0)
	v_bfe_u32 v47, v90, 16, 1
	v_lshrrev_b32_e32 v2, 16, v2
	v_add3_u32 v47, v90, v47, s54
	v_and_or_b32 v75, v47, s55, v2
	v_or_b32_e32 v2, s8, v64
	v_mul_u32_u24_e32 v2, 0x1600, v2
	v_lshlrev_b32_e32 v2, 1, v2
	v_lshl_add_u64 v[92:93], v[56:57], 0, v[2:3]
	v_bfe_u32 v2, v77, 16, 1
	v_add3_u32 v2, v77, v2, s54
	v_bfe_u32 v47, v79, 16, 1
	v_lshrrev_b32_e32 v2, 16, v2
	v_add3_u32 v47, v79, v47, s54
	global_store_dwordx4 v[92:93], v[72:75], off
	ds_read2_b32 v[76:77], v62 offset0:32 offset1:40
	s_nop 0
	v_and_or_b32 v72, v47, s55, v2
	v_bfe_u32 v2, v81, 16, 1
	v_add3_u32 v2, v81, v2, s54
	v_bfe_u32 v47, v83, 16, 1
	v_lshrrev_b32_e32 v2, 16, v2
	v_add3_u32 v47, v83, v47, s54
	v_and_or_b32 v73, v47, s55, v2
	v_bfe_u32 v2, v85, 16, 1
	v_add3_u32 v2, v85, v2, s54
	v_bfe_u32 v47, v87, 16, 1
	v_lshrrev_b32_e32 v2, 16, v2
	v_add3_u32 v47, v87, v47, s54
	v_and_or_b32 v74, v47, s55, v2
	v_bfe_u32 v2, v89, 16, 1
	v_add3_u32 v2, v89, v2, s54
	v_bfe_u32 v47, v91, 16, 1
	v_lshrrev_b32_e32 v2, 16, v2
	v_add3_u32 v47, v91, v47, s54
	v_and_or_b32 v75, v47, s55, v2
	v_or_b32_e32 v2, s8, v65
	v_mul_u32_u24_e32 v2, 0x1600, v2
	v_lshlrev_b32_e32 v2, 1, v2
	v_lshl_add_u64 v[78:79], v[56:57], 0, v[2:3]
	global_store_dwordx4 v[78:79], v[72:75], off
	ds_read2_b32 v[78:79], v62 offset0:97 offset1:105
	ds_read2_b32 v[80:81], v62 offset0:162 offset1:170
	ds_read2_b32 v[82:83], v62 offset0:227 offset1:235
	s_waitcnt lgkmcnt(3)
	v_bfe_u32 v2, v76, 16, 1
	v_add3_u32 v2, v76, v2, s54
	s_waitcnt lgkmcnt(2)
; DI unsigned pk2w(float lo, float hi) { return f2bfw(lo) | (f2bfw(hi) << 16); }
; DI void transpose_item(const float* W, int K, int N, bf16_t* WT, int mode, float* scr, int item, int lane) {
;     ...
;     const int c = lane & 7;
; #pragma unroll
;     for (int j = 0; j < 8; ++j) { const int n = (lane >> 3) + 8 * j; const float* sp = scr + (8 * c) * 65 + n;
;         u32x4 o; o.x = pk2w(sp[0 * 65], sp[1 * 65]); o.y = pk2w(sp[2 * 65], sp[3 * 65]); o.z = pk2w(sp[4 * 65], sp[5 * 65]); o.w = pk2w(sp[6 * 65], sp[7 * 65]);
;         *(u32x4*)(WT + (size_t)(drow0 + n) * K + k0 + 8 * c) = o; }
;     __builtin_amdgcn_s_waitcnt(0); __builtin_amdgcn_wave_barrier();
	v_bfe_u32 v47, v78, 16, 1
	ds_read2_b32 v[84:85], v45 offset0:36 offset1:44
	v_lshrrev_b32_e32 v2, 16, v2
	v_add3_u32 v47, v78, v47, s54
	ds_read2_b32 v[86:87], v45 offset0:101 offset1:109
	v_and_or_b32 v72, v47, s55, v2
	s_waitcnt lgkmcnt(3)
	v_bfe_u32 v2, v80, 16, 1
	v_add3_u32 v2, v80, v2, s54
	s_waitcnt lgkmcnt(2)
	v_bfe_u32 v47, v82, 16, 1
	ds_read2_b32 v[88:89], v45 offset0:166 offset1:174
	v_lshrrev_b32_e32 v2, 16, v2
	v_add3_u32 v47, v82, v47, s54
	ds_read2_b32 v[90:91], v45 offset0:231 offset1:239
	v_and_or_b32 v73, v47, s55, v2
	s_waitcnt lgkmcnt(3)
	v_bfe_u32 v2, v84, 16, 1
	v_add3_u32 v2, v84, v2, s54
	s_waitcnt lgkmcnt(2)
	v_bfe_u32 v47, v86, 16, 1
	v_lshrrev_b32_e32 v2, 16, v2
	v_add3_u32 v47, v86, v47, s54
	v_and_or_b32 v74, v47, s55, v2
	s_waitcnt lgkmcnt(1)
	v_bfe_u32 v2, v88, 16, 1
	v_add3_u32 v2, v88, v2, s54
	s_waitcnt lgkmcnt(0)
	v_bfe_u32 v47, v90, 16, 1
	v_lshrrev_b32_e32 v2, 16, v2
	v_add3_u32 v47, v90, v47, s54
	v_and_or_b32 v75, v47, s55, v2
	v_or_b32_e32 v2, s8, v67
	v_mul_u32_u24_e32 v2, 0x1600, v2
	v_lshlrev_b32_e32 v2, 1, v2
	v_lshl_add_u64 v[92:93], v[56:57], 0, v[2:3]
	v_bfe_u32 v2, v77, 16, 1
	v_add3_u32 v2, v77, v2, s54
	v_bfe_u32 v47, v79, 16, 1
	v_lshrrev_b32_e32 v2, 16, v2
	v_add3_u32 v47, v79, v47, s54
	global_store_dwordx4 v[92:93], v[72:75], off
	ds_read2_b32 v[76:77], v62 offset0:48 offset1:56
	s_nop 0
	v_and_or_b32 v72, v47, s55, v2
	v_bfe_u32 v2, v81, 16, 1
	v_add3_u32 v2, v81, v2, s54
	v_bfe_u32 v47, v83, 16, 1
	v_lshrrev_b32_e32 v2, 16, v2
	v_add3_u32 v47, v83, v47, s54
	v_and_or_b32 v73, v47, s55, v2
	v_bfe_u32 v2, v85, 16, 1
	v_add3_u32 v2, v85, v2, s54
	v_bfe_u32 v47, v87, 16, 1
	v_lshrrev_b32_e32 v2, 16, v2
	v_add3_u32 v47, v87, v47, s54
	v_and_or_b32 v74, v47, s55, v2
	v_bfe_u32 v2, v89, 16, 1
	v_add3_u32 v2, v89, v2, s54
	v_bfe_u32 v47, v91, 16, 1
	v_lshrrev_b32_e32 v2, 16, v2
	v_add3_u32 v47, v91, v47, s54
	v_and_or_b32 v75, v47, s55, v2
	v_or_b32_e32 v2, s8, v68
	v_mul_u32_u24_e32 v2, 0x1600, v2
	v_lshlrev_b32_e32 v2, 1, v2
	v_lshl_add_u64 v[78:79], v[56:57], 0, v[2:3]
	global_store_dwordx4 v[78:79], v[72:75], off
	ds_read2_b32 v[78:79], v62 offset0:113 offset1:121
	ds_read2_b32 v[80:81], v62 offset0:178 offset1:186
	ds_read2_b32 v[82:83], v62 offset0:243 offset1:251
	s_waitcnt lgkmcnt(3)
	v_bfe_u32 v2, v76, 16, 1
	v_add3_u32 v2, v76, v2, s54
	s_waitcnt lgkmcnt(2)
	v_bfe_u32 v47, v78, 16, 1
	ds_read2_b32 v[84:85], v45 offset0:52 offset1:60
	v_lshrrev_b32_e32 v2, 16, v2
	v_add3_u32 v47, v78, v47, s54
	ds_read2_b32 v[86:87], v45 offset0:117 offset1:125
	v_and_or_b32 v72, v47, s55, v2
	s_waitcnt lgkmcnt(3)
	v_bfe_u32 v2, v80, 16, 1
	v_add3_u32 v2, v80, v2, s54
	s_waitcnt lgkmcnt(2)
	v_bfe_u32 v47, v82, 16, 1
	ds_read2_b32 v[88:89], v45 offset0:182 offset1:190
	v_lshrrev_b32_e32 v2, 16, v2
	v_add3_u32 v47, v82, v47, s54
	ds_read2_b32 v[90:91], v45 offset0:247 offset1:255
	v_and_or_b32 v73, v47, s55, v2
	s_waitcnt lgkmcnt(3)
	v_bfe_u32 v2, v84, 16, 1
	v_add3_u32 v2, v84, v2, s54
	s_waitcnt lgkmcnt(2)
	v_bfe_u32 v47, v86, 16, 1
	v_lshrrev_b32_e32 v2, 16, v2
	v_add3_u32 v47, v86, v47, s54
	v_and_or_b32 v74, v47, s55, v2
	s_waitcnt lgkmcnt(1)
	v_bfe_u32 v2, v88, 16, 1
	v_add3_u32 v2, v88, v2, s54
	s_waitcnt lgkmcnt(0)
	v_bfe_u32 v45, v90, 16, 1
	v_lshrrev_b32_e32 v2, 16, v2
	v_add3_u32 v45, v90, v45, s54
	v_and_or_b32 v75, v45, s55, v2
	v_or_b32_e32 v2, s8, v69
	v_mul_u32_u24_e32 v2, 0x1600, v2
	v_lshlrev_b32_e32 v2, 1, v2
	v_lshl_add_u64 v[92:93], v[56:57], 0, v[2:3]
	v_bfe_u32 v2, v77, 16, 1
	v_add3_u32 v2, v77, v2, s54
	v_bfe_u32 v45, v79, 16, 1
	v_lshrrev_b32_e32 v2, 16, v2
	v_add3_u32 v45, v79, v45, s54
	global_store_dwordx4 v[92:93], v[72:75], off
	s_nop 1
	v_and_or_b32 v72, v45, s55, v2
	v_bfe_u32 v2, v81, 16, 1
	v_add3_u32 v2, v81, v2, s54
	v_bfe_u32 v45, v83, 16, 1
	v_lshrrev_b32_e32 v2, 16, v2
	v_add3_u32 v45, v83, v45, s54
	v_and_or_b32 v73, v45, s55, v2
	v_bfe_u32 v2, v85, 16, 1
	v_add3_u32 v2, v85, v2, s54
	v_bfe_u32 v45, v87, 16, 1
	v_lshrrev_b32_e32 v2, 16, v2
	v_add3_u32 v45, v87, v45, s54
	v_and_or_b32 v74, v45, s55, v2
	v_bfe_u32 v2, v89, 16, 1
	v_add3_u32 v2, v89, v2, s54
	v_bfe_u32 v45, v91, 16, 1
	v_lshrrev_b32_e32 v2, 16, v2
	v_add3_u32 v45, v91, v45, s54
	v_and_or_b32 v75, v45, s55, v2
	v_or_b32_e32 v2, s8, v70
	v_mul_u32_u24_e32 v2, 0x1600, v2
	v_lshlrev_b32_e32 v2, 1, v2
	v_lshl_add_u64 v[56:57], v[56:57], 0, v[2:3]
	global_store_dwordx4 v[56:57], v[72:75], off
	s_waitcnt lgkmcnt(0)

; DI unsigned pk2w(float lo, float hi) { return f2bfw(lo) | (f2bfw(hi) << 16); }
; DI void transpose_item(const float* W, int K, int N, bf16_t* WT, int mode, float* scr, int item, int lane) {
;     const int nblk = N / 64, kb = item / nblk, nb = item % nblk, k0 = 64 * kb, n0 = 64 * nb;
;     int drow0 = n0;
;     if (mode == 1) { const int seg = n0 >> 10; const int dst = seg < 2 ? seg : (seg == 2 ? 6 : seg - 1); drow0 = dst * 1024 + (n0 & 1023); }
;     else if (mode == 2) { drow0 = n0 < DFF ? (n0 / 128) * 256 + (n0 % 128) : ((n0 - DFF) / 128) * 256 + 128 + ((n0 - DFF) % 128); }
;     else if (mode == 3) { drow0 = (n0 / 128) * 256 + (n0 % 128); }
;     else if (mode == 4) { drow0 = (n0 / 128) * 256 + 128 + (n0 % 128); }
;     f32x4 v[16];
; #pragma unroll
;     for (int i = 0; i < 16; ++i) v[i] = __builtin_nontemporal_load((const f32x4*)(W + (size_t)(k0 + 4 * i + (lane >> 4)) * N + n0 + 4 * (lane & 15)));
; #pragma unroll
;     for (int i = 0; i < 16; ++i) { float* d = scr + (4 * i + (lane >> 4)) * 65 + 4 * (lane & 15); d[0] = v[i][0]; d[1] = v[i][1]; d[2] = v[i][2]; d[3] = v[i][3]; }
;     __builtin_amdgcn_s_waitcnt(0); __builtin_amdgcn_wave_barrier();
;     const int c = lane & 7;
; #pragma unroll
;     for (int j = 0; j < 8; ++j) { const int n = (lane >> 3) + 8 * j; const float* sp = scr + (8 * c) * 65 + n;
;         u32x4 o; o.x = pk2w(sp[0 * 65], sp[1 * 65]); o.y = pk2w(sp[2 * 65], sp[3 * 65]); o.z = pk2w(sp[4 * 65], sp[5 * 65]); o.w = pk2w(sp[6 * 65], sp[7 * 65]);
.LBB0_36:
	s_lshl_b32 s8, s11, 6
	s_and_b32 s8, s8, 0x7fc0
	v_or_b32_e32 v2, s8, v59
	s_lshl_b32 s40, s40, 2
	v_mul_u32_u24_e32 v2, 0x2c00, v2
	v_lshl_add_u64 v[56:57], v[54:55], 0, s[40:41]
	v_lshlrev_b32_e32 v2, 2, v2
	v_lshl_add_u64 v[56:57], v[56:57], 0, v[2:3]
	v_add_co_u32_e32 v76, vcc, 0x2c000, v56
	v_add_u32_e32 v2, 0x410, v60
	s_nop 0
	v_addc_co_u32_e32 v77, vcc, 0, v57, vcc
	v_add_co_u32_e32 v80, vcc, s56, v56
	global_load_dwordx4 v[72:75], v[56:57], off nt
	s_nop 0
	global_load_dwordx4 v[76:79], v[76:77], off nt
	v_addc_co_u32_e32 v81, vcc, 0, v57, vcc
	v_add_co_u32_e32 v84, vcc, 0x84000, v56
	s_lshl_b32 s40, s8, 1
	s_nop 0
	v_addc_co_u32_e32 v85, vcc, 0, v57, vcc
	global_load_dwordx4 v[80:83], v[80:81], off nt
	s_nop 0
	global_load_dwordx4 v[84:87], v[84:85], off nt
	v_add_co_u32_e32 v88, vcc, 0xb0000, v56
	s_nop 1
	v_addc_co_u32_e32 v89, vcc, 0, v57, vcc
	v_add_co_u32_e32 v92, vcc, 0xdc000, v56
	s_nop 1
	v_addc_co_u32_e32 v93, vcc, 0, v57, vcc
	global_load_dwordx4 v[88:91], v[88:89], off nt
	s_nop 0
	global_load_dwordx4 v[92:95], v[92:93], off nt
	v_add_co_u32_e32 v96, vcc, 0x108000, v56
	s_nop 1
	v_addc_co_u32_e32 v97, vcc, 0, v57, vcc
	v_add_co_u32_e32 v100, vcc, 0x134000, v56
	s_nop 1
	v_addc_co_u32_e32 v101, vcc, 0, v57, vcc
	global_load_dwordx4 v[96:99], v[96:97], off nt
	s_nop 0
	global_load_dwordx4 v[100:103], v[100:101], off nt
	v_add_co_u32_e32 v104, vcc, 0x160000, v56
	s_nop 1
	v_addc_co_u32_e32 v105, vcc, 0, v57, vcc
	v_add_co_u32_e32 v108, vcc, 0x18c000, v56
	s_nop 1
	v_addc_co_u32_e32 v109, vcc, 0, v57, vcc
	global_load_dwordx4 v[104:107], v[104:105], off nt
	s_nop 0
	global_load_dwordx4 v[108:111], v[108:109], off nt
	v_add_co_u32_e32 v112, vcc, 0x1b8000, v56
	s_nop 1
	v_addc_co_u32_e32 v113, vcc, 0, v57, vcc
	v_add_co_u32_e32 v116, vcc, 0x1e4000, v56
	s_nop 1
	v_addc_co_u32_e32 v117, vcc, 0, v57, vcc
	global_load_dwordx4 v[112:115], v[112:113], off nt
	s_nop 0
	global_load_dwordx4 v[116:119], v[116:117], off nt
	v_add_co_u32_e32 v120, vcc, 0x210000, v56
	s_nop 1
	v_addc_co_u32_e32 v121, vcc, 0, v57, vcc
	v_add_co_u32_e32 v124, vcc, 0x23c000, v56
	s_nop 1
	v_addc_co_u32_e32 v125, vcc, 0, v57, vcc
	global_load_dwordx4 v[120:123], v[120:121], off nt
	s_nop 0
	global_load_dwordx4 v[124:127], v[124:125], off nt
	v_add_co_u32_e32 v128, vcc, 0x268000, v56
	s_nop 1
	v_addc_co_u32_e32 v129, vcc, 0, v57, vcc
	global_load_dwordx4 v[128:131], v[128:129], off nt
	v_add_co_u32_e32 v56, vcc, 0x294000, v56
	s_nop 1
	v_addc_co_u32_e32 v57, vcc, 0, v57, vcc
	global_load_dwordx4 v[132:135], v[56:57], off nt
	s_waitcnt vmcnt(15)
	ds_write2_b32 v60, v72, v73 offset1:1
	ds_write2_b32 v60, v74, v75 offset0:2 offset1:3
	s_waitcnt vmcnt(14)
	ds_write2_b32 v2, v76, v77 offset1:1
	v_add_u32_e32 v2, 0x418, v60
	ds_write2_b32 v2, v78, v79 offset1:1
	v_add_u32_e32 v2, 0x820, v60
	v_lshl_add_u64 v[56:57], v[26:27], 0, s[40:41]
	s_waitcnt vmcnt(13)
	ds_write2_b32 v2, v80, v81 offset1:1
	v_add_u32_e32 v2, 0x828, v60
	ds_write2_b32 v2, v82, v83 offset1:1
	v_add_u32_e32 v2, 0xc30, v60
	s_waitcnt vmcnt(12)
	ds_write2_b32 v2, v84, v85 offset1:1
	v_add_u32_e32 v2, 0xc38, v60
	ds_write2_b32 v2, v86, v87 offset1:1
	v_add_u32_e32 v2, 0x1040, v60
	s_waitcnt vmcnt(11)
	ds_write2_b32 v2, v88, v89 offset1:1
	v_add_u32_e32 v2, 0x1048, v60
	ds_write2_b32 v2, v90, v91 offset1:1
	v_add_u32_e32 v2, 0x1450, v60
	s_waitcnt vmcnt(10)
	ds_write2_b32 v2, v92, v93 offset1:1
	v_add_u32_e32 v2, 0x1458, v60
	ds_write2_b32 v2, v94, v95 offset1:1
	v_add_u32_e32 v2, 0x1860, v60
	s_waitcnt vmcnt(9)
	ds_write2_b32 v2, v96, v97 offset1:1
	v_add_u32_e32 v2, 0x1868, v60
	ds_write2_b32 v2, v98, v99 offset1:1
	v_add_u32_e32 v2, 0x1c70, v60
	s_waitcnt vmcnt(8)
	ds_write2_b32 v2, v100, v101 offset1:1
	v_add_u32_e32 v2, 0x1c78, v60
	ds_write2_b32 v2, v102, v103 offset1:1
	v_add_u32_e32 v2, 0x2080, v60
	s_waitcnt vmcnt(7)
	ds_write2_b32 v2, v104, v105 offset1:1
	v_add_u32_e32 v2, 0x2088, v60
	ds_write2_b32 v2, v106, v107 offset1:1
	v_add_u32_e32 v2, 0x2490, v60
	s_waitcnt vmcnt(6)
	ds_write2_b32 v2, v108, v109 offset1:1
	v_add_u32_e32 v2, 0x2498, v60
	ds_write2_b32 v2, v110, v111 offset1:1
	v_add_u32_e32 v2, 0x28a0, v60
	s_waitcnt vmcnt(5)
	ds_write2_b32 v2, v112, v113 offset1:1
	v_add_u32_e32 v2, 0x28a8, v60
	ds_write2_b32 v2, v114, v115 offset1:1
	v_add_u32_e32 v2, 0x2cb0, v60
	s_waitcnt vmcnt(4)
	ds_write2_b32 v2, v116, v117 offset1:1
	v_add_u32_e32 v2, 0x2cb8, v60
	ds_write2_b32 v2, v118, v119 offset1:1
	v_add_u32_e32 v2, 0x30c0, v60
	s_waitcnt vmcnt(3)
	ds_write2_b32 v2, v120, v121 offset1:1
	v_add_u32_e32 v2, 0x30c8, v60
	ds_write2_b32 v2, v122, v123 offset1:1
	v_add_u32_e32 v2, 0x34d0, v60
	s_waitcnt vmcnt(2)
	ds_write2_b32 v2, v124, v125 offset1:1
	v_add_u32_e32 v2, 0x34d8, v60
	ds_write2_b32 v2, v126, v127 offset1:1
	v_add_u32_e32 v2, 0x38e0, v60
	s_waitcnt vmcnt(1)
	ds_write2_b32 v2, v128, v129 offset1:1
	v_add_u32_e32 v2, 0x38e8, v60
	ds_write2_b32 v2, v130, v131 offset1:1
	v_add_u32_e32 v2, 0x3cf0, v60
	s_waitcnt vmcnt(0)
	ds_write2_b32 v2, v132, v133 offset1:1
	v_add_u32_e32 v2, 0x3cf8, v60
	ds_write2_b32 v2, v134, v135 offset1:1
	s_waitcnt vmcnt(0) expcnt(0) lgkmcnt(0)
	ds_read2_b32 v[76:77], v62 offset1:8
	ds_read2_b32 v[78:79], v62 offset0:65 offset1:73
	ds_read2_b32 v[80:81], v62 offset0:130 offset1:138
	ds_read2_b32 v[82:83], v62 offset0:195 offset1:203
	s_waitcnt lgkmcnt(3)
	v_bfe_u32 v2, v76, 16, 1
	v_add3_u32 v2, v76, v2, s54
	s_waitcnt lgkmcnt(2)
	v_bfe_u32 v45, v78, 16, 1
	v_lshrrev_b32_e32 v2, 16, v2
	v_add3_u32 v45, v78, v45, s54
	v_and_or_b32 v72, v45, s55, v2
	v_add_u32_e32 v45, 0x400, v62
	ds_read2_b32 v[84:85], v45 offset0:4 offset1:12
	ds_read2_b32 v[86:87], v45 offset0:69 offset1:77
	s_waitcnt lgkmcnt(3)
; DI unsigned pk2w(float lo, float hi) { return f2bfw(lo) | (f2bfw(hi) << 16); }
; DI void transpose_item(const float* W, int K, int N, bf16_t* WT, int mode, float* scr, int item, int lane) {
;     ...
;     const int c = lane & 7;
; #pragma unroll
;     for (int j = 0; j < 8; ++j) { const int n = (lane >> 3) + 8 * j; const float* sp = scr + (8 * c) * 65 + n;
;         u32x4 o; o.x = pk2w(sp[0 * 65], sp[1 * 65]); o.y = pk2w(sp[2 * 65], sp[3 * 65]); o.z = pk2w(sp[4 * 65], sp[5 * 65]); o.w = pk2w(sp[6 * 65], sp[7 * 65]);
;         *(u32x4*)(WT + (size_t)(drow0 + n) * K + k0 + 8 * c) = o; }
	v_bfe_u32 v2, v80, 16, 1
	v_add3_u32 v2, v80, v2, s54
	s_waitcnt lgkmcnt(2)
	v_bfe_u32 v47, v82, 16, 1
	ds_read2_b32 v[88:89], v45 offset0:134 offset1:142
	v_lshrrev_b32_e32 v2, 16, v2
	v_add3_u32 v47, v82, v47, s54
	ds_read2_b32 v[90:91], v45 offset0:199 offset1:207
	v_and_or_b32 v73, v47, s55, v2
	s_waitcnt lgkmcnt(3)
	v_bfe_u32 v2, v84, 16, 1
	v_add3_u32 v2, v84, v2, s54
	s_waitcnt lgkmcnt(2)
	v_bfe_u32 v47, v86, 16, 1
	v_lshrrev_b32_e32 v2, 16, v2
	v_add3_u32 v47, v86, v47, s54
	v_and_or_b32 v74, v47, s55, v2
	s_waitcnt lgkmcnt(1)
	v_bfe_u32 v2, v88, 16, 1
	v_add3_u32 v2, v88, v2, s54
	s_waitcnt lgkmcnt(0)
	v_bfe_u32 v47, v90, 16, 1
	v_lshrrev_b32_e32 v2, 16, v2
	v_add3_u32 v47, v90, v47, s54
	v_and_or_b32 v75, v47, s55, v2
	v_add_u32_e32 v2, s10, v61
	v_lshlrev_b64 v[92:93], 12, v[2:3]
	v_bfe_u32 v2, v77, 16, 1
	v_add3_u32 v2, v77, v2, s54
	v_bfe_u32 v47, v79, 16, 1
	v_lshl_add_u64 v[92:93], v[56:57], 0, v[92:93]
	v_lshrrev_b32_e32 v2, 16, v2
	v_add3_u32 v47, v79, v47, s54
	global_store_dwordx4 v[92:93], v[72:75], off
	ds_read2_b32 v[76:77], v62 offset0:16 offset1:24
	s_nop 0
	v_and_or_b32 v72, v47, s55, v2
	v_bfe_u32 v2, v81, 16, 1
	v_add3_u32 v2, v81, v2, s54
	v_bfe_u32 v47, v83, 16, 1
	v_lshrrev_b32_e32 v2, 16, v2
	v_add3_u32 v47, v83, v47, s54
	v_and_or_b32 v73, v47, s55, v2
	v_bfe_u32 v2, v85, 16, 1
	v_add3_u32 v2, v85, v2, s54
	v_bfe_u32 v47, v87, 16, 1
	v_lshrrev_b32_e32 v2, 16, v2
	v_add3_u32 v47, v87, v47, s54
	v_and_or_b32 v74, v47, s55, v2
	v_bfe_u32 v2, v89, 16, 1
	v_add3_u32 v2, v89, v2, s54
	v_bfe_u32 v47, v91, 16, 1
	v_lshrrev_b32_e32 v2, 16, v2
	v_add3_u32 v47, v91, v47, s54
	v_and_or_b32 v75, v47, s55, v2
	v_add_u32_e32 v2, s10, v63
	v_lshlrev_b64 v[78:79], 12, v[2:3]
	v_lshl_add_u64 v[78:79], v[56:57], 0, v[78:79]
	global_store_dwordx4 v[78:79], v[72:75], off
	ds_read2_b32 v[78:79], v62 offset0:81 offset1:89
	ds_read2_b32 v[80:81], v62 offset0:146 offset1:154
	ds_read2_b32 v[82:83], v62 offset0:211 offset1:219
	s_waitcnt lgkmcnt(3)
	v_bfe_u32 v2, v76, 16, 1
	v_add3_u32 v2, v76, v2, s54
	s_waitcnt lgkmcnt(2)
	v_bfe_u32 v47, v78, 16, 1
	ds_read2_b32 v[84:85], v45 offset0:20 offset1:28
	v_lshrrev_b32_e32 v2, 16, v2
	v_add3_u32 v47, v78, v47, s54
	ds_read2_b32 v[86:87], v45 offset0:85 offset1:93
	v_and_or_b32 v72, v47, s55, v2
	s_waitcnt lgkmcnt(3)
	v_bfe_u32 v2, v80, 16, 1
	v_add3_u32 v2, v80, v2, s54
	s_waitcnt lgkmcnt(2)
	v_bfe_u32 v47, v82, 16, 1
	ds_read2_b32 v[88:89], v45 offset0:150 offset1:158
	v_lshrrev_b32_e32 v2, 16, v2
	v_add3_u32 v47, v82, v47, s54
	ds_read2_b32 v[90:91], v45 offset0:215 offset1:223
	v_and_or_b32 v73, v47, s55, v2
	s_waitcnt lgkmcnt(3)
	v_bfe_u32 v2, v84, 16, 1
	v_add3_u32 v2, v84, v2, s54
	s_waitcnt lgkmcnt(2)
	v_bfe_u32 v47, v86, 16, 1
	v_lshrrev_b32_e32 v2, 16, v2
	v_add3_u32 v47, v86, v47, s54
	v_and_or_b32 v74, v47, s55, v2
	s_waitcnt lgkmcnt(1)
	v_bfe_u32 v2, v88, 16, 1
	v_add3_u32 v2, v88, v2, s54
	s_waitcnt lgkmcnt(0)
	v_bfe_u32 v47, v90, 16, 1
	v_lshrrev_b32_e32 v2, 16, v2
	v_add3_u32 v47, v90, v47, s54
	v_and_or_b32 v75, v47, s55, v2
	v_add_u32_e32 v2, s10, v64
	v_lshlrev_b64 v[92:93], 12, v[2:3]
	v_bfe_u32 v2, v77, 16, 1
	v_add3_u32 v2, v77, v2, s54
	v_bfe_u32 v47, v79, 16, 1
	v_lshl_add_u64 v[92:93], v[56:57], 0, v[92:93]
	v_lshrrev_b32_e32 v2, 16, v2
	v_add3_u32 v47, v79, v47, s54
	global_store_dwordx4 v[92:93], v[72:75], off
	ds_read2_b32 v[76:77], v62 offset0:32 offset1:40
	s_nop 0
	v_and_or_b32 v72, v47, s55, v2
	v_bfe_u32 v2, v81, 16, 1
	v_add3_u32 v2, v81, v2, s54
	v_bfe_u32 v47, v83, 16, 1
	v_lshrrev_b32_e32 v2, 16, v2
	v_add3_u32 v47, v83, v47, s54
	v_and_or_b32 v73, v47, s55, v2
	v_bfe_u32 v2, v85, 16, 1
	v_add3_u32 v2, v85, v2, s54
	v_bfe_u32 v47, v87, 16, 1
	v_lshrrev_b32_e32 v2, 16, v2
	v_add3_u32 v47, v87, v47, s54
	v_and_or_b32 v74, v47, s55, v2
	v_bfe_u32 v2, v89, 16, 1
	v_add3_u32 v2, v89, v2, s54
	v_bfe_u32 v47, v91, 16, 1
	v_lshrrev_b32_e32 v2, 16, v2
	v_add3_u32 v47, v91, v47, s54
	v_and_or_b32 v75, v47, s55, v2
	v_add_u32_e32 v2, s10, v65
	v_lshlrev_b64 v[78:79], 12, v[2:3]
	v_lshl_add_u64 v[78:79], v[56:57], 0, v[78:79]
	global_store_dwordx4 v[78:79], v[72:75], off
	ds_read2_b32 v[78:79], v62 offset0:97 offset1:105
	ds_read2_b32 v[80:81], v62 offset0:162 offset1:170
	ds_read2_b32 v[82:83], v62 offset0:227 offset1:235
	s_waitcnt lgkmcnt(3)
	v_bfe_u32 v2, v76, 16, 1
	v_add3_u32 v2, v76, v2, s54
	s_waitcnt lgkmcnt(2)
; DI unsigned pk2w(float lo, float hi) { return f2bfw(lo) | (f2bfw(hi) << 16); }
; DI void transpose_item(const float* W, int K, int N, bf16_t* WT, int mode, float* scr, int item, int lane) {
;     ...
;     const int c = lane & 7;
; #pragma unroll
;     for (int j = 0; j < 8; ++j) { const int n = (lane >> 3) + 8 * j; const float* sp = scr + (8 * c) * 65 + n;
;         u32x4 o; o.x = pk2w(sp[0 * 65], sp[1 * 65]); o.y = pk2w(sp[2 * 65], sp[3 * 65]); o.z = pk2w(sp[4 * 65], sp[5 * 65]); o.w = pk2w(sp[6 * 65], sp[7 * 65]);
;         *(u32x4*)(WT + (size_t)(drow0 + n) * K + k0 + 8 * c) = o; }
;     __builtin_amdgcn_s_waitcnt(0); __builtin_amdgcn_wave_barrier();
	v_bfe_u32 v47, v78, 16, 1
	ds_read2_b32 v[84:85], v45 offset0:36 offset1:44
	v_lshrrev_b32_e32 v2, 16, v2
	v_add3_u32 v47, v78, v47, s54
	ds_read2_b32 v[86:87], v45 offset0:101 offset1:109
	v_and_or_b32 v72, v47, s55, v2
	s_waitcnt lgkmcnt(3)
	v_bfe_u32 v2, v80, 16, 1
	v_add3_u32 v2, v80, v2, s54
	s_waitcnt lgkmcnt(2)
	v_bfe_u32 v47, v82, 16, 1
	ds_read2_b32 v[88:89], v45 offset0:166 offset1:174
	v_lshrrev_b32_e32 v2, 16, v2
	v_add3_u32 v47, v82, v47, s54
	ds_read2_b32 v[90:91], v45 offset0:231 offset1:239
	v_and_or_b32 v73, v47, s55, v2
	s_waitcnt lgkmcnt(3)
	v_bfe_u32 v2, v84, 16, 1
	v_add3_u32 v2, v84, v2, s54
	s_waitcnt lgkmcnt(2)
	v_bfe_u32 v47, v86, 16, 1
	v_lshrrev_b32_e32 v2, 16, v2
	v_add3_u32 v47, v86, v47, s54
	v_and_or_b32 v74, v47, s55, v2
	s_waitcnt lgkmcnt(1)
	v_bfe_u32 v2, v88, 16, 1
	v_add3_u32 v2, v88, v2, s54
	s_waitcnt lgkmcnt(0)
	v_bfe_u32 v47, v90, 16, 1
	v_lshrrev_b32_e32 v2, 16, v2
	v_add3_u32 v47, v90, v47, s54
	v_and_or_b32 v75, v47, s55, v2
	v_add_u32_e32 v2, s10, v67
	v_lshlrev_b64 v[92:93], 12, v[2:3]
	v_bfe_u32 v2, v77, 16, 1
	v_add3_u32 v2, v77, v2, s54
	v_bfe_u32 v47, v79, 16, 1
	v_lshl_add_u64 v[92:93], v[56:57], 0, v[92:93]
	v_lshrrev_b32_e32 v2, 16, v2
	v_add3_u32 v47, v79, v47, s54
	global_store_dwordx4 v[92:93], v[72:75], off
	ds_read2_b32 v[76:77], v62 offset0:48 offset1:56
	s_nop 0
	v_and_or_b32 v72, v47, s55, v2
	v_bfe_u32 v2, v81, 16, 1
	v_add3_u32 v2, v81, v2, s54
	v_bfe_u32 v47, v83, 16, 1
	v_lshrrev_b32_e32 v2, 16, v2
	v_add3_u32 v47, v83, v47, s54
	v_and_or_b32 v73, v47, s55, v2
	v_bfe_u32 v2, v85, 16, 1
	v_add3_u32 v2, v85, v2, s54
	v_bfe_u32 v47, v87, 16, 1
	v_lshrrev_b32_e32 v2, 16, v2
	v_add3_u32 v47, v87, v47, s54
	v_and_or_b32 v74, v47, s55, v2
	v_bfe_u32 v2, v89, 16, 1
	v_add3_u32 v2, v89, v2, s54
	v_bfe_u32 v47, v91, 16, 1
	v_lshrrev_b32_e32 v2, 16, v2
	v_add3_u32 v47, v91, v47, s54
	v_and_or_b32 v75, v47, s55, v2
	v_add_u32_e32 v2, s10, v68
	v_lshlrev_b64 v[78:79], 12, v[2:3]
	v_lshl_add_u64 v[78:79], v[56:57], 0, v[78:79]
	global_store_dwordx4 v[78:79], v[72:75], off
	ds_read2_b32 v[78:79], v62 offset0:113 offset1:121
	ds_read2_b32 v[80:81], v62 offset0:178 offset1:186
	ds_read2_b32 v[82:83], v62 offset0:243 offset1:251
	s_waitcnt lgkmcnt(3)
	v_bfe_u32 v2, v76, 16, 1
	v_add3_u32 v2, v76, v2, s54
	s_waitcnt lgkmcnt(2)
	v_bfe_u32 v47, v78, 16, 1
	ds_read2_b32 v[84:85], v45 offset0:52 offset1:60
	v_lshrrev_b32_e32 v2, 16, v2
	v_add3_u32 v47, v78, v47, s54
	ds_read2_b32 v[86:87], v45 offset0:117 offset1:125
	v_and_or_b32 v72, v47, s55, v2
	s_waitcnt lgkmcnt(3)
	v_bfe_u32 v2, v80, 16, 1
	v_add3_u32 v2, v80, v2, s54
	s_waitcnt lgkmcnt(2)
	v_bfe_u32 v47, v82, 16, 1
	ds_read2_b32 v[88:89], v45 offset0:182 offset1:190
	v_lshrrev_b32_e32 v2, 16, v2
	v_add3_u32 v47, v82, v47, s54
	ds_read2_b32 v[90:91], v45 offset0:247 offset1:255
	v_and_or_b32 v73, v47, s55, v2
	s_waitcnt lgkmcnt(3)
	v_bfe_u32 v2, v84, 16, 1
	v_add3_u32 v2, v84, v2, s54
	s_waitcnt lgkmcnt(2)
	v_bfe_u32 v47, v86, 16, 1
	v_lshrrev_b32_e32 v2, 16, v2
	v_add3_u32 v47, v86, v47, s54
	v_and_or_b32 v74, v47, s55, v2
	s_waitcnt lgkmcnt(1)
	v_bfe_u32 v2, v88, 16, 1
	v_add3_u32 v2, v88, v2, s54
	s_waitcnt lgkmcnt(0)
	v_bfe_u32 v45, v90, 16, 1
	v_lshrrev_b32_e32 v2, 16, v2
	v_add3_u32 v45, v90, v45, s54
	v_and_or_b32 v75, v45, s55, v2
	v_add_u32_e32 v2, s10, v69
	v_lshlrev_b64 v[92:93], 12, v[2:3]
	v_bfe_u32 v2, v77, 16, 1
	v_add3_u32 v2, v77, v2, s54
	v_bfe_u32 v45, v79, 16, 1
	v_lshl_add_u64 v[92:93], v[56:57], 0, v[92:93]
	v_lshrrev_b32_e32 v2, 16, v2
	v_add3_u32 v45, v79, v45, s54
	global_store_dwordx4 v[92:93], v[72:75], off
	s_nop 1
	v_and_or_b32 v72, v45, s55, v2
	v_bfe_u32 v2, v81, 16, 1
	v_add3_u32 v2, v81, v2, s54
	v_bfe_u32 v45, v83, 16, 1
	v_lshrrev_b32_e32 v2, 16, v2
	v_add3_u32 v45, v83, v45, s54
	v_and_or_b32 v73, v45, s55, v2
	v_bfe_u32 v2, v85, 16, 1
	v_add3_u32 v2, v85, v2, s54
	v_bfe_u32 v45, v87, 16, 1
	v_lshrrev_b32_e32 v2, 16, v2
	v_add3_u32 v45, v87, v45, s54
	v_and_or_b32 v74, v45, s55, v2
	v_bfe_u32 v2, v89, 16, 1
	v_add3_u32 v2, v89, v2, s54
	v_bfe_u32 v45, v91, 16, 1
	v_lshrrev_b32_e32 v2, 16, v2
	v_add3_u32 v45, v91, v45, s54
	v_and_or_b32 v75, v45, s55, v2
	v_add_u32_e32 v2, s10, v70
	v_lshlrev_b64 v[76:77], 12, v[2:3]
	v_lshl_add_u64 v[56:57], v[56:57], 0, v[76:77]
	global_store_dwordx4 v[56:57], v[72:75], off
	s_waitcnt lgkmcnt(0)

; DI unsigned pk2w(float lo, float hi) { return f2bfw(lo) | (f2bfw(hi) << 16); }
; DI void transpose_item(const float* W, int K, int N, bf16_t* WT, int mode, float* scr, int item, int lane) {
;     const int nblk = N / 64, kb = item / nblk, nb = item % nblk, k0 = 64 * kb, n0 = 64 * nb;
;     int drow0 = n0;
;     if (mode == 1) { const int seg = n0 >> 10; const int dst = seg < 2 ? seg : (seg == 2 ? 6 : seg - 1); drow0 = dst * 1024 + (n0 & 1023); }
;     else if (mode == 2) { drow0 = n0 < DFF ? (n0 / 128) * 256 + (n0 % 128) : ((n0 - DFF) / 128) * 256 + 128 + ((n0 - DFF) % 128); }
;     else if (mode == 3) { drow0 = (n0 / 128) * 256 + (n0 % 128); }
;     else if (mode == 4) { drow0 = (n0 / 128) * 256 + 128 + (n0 % 128); }
;     f32x4 v[16];
; #pragma unroll
;     for (int i = 0; i < 16; ++i) v[i] = __builtin_nontemporal_load((const f32x4*)(W + (size_t)(k0 + 4 * i + (lane >> 4)) * N + n0 + 4 * (lane & 15)));
; #pragma unroll
;     for (int i = 0; i < 16; ++i) { float* d = scr + (4 * i + (lane >> 4)) * 65 + 4 * (lane & 15); d[0] = v[i][0]; d[1] = v[i][1]; d[2] = v[i][2]; d[3] = v[i][3]; }
;     __builtin_amdgcn_s_waitcnt(0); __builtin_amdgcn_wave_barrier();
;     const int c = lane & 7;
; #pragma unroll
;     for (int j = 0; j < 8; ++j) { const int n = (lane >> 3) + 8 * j; const float* sp = scr + (8 * c) * 65 + n;
;         u32x4 o; o.x = pk2w(sp[0 * 65], sp[1 * 65]); o.y = pk2w(sp[2 * 65], sp[3 * 65]); o.z = pk2w(sp[4 * 65], sp[5 * 65]); o.w = pk2w(sp[6 * 65], sp[7 * 65]);
.LBB0_38:
	s_andn2_b64 vcc, exec, s[8:9]
	s_cbranch_vccnz .LBB0_40
	s_add_i32 s9, s42, 0x4e00
	s_and_b32 s8, s15, 0x7c0
	s_and_b32 s9, s9, 0x1ffc0
	v_or_b32_e32 v2, s9, v59
	s_lshl_b32 s40, s8, 2
	v_lshl_add_u64 v[56:57], v[4:5], 0, s[40:41]
	v_lshlrev_b32_e32 v2, 13, v2
	v_lshl_add_u64 v[56:57], v[56:57], 0, v[2:3]
	v_add_co_u32_e32 v76, vcc, 0x8000, v56
	v_add_u32_e32 v2, 0x410, v60
	s_nop 0
	v_addc_co_u32_e32 v77, vcc, 0, v57, vcc
	v_add_co_u32_e32 v80, vcc, 0x10000, v56
	global_load_dwordx4 v[72:75], v[56:57], off nt
	s_nop 0
	global_load_dwordx4 v[76:79], v[76:77], off nt
	v_addc_co_u32_e32 v81, vcc, 0, v57, vcc
	v_add_co_u32_e32 v84, vcc, 0x18000, v56
	s_lshl_b32 s40, s9, 1
	s_nop 0
	v_addc_co_u32_e32 v85, vcc, 0, v57, vcc
	global_load_dwordx4 v[80:83], v[80:81], off nt
	s_nop 0
	global_load_dwordx4 v[84:87], v[84:85], off nt
	v_add_co_u32_e32 v88, vcc, 0x20000, v56
	s_nop 1
	v_addc_co_u32_e32 v89, vcc, 0, v57, vcc
	v_add_co_u32_e32 v92, vcc, 0x28000, v56
	s_nop 1
	v_addc_co_u32_e32 v93, vcc, 0, v57, vcc
	global_load_dwordx4 v[88:91], v[88:89], off nt
	s_nop 0
	global_load_dwordx4 v[92:95], v[92:93], off nt
	v_add_co_u32_e32 v96, vcc, 0x30000, v56
	s_nop 1
	v_addc_co_u32_e32 v97, vcc, 0, v57, vcc
	v_add_co_u32_e32 v100, vcc, 0x38000, v56
	s_nop 1
	v_addc_co_u32_e32 v101, vcc, 0, v57, vcc
	global_load_dwordx4 v[96:99], v[96:97], off nt
	s_nop 0
	global_load_dwordx4 v[100:103], v[100:101], off nt
	v_add_co_u32_e32 v104, vcc, 0x40000, v56
	s_nop 1
	v_addc_co_u32_e32 v105, vcc, 0, v57, vcc
	v_add_co_u32_e32 v108, vcc, 0x48000, v56
	s_nop 1
	v_addc_co_u32_e32 v109, vcc, 0, v57, vcc
	global_load_dwordx4 v[104:107], v[104:105], off nt
	s_nop 0
	global_load_dwordx4 v[108:111], v[108:109], off nt
	v_add_co_u32_e32 v112, vcc, 0x50000, v56
	s_nop 1
	v_addc_co_u32_e32 v113, vcc, 0, v57, vcc
	v_add_co_u32_e32 v116, vcc, 0x58000, v56
	s_nop 1
	v_addc_co_u32_e32 v117, vcc, 0, v57, vcc
	global_load_dwordx4 v[112:115], v[112:113], off nt
	s_nop 0
	global_load_dwordx4 v[116:119], v[116:117], off nt
	v_add_co_u32_e32 v120, vcc, 0x60000, v56
	s_nop 1
	v_addc_co_u32_e32 v121, vcc, 0, v57, vcc
	v_add_co_u32_e32 v124, vcc, 0x68000, v56
	s_nop 1
	v_addc_co_u32_e32 v125, vcc, 0, v57, vcc
	global_load_dwordx4 v[120:123], v[120:121], off nt
	s_nop 0
	global_load_dwordx4 v[124:127], v[124:125], off nt
	v_add_co_u32_e32 v128, vcc, 0x70000, v56
	s_nop 1
	v_addc_co_u32_e32 v129, vcc, 0, v57, vcc
	global_load_dwordx4 v[128:131], v[128:129], off nt
	v_add_co_u32_e32 v56, vcc, 0x78000, v56
	s_nop 1
	v_addc_co_u32_e32 v57, vcc, 0, v57, vcc
	global_load_dwordx4 v[132:135], v[56:57], off nt
	s_waitcnt vmcnt(15)
	ds_write2_b32 v60, v72, v73 offset1:1
	ds_write2_b32 v60, v74, v75 offset0:2 offset1:3
	s_waitcnt vmcnt(14)
	ds_write2_b32 v2, v76, v77 offset1:1
	v_add_u32_e32 v2, 0x418, v60
	ds_write2_b32 v2, v78, v79 offset1:1
	v_add_u32_e32 v2, 0x820, v60
	v_lshl_add_u64 v[56:57], v[28:29], 0, s[40:41]
	s_waitcnt vmcnt(13)
	ds_write2_b32 v2, v80, v81 offset1:1
	v_add_u32_e32 v2, 0x828, v60
	ds_write2_b32 v2, v82, v83 offset1:1
	v_add_u32_e32 v2, 0xc30, v60
	s_waitcnt vmcnt(12)
	ds_write2_b32 v2, v84, v85 offset1:1
	v_add_u32_e32 v2, 0xc38, v60
	ds_write2_b32 v2, v86, v87 offset1:1
	v_add_u32_e32 v2, 0x1040, v60
	s_waitcnt vmcnt(11)
	ds_write2_b32 v2, v88, v89 offset1:1
	v_add_u32_e32 v2, 0x1048, v60
	ds_write2_b32 v2, v90, v91 offset1:1
	v_add_u32_e32 v2, 0x1450, v60
	s_waitcnt vmcnt(10)
	ds_write2_b32 v2, v92, v93 offset1:1
	v_add_u32_e32 v2, 0x1458, v60
	ds_write2_b32 v2, v94, v95 offset1:1
	v_add_u32_e32 v2, 0x1860, v60
	s_waitcnt vmcnt(9)
	ds_write2_b32 v2, v96, v97 offset1:1
	v_add_u32_e32 v2, 0x1868, v60
	ds_write2_b32 v2, v98, v99 offset1:1
	v_add_u32_e32 v2, 0x1c70, v60
	s_waitcnt vmcnt(8)
	ds_write2_b32 v2, v100, v101 offset1:1
	v_add_u32_e32 v2, 0x1c78, v60
	ds_write2_b32 v2, v102, v103 offset1:1
	v_add_u32_e32 v2, 0x2080, v60
	s_waitcnt vmcnt(7)
	ds_write2_b32 v2, v104, v105 offset1:1
	v_add_u32_e32 v2, 0x2088, v60
	ds_write2_b32 v2, v106, v107 offset1:1
	v_add_u32_e32 v2, 0x2490, v60
	s_waitcnt vmcnt(6)
	ds_write2_b32 v2, v108, v109 offset1:1
	v_add_u32_e32 v2, 0x2498, v60
	ds_write2_b32 v2, v110, v111 offset1:1
	v_add_u32_e32 v2, 0x28a0, v60
	s_waitcnt vmcnt(5)
	ds_write2_b32 v2, v112, v113 offset1:1
	v_add_u32_e32 v2, 0x28a8, v60
	ds_write2_b32 v2, v114, v115 offset1:1
	v_add_u32_e32 v2, 0x2cb0, v60
	s_waitcnt vmcnt(4)
	ds_write2_b32 v2, v116, v117 offset1:1
	v_add_u32_e32 v2, 0x2cb8, v60
	ds_write2_b32 v2, v118, v119 offset1:1
	v_add_u32_e32 v2, 0x30c0, v60
	s_waitcnt vmcnt(3)
	ds_write2_b32 v2, v120, v121 offset1:1
	v_add_u32_e32 v2, 0x30c8, v60
	ds_write2_b32 v2, v122, v123 offset1:1
	v_add_u32_e32 v2, 0x34d0, v60
	s_waitcnt vmcnt(2)
	ds_write2_b32 v2, v124, v125 offset1:1
	v_add_u32_e32 v2, 0x34d8, v60
	ds_write2_b32 v2, v126, v127 offset1:1
	v_add_u32_e32 v2, 0x38e0, v60
	s_waitcnt vmcnt(1)
	ds_write2_b32 v2, v128, v129 offset1:1
	v_add_u32_e32 v2, 0x38e8, v60
	ds_write2_b32 v2, v130, v131 offset1:1
	v_add_u32_e32 v2, 0x3cf0, v60
	s_waitcnt vmcnt(0)
	ds_write2_b32 v2, v132, v133 offset1:1
	v_add_u32_e32 v2, 0x3cf8, v60
	ds_write2_b32 v2, v134, v135 offset1:1
	s_waitcnt vmcnt(0) expcnt(0) lgkmcnt(0)
	ds_read2_b32 v[76:77], v62 offset1:8
	ds_read2_b32 v[78:79], v62 offset0:65 offset1:73
	ds_read2_b32 v[80:81], v62 offset0:130 offset1:138
	ds_read2_b32 v[82:83], v62 offset0:195 offset1:203
	s_waitcnt lgkmcnt(3)
	v_bfe_u32 v2, v76, 16, 1
	v_add3_u32 v2, v76, v2, s54
	s_waitcnt lgkmcnt(2)
	v_bfe_u32 v45, v78, 16, 1
	v_lshrrev_b32_e32 v2, 16, v2
	v_add3_u32 v45, v78, v45, s54
	v_and_or_b32 v72, v45, s55, v2
	v_add_u32_e32 v45, 0x400, v62
	ds_read2_b32 v[84:85], v45 offset0:4 offset1:12
	ds_read2_b32 v[86:87], v45 offset0:69 offset1:77
	s_waitcnt lgkmcnt(3)
; DI unsigned pk2w(float lo, float hi) { return f2bfw(lo) | (f2bfw(hi) << 16); }
; DI void transpose_item(const float* W, int K, int N, bf16_t* WT, int mode, float* scr, int item, int lane) {
;     ...
;     const int c = lane & 7;
; #pragma unroll
;     for (int j = 0; j < 8; ++j) { const int n = (lane >> 3) + 8 * j; const float* sp = scr + (8 * c) * 65 + n;
;         u32x4 o; o.x = pk2w(sp[0 * 65], sp[1 * 65]); o.y = pk2w(sp[2 * 65], sp[3 * 65]); o.z = pk2w(sp[4 * 65], sp[5 * 65]); o.w = pk2w(sp[6 * 65], sp[7 * 65]);
;         *(u32x4*)(WT + (size_t)(drow0 + n) * K + k0 + 8 * c) = o; }
	v_bfe_u32 v2, v80, 16, 1
	v_add3_u32 v2, v80, v2, s54
	s_waitcnt lgkmcnt(2)
	v_bfe_u32 v47, v82, 16, 1
	ds_read2_b32 v[88:89], v45 offset0:134 offset1:142
	v_lshrrev_b32_e32 v2, 16, v2
	v_add3_u32 v47, v82, v47, s54
	ds_read2_b32 v[90:91], v45 offset0:199 offset1:207
	v_and_or_b32 v73, v47, s55, v2
	s_waitcnt lgkmcnt(3)
	v_bfe_u32 v2, v84, 16, 1
	v_add3_u32 v2, v84, v2, s54
	s_waitcnt lgkmcnt(2)
	v_bfe_u32 v47, v86, 16, 1
	v_lshrrev_b32_e32 v2, 16, v2
	v_add3_u32 v47, v86, v47, s54
	v_and_or_b32 v74, v47, s55, v2
	s_waitcnt lgkmcnt(1)
	v_bfe_u32 v2, v88, 16, 1
	v_add3_u32 v2, v88, v2, s54
	s_waitcnt lgkmcnt(0)
	v_bfe_u32 v47, v90, 16, 1
	v_lshrrev_b32_e32 v2, 16, v2
	v_add3_u32 v47, v90, v47, s54
	v_and_or_b32 v75, v47, s55, v2
	v_or_b32_e32 v2, s8, v61
	v_mul_u32_u24_e32 v2, 0xb00, v2
	v_lshlrev_b32_e32 v2, 1, v2
	v_lshl_add_u64 v[92:93], v[56:57], 0, v[2:3]
	v_bfe_u32 v2, v77, 16, 1
	v_add3_u32 v2, v77, v2, s54
	v_bfe_u32 v47, v79, 16, 1
	v_lshrrev_b32_e32 v2, 16, v2
	v_add3_u32 v47, v79, v47, s54
	global_store_dwordx4 v[92:93], v[72:75], off
	ds_read2_b32 v[76:77], v62 offset0:16 offset1:24
	s_nop 0
	v_and_or_b32 v72, v47, s55, v2
	v_bfe_u32 v2, v81, 16, 1
	v_add3_u32 v2, v81, v2, s54
	v_bfe_u32 v47, v83, 16, 1
	v_lshrrev_b32_e32 v2, 16, v2
	v_add3_u32 v47, v83, v47, s54
	v_and_or_b32 v73, v47, s55, v2
	v_bfe_u32 v2, v85, 16, 1
	v_add3_u32 v2, v85, v2, s54
	v_bfe_u32 v47, v87, 16, 1
	v_lshrrev_b32_e32 v2, 16, v2
	v_add3_u32 v47, v87, v47, s54
	v_and_or_b32 v74, v47, s55, v2
	v_bfe_u32 v2, v89, 16, 1
	v_add3_u32 v2, v89, v2, s54
	v_bfe_u32 v47, v91, 16, 1
	v_lshrrev_b32_e32 v2, 16, v2
	v_add3_u32 v47, v91, v47, s54
	v_and_or_b32 v75, v47, s55, v2
	v_or_b32_e32 v2, s8, v63
	v_mul_u32_u24_e32 v2, 0xb00, v2
	v_lshlrev_b32_e32 v2, 1, v2
	v_lshl_add_u64 v[78:79], v[56:57], 0, v[2:3]
	global_store_dwordx4 v[78:79], v[72:75], off
	ds_read2_b32 v[78:79], v62 offset0:81 offset1:89
	ds_read2_b32 v[80:81], v62 offset0:146 offset1:154
	ds_read2_b32 v[82:83], v62 offset0:211 offset1:219
	s_waitcnt lgkmcnt(3)
	v_bfe_u32 v2, v76, 16, 1
	v_add3_u32 v2, v76, v2, s54
	s_waitcnt lgkmcnt(2)
	v_bfe_u32 v47, v78, 16, 1
	ds_read2_b32 v[84:85], v45 offset0:20 offset1:28
	v_lshrrev_b32_e32 v2, 16, v2
	v_add3_u32 v47, v78, v47, s54
	ds_read2_b32 v[86:87], v45 offset0:85 offset1:93
	v_and_or_b32 v72, v47, s55, v2
	s_waitcnt lgkmcnt(3)
	v_bfe_u32 v2, v80, 16, 1
	v_add3_u32 v2, v80, v2, s54
	s_waitcnt lgkmcnt(2)
	v_bfe_u32 v47, v82, 16, 1
	ds_read2_b32 v[88:89], v45 offset0:150 offset1:158
	v_lshrrev_b32_e32 v2, 16, v2
	v_add3_u32 v47, v82, v47, s54
	ds_read2_b32 v[90:91], v45 offset0:215 offset1:223
	v_and_or_b32 v73, v47, s55, v2
	s_waitcnt lgkmcnt(3)
	v_bfe_u32 v2, v84, 16, 1
	v_add3_u32 v2, v84, v2, s54
	s_waitcnt lgkmcnt(2)
	v_bfe_u32 v47, v86, 16, 1
	v_lshrrev_b32_e32 v2, 16, v2
	v_add3_u32 v47, v86, v47, s54
	v_and_or_b32 v74, v47, s55, v2
	s_waitcnt lgkmcnt(1)
	v_bfe_u32 v2, v88, 16, 1
	v_add3_u32 v2, v88, v2, s54
	s_waitcnt lgkmcnt(0)
	v_bfe_u32 v47, v90, 16, 1
	v_lshrrev_b32_e32 v2, 16, v2
	v_add3_u32 v47, v90, v47, s54
	v_and_or_b32 v75, v47, s55, v2
	v_or_b32_e32 v2, s8, v64
	v_mul_u32_u24_e32 v2, 0xb00, v2
	v_lshlrev_b32_e32 v2, 1, v2
	v_lshl_add_u64 v[92:93], v[56:57], 0, v[2:3]
	v_bfe_u32 v2, v77, 16, 1
	v_add3_u32 v2, v77, v2, s54
	v_bfe_u32 v47, v79, 16, 1
	v_lshrrev_b32_e32 v2, 16, v2
	v_add3_u32 v47, v79, v47, s54
	global_store_dwordx4 v[92:93], v[72:75], off
	ds_read2_b32 v[76:77], v62 offset0:32 offset1:40
	s_nop 0
	v_and_or_b32 v72, v47, s55, v2
	v_bfe_u32 v2, v81, 16, 1
	v_add3_u32 v2, v81, v2, s54
	v_bfe_u32 v47, v83, 16, 1
	v_lshrrev_b32_e32 v2, 16, v2
	v_add3_u32 v47, v83, v47, s54
	v_and_or_b32 v73, v47, s55, v2
	v_bfe_u32 v2, v85, 16, 1
	v_add3_u32 v2, v85, v2, s54
	v_bfe_u32 v47, v87, 16, 1
	v_lshrrev_b32_e32 v2, 16, v2
	v_add3_u32 v47, v87, v47, s54
	v_and_or_b32 v74, v47, s55, v2
	v_bfe_u32 v2, v89, 16, 1
	v_add3_u32 v2, v89, v2, s54
	v_bfe_u32 v47, v91, 16, 1
	v_lshrrev_b32_e32 v2, 16, v2
	v_add3_u32 v47, v91, v47, s54
	v_and_or_b32 v75, v47, s55, v2
	v_or_b32_e32 v2, s8, v65
	v_mul_u32_u24_e32 v2, 0xb00, v2
	v_lshlrev_b32_e32 v2, 1, v2
	v_lshl_add_u64 v[78:79], v[56:57], 0, v[2:3]
	global_store_dwordx4 v[78:79], v[72:75], off
	ds_read2_b32 v[78:79], v62 offset0:97 offset1:105
	ds_read2_b32 v[80:81], v62 offset0:162 offset1:170
	ds_read2_b32 v[82:83], v62 offset0:227 offset1:235
	s_waitcnt lgkmcnt(3)
	v_bfe_u32 v2, v76, 16, 1
	v_add3_u32 v2, v76, v2, s54
	s_waitcnt lgkmcnt(2)
; DI unsigned pk2w(float lo, float hi) { return f2bfw(lo) | (f2bfw(hi) << 16); }
; DI void transpose_item(const float* W, int K, int N, bf16_t* WT, int mode, float* scr, int item, int lane) {
;     ...
;     const int c = lane & 7;
; #pragma unroll
;     for (int j = 0; j < 8; ++j) { const int n = (lane >> 3) + 8 * j; const float* sp = scr + (8 * c) * 65 + n;
;         u32x4 o; o.x = pk2w(sp[0 * 65], sp[1 * 65]); o.y = pk2w(sp[2 * 65], sp[3 * 65]); o.z = pk2w(sp[4 * 65], sp[5 * 65]); o.w = pk2w(sp[6 * 65], sp[7 * 65]);
;         *(u32x4*)(WT + (size_t)(drow0 + n) * K + k0 + 8 * c) = o; }
;     __builtin_amdgcn_s_waitcnt(0); __builtin_amdgcn_wave_barrier();
	v_bfe_u32 v47, v78, 16, 1
	ds_read2_b32 v[84:85], v45 offset0:36 offset1:44
	v_lshrrev_b32_e32 v2, 16, v2
	v_add3_u32 v47, v78, v47, s54
	ds_read2_b32 v[86:87], v45 offset0:101 offset1:109
	v_and_or_b32 v72, v47, s55, v2
	s_waitcnt lgkmcnt(3)
	v_bfe_u32 v2, v80, 16, 1
	v_add3_u32 v2, v80, v2, s54
	s_waitcnt lgkmcnt(2)
	v_bfe_u32 v47, v82, 16, 1
	ds_read2_b32 v[88:89], v45 offset0:166 offset1:174
	v_lshrrev_b32_e32 v2, 16, v2
	v_add3_u32 v47, v82, v47, s54
	ds_read2_b32 v[90:91], v45 offset0:231 offset1:239
	v_and_or_b32 v73, v47, s55, v2
	s_waitcnt lgkmcnt(3)
	v_bfe_u32 v2, v84, 16, 1
	v_add3_u32 v2, v84, v2, s54
	s_waitcnt lgkmcnt(2)
	v_bfe_u32 v47, v86, 16, 1
	v_lshrrev_b32_e32 v2, 16, v2
	v_add3_u32 v47, v86, v47, s54
	v_and_or_b32 v74, v47, s55, v2
	s_waitcnt lgkmcnt(1)
	v_bfe_u32 v2, v88, 16, 1
	v_add3_u32 v2, v88, v2, s54
	s_waitcnt lgkmcnt(0)
	v_bfe_u32 v47, v90, 16, 1
	v_lshrrev_b32_e32 v2, 16, v2
	v_add3_u32 v47, v90, v47, s54
	v_and_or_b32 v75, v47, s55, v2
	v_or_b32_e32 v2, s8, v67
	v_mul_u32_u24_e32 v2, 0xb00, v2
	v_lshlrev_b32_e32 v2, 1, v2
	v_lshl_add_u64 v[92:93], v[56:57], 0, v[2:3]
	v_bfe_u32 v2, v77, 16, 1
	v_add3_u32 v2, v77, v2, s54
	v_bfe_u32 v47, v79, 16, 1
	v_lshrrev_b32_e32 v2, 16, v2
	v_add3_u32 v47, v79, v47, s54
	global_store_dwordx4 v[92:93], v[72:75], off
	ds_read2_b32 v[76:77], v62 offset0:48 offset1:56
	s_nop 0
	v_and_or_b32 v72, v47, s55, v2
	v_bfe_u32 v2, v81, 16, 1
	v_add3_u32 v2, v81, v2, s54
	v_bfe_u32 v47, v83, 16, 1
	v_lshrrev_b32_e32 v2, 16, v2
	v_add3_u32 v47, v83, v47, s54
	v_and_or_b32 v73, v47, s55, v2
	v_bfe_u32 v2, v85, 16, 1
	v_add3_u32 v2, v85, v2, s54
	v_bfe_u32 v47, v87, 16, 1
	v_lshrrev_b32_e32 v2, 16, v2
	v_add3_u32 v47, v87, v47, s54
	v_and_or_b32 v74, v47, s55, v2
	v_bfe_u32 v2, v89, 16, 1
	v_add3_u32 v2, v89, v2, s54
	v_bfe_u32 v47, v91, 16, 1
	v_lshrrev_b32_e32 v2, 16, v2
	v_add3_u32 v47, v91, v47, s54
	v_and_or_b32 v75, v47, s55, v2
	v_or_b32_e32 v2, s8, v68
	v_mul_u32_u24_e32 v2, 0xb00, v2
	v_lshlrev_b32_e32 v2, 1, v2
	v_lshl_add_u64 v[78:79], v[56:57], 0, v[2:3]
	global_store_dwordx4 v[78:79], v[72:75], off
	ds_read2_b32 v[78:79], v62 offset0:113 offset1:121
	ds_read2_b32 v[80:81], v62 offset0:178 offset1:186
	ds_read2_b32 v[82:83], v62 offset0:243 offset1:251
	s_waitcnt lgkmcnt(3)
	v_bfe_u32 v2, v76, 16, 1
	v_add3_u32 v2, v76, v2, s54
	s_waitcnt lgkmcnt(2)
	v_bfe_u32 v47, v78, 16, 1
	ds_read2_b32 v[84:85], v45 offset0:52 offset1:60
	v_lshrrev_b32_e32 v2, 16, v2
	v_add3_u32 v47, v78, v47, s54
	ds_read2_b32 v[86:87], v45 offset0:117 offset1:125
	v_and_or_b32 v72, v47, s55, v2
	s_waitcnt lgkmcnt(3)
	v_bfe_u32 v2, v80, 16, 1
	v_add3_u32 v2, v80, v2, s54
	s_waitcnt lgkmcnt(2)
	v_bfe_u32 v47, v82, 16, 1
	ds_read2_b32 v[88:89], v45 offset0:182 offset1:190
	v_lshrrev_b32_e32 v2, 16, v2
	v_add3_u32 v47, v82, v47, s54
	ds_read2_b32 v[90:91], v45 offset0:247 offset1:255
	v_and_or_b32 v73, v47, s55, v2
	s_waitcnt lgkmcnt(3)
	v_bfe_u32 v2, v84, 16, 1
	v_add3_u32 v2, v84, v2, s54
	s_waitcnt lgkmcnt(2)
	v_bfe_u32 v47, v86, 16, 1
	v_lshrrev_b32_e32 v2, 16, v2
	v_add3_u32 v47, v86, v47, s54
	v_and_or_b32 v74, v47, s55, v2
	s_waitcnt lgkmcnt(1)
	v_bfe_u32 v2, v88, 16, 1
	v_add3_u32 v2, v88, v2, s54
	s_waitcnt lgkmcnt(0)
	v_bfe_u32 v45, v90, 16, 1
	v_lshrrev_b32_e32 v2, 16, v2
	v_add3_u32 v45, v90, v45, s54
	v_and_or_b32 v75, v45, s55, v2
	v_or_b32_e32 v2, s8, v69
	v_mul_u32_u24_e32 v2, 0xb00, v2
	v_lshlrev_b32_e32 v2, 1, v2
	v_lshl_add_u64 v[92:93], v[56:57], 0, v[2:3]
	v_bfe_u32 v2, v77, 16, 1
	v_add3_u32 v2, v77, v2, s54
	v_bfe_u32 v45, v79, 16, 1
	v_lshrrev_b32_e32 v2, 16, v2
	v_add3_u32 v45, v79, v45, s54
	global_store_dwordx4 v[92:93], v[72:75], off
	s_nop 1
	v_and_or_b32 v72, v45, s55, v2
	v_bfe_u32 v2, v81, 16, 1
	v_add3_u32 v2, v81, v2, s54
	v_bfe_u32 v45, v83, 16, 1
	v_lshrrev_b32_e32 v2, 16, v2
	v_add3_u32 v45, v83, v45, s54
	v_and_or_b32 v73, v45, s55, v2
	v_bfe_u32 v2, v85, 16, 1
	v_add3_u32 v2, v85, v2, s54
	v_bfe_u32 v45, v87, 16, 1
	v_lshrrev_b32_e32 v2, 16, v2
	v_add3_u32 v45, v87, v45, s54
	v_and_or_b32 v74, v45, s55, v2
	v_bfe_u32 v2, v89, 16, 1
	v_add3_u32 v2, v89, v2, s54
	v_bfe_u32 v45, v91, 16, 1
	v_lshrrev_b32_e32 v2, 16, v2
	v_add3_u32 v45, v91, v45, s54
	v_and_or_b32 v75, v45, s55, v2
	v_or_b32_e32 v2, s8, v70
	v_mul_u32_u24_e32 v2, 0xb00, v2
	v_lshlrev_b32_e32 v2, 1, v2
	v_lshl_add_u64 v[56:57], v[56:57], 0, v[2:3]
	global_store_dwordx4 v[56:57], v[72:75], off
	s_waitcnt lgkmcnt(0)

; DI unsigned pk2w(float lo, float hi) { return f2bfw(lo) | (f2bfw(hi) << 16); }
; DI void transpose_item(const float* W, int K, int N, bf16_t* WT, int mode, float* scr, int item, int lane) {
;     const int nblk = N / 64, kb = item / nblk, nb = item % nblk, k0 = 64 * kb, n0 = 64 * nb;
;     int drow0 = n0;
;     if (mode == 1) { const int seg = n0 >> 10; const int dst = seg < 2 ? seg : (seg == 2 ? 6 : seg - 1); drow0 = dst * 1024 + (n0 & 1023); }
;     else if (mode == 2) { drow0 = n0 < DFF ? (n0 / 128) * 256 + (n0 % 128) : ((n0 - DFF) / 128) * 256 + 128 + ((n0 - DFF) % 128); }
;     else if (mode == 3) { drow0 = (n0 / 128) * 256 + (n0 % 128); }
;     else if (mode == 4) { drow0 = (n0 / 128) * 256 + 128 + (n0 % 128); }
;     f32x4 v[16];
; #pragma unroll
;     for (int i = 0; i < 16; ++i) v[i] = __builtin_nontemporal_load((const f32x4*)(W + (size_t)(k0 + 4 * i + (lane >> 4)) * N + n0 + 4 * (lane & 15)));
; #pragma unroll
;     for (int i = 0; i < 16; ++i) { float* d = scr + (4 * i + (lane >> 4)) * 65 + 4 * (lane & 15); d[0] = v[i][0]; d[1] = v[i][1]; d[2] = v[i][2]; d[3] = v[i][3]; }
;     __builtin_amdgcn_s_waitcnt(0); __builtin_amdgcn_wave_barrier();
;     const int c = lane & 7;
; #pragma unroll
;     for (int j = 0; j < 8; ++j) { const int n = (lane >> 3) + 8 * j; const float* sp = scr + (8 * c) * 65 + n;
;         u32x4 o; o.x = pk2w(sp[0 * 65], sp[1 * 65]); o.y = pk2w(sp[2 * 65], sp[3 * 65]); o.z = pk2w(sp[4 * 65], sp[5 * 65]); o.w = pk2w(sp[6 * 65], sp[7 * 65]);
.LBB0_41:
	s_andn2_b64 vcc, exec, s[8:9]
	s_cbranch_vccnz .LBB0_43
	s_add_i32 s8, s81, 0xc880
	s_and_b32 s9, s8, 0xffff
	s_mul_i32 s9, s9, 0xba2f
	s_lshr_b32 s10, s9, 16
	s_lshr_b32 s9, s9, 22
	s_mulk_i32 s9, 0x58
	s_sub_i32 s8, s8, s9
	s_lshl_b32 s8, s8, 6
	s_and_b32 s9, s10, 0xffc0
	s_and_b32 s8, s8, 0xffc0
	v_or_b32_e32 v2, s9, v59
	s_lshl_b32 s40, s8, 2
	v_mul_u32_u24_e32 v2, 0x1600, v2
	v_lshl_add_u64 v[56:57], v[6:7], 0, s[40:41]
	v_lshlrev_b32_e32 v2, 2, v2
	v_lshl_add_u64 v[56:57], v[56:57], 0, v[2:3]
	v_add_co_u32_e32 v76, vcc, s67, v56
	v_add_u32_e32 v2, 0x410, v60
	s_nop 0
	v_addc_co_u32_e32 v77, vcc, 0, v57, vcc
	v_add_co_u32_e32 v80, vcc, s57, v56
	global_load_dwordx4 v[72:75], v[56:57], off nt
	s_nop 0
	global_load_dwordx4 v[76:79], v[76:77], off nt
	v_addc_co_u32_e32 v81, vcc, 0, v57, vcc
	v_add_co_u32_e32 v84, vcc, s68, v56
	s_lshl_b32 s40, s9, 1
	s_nop 0
	v_addc_co_u32_e32 v85, vcc, 0, v57, vcc
	global_load_dwordx4 v[80:83], v[80:81], off nt
	s_nop 0
	global_load_dwordx4 v[84:87], v[84:85], off nt
	v_add_co_u32_e32 v88, vcc, s56, v56
	s_nop 1
	v_addc_co_u32_e32 v89, vcc, 0, v57, vcc
	v_add_co_u32_e32 v92, vcc, s69, v56
	s_nop 1
	v_addc_co_u32_e32 v93, vcc, 0, v57, vcc
	global_load_dwordx4 v[88:91], v[88:89], off nt
	s_nop 0
	global_load_dwordx4 v[92:95], v[92:93], off nt
	v_add_co_u32_e32 v96, vcc, s58, v56
	s_nop 1
	v_addc_co_u32_e32 v97, vcc, 0, v57, vcc
	v_add_co_u32_e32 v100, vcc, s70, v56
	s_nop 1
	v_addc_co_u32_e32 v101, vcc, 0, v57, vcc
	global_load_dwordx4 v[96:99], v[96:97], off nt
	s_nop 0
	global_load_dwordx4 v[100:103], v[100:101], off nt
	v_add_co_u32_e32 v104, vcc, s59, v56
	s_nop 1
	v_addc_co_u32_e32 v105, vcc, 0, v57, vcc
	v_add_co_u32_e32 v108, vcc, s71, v56
	s_nop 1
	v_addc_co_u32_e32 v109, vcc, 0, v57, vcc
	global_load_dwordx4 v[104:107], v[104:105], off nt
	s_nop 0
	global_load_dwordx4 v[108:111], v[108:109], off nt
	v_add_co_u32_e32 v112, vcc, s64, v56
	s_nop 1
	v_addc_co_u32_e32 v113, vcc, 0, v57, vcc
	v_add_co_u32_e32 v116, vcc, s78, v56
	s_nop 1
	v_addc_co_u32_e32 v117, vcc, 0, v57, vcc
	global_load_dwordx4 v[112:115], v[112:113], off nt
	s_nop 0
	global_load_dwordx4 v[116:119], v[116:117], off nt
	v_add_co_u32_e32 v120, vcc, s65, v56
	s_nop 1
	v_addc_co_u32_e32 v121, vcc, 0, v57, vcc
	global_load_dwordx4 v[120:123], v[120:121], off nt
	v_add_co_u32_e32 v124, vcc, s79, v56
	s_nop 1
	v_addc_co_u32_e32 v125, vcc, 0, v57, vcc
	global_load_dwordx4 v[124:127], v[124:125], off nt
	v_add_co_u32_e32 v128, vcc, s66, v56
	s_nop 1
	v_addc_co_u32_e32 v129, vcc, 0, v57, vcc
	global_load_dwordx4 v[128:131], v[128:129], off nt
	v_add_co_u32_e32 v56, vcc, s80, v56
	s_nop 1
	v_addc_co_u32_e32 v57, vcc, 0, v57, vcc
	global_load_dwordx4 v[132:135], v[56:57], off nt
	s_waitcnt vmcnt(15)
	ds_write2_b32 v60, v72, v73 offset1:1
	ds_write2_b32 v60, v74, v75 offset0:2 offset1:3
	s_waitcnt vmcnt(14)
	ds_write2_b32 v2, v76, v77 offset1:1
	v_add_u32_e32 v2, 0x418, v60
	ds_write2_b32 v2, v78, v79 offset1:1
	v_add_u32_e32 v2, 0x820, v60
	v_lshl_add_u64 v[56:57], v[30:31], 0, s[40:41]
	s_waitcnt vmcnt(13)
	ds_write2_b32 v2, v80, v81 offset1:1
	v_add_u32_e32 v2, 0x828, v60
	ds_write2_b32 v2, v82, v83 offset1:1
	v_add_u32_e32 v2, 0xc30, v60
	s_waitcnt vmcnt(12)
	ds_write2_b32 v2, v84, v85 offset1:1
	v_add_u32_e32 v2, 0xc38, v60
	ds_write2_b32 v2, v86, v87 offset1:1
	v_add_u32_e32 v2, 0x1040, v60
	s_waitcnt vmcnt(11)
	ds_write2_b32 v2, v88, v89 offset1:1
	v_add_u32_e32 v2, 0x1048, v60
	ds_write2_b32 v2, v90, v91 offset1:1
	v_add_u32_e32 v2, 0x1450, v60
	s_waitcnt vmcnt(10)
	ds_write2_b32 v2, v92, v93 offset1:1
	v_add_u32_e32 v2, 0x1458, v60
	ds_write2_b32 v2, v94, v95 offset1:1
	v_add_u32_e32 v2, 0x1860, v60
	s_waitcnt vmcnt(9)
	ds_write2_b32 v2, v96, v97 offset1:1
	v_add_u32_e32 v2, 0x1868, v60
	ds_write2_b32 v2, v98, v99 offset1:1
	v_add_u32_e32 v2, 0x1c70, v60
	s_waitcnt vmcnt(8)
	ds_write2_b32 v2, v100, v101 offset1:1
	v_add_u32_e32 v2, 0x1c78, v60
	ds_write2_b32 v2, v102, v103 offset1:1
	v_add_u32_e32 v2, 0x2080, v60
	s_waitcnt vmcnt(7)
	ds_write2_b32 v2, v104, v105 offset1:1
	v_add_u32_e32 v2, 0x2088, v60
	ds_write2_b32 v2, v106, v107 offset1:1
	v_add_u32_e32 v2, 0x2490, v60
	s_waitcnt vmcnt(6)
	ds_write2_b32 v2, v108, v109 offset1:1
	v_add_u32_e32 v2, 0x2498, v60
	ds_write2_b32 v2, v110, v111 offset1:1
	v_add_u32_e32 v2, 0x28a0, v60
	s_waitcnt vmcnt(5)
	ds_write2_b32 v2, v112, v113 offset1:1
	v_add_u32_e32 v2, 0x28a8, v60
	ds_write2_b32 v2, v114, v115 offset1:1
	v_add_u32_e32 v2, 0x2cb0, v60
	s_waitcnt vmcnt(4)
	ds_write2_b32 v2, v116, v117 offset1:1
	v_add_u32_e32 v2, 0x2cb8, v60
	ds_write2_b32 v2, v118, v119 offset1:1
	v_add_u32_e32 v2, 0x30c0, v60
	s_waitcnt vmcnt(3)
	ds_write2_b32 v2, v120, v121 offset1:1
	v_add_u32_e32 v2, 0x30c8, v60
	ds_write2_b32 v2, v122, v123 offset1:1
	v_add_u32_e32 v2, 0x34d0, v60
	s_waitcnt vmcnt(2)
	ds_write2_b32 v2, v124, v125 offset1:1
	v_add_u32_e32 v2, 0x34d8, v60
	ds_write2_b32 v2, v126, v127 offset1:1
	v_add_u32_e32 v2, 0x38e0, v60
	s_waitcnt vmcnt(1)
	ds_write2_b32 v2, v128, v129 offset1:1
	v_add_u32_e32 v2, 0x38e8, v60
	ds_write2_b32 v2, v130, v131 offset1:1
	v_add_u32_e32 v2, 0x3cf0, v60
	s_waitcnt vmcnt(0)
	ds_write2_b32 v2, v132, v133 offset1:1
	v_add_u32_e32 v2, 0x3cf8, v60
	ds_write2_b32 v2, v134, v135 offset1:1
	s_waitcnt vmcnt(0) expcnt(0) lgkmcnt(0)
	ds_read2_b32 v[76:77], v62 offset1:8
	ds_read2_b32 v[78:79], v62 offset0:65 offset1:73
	ds_read2_b32 v[80:81], v62 offset0:130 offset1:138
	ds_read2_b32 v[82:83], v62 offset0:195 offset1:203
	s_waitcnt lgkmcnt(3)
	v_bfe_u32 v2, v76, 16, 1
	v_add3_u32 v2, v76, v2, s54
	s_waitcnt lgkmcnt(2)
; DI unsigned pk2w(float lo, float hi) { return f2bfw(lo) | (f2bfw(hi) << 16); }
; DI void transpose_item(const float* W, int K, int N, bf16_t* WT, int mode, float* scr, int item, int lane) {
;     ...
;     const int c = lane & 7;
; #pragma unroll
;     for (int j = 0; j < 8; ++j) { const int n = (lane >> 3) + 8 * j; const float* sp = scr + (8 * c) * 65 + n;
;         u32x4 o; o.x = pk2w(sp[0 * 65], sp[1 * 65]); o.y = pk2w(sp[2 * 65], sp[3 * 65]); o.z = pk2w(sp[4 * 65], sp[5 * 65]); o.w = pk2w(sp[6 * 65], sp[7 * 65]);
;         *(u32x4*)(WT + (size_t)(drow0 + n) * K + k0 + 8 * c) = o; }
	v_bfe_u32 v45, v78, 16, 1
	v_lshrrev_b32_e32 v2, 16, v2
	v_add3_u32 v45, v78, v45, s54
	v_and_or_b32 v72, v45, s55, v2
	v_add_u32_e32 v45, 0x400, v62
	ds_read2_b32 v[84:85], v45 offset0:4 offset1:12
	ds_read2_b32 v[86:87], v45 offset0:69 offset1:77
	s_waitcnt lgkmcnt(3)
	v_bfe_u32 v2, v80, 16, 1
	v_add3_u32 v2, v80, v2, s54
	s_waitcnt lgkmcnt(2)
	v_bfe_u32 v47, v82, 16, 1
	ds_read2_b32 v[88:89], v45 offset0:134 offset1:142
	v_lshrrev_b32_e32 v2, 16, v2
	v_add3_u32 v47, v82, v47, s54
	ds_read2_b32 v[90:91], v45 offset0:199 offset1:207
	v_and_or_b32 v73, v47, s55, v2
	s_waitcnt lgkmcnt(3)
	v_bfe_u32 v2, v84, 16, 1
	v_add3_u32 v2, v84, v2, s54
	s_waitcnt lgkmcnt(2)
	v_bfe_u32 v47, v86, 16, 1
	v_lshrrev_b32_e32 v2, 16, v2
	v_add3_u32 v47, v86, v47, s54
	v_and_or_b32 v74, v47, s55, v2
	s_waitcnt lgkmcnt(1)
	v_bfe_u32 v2, v88, 16, 1
	v_add3_u32 v2, v88, v2, s54
	s_waitcnt lgkmcnt(0)
	v_bfe_u32 v47, v90, 16, 1
	v_lshrrev_b32_e32 v2, 16, v2
	v_add3_u32 v47, v90, v47, s54
	v_and_or_b32 v75, v47, s55, v2
	v_or_b32_e32 v2, s8, v61
	v_lshlrev_b32_e32 v2, 12, v2
	v_lshl_add_u64 v[92:93], v[56:57], 0, v[2:3]
	v_bfe_u32 v2, v77, 16, 1
	v_add3_u32 v2, v77, v2, s54
	v_bfe_u32 v47, v79, 16, 1
	v_lshrrev_b32_e32 v2, 16, v2
	v_add3_u32 v47, v79, v47, s54
	global_store_dwordx4 v[92:93], v[72:75], off
	ds_read2_b32 v[76:77], v62 offset0:16 offset1:24
	s_nop 0
	v_and_or_b32 v72, v47, s55, v2
	v_bfe_u32 v2, v81, 16, 1
	v_add3_u32 v2, v81, v2, s54
	v_bfe_u32 v47, v83, 16, 1
	v_lshrrev_b32_e32 v2, 16, v2
	v_add3_u32 v47, v83, v47, s54
	v_and_or_b32 v73, v47, s55, v2
	v_bfe_u32 v2, v85, 16, 1
	v_add3_u32 v2, v85, v2, s54
	v_bfe_u32 v47, v87, 16, 1
	v_lshrrev_b32_e32 v2, 16, v2
	v_add3_u32 v47, v87, v47, s54
	v_and_or_b32 v74, v47, s55, v2
	v_bfe_u32 v2, v89, 16, 1
	v_add3_u32 v2, v89, v2, s54
	v_bfe_u32 v47, v91, 16, 1
	v_lshrrev_b32_e32 v2, 16, v2
	v_add3_u32 v47, v91, v47, s54
	v_and_or_b32 v75, v47, s55, v2
	v_or_b32_e32 v2, s8, v63
	v_lshlrev_b32_e32 v2, 12, v2
	v_lshl_add_u64 v[78:79], v[56:57], 0, v[2:3]
	global_store_dwordx4 v[78:79], v[72:75], off
	ds_read2_b32 v[78:79], v62 offset0:81 offset1:89
	ds_read2_b32 v[80:81], v62 offset0:146 offset1:154
	ds_read2_b32 v[82:83], v62 offset0:211 offset1:219
	s_waitcnt lgkmcnt(3)
	v_bfe_u32 v2, v76, 16, 1
	v_add3_u32 v2, v76, v2, s54
	s_waitcnt lgkmcnt(2)
	v_bfe_u32 v47, v78, 16, 1
	ds_read2_b32 v[84:85], v45 offset0:20 offset1:28
	v_lshrrev_b32_e32 v2, 16, v2
	v_add3_u32 v47, v78, v47, s54
	ds_read2_b32 v[86:87], v45 offset0:85 offset1:93
	v_and_or_b32 v72, v47, s55, v2
	s_waitcnt lgkmcnt(3)
	v_bfe_u32 v2, v80, 16, 1
	v_add3_u32 v2, v80, v2, s54
	s_waitcnt lgkmcnt(2)
	v_bfe_u32 v47, v82, 16, 1
	ds_read2_b32 v[88:89], v45 offset0:150 offset1:158
	v_lshrrev_b32_e32 v2, 16, v2
	v_add3_u32 v47, v82, v47, s54
	ds_read2_b32 v[90:91], v45 offset0:215 offset1:223
	v_and_or_b32 v73, v47, s55, v2
	s_waitcnt lgkmcnt(3)
	v_bfe_u32 v2, v84, 16, 1
	v_add3_u32 v2, v84, v2, s54
	s_waitcnt lgkmcnt(2)
	v_bfe_u32 v47, v86, 16, 1
	v_lshrrev_b32_e32 v2, 16, v2
	v_add3_u32 v47, v86, v47, s54
	v_and_or_b32 v74, v47, s55, v2
	s_waitcnt lgkmcnt(1)
	v_bfe_u32 v2, v88, 16, 1
	v_add3_u32 v2, v88, v2, s54
	s_waitcnt lgkmcnt(0)
	v_bfe_u32 v47, v90, 16, 1
	v_lshrrev_b32_e32 v2, 16, v2
	v_add3_u32 v47, v90, v47, s54
	v_and_or_b32 v75, v47, s55, v2
	v_or_b32_e32 v2, s8, v64
	v_lshlrev_b32_e32 v2, 12, v2
	v_lshl_add_u64 v[92:93], v[56:57], 0, v[2:3]
	v_bfe_u32 v2, v77, 16, 1
	v_add3_u32 v2, v77, v2, s54
	v_bfe_u32 v47, v79, 16, 1
	v_lshrrev_b32_e32 v2, 16, v2
	v_add3_u32 v47, v79, v47, s54
	global_store_dwordx4 v[92:93], v[72:75], off
	ds_read2_b32 v[76:77], v62 offset0:32 offset1:40
	s_nop 0
	v_and_or_b32 v72, v47, s55, v2
	v_bfe_u32 v2, v81, 16, 1
	v_add3_u32 v2, v81, v2, s54
	v_bfe_u32 v47, v83, 16, 1
	v_lshrrev_b32_e32 v2, 16, v2
	v_add3_u32 v47, v83, v47, s54
	v_and_or_b32 v73, v47, s55, v2
	v_bfe_u32 v2, v85, 16, 1
	v_add3_u32 v2, v85, v2, s54
	v_bfe_u32 v47, v87, 16, 1
	v_lshrrev_b32_e32 v2, 16, v2
	v_add3_u32 v47, v87, v47, s54
	v_and_or_b32 v74, v47, s55, v2
	v_bfe_u32 v2, v89, 16, 1
	v_add3_u32 v2, v89, v2, s54
	v_bfe_u32 v47, v91, 16, 1
	v_lshrrev_b32_e32 v2, 16, v2
	v_add3_u32 v47, v91, v47, s54
	v_and_or_b32 v75, v47, s55, v2
	v_or_b32_e32 v2, s8, v65
	v_lshlrev_b32_e32 v2, 12, v2
	v_lshl_add_u64 v[78:79], v[56:57], 0, v[2:3]
	global_store_dwordx4 v[78:79], v[72:75], off
	ds_read2_b32 v[78:79], v62 offset0:97 offset1:105
	ds_read2_b32 v[80:81], v62 offset0:162 offset1:170
	ds_read2_b32 v[82:83], v62 offset0:227 offset1:235
	s_waitcnt lgkmcnt(3)
; DI unsigned pk2w(float lo, float hi) { return f2bfw(lo) | (f2bfw(hi) << 16); }
; DI void transpose_item(const float* W, int K, int N, bf16_t* WT, int mode, float* scr, int item, int lane) {
;     ...
;     const int c = lane & 7;
; #pragma unroll
;     for (int j = 0; j < 8; ++j) { const int n = (lane >> 3) + 8 * j; const float* sp = scr + (8 * c) * 65 + n;
;         u32x4 o; o.x = pk2w(sp[0 * 65], sp[1 * 65]); o.y = pk2w(sp[2 * 65], sp[3 * 65]); o.z = pk2w(sp[4 * 65], sp[5 * 65]); o.w = pk2w(sp[6 * 65], sp[7 * 65]);
;         *(u32x4*)(WT + (size_t)(drow0 + n) * K + k0 + 8 * c) = o; }
;     __builtin_amdgcn_s_waitcnt(0); __builtin_amdgcn_wave_barrier();
	v_bfe_u32 v2, v76, 16, 1
	v_add3_u32 v2, v76, v2, s54
	s_waitcnt lgkmcnt(2)
	v_bfe_u32 v47, v78, 16, 1
	ds_read2_b32 v[84:85], v45 offset0:36 offset1:44
	v_lshrrev_b32_e32 v2, 16, v2
	v_add3_u32 v47, v78, v47, s54
	ds_read2_b32 v[86:87], v45 offset0:101 offset1:109
	v_and_or_b32 v72, v47, s55, v2
	s_waitcnt lgkmcnt(3)
	v_bfe_u32 v2, v80, 16, 1
	v_add3_u32 v2, v80, v2, s54
	s_waitcnt lgkmcnt(2)
	v_bfe_u32 v47, v82, 16, 1
	ds_read2_b32 v[88:89], v45 offset0:166 offset1:174
	v_lshrrev_b32_e32 v2, 16, v2
	v_add3_u32 v47, v82, v47, s54
	ds_read2_b32 v[90:91], v45 offset0:231 offset1:239
	v_and_or_b32 v73, v47, s55, v2
	s_waitcnt lgkmcnt(3)
	v_bfe_u32 v2, v84, 16, 1
	v_add3_u32 v2, v84, v2, s54
	s_waitcnt lgkmcnt(2)
	v_bfe_u32 v47, v86, 16, 1
	v_lshrrev_b32_e32 v2, 16, v2
	v_add3_u32 v47, v86, v47, s54
	v_and_or_b32 v74, v47, s55, v2
	s_waitcnt lgkmcnt(1)
	v_bfe_u32 v2, v88, 16, 1
	v_add3_u32 v2, v88, v2, s54
	s_waitcnt lgkmcnt(0)
	v_bfe_u32 v47, v90, 16, 1
	v_lshrrev_b32_e32 v2, 16, v2
	v_add3_u32 v47, v90, v47, s54
	v_and_or_b32 v75, v47, s55, v2
	v_or_b32_e32 v2, s8, v67
	v_lshlrev_b32_e32 v2, 12, v2
	v_lshl_add_u64 v[92:93], v[56:57], 0, v[2:3]
	v_bfe_u32 v2, v77, 16, 1
	v_add3_u32 v2, v77, v2, s54
	v_bfe_u32 v47, v79, 16, 1
	v_lshrrev_b32_e32 v2, 16, v2
	v_add3_u32 v47, v79, v47, s54
	global_store_dwordx4 v[92:93], v[72:75], off
	ds_read2_b32 v[76:77], v62 offset0:48 offset1:56
	s_nop 0
	v_and_or_b32 v72, v47, s55, v2
	v_bfe_u32 v2, v81, 16, 1
	v_add3_u32 v2, v81, v2, s54
	v_bfe_u32 v47, v83, 16, 1
	v_lshrrev_b32_e32 v2, 16, v2
	v_add3_u32 v47, v83, v47, s54
	v_and_or_b32 v73, v47, s55, v2
	v_bfe_u32 v2, v85, 16, 1
	v_add3_u32 v2, v85, v2, s54
	v_bfe_u32 v47, v87, 16, 1
	v_lshrrev_b32_e32 v2, 16, v2
	v_add3_u32 v47, v87, v47, s54
	v_and_or_b32 v74, v47, s55, v2
	v_bfe_u32 v2, v89, 16, 1
	v_add3_u32 v2, v89, v2, s54
	v_bfe_u32 v47, v91, 16, 1
	v_lshrrev_b32_e32 v2, 16, v2
	v_add3_u32 v47, v91, v47, s54
	v_and_or_b32 v75, v47, s55, v2
	v_or_b32_e32 v2, s8, v68
	v_lshlrev_b32_e32 v2, 12, v2
	v_lshl_add_u64 v[78:79], v[56:57], 0, v[2:3]
	global_store_dwordx4 v[78:79], v[72:75], off
	ds_read2_b32 v[78:79], v62 offset0:113 offset1:121
	ds_read2_b32 v[80:81], v62 offset0:178 offset1:186
	ds_read2_b32 v[82:83], v62 offset0:243 offset1:251
	s_waitcnt lgkmcnt(3)
	v_bfe_u32 v2, v76, 16, 1
	v_add3_u32 v2, v76, v2, s54
	s_waitcnt lgkmcnt(2)
	v_bfe_u32 v47, v78, 16, 1
	ds_read2_b32 v[84:85], v45 offset0:52 offset1:60
	v_lshrrev_b32_e32 v2, 16, v2
	v_add3_u32 v47, v78, v47, s54
	ds_read2_b32 v[86:87], v45 offset0:117 offset1:125
	v_and_or_b32 v72, v47, s55, v2
	s_waitcnt lgkmcnt(3)
	v_bfe_u32 v2, v80, 16, 1
	v_add3_u32 v2, v80, v2, s54
	s_waitcnt lgkmcnt(2)
	v_bfe_u32 v47, v82, 16, 1
	ds_read2_b32 v[88:89], v45 offset0:182 offset1:190
	v_lshrrev_b32_e32 v2, 16, v2
	v_add3_u32 v47, v82, v47, s54
	ds_read2_b32 v[90:91], v45 offset0:247 offset1:255
	v_and_or_b32 v73, v47, s55, v2
	s_waitcnt lgkmcnt(3)
	v_bfe_u32 v2, v84, 16, 1
	v_add3_u32 v2, v84, v2, s54
	s_waitcnt lgkmcnt(2)
	v_bfe_u32 v47, v86, 16, 1
	v_lshrrev_b32_e32 v2, 16, v2
	v_add3_u32 v47, v86, v47, s54
	v_and_or_b32 v74, v47, s55, v2
	s_waitcnt lgkmcnt(1)
	v_bfe_u32 v2, v88, 16, 1
	v_add3_u32 v2, v88, v2, s54
	s_waitcnt lgkmcnt(0)
	v_bfe_u32 v45, v90, 16, 1
	v_lshrrev_b32_e32 v2, 16, v2
	v_add3_u32 v45, v90, v45, s54
	v_and_or_b32 v75, v45, s55, v2
	v_or_b32_e32 v2, s8, v69
	v_lshlrev_b32_e32 v2, 12, v2
	v_lshl_add_u64 v[92:93], v[56:57], 0, v[2:3]
	v_bfe_u32 v2, v77, 16, 1
	v_add3_u32 v2, v77, v2, s54
	v_bfe_u32 v45, v79, 16, 1
	v_lshrrev_b32_e32 v2, 16, v2
	v_add3_u32 v45, v79, v45, s54
	global_store_dwordx4 v[92:93], v[72:75], off
	s_nop 1
	v_and_or_b32 v72, v45, s55, v2
	v_bfe_u32 v2, v81, 16, 1
	v_add3_u32 v2, v81, v2, s54
	v_bfe_u32 v45, v83, 16, 1
	v_lshrrev_b32_e32 v2, 16, v2
	v_add3_u32 v45, v83, v45, s54
	v_and_or_b32 v73, v45, s55, v2
	v_bfe_u32 v2, v85, 16, 1
	v_add3_u32 v2, v85, v2, s54
	v_bfe_u32 v45, v87, 16, 1
	v_lshrrev_b32_e32 v2, 16, v2
	v_add3_u32 v45, v87, v45, s54
	v_and_or_b32 v74, v45, s55, v2
	v_bfe_u32 v2, v89, 16, 1
	v_add3_u32 v2, v89, v2, s54
	v_bfe_u32 v45, v91, 16, 1
	v_lshrrev_b32_e32 v2, 16, v2
	v_add3_u32 v45, v91, v45, s54
	v_and_or_b32 v75, v45, s55, v2
	v_or_b32_e32 v2, s8, v70
	v_lshlrev_b32_e32 v2, 12, v2
	v_lshl_add_u64 v[56:57], v[56:57], 0, v[2:3]
	global_store_dwordx4 v[56:57], v[72:75], off
	s_waitcnt lgkmcnt(0)

; DI unsigned pk2w(float lo, float hi) { return f2bfw(lo) | (f2bfw(hi) << 16); }
; DI void transpose_item(const float* W, int K, int N, bf16_t* WT, int mode, float* scr, int item, int lane) {
;     const int nblk = N / 64, kb = item / nblk, nb = item % nblk, k0 = 64 * kb, n0 = 64 * nb;
;     int drow0 = n0;
;     if (mode == 1) { const int seg = n0 >> 10; const int dst = seg < 2 ? seg : (seg == 2 ? 6 : seg - 1); drow0 = dst * 1024 + (n0 & 1023); }
;     else if (mode == 2) { drow0 = n0 < DFF ? (n0 / 128) * 256 + (n0 % 128) : ((n0 - DFF) / 128) * 256 + 128 + ((n0 - DFF) % 128); }
;     else if (mode == 3) { drow0 = (n0 / 128) * 256 + (n0 % 128); }
;     else if (mode == 4) { drow0 = (n0 / 128) * 256 + 128 + (n0 % 128); }
;     f32x4 v[16];
; #pragma unroll
;     for (int i = 0; i < 16; ++i) v[i] = __builtin_nontemporal_load((const f32x4*)(W + (size_t)(k0 + 4 * i + (lane >> 4)) * N + n0 + 4 * (lane & 15)));
; #pragma unroll
;     for (int i = 0; i < 16; ++i) { float* d = scr + (4 * i + (lane >> 4)) * 65 + 4 * (lane & 15); d[0] = v[i][0]; d[1] = v[i][1]; d[2] = v[i][2]; d[3] = v[i][3]; }
;     __builtin_amdgcn_s_waitcnt(0); __builtin_amdgcn_wave_barrier();
;     const int c = lane & 7;
; #pragma unroll
;     for (int j = 0; j < 8; ++j) { const int n = (lane >> 3) + 8 * j; const float* sp = scr + (8 * c) * 65 + n;
;         u32x4 o; o.x = pk2w(sp[0 * 65], sp[1 * 65]); o.y = pk2w(sp[2 * 65], sp[3 * 65]); o.z = pk2w(sp[4 * 65], sp[5 * 65]); o.w = pk2w(sp[6 * 65], sp[7 * 65]);
.LBB0_44:
	s_andn2_b64 vcc, exec, s[8:9]
	s_cbranch_vccnz .LBB0_46
	s_add_i32 s9, s42, 0x6c00
	s_and_b32 s8, s15, 0x7c0
	s_and_b32 s9, s9, 0x1ffc0
	v_or_b32_e32 v2, s9, v59
	s_lshl_b32 s40, s8, 2
	v_lshl_add_u64 v[56:57], v[8:9], 0, s[40:41]
	v_lshlrev_b32_e32 v2, 13, v2
	v_lshl_add_u64 v[56:57], v[56:57], 0, v[2:3]
	v_add_co_u32_e32 v76, vcc, 0x8000, v56
	v_add_u32_e32 v2, 0x410, v60
	s_nop 0
	v_addc_co_u32_e32 v77, vcc, 0, v57, vcc
	v_add_co_u32_e32 v80, vcc, 0x10000, v56
	global_load_dwordx4 v[72:75], v[56:57], off nt
	s_nop 0
	global_load_dwordx4 v[76:79], v[76:77], off nt
	v_addc_co_u32_e32 v81, vcc, 0, v57, vcc
	v_add_co_u32_e32 v84, vcc, 0x18000, v56
	s_lshl_b32 s40, s9, 1
	s_nop 0
	v_addc_co_u32_e32 v85, vcc, 0, v57, vcc
	global_load_dwordx4 v[80:83], v[80:81], off nt
	s_nop 0
	global_load_dwordx4 v[84:87], v[84:85], off nt
	v_add_co_u32_e32 v88, vcc, 0x20000, v56
	s_nop 1
	v_addc_co_u32_e32 v89, vcc, 0, v57, vcc
	v_add_co_u32_e32 v92, vcc, 0x28000, v56
	s_nop 1
	v_addc_co_u32_e32 v93, vcc, 0, v57, vcc
	global_load_dwordx4 v[88:91], v[88:89], off nt
	s_nop 0
	global_load_dwordx4 v[92:95], v[92:93], off nt
	v_add_co_u32_e32 v96, vcc, 0x30000, v56
	s_nop 1
	v_addc_co_u32_e32 v97, vcc, 0, v57, vcc
	v_add_co_u32_e32 v100, vcc, 0x38000, v56
	s_nop 1
	v_addc_co_u32_e32 v101, vcc, 0, v57, vcc
	global_load_dwordx4 v[96:99], v[96:97], off nt
	s_nop 0
	global_load_dwordx4 v[100:103], v[100:101], off nt
	v_add_co_u32_e32 v104, vcc, 0x40000, v56
	s_nop 1
	v_addc_co_u32_e32 v105, vcc, 0, v57, vcc
	v_add_co_u32_e32 v108, vcc, 0x48000, v56
	s_nop 1
	v_addc_co_u32_e32 v109, vcc, 0, v57, vcc
	global_load_dwordx4 v[104:107], v[104:105], off nt
	s_nop 0
	global_load_dwordx4 v[108:111], v[108:109], off nt
	v_add_co_u32_e32 v112, vcc, 0x50000, v56
	s_nop 1
	v_addc_co_u32_e32 v113, vcc, 0, v57, vcc
	v_add_co_u32_e32 v116, vcc, 0x58000, v56
	s_nop 1
	v_addc_co_u32_e32 v117, vcc, 0, v57, vcc
	global_load_dwordx4 v[112:115], v[112:113], off nt
	s_nop 0
	global_load_dwordx4 v[116:119], v[116:117], off nt
	v_add_co_u32_e32 v120, vcc, 0x60000, v56
	s_nop 1
	v_addc_co_u32_e32 v121, vcc, 0, v57, vcc
	v_add_co_u32_e32 v124, vcc, 0x68000, v56
	s_nop 1
	v_addc_co_u32_e32 v125, vcc, 0, v57, vcc
	global_load_dwordx4 v[120:123], v[120:121], off nt
	s_nop 0
	global_load_dwordx4 v[124:127], v[124:125], off nt
	v_add_co_u32_e32 v128, vcc, 0x70000, v56
	s_nop 1
	v_addc_co_u32_e32 v129, vcc, 0, v57, vcc
	global_load_dwordx4 v[128:131], v[128:129], off nt
	v_add_co_u32_e32 v56, vcc, 0x78000, v56
	s_nop 1
	v_addc_co_u32_e32 v57, vcc, 0, v57, vcc
	global_load_dwordx4 v[132:135], v[56:57], off nt
	s_waitcnt vmcnt(15)
	ds_write2_b32 v60, v72, v73 offset1:1
	ds_write2_b32 v60, v74, v75 offset0:2 offset1:3
	s_waitcnt vmcnt(14)
	ds_write2_b32 v2, v76, v77 offset1:1
	v_add_u32_e32 v2, 0x418, v60
	ds_write2_b32 v2, v78, v79 offset1:1
	v_add_u32_e32 v2, 0x820, v60
	v_lshl_add_u64 v[56:57], v[32:33], 0, s[40:41]
	s_waitcnt vmcnt(13)
	ds_write2_b32 v2, v80, v81 offset1:1
	v_add_u32_e32 v2, 0x828, v60
	ds_write2_b32 v2, v82, v83 offset1:1
	v_add_u32_e32 v2, 0xc30, v60
	s_waitcnt vmcnt(12)
	ds_write2_b32 v2, v84, v85 offset1:1
	v_add_u32_e32 v2, 0xc38, v60
	ds_write2_b32 v2, v86, v87 offset1:1
	v_add_u32_e32 v2, 0x1040, v60
	s_waitcnt vmcnt(11)
	ds_write2_b32 v2, v88, v89 offset1:1
	v_add_u32_e32 v2, 0x1048, v60
	ds_write2_b32 v2, v90, v91 offset1:1
	v_add_u32_e32 v2, 0x1450, v60
	s_waitcnt vmcnt(10)
	ds_write2_b32 v2, v92, v93 offset1:1
	v_add_u32_e32 v2, 0x1458, v60
	ds_write2_b32 v2, v94, v95 offset1:1
	v_add_u32_e32 v2, 0x1860, v60
	s_waitcnt vmcnt(9)
	ds_write2_b32 v2, v96, v97 offset1:1
	v_add_u32_e32 v2, 0x1868, v60
	ds_write2_b32 v2, v98, v99 offset1:1
	v_add_u32_e32 v2, 0x1c70, v60
	s_waitcnt vmcnt(8)
	ds_write2_b32 v2, v100, v101 offset1:1
	v_add_u32_e32 v2, 0x1c78, v60
	ds_write2_b32 v2, v102, v103 offset1:1
	v_add_u32_e32 v2, 0x2080, v60
	s_waitcnt vmcnt(7)
	ds_write2_b32 v2, v104, v105 offset1:1
	v_add_u32_e32 v2, 0x2088, v60
	ds_write2_b32 v2, v106, v107 offset1:1
	v_add_u32_e32 v2, 0x2490, v60
	s_waitcnt vmcnt(6)
	ds_write2_b32 v2, v108, v109 offset1:1
	v_add_u32_e32 v2, 0x2498, v60
	ds_write2_b32 v2, v110, v111 offset1:1
	v_add_u32_e32 v2, 0x28a0, v60
	s_waitcnt vmcnt(5)
	ds_write2_b32 v2, v112, v113 offset1:1
	v_add_u32_e32 v2, 0x28a8, v60
	ds_write2_b32 v2, v114, v115 offset1:1
	v_add_u32_e32 v2, 0x2cb0, v60
	s_waitcnt vmcnt(4)
	ds_write2_b32 v2, v116, v117 offset1:1
	v_add_u32_e32 v2, 0x2cb8, v60
	ds_write2_b32 v2, v118, v119 offset1:1
	v_add_u32_e32 v2, 0x30c0, v60
	s_waitcnt vmcnt(3)
	ds_write2_b32 v2, v120, v121 offset1:1
	v_add_u32_e32 v2, 0x30c8, v60
	ds_write2_b32 v2, v122, v123 offset1:1
	v_add_u32_e32 v2, 0x34d0, v60
	s_waitcnt vmcnt(2)
	ds_write2_b32 v2, v124, v125 offset1:1
	v_add_u32_e32 v2, 0x34d8, v60
	ds_write2_b32 v2, v126, v127 offset1:1
	v_add_u32_e32 v2, 0x38e0, v60
	s_waitcnt vmcnt(1)
	ds_write2_b32 v2, v128, v129 offset1:1
	v_add_u32_e32 v2, 0x38e8, v60
	ds_write2_b32 v2, v130, v131 offset1:1
	v_add_u32_e32 v2, 0x3cf0, v60
	s_waitcnt vmcnt(0)
	ds_write2_b32 v2, v132, v133 offset1:1
	v_add_u32_e32 v2, 0x3cf8, v60
	ds_write2_b32 v2, v134, v135 offset1:1
	s_waitcnt vmcnt(0) expcnt(0) lgkmcnt(0)
	ds_read2_b32 v[76:77], v62 offset1:8
	ds_read2_b32 v[78:79], v62 offset0:65 offset1:73
	ds_read2_b32 v[80:81], v62 offset0:130 offset1:138
	ds_read2_b32 v[82:83], v62 offset0:195 offset1:203
	s_waitcnt lgkmcnt(3)
	v_bfe_u32 v2, v76, 16, 1
	v_add3_u32 v2, v76, v2, s54
	s_waitcnt lgkmcnt(2)
	v_bfe_u32 v45, v78, 16, 1
	v_lshrrev_b32_e32 v2, 16, v2
	v_add3_u32 v45, v78, v45, s54
	v_and_or_b32 v72, v45, s55, v2
	v_add_u32_e32 v45, 0x400, v62
	ds_read2_b32 v[84:85], v45 offset0:4 offset1:12
	ds_read2_b32 v[86:87], v45 offset0:69 offset1:77
	s_waitcnt lgkmcnt(3)
; DI unsigned pk2w(float lo, float hi) { return f2bfw(lo) | (f2bfw(hi) << 16); }
; DI void transpose_item(const float* W, int K, int N, bf16_t* WT, int mode, float* scr, int item, int lane) {
;     ...
;     const int c = lane & 7;
; #pragma unroll
;     for (int j = 0; j < 8; ++j) { const int n = (lane >> 3) + 8 * j; const float* sp = scr + (8 * c) * 65 + n;
;         u32x4 o; o.x = pk2w(sp[0 * 65], sp[1 * 65]); o.y = pk2w(sp[2 * 65], sp[3 * 65]); o.z = pk2w(sp[4 * 65], sp[5 * 65]); o.w = pk2w(sp[6 * 65], sp[7 * 65]);
;         *(u32x4*)(WT + (size_t)(drow0 + n) * K + k0 + 8 * c) = o; }
	v_bfe_u32 v2, v80, 16, 1
	v_add3_u32 v2, v80, v2, s54
	s_waitcnt lgkmcnt(2)
	v_bfe_u32 v47, v82, 16, 1
	ds_read2_b32 v[88:89], v45 offset0:134 offset1:142
	v_lshrrev_b32_e32 v2, 16, v2
	v_add3_u32 v47, v82, v47, s54
	ds_read2_b32 v[90:91], v45 offset0:199 offset1:207
	v_and_or_b32 v73, v47, s55, v2
	s_waitcnt lgkmcnt(3)
	v_bfe_u32 v2, v84, 16, 1
	v_add3_u32 v2, v84, v2, s54
	s_waitcnt lgkmcnt(2)
	v_bfe_u32 v47, v86, 16, 1
	v_lshrrev_b32_e32 v2, 16, v2
	v_add3_u32 v47, v86, v47, s54
	v_and_or_b32 v74, v47, s55, v2
	s_waitcnt lgkmcnt(1)
	v_bfe_u32 v2, v88, 16, 1
	v_add3_u32 v2, v88, v2, s54
	s_waitcnt lgkmcnt(0)
	v_bfe_u32 v47, v90, 16, 1
	v_lshrrev_b32_e32 v2, 16, v2
	v_add3_u32 v47, v90, v47, s54
	v_and_or_b32 v75, v47, s55, v2
	v_or_b32_e32 v2, s8, v61
	v_lshlrev_b32_e32 v2, 12, v2
	v_lshl_add_u64 v[92:93], v[56:57], 0, v[2:3]
	v_bfe_u32 v2, v77, 16, 1
	v_add3_u32 v2, v77, v2, s54
	v_bfe_u32 v47, v79, 16, 1
	v_lshrrev_b32_e32 v2, 16, v2
	v_add3_u32 v47, v79, v47, s54
	global_store_dwordx4 v[92:93], v[72:75], off
	ds_read2_b32 v[76:77], v62 offset0:16 offset1:24
	s_nop 0
	v_and_or_b32 v72, v47, s55, v2
	v_bfe_u32 v2, v81, 16, 1
	v_add3_u32 v2, v81, v2, s54
	v_bfe_u32 v47, v83, 16, 1
	v_lshrrev_b32_e32 v2, 16, v2
	v_add3_u32 v47, v83, v47, s54
	v_and_or_b32 v73, v47, s55, v2
	v_bfe_u32 v2, v85, 16, 1
	v_add3_u32 v2, v85, v2, s54
	v_bfe_u32 v47, v87, 16, 1
	v_lshrrev_b32_e32 v2, 16, v2
	v_add3_u32 v47, v87, v47, s54
	v_and_or_b32 v74, v47, s55, v2
	v_bfe_u32 v2, v89, 16, 1
	v_add3_u32 v2, v89, v2, s54
	v_bfe_u32 v47, v91, 16, 1
	v_lshrrev_b32_e32 v2, 16, v2
	v_add3_u32 v47, v91, v47, s54
	v_and_or_b32 v75, v47, s55, v2
	v_or_b32_e32 v2, s8, v63
	v_lshlrev_b32_e32 v2, 12, v2
	v_lshl_add_u64 v[78:79], v[56:57], 0, v[2:3]
	global_store_dwordx4 v[78:79], v[72:75], off
	ds_read2_b32 v[78:79], v62 offset0:81 offset1:89
	ds_read2_b32 v[80:81], v62 offset0:146 offset1:154
	ds_read2_b32 v[82:83], v62 offset0:211 offset1:219
	s_waitcnt lgkmcnt(3)
	v_bfe_u32 v2, v76, 16, 1
	v_add3_u32 v2, v76, v2, s54
	s_waitcnt lgkmcnt(2)
	v_bfe_u32 v47, v78, 16, 1
	ds_read2_b32 v[84:85], v45 offset0:20 offset1:28
	v_lshrrev_b32_e32 v2, 16, v2
	v_add3_u32 v47, v78, v47, s54
	ds_read2_b32 v[86:87], v45 offset0:85 offset1:93
	v_and_or_b32 v72, v47, s55, v2
	s_waitcnt lgkmcnt(3)
	v_bfe_u32 v2, v80, 16, 1
	v_add3_u32 v2, v80, v2, s54
	s_waitcnt lgkmcnt(2)
	v_bfe_u32 v47, v82, 16, 1
	ds_read2_b32 v[88:89], v45 offset0:150 offset1:158
	v_lshrrev_b32_e32 v2, 16, v2
	v_add3_u32 v47, v82, v47, s54
	ds_read2_b32 v[90:91], v45 offset0:215 offset1:223
	v_and_or_b32 v73, v47, s55, v2
	s_waitcnt lgkmcnt(3)
	v_bfe_u32 v2, v84, 16, 1
	v_add3_u32 v2, v84, v2, s54
	s_waitcnt lgkmcnt(2)
	v_bfe_u32 v47, v86, 16, 1
	v_lshrrev_b32_e32 v2, 16, v2
	v_add3_u32 v47, v86, v47, s54
	v_and_or_b32 v74, v47, s55, v2
	s_waitcnt lgkmcnt(1)
	v_bfe_u32 v2, v88, 16, 1
	v_add3_u32 v2, v88, v2, s54
	s_waitcnt lgkmcnt(0)
	v_bfe_u32 v47, v90, 16, 1
	v_lshrrev_b32_e32 v2, 16, v2
	v_add3_u32 v47, v90, v47, s54
	v_and_or_b32 v75, v47, s55, v2
	v_or_b32_e32 v2, s8, v64
	v_lshlrev_b32_e32 v2, 12, v2
	v_lshl_add_u64 v[92:93], v[56:57], 0, v[2:3]
	v_bfe_u32 v2, v77, 16, 1
	v_add3_u32 v2, v77, v2, s54
	v_bfe_u32 v47, v79, 16, 1
	v_lshrrev_b32_e32 v2, 16, v2
	v_add3_u32 v47, v79, v47, s54
	global_store_dwordx4 v[92:93], v[72:75], off
	ds_read2_b32 v[76:77], v62 offset0:32 offset1:40
	s_nop 0
	v_and_or_b32 v72, v47, s55, v2
	v_bfe_u32 v2, v81, 16, 1
	v_add3_u32 v2, v81, v2, s54
	v_bfe_u32 v47, v83, 16, 1
	v_lshrrev_b32_e32 v2, 16, v2
	v_add3_u32 v47, v83, v47, s54
	v_and_or_b32 v73, v47, s55, v2
	v_bfe_u32 v2, v85, 16, 1
	v_add3_u32 v2, v85, v2, s54
	v_bfe_u32 v47, v87, 16, 1
	v_lshrrev_b32_e32 v2, 16, v2
	v_add3_u32 v47, v87, v47, s54
	v_and_or_b32 v74, v47, s55, v2
	v_bfe_u32 v2, v89, 16, 1
	v_add3_u32 v2, v89, v2, s54
	v_bfe_u32 v47, v91, 16, 1
	v_lshrrev_b32_e32 v2, 16, v2
	v_add3_u32 v47, v91, v47, s54
	v_and_or_b32 v75, v47, s55, v2
	v_or_b32_e32 v2, s8, v65
	v_lshlrev_b32_e32 v2, 12, v2
	v_lshl_add_u64 v[78:79], v[56:57], 0, v[2:3]
	global_store_dwordx4 v[78:79], v[72:75], off
	ds_read2_b32 v[78:79], v62 offset0:97 offset1:105
	ds_read2_b32 v[80:81], v62 offset0:162 offset1:170
	ds_read2_b32 v[82:83], v62 offset0:227 offset1:235
	s_waitcnt lgkmcnt(3)
	v_bfe_u32 v2, v76, 16, 1
	v_add3_u32 v2, v76, v2, s54
	s_waitcnt lgkmcnt(2)
; DI unsigned pk2w(float lo, float hi) { return f2bfw(lo) | (f2bfw(hi) << 16); }
; DI void transpose_item(const float* W, int K, int N, bf16_t* WT, int mode, float* scr, int item, int lane) {
;     ...
;     const int c = lane & 7;
; #pragma unroll
;     for (int j = 0; j < 8; ++j) { const int n = (lane >> 3) + 8 * j; const float* sp = scr + (8 * c) * 65 + n;
;         u32x4 o; o.x = pk2w(sp[0 * 65], sp[1 * 65]); o.y = pk2w(sp[2 * 65], sp[3 * 65]); o.z = pk2w(sp[4 * 65], sp[5 * 65]); o.w = pk2w(sp[6 * 65], sp[7 * 65]);
;         *(u32x4*)(WT + (size_t)(drow0 + n) * K + k0 + 8 * c) = o; }
;     __builtin_amdgcn_s_waitcnt(0); __builtin_amdgcn_wave_barrier();
	v_bfe_u32 v47, v78, 16, 1
	ds_read2_b32 v[84:85], v45 offset0:36 offset1:44
	v_lshrrev_b32_e32 v2, 16, v2
	v_add3_u32 v47, v78, v47, s54
	ds_read2_b32 v[86:87], v45 offset0:101 offset1:109
	v_and_or_b32 v72, v47, s55, v2
	s_waitcnt lgkmcnt(3)
	v_bfe_u32 v2, v80, 16, 1
	v_add3_u32 v2, v80, v2, s54
	s_waitcnt lgkmcnt(2)
	v_bfe_u32 v47, v82, 16, 1
	ds_read2_b32 v[88:89], v45 offset0:166 offset1:174
	v_lshrrev_b32_e32 v2, 16, v2
	v_add3_u32 v47, v82, v47, s54
	ds_read2_b32 v[90:91], v45 offset0:231 offset1:239
	v_and_or_b32 v73, v47, s55, v2
	s_waitcnt lgkmcnt(3)
	v_bfe_u32 v2, v84, 16, 1
	v_add3_u32 v2, v84, v2, s54
	s_waitcnt lgkmcnt(2)
	v_bfe_u32 v47, v86, 16, 1
	v_lshrrev_b32_e32 v2, 16, v2
	v_add3_u32 v47, v86, v47, s54
	v_and_or_b32 v74, v47, s55, v2
	s_waitcnt lgkmcnt(1)
	v_bfe_u32 v2, v88, 16, 1
	v_add3_u32 v2, v88, v2, s54
	s_waitcnt lgkmcnt(0)
	v_bfe_u32 v47, v90, 16, 1
	v_lshrrev_b32_e32 v2, 16, v2
	v_add3_u32 v47, v90, v47, s54
	v_and_or_b32 v75, v47, s55, v2
	v_or_b32_e32 v2, s8, v67
	v_lshlrev_b32_e32 v2, 12, v2
	v_lshl_add_u64 v[92:93], v[56:57], 0, v[2:3]
	v_bfe_u32 v2, v77, 16, 1
	v_add3_u32 v2, v77, v2, s54
	v_bfe_u32 v47, v79, 16, 1
	v_lshrrev_b32_e32 v2, 16, v2
	v_add3_u32 v47, v79, v47, s54
	global_store_dwordx4 v[92:93], v[72:75], off
	ds_read2_b32 v[76:77], v62 offset0:48 offset1:56
	s_nop 0
	v_and_or_b32 v72, v47, s55, v2
	v_bfe_u32 v2, v81, 16, 1
	v_add3_u32 v2, v81, v2, s54
	v_bfe_u32 v47, v83, 16, 1
	v_lshrrev_b32_e32 v2, 16, v2
	v_add3_u32 v47, v83, v47, s54
	v_and_or_b32 v73, v47, s55, v2
	v_bfe_u32 v2, v85, 16, 1
	v_add3_u32 v2, v85, v2, s54
	v_bfe_u32 v47, v87, 16, 1
	v_lshrrev_b32_e32 v2, 16, v2
	v_add3_u32 v47, v87, v47, s54
	v_and_or_b32 v74, v47, s55, v2
	v_bfe_u32 v2, v89, 16, 1
	v_add3_u32 v2, v89, v2, s54
	v_bfe_u32 v47, v91, 16, 1
	v_lshrrev_b32_e32 v2, 16, v2
	v_add3_u32 v47, v91, v47, s54
	v_and_or_b32 v75, v47, s55, v2
	v_or_b32_e32 v2, s8, v68
	v_lshlrev_b32_e32 v2, 12, v2
	v_lshl_add_u64 v[78:79], v[56:57], 0, v[2:3]
	global_store_dwordx4 v[78:79], v[72:75], off
	ds_read2_b32 v[78:79], v62 offset0:113 offset1:121
	ds_read2_b32 v[80:81], v62 offset0:178 offset1:186
	ds_read2_b32 v[82:83], v62 offset0:243 offset1:251
	s_waitcnt lgkmcnt(3)
	v_bfe_u32 v2, v76, 16, 1
	v_add3_u32 v2, v76, v2, s54
	s_waitcnt lgkmcnt(2)
	v_bfe_u32 v47, v78, 16, 1
	ds_read2_b32 v[84:85], v45 offset0:52 offset1:60
	v_lshrrev_b32_e32 v2, 16, v2
	v_add3_u32 v47, v78, v47, s54
	ds_read2_b32 v[86:87], v45 offset0:117 offset1:125
	v_and_or_b32 v72, v47, s55, v2
	s_waitcnt lgkmcnt(3)
	v_bfe_u32 v2, v80, 16, 1
	v_add3_u32 v2, v80, v2, s54
	s_waitcnt lgkmcnt(2)
	v_bfe_u32 v47, v82, 16, 1
	ds_read2_b32 v[88:89], v45 offset0:182 offset1:190
	v_lshrrev_b32_e32 v2, 16, v2
	v_add3_u32 v47, v82, v47, s54
	ds_read2_b32 v[90:91], v45 offset0:247 offset1:255
	v_and_or_b32 v73, v47, s55, v2
	s_waitcnt lgkmcnt(3)
	v_bfe_u32 v2, v84, 16, 1
	v_add3_u32 v2, v84, v2, s54
	s_waitcnt lgkmcnt(2)
	v_bfe_u32 v47, v86, 16, 1
	v_lshrrev_b32_e32 v2, 16, v2
	v_add3_u32 v47, v86, v47, s54
	v_and_or_b32 v74, v47, s55, v2
	s_waitcnt lgkmcnt(1)
	v_bfe_u32 v2, v88, 16, 1
	v_add3_u32 v2, v88, v2, s54
	s_waitcnt lgkmcnt(0)
	v_bfe_u32 v45, v90, 16, 1
	v_lshrrev_b32_e32 v2, 16, v2
	v_add3_u32 v45, v90, v45, s54
	v_and_or_b32 v75, v45, s55, v2
	v_or_b32_e32 v2, s8, v69
	v_lshlrev_b32_e32 v2, 12, v2
	v_lshl_add_u64 v[92:93], v[56:57], 0, v[2:3]
	v_bfe_u32 v2, v77, 16, 1
	v_add3_u32 v2, v77, v2, s54
	v_bfe_u32 v45, v79, 16, 1
	v_lshrrev_b32_e32 v2, 16, v2
	v_add3_u32 v45, v79, v45, s54
	global_store_dwordx4 v[92:93], v[72:75], off
	s_nop 1
	v_and_or_b32 v72, v45, s55, v2
	v_bfe_u32 v2, v81, 16, 1
	v_add3_u32 v2, v81, v2, s54
	v_bfe_u32 v45, v83, 16, 1
	v_lshrrev_b32_e32 v2, 16, v2
	v_add3_u32 v45, v83, v45, s54
	v_and_or_b32 v73, v45, s55, v2
	v_bfe_u32 v2, v85, 16, 1
	v_add3_u32 v2, v85, v2, s54
	v_bfe_u32 v45, v87, 16, 1
	v_lshrrev_b32_e32 v2, 16, v2
	v_add3_u32 v45, v87, v45, s54
	v_and_or_b32 v74, v45, s55, v2
	v_bfe_u32 v2, v89, 16, 1
	v_add3_u32 v2, v89, v2, s54
	v_bfe_u32 v45, v91, 16, 1
	v_lshrrev_b32_e32 v2, 16, v2
	v_add3_u32 v45, v91, v45, s54
	v_and_or_b32 v75, v45, s55, v2
	v_or_b32_e32 v2, s8, v70
	v_lshlrev_b32_e32 v2, 12, v2
	v_lshl_add_u64 v[56:57], v[56:57], 0, v[2:3]
	global_store_dwordx4 v[56:57], v[72:75], off
	s_waitcnt lgkmcnt(0)

; DI unsigned pk2w(float lo, float hi) { return f2bfw(lo) | (f2bfw(hi) << 16); }
; DI void transpose_item(const float* W, int K, int N, bf16_t* WT, int mode, float* scr, int item, int lane) {
;     const int nblk = N / 64, kb = item / nblk, nb = item % nblk, k0 = 64 * kb, n0 = 64 * nb;
;     int drow0 = n0;
;     if (mode == 1) { const int seg = n0 >> 10; const int dst = seg < 2 ? seg : (seg == 2 ? 6 : seg - 1); drow0 = dst * 1024 + (n0 & 1023); }
;     else if (mode == 2) { drow0 = n0 < DFF ? (n0 / 128) * 256 + (n0 % 128) : ((n0 - DFF) / 128) * 256 + 128 + ((n0 - DFF) % 128); }
;     else if (mode == 3) { drow0 = (n0 / 128) * 256 + (n0 % 128); }
;     else if (mode == 4) { drow0 = (n0 / 128) * 256 + 128 + (n0 % 128); }
;     f32x4 v[16];
; #pragma unroll
;     for (int i = 0; i < 16; ++i) v[i] = __builtin_nontemporal_load((const f32x4*)(W + (size_t)(k0 + 4 * i + (lane >> 4)) * N + n0 + 4 * (lane & 15)));
; #pragma unroll
;     for (int i = 0; i < 16; ++i) { float* d = scr + (4 * i + (lane >> 4)) * 65 + 4 * (lane & 15); d[0] = v[i][0]; d[1] = v[i][1]; d[2] = v[i][2]; d[3] = v[i][3]; }
;     __builtin_amdgcn_s_waitcnt(0); __builtin_amdgcn_wave_barrier();
;     const int c = lane & 7;
; #pragma unroll
;     for (int j = 0; j < 8; ++j) { const int n = (lane >> 3) + 8 * j; const float* sp = scr + (8 * c) * 65 + n;
;         u32x4 o; o.x = pk2w(sp[0 * 65], sp[1 * 65]); o.y = pk2w(sp[2 * 65], sp[3 * 65]); o.z = pk2w(sp[4 * 65], sp[5 * 65]); o.w = pk2w(sp[6 * 65], sp[7 * 65]);
.LBB0_47:
	s_andn2_b64 vcc, exec, s[8:9]
	s_cbranch_vccnz .LBB0_49
	s_add_i32 s9, s42, 0xfffed300
	s_and_b32 s8, s15, 0x7c0
	s_and_b32 s9, s9, 0x1c0
	v_or_b32_e32 v2, s9, v59
	s_lshl_b32 s40, s8, 2
	v_lshl_add_u64 v[56:57], v[10:11], 0, s[40:41]
	v_lshlrev_b32_e32 v2, 13, v2
	v_lshl_add_u64 v[56:57], v[56:57], 0, v[2:3]
	v_add_co_u32_e32 v76, vcc, 0x8000, v56
	v_add_u32_e32 v2, 0x410, v60
	s_nop 0
	v_addc_co_u32_e32 v77, vcc, 0, v57, vcc
	v_add_co_u32_e32 v80, vcc, 0x10000, v56
	global_load_dwordx4 v[72:75], v[56:57], off nt
	s_nop 0
	global_load_dwordx4 v[76:79], v[76:77], off nt
	v_addc_co_u32_e32 v81, vcc, 0, v57, vcc
	v_add_co_u32_e32 v84, vcc, 0x18000, v56
	s_lshl_b32 s40, s9, 1
	s_nop 0
	v_addc_co_u32_e32 v85, vcc, 0, v57, vcc
	global_load_dwordx4 v[80:83], v[80:81], off nt
	s_nop 0
	global_load_dwordx4 v[84:87], v[84:85], off nt
	v_add_co_u32_e32 v88, vcc, 0x20000, v56
	s_nop 1
	v_addc_co_u32_e32 v89, vcc, 0, v57, vcc
	v_add_co_u32_e32 v92, vcc, 0x28000, v56
	s_nop 1
	v_addc_co_u32_e32 v93, vcc, 0, v57, vcc
	global_load_dwordx4 v[88:91], v[88:89], off nt
	s_nop 0
	global_load_dwordx4 v[92:95], v[92:93], off nt
	v_add_co_u32_e32 v96, vcc, 0x30000, v56
	s_nop 1
	v_addc_co_u32_e32 v97, vcc, 0, v57, vcc
	v_add_co_u32_e32 v100, vcc, 0x38000, v56
	s_nop 1
	v_addc_co_u32_e32 v101, vcc, 0, v57, vcc
	global_load_dwordx4 v[96:99], v[96:97], off nt
	s_nop 0
	global_load_dwordx4 v[100:103], v[100:101], off nt
	v_add_co_u32_e32 v104, vcc, 0x40000, v56
	s_nop 1
	v_addc_co_u32_e32 v105, vcc, 0, v57, vcc
	v_add_co_u32_e32 v108, vcc, 0x48000, v56
	s_nop 1
	v_addc_co_u32_e32 v109, vcc, 0, v57, vcc
	global_load_dwordx4 v[104:107], v[104:105], off nt
	s_nop 0
	global_load_dwordx4 v[108:111], v[108:109], off nt
	v_add_co_u32_e32 v112, vcc, 0x50000, v56
	s_nop 1
	v_addc_co_u32_e32 v113, vcc, 0, v57, vcc
	v_add_co_u32_e32 v116, vcc, 0x58000, v56
	s_nop 1
	v_addc_co_u32_e32 v117, vcc, 0, v57, vcc
	global_load_dwordx4 v[112:115], v[112:113], off nt
	s_nop 0
	global_load_dwordx4 v[116:119], v[116:117], off nt
	v_add_co_u32_e32 v120, vcc, 0x60000, v56
	s_nop 1
	v_addc_co_u32_e32 v121, vcc, 0, v57, vcc
	v_add_co_u32_e32 v124, vcc, 0x68000, v56
	s_nop 1
	v_addc_co_u32_e32 v125, vcc, 0, v57, vcc
	global_load_dwordx4 v[120:123], v[120:121], off nt
	s_nop 0
	global_load_dwordx4 v[124:127], v[124:125], off nt
	v_add_co_u32_e32 v128, vcc, 0x70000, v56
	s_nop 1
	v_addc_co_u32_e32 v129, vcc, 0, v57, vcc
	global_load_dwordx4 v[128:131], v[128:129], off nt
	v_add_co_u32_e32 v56, vcc, 0x78000, v56
	s_nop 1
	v_addc_co_u32_e32 v57, vcc, 0, v57, vcc
	global_load_dwordx4 v[132:135], v[56:57], off nt
	s_waitcnt vmcnt(15)
	ds_write2_b32 v60, v72, v73 offset1:1
	ds_write2_b32 v60, v74, v75 offset0:2 offset1:3
	s_waitcnt vmcnt(14)
	ds_write2_b32 v2, v76, v77 offset1:1
	v_add_u32_e32 v2, 0x418, v60
	ds_write2_b32 v2, v78, v79 offset1:1
	v_add_u32_e32 v2, 0x820, v60
	v_lshl_add_u64 v[56:57], v[34:35], 0, s[40:41]
	s_waitcnt vmcnt(13)
	ds_write2_b32 v2, v80, v81 offset1:1
	v_add_u32_e32 v2, 0x828, v60
	ds_write2_b32 v2, v82, v83 offset1:1
	v_add_u32_e32 v2, 0xc30, v60
	s_waitcnt vmcnt(12)
	ds_write2_b32 v2, v84, v85 offset1:1
	v_add_u32_e32 v2, 0xc38, v60
	ds_write2_b32 v2, v86, v87 offset1:1
	v_add_u32_e32 v2, 0x1040, v60
	s_waitcnt vmcnt(11)
	ds_write2_b32 v2, v88, v89 offset1:1
	v_add_u32_e32 v2, 0x1048, v60
	ds_write2_b32 v2, v90, v91 offset1:1
	v_add_u32_e32 v2, 0x1450, v60
	s_waitcnt vmcnt(10)
	ds_write2_b32 v2, v92, v93 offset1:1
	v_add_u32_e32 v2, 0x1458, v60
	ds_write2_b32 v2, v94, v95 offset1:1
	v_add_u32_e32 v2, 0x1860, v60
	s_waitcnt vmcnt(9)
	ds_write2_b32 v2, v96, v97 offset1:1
	v_add_u32_e32 v2, 0x1868, v60
	ds_write2_b32 v2, v98, v99 offset1:1
	v_add_u32_e32 v2, 0x1c70, v60
	s_waitcnt vmcnt(8)
	ds_write2_b32 v2, v100, v101 offset1:1
	v_add_u32_e32 v2, 0x1c78, v60
	ds_write2_b32 v2, v102, v103 offset1:1
	v_add_u32_e32 v2, 0x2080, v60
	s_waitcnt vmcnt(7)
	ds_write2_b32 v2, v104, v105 offset1:1
	v_add_u32_e32 v2, 0x2088, v60
	ds_write2_b32 v2, v106, v107 offset1:1
	v_add_u32_e32 v2, 0x2490, v60
	s_waitcnt vmcnt(6)
	ds_write2_b32 v2, v108, v109 offset1:1
	v_add_u32_e32 v2, 0x2498, v60
	ds_write2_b32 v2, v110, v111 offset1:1
	v_add_u32_e32 v2, 0x28a0, v60
	s_waitcnt vmcnt(5)
	ds_write2_b32 v2, v112, v113 offset1:1
	v_add_u32_e32 v2, 0x28a8, v60
	ds_write2_b32 v2, v114, v115 offset1:1
	v_add_u32_e32 v2, 0x2cb0, v60
	s_waitcnt vmcnt(4)
	ds_write2_b32 v2, v116, v117 offset1:1
	v_add_u32_e32 v2, 0x2cb8, v60
	ds_write2_b32 v2, v118, v119 offset1:1
	v_add_u32_e32 v2, 0x30c0, v60
	s_waitcnt vmcnt(3)
	ds_write2_b32 v2, v120, v121 offset1:1
	v_add_u32_e32 v2, 0x30c8, v60
	ds_write2_b32 v2, v122, v123 offset1:1
	v_add_u32_e32 v2, 0x34d0, v60
	s_waitcnt vmcnt(2)
	ds_write2_b32 v2, v124, v125 offset1:1
	v_add_u32_e32 v2, 0x34d8, v60
	ds_write2_b32 v2, v126, v127 offset1:1
	v_add_u32_e32 v2, 0x38e0, v60
	s_waitcnt vmcnt(1)
	ds_write2_b32 v2, v128, v129 offset1:1
	v_add_u32_e32 v2, 0x38e8, v60
	ds_write2_b32 v2, v130, v131 offset1:1
	v_add_u32_e32 v2, 0x3cf0, v60
	s_waitcnt vmcnt(0)
	ds_write2_b32 v2, v132, v133 offset1:1
	v_add_u32_e32 v2, 0x3cf8, v60
	ds_write2_b32 v2, v134, v135 offset1:1
	s_waitcnt vmcnt(0) expcnt(0) lgkmcnt(0)
	ds_read2_b32 v[76:77], v62 offset1:8
	ds_read2_b32 v[78:79], v62 offset0:65 offset1:73
	ds_read2_b32 v[80:81], v62 offset0:130 offset1:138
	ds_read2_b32 v[82:83], v62 offset0:195 offset1:203
	s_waitcnt lgkmcnt(3)
	v_bfe_u32 v2, v76, 16, 1
	v_add3_u32 v2, v76, v2, s54
	s_waitcnt lgkmcnt(2)
	v_bfe_u32 v45, v78, 16, 1
	v_lshrrev_b32_e32 v2, 16, v2
	v_add3_u32 v45, v78, v45, s54
	v_and_or_b32 v72, v45, s55, v2
	v_add_u32_e32 v45, 0x400, v62
	ds_read2_b32 v[84:85], v45 offset0:4 offset1:12
	ds_read2_b32 v[86:87], v45 offset0:69 offset1:77
	s_waitcnt lgkmcnt(3)
; DI unsigned pk2w(float lo, float hi) { return f2bfw(lo) | (f2bfw(hi) << 16); }
; DI void transpose_item(const float* W, int K, int N, bf16_t* WT, int mode, float* scr, int item, int lane) {
;     ...
;     const int c = lane & 7;
; #pragma unroll
;     for (int j = 0; j < 8; ++j) { const int n = (lane >> 3) + 8 * j; const float* sp = scr + (8 * c) * 65 + n;
;         u32x4 o; o.x = pk2w(sp[0 * 65], sp[1 * 65]); o.y = pk2w(sp[2 * 65], sp[3 * 65]); o.z = pk2w(sp[4 * 65], sp[5 * 65]); o.w = pk2w(sp[6 * 65], sp[7 * 65]);
;         *(u32x4*)(WT + (size_t)(drow0 + n) * K + k0 + 8 * c) = o; }
	v_bfe_u32 v2, v80, 16, 1
	v_add3_u32 v2, v80, v2, s54
	s_waitcnt lgkmcnt(2)
	v_bfe_u32 v47, v82, 16, 1
	ds_read2_b32 v[88:89], v45 offset0:134 offset1:142
	v_lshrrev_b32_e32 v2, 16, v2
	v_add3_u32 v47, v82, v47, s54
	ds_read2_b32 v[90:91], v45 offset0:199 offset1:207
	v_and_or_b32 v73, v47, s55, v2
	s_waitcnt lgkmcnt(3)
	v_bfe_u32 v2, v84, 16, 1
	v_add3_u32 v2, v84, v2, s54
	s_waitcnt lgkmcnt(2)
	v_bfe_u32 v47, v86, 16, 1
	v_lshrrev_b32_e32 v2, 16, v2
	v_add3_u32 v47, v86, v47, s54
	v_and_or_b32 v74, v47, s55, v2
	s_waitcnt lgkmcnt(1)
	v_bfe_u32 v2, v88, 16, 1
	v_add3_u32 v2, v88, v2, s54
	s_waitcnt lgkmcnt(0)
	v_bfe_u32 v47, v90, 16, 1
	v_lshrrev_b32_e32 v2, 16, v2
	v_add3_u32 v47, v90, v47, s54
	v_and_or_b32 v75, v47, s55, v2
	v_or_b32_e32 v2, s8, v61
	v_lshlrev_b32_e32 v2, 9, v2
	v_lshl_add_u64 v[92:93], v[56:57], 0, v[2:3]
	v_bfe_u32 v2, v77, 16, 1
	v_add3_u32 v2, v77, v2, s54
	v_bfe_u32 v47, v79, 16, 1
	v_lshrrev_b32_e32 v2, 16, v2
	v_add3_u32 v47, v79, v47, s54
	global_store_dwordx4 v[92:93], v[72:75], off
	ds_read2_b32 v[76:77], v62 offset0:16 offset1:24
	s_nop 0
	v_and_or_b32 v72, v47, s55, v2
	v_bfe_u32 v2, v81, 16, 1
	v_add3_u32 v2, v81, v2, s54
	v_bfe_u32 v47, v83, 16, 1
	v_lshrrev_b32_e32 v2, 16, v2
	v_add3_u32 v47, v83, v47, s54
	v_and_or_b32 v73, v47, s55, v2
	v_bfe_u32 v2, v85, 16, 1
	v_add3_u32 v2, v85, v2, s54
	v_bfe_u32 v47, v87, 16, 1
	v_lshrrev_b32_e32 v2, 16, v2
	v_add3_u32 v47, v87, v47, s54
	v_and_or_b32 v74, v47, s55, v2
	v_bfe_u32 v2, v89, 16, 1
	v_add3_u32 v2, v89, v2, s54
	v_bfe_u32 v47, v91, 16, 1
	v_lshrrev_b32_e32 v2, 16, v2
	v_add3_u32 v47, v91, v47, s54
	v_and_or_b32 v75, v47, s55, v2
	v_or_b32_e32 v2, s8, v63
	v_lshlrev_b32_e32 v2, 9, v2
	v_lshl_add_u64 v[78:79], v[56:57], 0, v[2:3]
	global_store_dwordx4 v[78:79], v[72:75], off
	ds_read2_b32 v[78:79], v62 offset0:81 offset1:89
	ds_read2_b32 v[80:81], v62 offset0:146 offset1:154
	ds_read2_b32 v[82:83], v62 offset0:211 offset1:219
	s_waitcnt lgkmcnt(3)
	v_bfe_u32 v2, v76, 16, 1
	v_add3_u32 v2, v76, v2, s54
	s_waitcnt lgkmcnt(2)
	v_bfe_u32 v47, v78, 16, 1
	ds_read2_b32 v[84:85], v45 offset0:20 offset1:28
	v_lshrrev_b32_e32 v2, 16, v2
	v_add3_u32 v47, v78, v47, s54
	ds_read2_b32 v[86:87], v45 offset0:85 offset1:93
	v_and_or_b32 v72, v47, s55, v2
	s_waitcnt lgkmcnt(3)
	v_bfe_u32 v2, v80, 16, 1
	v_add3_u32 v2, v80, v2, s54
	s_waitcnt lgkmcnt(2)
	v_bfe_u32 v47, v82, 16, 1
	ds_read2_b32 v[88:89], v45 offset0:150 offset1:158
	v_lshrrev_b32_e32 v2, 16, v2
	v_add3_u32 v47, v82, v47, s54
	ds_read2_b32 v[90:91], v45 offset0:215 offset1:223
	v_and_or_b32 v73, v47, s55, v2
	s_waitcnt lgkmcnt(3)
	v_bfe_u32 v2, v84, 16, 1
	v_add3_u32 v2, v84, v2, s54
	s_waitcnt lgkmcnt(2)
	v_bfe_u32 v47, v86, 16, 1
	v_lshrrev_b32_e32 v2, 16, v2
	v_add3_u32 v47, v86, v47, s54
	v_and_or_b32 v74, v47, s55, v2
	s_waitcnt lgkmcnt(1)
	v_bfe_u32 v2, v88, 16, 1
	v_add3_u32 v2, v88, v2, s54
	s_waitcnt lgkmcnt(0)
	v_bfe_u32 v47, v90, 16, 1
	v_lshrrev_b32_e32 v2, 16, v2
	v_add3_u32 v47, v90, v47, s54
	v_and_or_b32 v75, v47, s55, v2
	v_or_b32_e32 v2, s8, v64
	v_lshlrev_b32_e32 v2, 9, v2
	v_lshl_add_u64 v[92:93], v[56:57], 0, v[2:3]
	v_bfe_u32 v2, v77, 16, 1
	v_add3_u32 v2, v77, v2, s54
	v_bfe_u32 v47, v79, 16, 1
	v_lshrrev_b32_e32 v2, 16, v2
	v_add3_u32 v47, v79, v47, s54
	global_store_dwordx4 v[92:93], v[72:75], off
	ds_read2_b32 v[76:77], v62 offset0:32 offset1:40
	s_nop 0
	v_and_or_b32 v72, v47, s55, v2
	v_bfe_u32 v2, v81, 16, 1
	v_add3_u32 v2, v81, v2, s54
	v_bfe_u32 v47, v83, 16, 1
	v_lshrrev_b32_e32 v2, 16, v2
	v_add3_u32 v47, v83, v47, s54
	v_and_or_b32 v73, v47, s55, v2
	v_bfe_u32 v2, v85, 16, 1
	v_add3_u32 v2, v85, v2, s54
	v_bfe_u32 v47, v87, 16, 1
	v_lshrrev_b32_e32 v2, 16, v2
	v_add3_u32 v47, v87, v47, s54
	v_and_or_b32 v74, v47, s55, v2
	v_bfe_u32 v2, v89, 16, 1
	v_add3_u32 v2, v89, v2, s54
	v_bfe_u32 v47, v91, 16, 1
	v_lshrrev_b32_e32 v2, 16, v2
	v_add3_u32 v47, v91, v47, s54
	v_and_or_b32 v75, v47, s55, v2
	v_or_b32_e32 v2, s8, v65
	v_lshlrev_b32_e32 v2, 9, v2
	v_lshl_add_u64 v[78:79], v[56:57], 0, v[2:3]
	global_store_dwordx4 v[78:79], v[72:75], off
	ds_read2_b32 v[78:79], v62 offset0:97 offset1:105
	ds_read2_b32 v[80:81], v62 offset0:162 offset1:170
	ds_read2_b32 v[82:83], v62 offset0:227 offset1:235
	s_waitcnt lgkmcnt(3)
	v_bfe_u32 v2, v76, 16, 1
	v_add3_u32 v2, v76, v2, s54
	s_waitcnt lgkmcnt(2)
; DI unsigned pk2w(float lo, float hi) { return f2bfw(lo) | (f2bfw(hi) << 16); }
; DI void transpose_item(const float* W, int K, int N, bf16_t* WT, int mode, float* scr, int item, int lane) {
;     ...
;     const int c = lane & 7;
; #pragma unroll
;     for (int j = 0; j < 8; ++j) { const int n = (lane >> 3) + 8 * j; const float* sp = scr + (8 * c) * 65 + n;
;         u32x4 o; o.x = pk2w(sp[0 * 65], sp[1 * 65]); o.y = pk2w(sp[2 * 65], sp[3 * 65]); o.z = pk2w(sp[4 * 65], sp[5 * 65]); o.w = pk2w(sp[6 * 65], sp[7 * 65]);
;         *(u32x4*)(WT + (size_t)(drow0 + n) * K + k0 + 8 * c) = o; }
;     __builtin_amdgcn_s_waitcnt(0); __builtin_amdgcn_wave_barrier();
	v_bfe_u32 v47, v78, 16, 1
	ds_read2_b32 v[84:85], v45 offset0:36 offset1:44
	v_lshrrev_b32_e32 v2, 16, v2
	v_add3_u32 v47, v78, v47, s54
	ds_read2_b32 v[86:87], v45 offset0:101 offset1:109
	v_and_or_b32 v72, v47, s55, v2
	s_waitcnt lgkmcnt(3)
	v_bfe_u32 v2, v80, 16, 1
	v_add3_u32 v2, v80, v2, s54
	s_waitcnt lgkmcnt(2)
	v_bfe_u32 v47, v82, 16, 1
	ds_read2_b32 v[88:89], v45 offset0:166 offset1:174
	v_lshrrev_b32_e32 v2, 16, v2
	v_add3_u32 v47, v82, v47, s54
	ds_read2_b32 v[90:91], v45 offset0:231 offset1:239
	v_and_or_b32 v73, v47, s55, v2
	s_waitcnt lgkmcnt(3)
	v_bfe_u32 v2, v84, 16, 1
	v_add3_u32 v2, v84, v2, s54
	s_waitcnt lgkmcnt(2)
	v_bfe_u32 v47, v86, 16, 1
	v_lshrrev_b32_e32 v2, 16, v2
	v_add3_u32 v47, v86, v47, s54
	v_and_or_b32 v74, v47, s55, v2
	s_waitcnt lgkmcnt(1)
	v_bfe_u32 v2, v88, 16, 1
	v_add3_u32 v2, v88, v2, s54
	s_waitcnt lgkmcnt(0)
	v_bfe_u32 v47, v90, 16, 1
	v_lshrrev_b32_e32 v2, 16, v2
	v_add3_u32 v47, v90, v47, s54
	v_and_or_b32 v75, v47, s55, v2
	v_or_b32_e32 v2, s8, v67
	v_lshlrev_b32_e32 v2, 9, v2
	v_lshl_add_u64 v[92:93], v[56:57], 0, v[2:3]
	v_bfe_u32 v2, v77, 16, 1
	v_add3_u32 v2, v77, v2, s54
	v_bfe_u32 v47, v79, 16, 1
	v_lshrrev_b32_e32 v2, 16, v2
	v_add3_u32 v47, v79, v47, s54
	global_store_dwordx4 v[92:93], v[72:75], off
	ds_read2_b32 v[76:77], v62 offset0:48 offset1:56
	s_nop 0
	v_and_or_b32 v72, v47, s55, v2
	v_bfe_u32 v2, v81, 16, 1
	v_add3_u32 v2, v81, v2, s54
	v_bfe_u32 v47, v83, 16, 1
	v_lshrrev_b32_e32 v2, 16, v2
	v_add3_u32 v47, v83, v47, s54
	v_and_or_b32 v73, v47, s55, v2
	v_bfe_u32 v2, v85, 16, 1
	v_add3_u32 v2, v85, v2, s54
	v_bfe_u32 v47, v87, 16, 1
	v_lshrrev_b32_e32 v2, 16, v2
	v_add3_u32 v47, v87, v47, s54
	v_and_or_b32 v74, v47, s55, v2
	v_bfe_u32 v2, v89, 16, 1
	v_add3_u32 v2, v89, v2, s54
	v_bfe_u32 v47, v91, 16, 1
	v_lshrrev_b32_e32 v2, 16, v2
	v_add3_u32 v47, v91, v47, s54
	v_and_or_b32 v75, v47, s55, v2
	v_or_b32_e32 v2, s8, v68
	v_lshlrev_b32_e32 v2, 9, v2
	v_lshl_add_u64 v[78:79], v[56:57], 0, v[2:3]
	global_store_dwordx4 v[78:79], v[72:75], off
	ds_read2_b32 v[78:79], v62 offset0:113 offset1:121
	ds_read2_b32 v[80:81], v62 offset0:178 offset1:186
	ds_read2_b32 v[82:83], v62 offset0:243 offset1:251
	s_waitcnt lgkmcnt(3)
	v_bfe_u32 v2, v76, 16, 1
	v_add3_u32 v2, v76, v2, s54
	s_waitcnt lgkmcnt(2)
	v_bfe_u32 v47, v78, 16, 1
	ds_read2_b32 v[84:85], v45 offset0:52 offset1:60
	v_lshrrev_b32_e32 v2, 16, v2
	v_add3_u32 v47, v78, v47, s54
	ds_read2_b32 v[86:87], v45 offset0:117 offset1:125
	v_and_or_b32 v72, v47, s55, v2
	s_waitcnt lgkmcnt(3)
	v_bfe_u32 v2, v80, 16, 1
	v_add3_u32 v2, v80, v2, s54
	s_waitcnt lgkmcnt(2)
	v_bfe_u32 v47, v82, 16, 1
	ds_read2_b32 v[88:89], v45 offset0:182 offset1:190
	v_lshrrev_b32_e32 v2, 16, v2
	v_add3_u32 v47, v82, v47, s54
	ds_read2_b32 v[90:91], v45 offset0:247 offset1:255
	v_and_or_b32 v73, v47, s55, v2
	s_waitcnt lgkmcnt(3)
	v_bfe_u32 v2, v84, 16, 1
	v_add3_u32 v2, v84, v2, s54
	s_waitcnt lgkmcnt(2)
	v_bfe_u32 v47, v86, 16, 1
	v_lshrrev_b32_e32 v2, 16, v2
	v_add3_u32 v47, v86, v47, s54
	v_and_or_b32 v74, v47, s55, v2
	s_waitcnt lgkmcnt(1)
	v_bfe_u32 v2, v88, 16, 1
	v_add3_u32 v2, v88, v2, s54
	s_waitcnt lgkmcnt(0)
	v_bfe_u32 v45, v90, 16, 1
	v_lshrrev_b32_e32 v2, 16, v2
	v_add3_u32 v45, v90, v45, s54
	v_and_or_b32 v75, v45, s55, v2
	v_or_b32_e32 v2, s8, v69
	v_lshlrev_b32_e32 v2, 9, v2
	v_lshl_add_u64 v[92:93], v[56:57], 0, v[2:3]
	v_bfe_u32 v2, v77, 16, 1
	v_add3_u32 v2, v77, v2, s54
	v_bfe_u32 v45, v79, 16, 1
	v_lshrrev_b32_e32 v2, 16, v2
	v_add3_u32 v45, v79, v45, s54
	global_store_dwordx4 v[92:93], v[72:75], off
	s_nop 1
	v_and_or_b32 v72, v45, s55, v2
	v_bfe_u32 v2, v81, 16, 1
	v_add3_u32 v2, v81, v2, s54
	v_bfe_u32 v45, v83, 16, 1
	v_lshrrev_b32_e32 v2, 16, v2
	v_add3_u32 v45, v83, v45, s54
	v_and_or_b32 v73, v45, s55, v2
	v_bfe_u32 v2, v85, 16, 1
	v_add3_u32 v2, v85, v2, s54
	v_bfe_u32 v45, v87, 16, 1
	v_lshrrev_b32_e32 v2, 16, v2
	v_add3_u32 v45, v87, v45, s54
	v_and_or_b32 v74, v45, s55, v2
	v_bfe_u32 v2, v89, 16, 1
	v_add3_u32 v2, v89, v2, s54
	v_bfe_u32 v45, v91, 16, 1
	v_lshrrev_b32_e32 v2, 16, v2
	v_add3_u32 v45, v91, v45, s54
	v_and_or_b32 v75, v45, s55, v2
	v_or_b32_e32 v2, s8, v70
	v_lshlrev_b32_e32 v2, 9, v2
	v_lshl_add_u64 v[56:57], v[56:57], 0, v[2:3]
	global_store_dwordx4 v[56:57], v[72:75], off
	s_waitcnt lgkmcnt(0)

; DI unsigned pk2w(float lo, float hi) { return f2bfw(lo) | (f2bfw(hi) << 16); }
; DI void transpose_item(const float* W, int K, int N, bf16_t* WT, int mode, float* scr, int item, int lane) {
;     const int nblk = N / 64, kb = item / nblk, nb = item % nblk, k0 = 64 * kb, n0 = 64 * nb;
;     int drow0 = n0;
;     if (mode == 1) { const int seg = n0 >> 10; const int dst = seg < 2 ? seg : (seg == 2 ? 6 : seg - 1); drow0 = dst * 1024 + (n0 & 1023); }
;     else if (mode == 2) { drow0 = n0 < DFF ? (n0 / 128) * 256 + (n0 % 128) : ((n0 - DFF) / 128) * 256 + 128 + ((n0 - DFF) % 128); }
;     else if (mode == 3) { drow0 = (n0 / 128) * 256 + (n0 % 128); }
;     else if (mode == 4) { drow0 = (n0 / 128) * 256 + 128 + (n0 % 128); }
;     f32x4 v[16];
; #pragma unroll
;     for (int i = 0; i < 16; ++i) v[i] = __builtin_nontemporal_load((const f32x4*)(W + (size_t)(k0 + 4 * i + (lane >> 4)) * N + n0 + 4 * (lane & 15)));
; #pragma unroll
;     for (int i = 0; i < 16; ++i) { float* d = scr + (4 * i + (lane >> 4)) * 65 + 4 * (lane & 15); d[0] = v[i][0]; d[1] = v[i][1]; d[2] = v[i][2]; d[3] = v[i][3]; }
;     __builtin_amdgcn_s_waitcnt(0); __builtin_amdgcn_wave_barrier();
;     const int c = lane & 7;
; #pragma unroll
;     for (int j = 0; j < 8; ++j) { const int n = (lane >> 3) + 8 * j; const float* sp = scr + (8 * c) * 65 + n;
;         u32x4 o; o.x = pk2w(sp[0 * 65], sp[1 * 65]); o.y = pk2w(sp[2 * 65], sp[3 * 65]); o.z = pk2w(sp[4 * 65], sp[5 * 65]); o.w = pk2w(sp[6 * 65], sp[7 * 65]);
.LBB0_50:
	s_andn2_b64 vcc, exec, s[8:9]
	s_cbranch_vccnz .LBB0_52
	s_add_i32 s9, s42, 0x8300
	s_and_b32 s8, s15, 0x7c0
	s_and_b32 s9, s9, 0x1ffc0
	v_or_b32_e32 v2, s9, v59
	s_lshl_b32 s40, s8, 2
	v_lshl_add_u64 v[56:57], v[12:13], 0, s[40:41]
	v_lshlrev_b32_e32 v2, 13, v2
	v_lshl_add_u64 v[56:57], v[56:57], 0, v[2:3]
	v_add_co_u32_e32 v76, vcc, 0x8000, v56
	v_add_u32_e32 v2, 0x410, v60
	s_nop 0
	v_addc_co_u32_e32 v77, vcc, 0, v57, vcc
	v_add_co_u32_e32 v80, vcc, 0x10000, v56
	global_load_dwordx4 v[72:75], v[56:57], off nt
	s_nop 0
	global_load_dwordx4 v[76:79], v[76:77], off nt
	v_addc_co_u32_e32 v81, vcc, 0, v57, vcc
	v_add_co_u32_e32 v84, vcc, 0x18000, v56
	s_lshl_b32 s40, s9, 1
	s_nop 0
	v_addc_co_u32_e32 v85, vcc, 0, v57, vcc
	global_load_dwordx4 v[80:83], v[80:81], off nt
	s_nop 0
	global_load_dwordx4 v[84:87], v[84:85], off nt
	v_add_co_u32_e32 v88, vcc, 0x20000, v56
	s_nop 1
	v_addc_co_u32_e32 v89, vcc, 0, v57, vcc
	v_add_co_u32_e32 v92, vcc, 0x28000, v56
	s_nop 1
	v_addc_co_u32_e32 v93, vcc, 0, v57, vcc
	global_load_dwordx4 v[88:91], v[88:89], off nt
	s_nop 0
	global_load_dwordx4 v[92:95], v[92:93], off nt
	v_add_co_u32_e32 v96, vcc, 0x30000, v56
	s_nop 1
	v_addc_co_u32_e32 v97, vcc, 0, v57, vcc
	v_add_co_u32_e32 v100, vcc, 0x38000, v56
	s_nop 1
	v_addc_co_u32_e32 v101, vcc, 0, v57, vcc
	global_load_dwordx4 v[96:99], v[96:97], off nt
	s_nop 0
	global_load_dwordx4 v[100:103], v[100:101], off nt
	v_add_co_u32_e32 v104, vcc, 0x40000, v56
	s_nop 1
	v_addc_co_u32_e32 v105, vcc, 0, v57, vcc
	v_add_co_u32_e32 v108, vcc, 0x48000, v56
	s_nop 1
	v_addc_co_u32_e32 v109, vcc, 0, v57, vcc
	global_load_dwordx4 v[104:107], v[104:105], off nt
	s_nop 0
	global_load_dwordx4 v[108:111], v[108:109], off nt
	v_add_co_u32_e32 v112, vcc, 0x50000, v56
	s_nop 1
	v_addc_co_u32_e32 v113, vcc, 0, v57, vcc
	v_add_co_u32_e32 v116, vcc, 0x58000, v56
	s_nop 1
	v_addc_co_u32_e32 v117, vcc, 0, v57, vcc
	global_load_dwordx4 v[112:115], v[112:113], off nt
	s_nop 0
	global_load_dwordx4 v[116:119], v[116:117], off nt
	v_add_co_u32_e32 v120, vcc, 0x60000, v56
	s_nop 1
	v_addc_co_u32_e32 v121, vcc, 0, v57, vcc
	v_add_co_u32_e32 v124, vcc, 0x68000, v56
	s_nop 1
	v_addc_co_u32_e32 v125, vcc, 0, v57, vcc
	global_load_dwordx4 v[120:123], v[120:121], off nt
	s_nop 0
	global_load_dwordx4 v[124:127], v[124:125], off nt
	v_add_co_u32_e32 v128, vcc, 0x70000, v56
	s_nop 1
	v_addc_co_u32_e32 v129, vcc, 0, v57, vcc
	global_load_dwordx4 v[128:131], v[128:129], off nt
	v_add_co_u32_e32 v56, vcc, 0x78000, v56
	s_nop 1
	v_addc_co_u32_e32 v57, vcc, 0, v57, vcc
	global_load_dwordx4 v[132:135], v[56:57], off nt
	s_waitcnt vmcnt(15)
	ds_write2_b32 v60, v72, v73 offset1:1
	ds_write2_b32 v60, v74, v75 offset0:2 offset1:3
	s_waitcnt vmcnt(14)
	ds_write2_b32 v2, v76, v77 offset1:1
	v_add_u32_e32 v2, 0x418, v60
	ds_write2_b32 v2, v78, v79 offset1:1
	v_add_u32_e32 v2, 0x820, v60
	v_lshl_add_u64 v[56:57], v[36:37], 0, s[40:41]
	s_waitcnt vmcnt(13)
	ds_write2_b32 v2, v80, v81 offset1:1
	v_add_u32_e32 v2, 0x828, v60
	ds_write2_b32 v2, v82, v83 offset1:1
	v_add_u32_e32 v2, 0xc30, v60
	s_waitcnt vmcnt(12)
	ds_write2_b32 v2, v84, v85 offset1:1
	v_add_u32_e32 v2, 0xc38, v60
	ds_write2_b32 v2, v86, v87 offset1:1
	v_add_u32_e32 v2, 0x1040, v60
	s_waitcnt vmcnt(11)
	ds_write2_b32 v2, v88, v89 offset1:1
	v_add_u32_e32 v2, 0x1048, v60
	ds_write2_b32 v2, v90, v91 offset1:1
	v_add_u32_e32 v2, 0x1450, v60
	s_waitcnt vmcnt(10)
	ds_write2_b32 v2, v92, v93 offset1:1
	v_add_u32_e32 v2, 0x1458, v60
	ds_write2_b32 v2, v94, v95 offset1:1
	v_add_u32_e32 v2, 0x1860, v60
	s_waitcnt vmcnt(9)
	ds_write2_b32 v2, v96, v97 offset1:1
	v_add_u32_e32 v2, 0x1868, v60
	ds_write2_b32 v2, v98, v99 offset1:1
	v_add_u32_e32 v2, 0x1c70, v60
	s_waitcnt vmcnt(8)
	ds_write2_b32 v2, v100, v101 offset1:1
	v_add_u32_e32 v2, 0x1c78, v60
	ds_write2_b32 v2, v102, v103 offset1:1
	v_add_u32_e32 v2, 0x2080, v60
	s_waitcnt vmcnt(7)
	ds_write2_b32 v2, v104, v105 offset1:1
	v_add_u32_e32 v2, 0x2088, v60
	ds_write2_b32 v2, v106, v107 offset1:1
	v_add_u32_e32 v2, 0x2490, v60
	s_waitcnt vmcnt(6)
	ds_write2_b32 v2, v108, v109 offset1:1
	v_add_u32_e32 v2, 0x2498, v60
	ds_write2_b32 v2, v110, v111 offset1:1
	v_add_u32_e32 v2, 0x28a0, v60
	s_waitcnt vmcnt(5)
	ds_write2_b32 v2, v112, v113 offset1:1
	v_add_u32_e32 v2, 0x28a8, v60
	ds_write2_b32 v2, v114, v115 offset1:1
	v_add_u32_e32 v2, 0x2cb0, v60
	s_waitcnt vmcnt(4)
	ds_write2_b32 v2, v116, v117 offset1:1
	v_add_u32_e32 v2, 0x2cb8, v60
	ds_write2_b32 v2, v118, v119 offset1:1
	v_add_u32_e32 v2, 0x30c0, v60
	s_waitcnt vmcnt(3)
	ds_write2_b32 v2, v120, v121 offset1:1
	v_add_u32_e32 v2, 0x30c8, v60
	ds_write2_b32 v2, v122, v123 offset1:1
	v_add_u32_e32 v2, 0x34d0, v60
	s_waitcnt vmcnt(2)
	ds_write2_b32 v2, v124, v125 offset1:1
	v_add_u32_e32 v2, 0x34d8, v60
	ds_write2_b32 v2, v126, v127 offset1:1
	v_add_u32_e32 v2, 0x38e0, v60
	s_waitcnt vmcnt(1)
	ds_write2_b32 v2, v128, v129 offset1:1
	v_add_u32_e32 v2, 0x38e8, v60
	ds_write2_b32 v2, v130, v131 offset1:1
	v_add_u32_e32 v2, 0x3cf0, v60
	s_waitcnt vmcnt(0)
	ds_write2_b32 v2, v132, v133 offset1:1
	v_add_u32_e32 v2, 0x3cf8, v60
	ds_write2_b32 v2, v134, v135 offset1:1
	s_waitcnt vmcnt(0) expcnt(0) lgkmcnt(0)
	ds_read2_b32 v[76:77], v62 offset1:8
	ds_read2_b32 v[78:79], v62 offset0:65 offset1:73
	ds_read2_b32 v[80:81], v62 offset0:130 offset1:138
	ds_read2_b32 v[82:83], v62 offset0:195 offset1:203
	s_waitcnt lgkmcnt(3)
	v_bfe_u32 v2, v76, 16, 1
	v_add3_u32 v2, v76, v2, s54
	s_waitcnt lgkmcnt(2)
	v_bfe_u32 v45, v78, 16, 1
	v_lshrrev_b32_e32 v2, 16, v2
	v_add3_u32 v45, v78, v45, s54
	v_and_or_b32 v72, v45, s55, v2
	v_add_u32_e32 v45, 0x400, v62
	ds_read2_b32 v[84:85], v45 offset0:4 offset1:12
	ds_read2_b32 v[86:87], v45 offset0:69 offset1:77
	s_waitcnt lgkmcnt(3)
; DI unsigned pk2w(float lo, float hi) { return f2bfw(lo) | (f2bfw(hi) << 16); }
; DI void transpose_item(const float* W, int K, int N, bf16_t* WT, int mode, float* scr, int item, int lane) {
;     ...
;     const int c = lane & 7;
; #pragma unroll
;     for (int j = 0; j < 8; ++j) { const int n = (lane >> 3) + 8 * j; const float* sp = scr + (8 * c) * 65 + n;
;         u32x4 o; o.x = pk2w(sp[0 * 65], sp[1 * 65]); o.y = pk2w(sp[2 * 65], sp[3 * 65]); o.z = pk2w(sp[4 * 65], sp[5 * 65]); o.w = pk2w(sp[6 * 65], sp[7 * 65]);
;         *(u32x4*)(WT + (size_t)(drow0 + n) * K + k0 + 8 * c) = o; }
	v_bfe_u32 v2, v80, 16, 1
	v_add3_u32 v2, v80, v2, s54
	s_waitcnt lgkmcnt(2)
	v_bfe_u32 v47, v82, 16, 1
	ds_read2_b32 v[88:89], v45 offset0:134 offset1:142
	v_lshrrev_b32_e32 v2, 16, v2
	v_add3_u32 v47, v82, v47, s54
	ds_read2_b32 v[90:91], v45 offset0:199 offset1:207
	v_and_or_b32 v73, v47, s55, v2
	s_waitcnt lgkmcnt(3)
	v_bfe_u32 v2, v84, 16, 1
	v_add3_u32 v2, v84, v2, s54
	s_waitcnt lgkmcnt(2)
	v_bfe_u32 v47, v86, 16, 1
	v_lshrrev_b32_e32 v2, 16, v2
	v_add3_u32 v47, v86, v47, s54
	v_and_or_b32 v74, v47, s55, v2
	s_waitcnt lgkmcnt(1)
	v_bfe_u32 v2, v88, 16, 1
	v_add3_u32 v2, v88, v2, s54
	s_waitcnt lgkmcnt(0)
	v_bfe_u32 v47, v90, 16, 1
	v_lshrrev_b32_e32 v2, 16, v2
	v_add3_u32 v47, v90, v47, s54
	v_and_or_b32 v75, v47, s55, v2
	v_or_b32_e32 v2, s8, v61
	v_mul_u32_u24_e32 v2, 0x1600, v2
	v_lshlrev_b32_e32 v2, 1, v2
	v_lshl_add_u64 v[92:93], v[56:57], 0, v[2:3]
	v_bfe_u32 v2, v77, 16, 1
	v_add3_u32 v2, v77, v2, s54
	v_bfe_u32 v47, v79, 16, 1
	v_lshrrev_b32_e32 v2, 16, v2
	v_add3_u32 v47, v79, v47, s54
	global_store_dwordx4 v[92:93], v[72:75], off
	ds_read2_b32 v[76:77], v62 offset0:16 offset1:24
	s_nop 0
	v_and_or_b32 v72, v47, s55, v2
	v_bfe_u32 v2, v81, 16, 1
	v_add3_u32 v2, v81, v2, s54
	v_bfe_u32 v47, v83, 16, 1
	v_lshrrev_b32_e32 v2, 16, v2
	v_add3_u32 v47, v83, v47, s54
	v_and_or_b32 v73, v47, s55, v2
	v_bfe_u32 v2, v85, 16, 1
	v_add3_u32 v2, v85, v2, s54
	v_bfe_u32 v47, v87, 16, 1
	v_lshrrev_b32_e32 v2, 16, v2
	v_add3_u32 v47, v87, v47, s54
	v_and_or_b32 v74, v47, s55, v2
	v_bfe_u32 v2, v89, 16, 1
	v_add3_u32 v2, v89, v2, s54
	v_bfe_u32 v47, v91, 16, 1
	v_lshrrev_b32_e32 v2, 16, v2
	v_add3_u32 v47, v91, v47, s54
	v_and_or_b32 v75, v47, s55, v2
	v_or_b32_e32 v2, s8, v63
	v_mul_u32_u24_e32 v2, 0x1600, v2
	v_lshlrev_b32_e32 v2, 1, v2
	v_lshl_add_u64 v[78:79], v[56:57], 0, v[2:3]
	global_store_dwordx4 v[78:79], v[72:75], off
	ds_read2_b32 v[78:79], v62 offset0:81 offset1:89
	ds_read2_b32 v[80:81], v62 offset0:146 offset1:154
	ds_read2_b32 v[82:83], v62 offset0:211 offset1:219
	s_waitcnt lgkmcnt(3)
	v_bfe_u32 v2, v76, 16, 1
	v_add3_u32 v2, v76, v2, s54
	s_waitcnt lgkmcnt(2)
	v_bfe_u32 v47, v78, 16, 1
	ds_read2_b32 v[84:85], v45 offset0:20 offset1:28
	v_lshrrev_b32_e32 v2, 16, v2
	v_add3_u32 v47, v78, v47, s54
	ds_read2_b32 v[86:87], v45 offset0:85 offset1:93
	v_and_or_b32 v72, v47, s55, v2
	s_waitcnt lgkmcnt(3)
	v_bfe_u32 v2, v80, 16, 1
	v_add3_u32 v2, v80, v2, s54
	s_waitcnt lgkmcnt(2)
	v_bfe_u32 v47, v82, 16, 1
	ds_read2_b32 v[88:89], v45 offset0:150 offset1:158
	v_lshrrev_b32_e32 v2, 16, v2
	v_add3_u32 v47, v82, v47, s54
	ds_read2_b32 v[90:91], v45 offset0:215 offset1:223
	v_and_or_b32 v73, v47, s55, v2
	s_waitcnt lgkmcnt(3)
	v_bfe_u32 v2, v84, 16, 1
	v_add3_u32 v2, v84, v2, s54
	s_waitcnt lgkmcnt(2)
	v_bfe_u32 v47, v86, 16, 1
	v_lshrrev_b32_e32 v2, 16, v2
	v_add3_u32 v47, v86, v47, s54
	v_and_or_b32 v74, v47, s55, v2
	s_waitcnt lgkmcnt(1)
	v_bfe_u32 v2, v88, 16, 1
	v_add3_u32 v2, v88, v2, s54
	s_waitcnt lgkmcnt(0)
	v_bfe_u32 v47, v90, 16, 1
	v_lshrrev_b32_e32 v2, 16, v2
	v_add3_u32 v47, v90, v47, s54
	v_and_or_b32 v75, v47, s55, v2
	v_or_b32_e32 v2, s8, v64
	v_mul_u32_u24_e32 v2, 0x1600, v2
	v_lshlrev_b32_e32 v2, 1, v2
	v_lshl_add_u64 v[92:93], v[56:57], 0, v[2:3]
	v_bfe_u32 v2, v77, 16, 1
	v_add3_u32 v2, v77, v2, s54
	v_bfe_u32 v47, v79, 16, 1
	v_lshrrev_b32_e32 v2, 16, v2
	v_add3_u32 v47, v79, v47, s54
	global_store_dwordx4 v[92:93], v[72:75], off
	ds_read2_b32 v[76:77], v62 offset0:32 offset1:40
	s_nop 0
	v_and_or_b32 v72, v47, s55, v2
	v_bfe_u32 v2, v81, 16, 1
	v_add3_u32 v2, v81, v2, s54
	v_bfe_u32 v47, v83, 16, 1
	v_lshrrev_b32_e32 v2, 16, v2
	v_add3_u32 v47, v83, v47, s54
	v_and_or_b32 v73, v47, s55, v2
	v_bfe_u32 v2, v85, 16, 1
	v_add3_u32 v2, v85, v2, s54
	v_bfe_u32 v47, v87, 16, 1
	v_lshrrev_b32_e32 v2, 16, v2
	v_add3_u32 v47, v87, v47, s54
	v_and_or_b32 v74, v47, s55, v2
	v_bfe_u32 v2, v89, 16, 1
	v_add3_u32 v2, v89, v2, s54
	v_bfe_u32 v47, v91, 16, 1
	v_lshrrev_b32_e32 v2, 16, v2
	v_add3_u32 v47, v91, v47, s54
	v_and_or_b32 v75, v47, s55, v2
	v_or_b32_e32 v2, s8, v65
	v_mul_u32_u24_e32 v2, 0x1600, v2
	v_lshlrev_b32_e32 v2, 1, v2
	v_lshl_add_u64 v[78:79], v[56:57], 0, v[2:3]
	global_store_dwordx4 v[78:79], v[72:75], off
	ds_read2_b32 v[78:79], v62 offset0:97 offset1:105
	ds_read2_b32 v[80:81], v62 offset0:162 offset1:170
	ds_read2_b32 v[82:83], v62 offset0:227 offset1:235
	s_waitcnt lgkmcnt(3)
	v_bfe_u32 v2, v76, 16, 1
	v_add3_u32 v2, v76, v2, s54
	s_waitcnt lgkmcnt(2)
; DI unsigned pk2w(float lo, float hi) { return f2bfw(lo) | (f2bfw(hi) << 16); }
; DI void transpose_item(const float* W, int K, int N, bf16_t* WT, int mode, float* scr, int item, int lane) {
;     ...
;     const int c = lane & 7;
; #pragma unroll
;     for (int j = 0; j < 8; ++j) { const int n = (lane >> 3) + 8 * j; const float* sp = scr + (8 * c) * 65 + n;
;         u32x4 o; o.x = pk2w(sp[0 * 65], sp[1 * 65]); o.y = pk2w(sp[2 * 65], sp[3 * 65]); o.z = pk2w(sp[4 * 65], sp[5 * 65]); o.w = pk2w(sp[6 * 65], sp[7 * 65]);
;         *(u32x4*)(WT + (size_t)(drow0 + n) * K + k0 + 8 * c) = o; }
;     __builtin_amdgcn_s_waitcnt(0); __builtin_amdgcn_wave_barrier();
	v_bfe_u32 v47, v78, 16, 1
	ds_read2_b32 v[84:85], v45 offset0:36 offset1:44
	v_lshrrev_b32_e32 v2, 16, v2
	v_add3_u32 v47, v78, v47, s54
	ds_read2_b32 v[86:87], v45 offset0:101 offset1:109
	v_and_or_b32 v72, v47, s55, v2
	s_waitcnt lgkmcnt(3)
	v_bfe_u32 v2, v80, 16, 1
	v_add3_u32 v2, v80, v2, s54
	s_waitcnt lgkmcnt(2)
	v_bfe_u32 v47, v82, 16, 1
	ds_read2_b32 v[88:89], v45 offset0:166 offset1:174
	v_lshrrev_b32_e32 v2, 16, v2
	v_add3_u32 v47, v82, v47, s54
	ds_read2_b32 v[90:91], v45 offset0:231 offset1:239
	v_and_or_b32 v73, v47, s55, v2
	s_waitcnt lgkmcnt(3)
	v_bfe_u32 v2, v84, 16, 1
	v_add3_u32 v2, v84, v2, s54
	s_waitcnt lgkmcnt(2)
	v_bfe_u32 v47, v86, 16, 1
	v_lshrrev_b32_e32 v2, 16, v2
	v_add3_u32 v47, v86, v47, s54
	v_and_or_b32 v74, v47, s55, v2
	s_waitcnt lgkmcnt(1)
	v_bfe_u32 v2, v88, 16, 1
	v_add3_u32 v2, v88, v2, s54
	s_waitcnt lgkmcnt(0)
	v_bfe_u32 v47, v90, 16, 1
	v_lshrrev_b32_e32 v2, 16, v2
	v_add3_u32 v47, v90, v47, s54
	v_and_or_b32 v75, v47, s55, v2
	v_or_b32_e32 v2, s8, v67
	v_mul_u32_u24_e32 v2, 0x1600, v2
	v_lshlrev_b32_e32 v2, 1, v2
	v_lshl_add_u64 v[92:93], v[56:57], 0, v[2:3]
	v_bfe_u32 v2, v77, 16, 1
	v_add3_u32 v2, v77, v2, s54
	v_bfe_u32 v47, v79, 16, 1
	v_lshrrev_b32_e32 v2, 16, v2
	v_add3_u32 v47, v79, v47, s54
	global_store_dwordx4 v[92:93], v[72:75], off
	ds_read2_b32 v[76:77], v62 offset0:48 offset1:56
	s_nop 0
	v_and_or_b32 v72, v47, s55, v2
	v_bfe_u32 v2, v81, 16, 1
	v_add3_u32 v2, v81, v2, s54
	v_bfe_u32 v47, v83, 16, 1
	v_lshrrev_b32_e32 v2, 16, v2
	v_add3_u32 v47, v83, v47, s54
	v_and_or_b32 v73, v47, s55, v2
	v_bfe_u32 v2, v85, 16, 1
	v_add3_u32 v2, v85, v2, s54
	v_bfe_u32 v47, v87, 16, 1
	v_lshrrev_b32_e32 v2, 16, v2
	v_add3_u32 v47, v87, v47, s54
	v_and_or_b32 v74, v47, s55, v2
	v_bfe_u32 v2, v89, 16, 1
	v_add3_u32 v2, v89, v2, s54
	v_bfe_u32 v47, v91, 16, 1
	v_lshrrev_b32_e32 v2, 16, v2
	v_add3_u32 v47, v91, v47, s54
	v_and_or_b32 v75, v47, s55, v2
	v_or_b32_e32 v2, s8, v68
	v_mul_u32_u24_e32 v2, 0x1600, v2
	v_lshlrev_b32_e32 v2, 1, v2
	v_lshl_add_u64 v[78:79], v[56:57], 0, v[2:3]
	global_store_dwordx4 v[78:79], v[72:75], off
	ds_read2_b32 v[78:79], v62 offset0:113 offset1:121
	ds_read2_b32 v[80:81], v62 offset0:178 offset1:186
	ds_read2_b32 v[82:83], v62 offset0:243 offset1:251
	s_waitcnt lgkmcnt(3)
	v_bfe_u32 v2, v76, 16, 1
	v_add3_u32 v2, v76, v2, s54
	s_waitcnt lgkmcnt(2)
	v_bfe_u32 v47, v78, 16, 1
	ds_read2_b32 v[84:85], v45 offset0:52 offset1:60
	v_lshrrev_b32_e32 v2, 16, v2
	v_add3_u32 v47, v78, v47, s54
	ds_read2_b32 v[86:87], v45 offset0:117 offset1:125
	v_and_or_b32 v72, v47, s55, v2
	s_waitcnt lgkmcnt(3)
	v_bfe_u32 v2, v80, 16, 1
	v_add3_u32 v2, v80, v2, s54
	s_waitcnt lgkmcnt(2)
	v_bfe_u32 v47, v82, 16, 1
	ds_read2_b32 v[88:89], v45 offset0:182 offset1:190
	v_lshrrev_b32_e32 v2, 16, v2
	v_add3_u32 v47, v82, v47, s54
	ds_read2_b32 v[90:91], v45 offset0:247 offset1:255
	v_and_or_b32 v73, v47, s55, v2
	s_waitcnt lgkmcnt(3)
	v_bfe_u32 v2, v84, 16, 1
	v_add3_u32 v2, v84, v2, s54
	s_waitcnt lgkmcnt(2)
	v_bfe_u32 v47, v86, 16, 1
	v_lshrrev_b32_e32 v2, 16, v2
	v_add3_u32 v47, v86, v47, s54
	v_and_or_b32 v74, v47, s55, v2
	s_waitcnt lgkmcnt(1)
	v_bfe_u32 v2, v88, 16, 1
	v_add3_u32 v2, v88, v2, s54
	s_waitcnt lgkmcnt(0)
	v_bfe_u32 v45, v90, 16, 1
	v_lshrrev_b32_e32 v2, 16, v2
	v_add3_u32 v45, v90, v45, s54
	v_and_or_b32 v75, v45, s55, v2
	v_or_b32_e32 v2, s8, v69
	v_mul_u32_u24_e32 v2, 0x1600, v2
	v_lshlrev_b32_e32 v2, 1, v2
	v_lshl_add_u64 v[92:93], v[56:57], 0, v[2:3]
	v_bfe_u32 v2, v77, 16, 1
	v_add3_u32 v2, v77, v2, s54
	v_bfe_u32 v45, v79, 16, 1
	v_lshrrev_b32_e32 v2, 16, v2
	v_add3_u32 v45, v79, v45, s54
	global_store_dwordx4 v[92:93], v[72:75], off
	s_nop 1
	v_and_or_b32 v72, v45, s55, v2
	v_bfe_u32 v2, v81, 16, 1
	v_add3_u32 v2, v81, v2, s54
	v_bfe_u32 v45, v83, 16, 1
	v_lshrrev_b32_e32 v2, 16, v2
	v_add3_u32 v45, v83, v45, s54
	v_and_or_b32 v73, v45, s55, v2
	v_bfe_u32 v2, v85, 16, 1
	v_add3_u32 v2, v85, v2, s54
	v_bfe_u32 v45, v87, 16, 1
	v_lshrrev_b32_e32 v2, 16, v2
	v_add3_u32 v45, v87, v45, s54
	v_and_or_b32 v74, v45, s55, v2
	v_bfe_u32 v2, v89, 16, 1
	v_add3_u32 v2, v89, v2, s54
	v_bfe_u32 v45, v91, 16, 1
	v_lshrrev_b32_e32 v2, 16, v2
	v_add3_u32 v45, v91, v45, s54
	v_and_or_b32 v75, v45, s55, v2
	v_or_b32_e32 v2, s8, v70
	v_mul_u32_u24_e32 v2, 0x1600, v2
	v_lshlrev_b32_e32 v2, 1, v2
	v_lshl_add_u64 v[56:57], v[56:57], 0, v[2:3]
	global_store_dwordx4 v[56:57], v[72:75], off
	s_waitcnt lgkmcnt(0)

; DI unsigned pk2w(float lo, float hi) { return f2bfw(lo) | (f2bfw(hi) << 16); }
; DI void transpose_item(const float* W, int K, int N, bf16_t* WT, int mode, float* scr, int item, int lane) {
;     const int nblk = N / 64, kb = item / nblk, nb = item % nblk, k0 = 64 * kb, n0 = 64 * nb;
;     int drow0 = n0;
;     if (mode == 1) { const int seg = n0 >> 10; const int dst = seg < 2 ? seg : (seg == 2 ? 6 : seg - 1); drow0 = dst * 1024 + (n0 & 1023); }
;     else if (mode == 2) { drow0 = n0 < DFF ? (n0 / 128) * 256 + (n0 % 128) : ((n0 - DFF) / 128) * 256 + 128 + ((n0 - DFF) % 128); }
;     else if (mode == 3) { drow0 = (n0 / 128) * 256 + (n0 % 128); }
;     else if (mode == 4) { drow0 = (n0 / 128) * 256 + 128 + (n0 % 128); }
;     f32x4 v[16];
; #pragma unroll
;     for (int i = 0; i < 16; ++i) v[i] = __builtin_nontemporal_load((const f32x4*)(W + (size_t)(k0 + 4 * i + (lane >> 4)) * N + n0 + 4 * (lane & 15)));
; #pragma unroll
;     for (int i = 0; i < 16; ++i) { float* d = scr + (4 * i + (lane >> 4)) * 65 + 4 * (lane & 15); d[0] = v[i][0]; d[1] = v[i][1]; d[2] = v[i][2]; d[3] = v[i][3]; }
;     __builtin_amdgcn_s_waitcnt(0); __builtin_amdgcn_wave_barrier();
;     const int c = lane & 7;
; #pragma unroll
;     for (int j = 0; j < 8; ++j) { const int n = (lane >> 3) + 8 * j; const float* sp = scr + (8 * c) * 65 + n;
;         u32x4 o; o.x = pk2w(sp[0 * 65], sp[1 * 65]); o.y = pk2w(sp[2 * 65], sp[3 * 65]); o.z = pk2w(sp[4 * 65], sp[5 * 65]); o.w = pk2w(sp[6 * 65], sp[7 * 65]);
.LBB0_58:
	s_lshl_b32 s8, s11, 6
	s_and_b32 s8, s8, 0x7fc0
	v_or_b32_e32 v2, s8, v59
	s_lshl_b32 s40, s40, 2
	v_mul_u32_u24_e32 v2, 0x2c00, v2
	v_lshl_add_u64 v[56:57], v[14:15], 0, s[40:41]
	v_lshlrev_b32_e32 v2, 2, v2
	v_lshl_add_u64 v[56:57], v[56:57], 0, v[2:3]
	v_add_co_u32_e32 v76, vcc, 0x2c000, v56
	v_add_u32_e32 v2, 0x410, v60
	s_nop 0
	v_addc_co_u32_e32 v77, vcc, 0, v57, vcc
	v_add_co_u32_e32 v80, vcc, s56, v56
	global_load_dwordx4 v[72:75], v[56:57], off nt
	s_nop 0
	global_load_dwordx4 v[76:79], v[76:77], off nt
	v_addc_co_u32_e32 v81, vcc, 0, v57, vcc
	v_add_co_u32_e32 v84, vcc, 0x84000, v56
	s_lshl_b32 s40, s8, 1
	s_nop 0
	v_addc_co_u32_e32 v85, vcc, 0, v57, vcc
	global_load_dwordx4 v[80:83], v[80:81], off nt
	s_nop 0
	global_load_dwordx4 v[84:87], v[84:85], off nt
	v_add_co_u32_e32 v88, vcc, 0xb0000, v56
	s_nop 1
	v_addc_co_u32_e32 v89, vcc, 0, v57, vcc
	v_add_co_u32_e32 v92, vcc, 0xdc000, v56
	s_nop 1
	v_addc_co_u32_e32 v93, vcc, 0, v57, vcc
	global_load_dwordx4 v[88:91], v[88:89], off nt
	s_nop 0
	global_load_dwordx4 v[92:95], v[92:93], off nt
	v_add_co_u32_e32 v96, vcc, 0x108000, v56
	s_nop 1
	v_addc_co_u32_e32 v97, vcc, 0, v57, vcc
	v_add_co_u32_e32 v100, vcc, 0x134000, v56
	s_nop 1
	v_addc_co_u32_e32 v101, vcc, 0, v57, vcc
	global_load_dwordx4 v[96:99], v[96:97], off nt
	s_nop 0
	global_load_dwordx4 v[100:103], v[100:101], off nt
	v_add_co_u32_e32 v104, vcc, 0x160000, v56
	s_nop 1
	v_addc_co_u32_e32 v105, vcc, 0, v57, vcc
	v_add_co_u32_e32 v108, vcc, 0x18c000, v56
	s_nop 1
	v_addc_co_u32_e32 v109, vcc, 0, v57, vcc
	global_load_dwordx4 v[104:107], v[104:105], off nt
	s_nop 0
	global_load_dwordx4 v[108:111], v[108:109], off nt
	v_add_co_u32_e32 v112, vcc, 0x1b8000, v56
	s_nop 1
	v_addc_co_u32_e32 v113, vcc, 0, v57, vcc
	v_add_co_u32_e32 v116, vcc, 0x1e4000, v56
	s_nop 1
	v_addc_co_u32_e32 v117, vcc, 0, v57, vcc
	global_load_dwordx4 v[112:115], v[112:113], off nt
	s_nop 0
	global_load_dwordx4 v[116:119], v[116:117], off nt
	v_add_co_u32_e32 v120, vcc, 0x210000, v56
	s_nop 1
	v_addc_co_u32_e32 v121, vcc, 0, v57, vcc
	v_add_co_u32_e32 v124, vcc, 0x23c000, v56
	s_nop 1
	v_addc_co_u32_e32 v125, vcc, 0, v57, vcc
	global_load_dwordx4 v[120:123], v[120:121], off nt
	s_nop 0
	global_load_dwordx4 v[124:127], v[124:125], off nt
	v_add_co_u32_e32 v128, vcc, 0x268000, v56
	s_nop 1
	v_addc_co_u32_e32 v129, vcc, 0, v57, vcc
	global_load_dwordx4 v[128:131], v[128:129], off nt
	v_add_co_u32_e32 v56, vcc, 0x294000, v56
	s_nop 1
	v_addc_co_u32_e32 v57, vcc, 0, v57, vcc
	global_load_dwordx4 v[132:135], v[56:57], off nt
	s_waitcnt vmcnt(15)
	ds_write2_b32 v60, v72, v73 offset1:1
	ds_write2_b32 v60, v74, v75 offset0:2 offset1:3
	s_waitcnt vmcnt(14)
	ds_write2_b32 v2, v76, v77 offset1:1
	v_add_u32_e32 v2, 0x418, v60
	ds_write2_b32 v2, v78, v79 offset1:1
	v_add_u32_e32 v2, 0x820, v60
	v_lshl_add_u64 v[56:57], v[38:39], 0, s[40:41]
	s_waitcnt vmcnt(13)
	ds_write2_b32 v2, v80, v81 offset1:1
	v_add_u32_e32 v2, 0x828, v60
	ds_write2_b32 v2, v82, v83 offset1:1
	v_add_u32_e32 v2, 0xc30, v60
	s_waitcnt vmcnt(12)
	ds_write2_b32 v2, v84, v85 offset1:1
	v_add_u32_e32 v2, 0xc38, v60
	ds_write2_b32 v2, v86, v87 offset1:1
	v_add_u32_e32 v2, 0x1040, v60
	s_waitcnt vmcnt(11)
	ds_write2_b32 v2, v88, v89 offset1:1
	v_add_u32_e32 v2, 0x1048, v60
	ds_write2_b32 v2, v90, v91 offset1:1
	v_add_u32_e32 v2, 0x1450, v60
	s_waitcnt vmcnt(10)
	ds_write2_b32 v2, v92, v93 offset1:1
	v_add_u32_e32 v2, 0x1458, v60
	ds_write2_b32 v2, v94, v95 offset1:1
	v_add_u32_e32 v2, 0x1860, v60
	s_waitcnt vmcnt(9)
	ds_write2_b32 v2, v96, v97 offset1:1
	v_add_u32_e32 v2, 0x1868, v60
	ds_write2_b32 v2, v98, v99 offset1:1
	v_add_u32_e32 v2, 0x1c70, v60
	s_waitcnt vmcnt(8)
	ds_write2_b32 v2, v100, v101 offset1:1
	v_add_u32_e32 v2, 0x1c78, v60
	ds_write2_b32 v2, v102, v103 offset1:1
	v_add_u32_e32 v2, 0x2080, v60
	s_waitcnt vmcnt(7)
	ds_write2_b32 v2, v104, v105 offset1:1
	v_add_u32_e32 v2, 0x2088, v60
	ds_write2_b32 v2, v106, v107 offset1:1
	v_add_u32_e32 v2, 0x2490, v60
	s_waitcnt vmcnt(6)
	ds_write2_b32 v2, v108, v109 offset1:1
	v_add_u32_e32 v2, 0x2498, v60
	ds_write2_b32 v2, v110, v111 offset1:1
	v_add_u32_e32 v2, 0x28a0, v60
	s_waitcnt vmcnt(5)
	ds_write2_b32 v2, v112, v113 offset1:1
	v_add_u32_e32 v2, 0x28a8, v60
	ds_write2_b32 v2, v114, v115 offset1:1
	v_add_u32_e32 v2, 0x2cb0, v60
	s_waitcnt vmcnt(4)
	ds_write2_b32 v2, v116, v117 offset1:1
	v_add_u32_e32 v2, 0x2cb8, v60
	ds_write2_b32 v2, v118, v119 offset1:1
	v_add_u32_e32 v2, 0x30c0, v60
	s_waitcnt vmcnt(3)
	ds_write2_b32 v2, v120, v121 offset1:1
	v_add_u32_e32 v2, 0x30c8, v60
	ds_write2_b32 v2, v122, v123 offset1:1
	v_add_u32_e32 v2, 0x34d0, v60
	s_waitcnt vmcnt(2)
	ds_write2_b32 v2, v124, v125 offset1:1
	v_add_u32_e32 v2, 0x34d8, v60
	ds_write2_b32 v2, v126, v127 offset1:1
	v_add_u32_e32 v2, 0x38e0, v60
	s_waitcnt vmcnt(1)
	ds_write2_b32 v2, v128, v129 offset1:1
	v_add_u32_e32 v2, 0x38e8, v60
	ds_write2_b32 v2, v130, v131 offset1:1
	v_add_u32_e32 v2, 0x3cf0, v60
	s_waitcnt vmcnt(0)
	ds_write2_b32 v2, v132, v133 offset1:1
	v_add_u32_e32 v2, 0x3cf8, v60
	ds_write2_b32 v2, v134, v135 offset1:1
	s_waitcnt vmcnt(0) expcnt(0) lgkmcnt(0)
	ds_read2_b32 v[76:77], v62 offset1:8
	ds_read2_b32 v[78:79], v62 offset0:65 offset1:73
	ds_read2_b32 v[80:81], v62 offset0:130 offset1:138
	ds_read2_b32 v[82:83], v62 offset0:195 offset1:203
	s_waitcnt lgkmcnt(3)
	v_bfe_u32 v2, v76, 16, 1
	v_add3_u32 v2, v76, v2, s54
	s_waitcnt lgkmcnt(2)
	v_bfe_u32 v45, v78, 16, 1
	v_lshrrev_b32_e32 v2, 16, v2
	v_add3_u32 v45, v78, v45, s54
	v_and_or_b32 v72, v45, s55, v2
	v_add_u32_e32 v45, 0x400, v62
	ds_read2_b32 v[84:85], v45 offset0:4 offset1:12
	ds_read2_b32 v[86:87], v45 offset0:69 offset1:77
	s_waitcnt lgkmcnt(3)
; DI unsigned pk2w(float lo, float hi) { return f2bfw(lo) | (f2bfw(hi) << 16); }
; DI void transpose_item(const float* W, int K, int N, bf16_t* WT, int mode, float* scr, int item, int lane) {
;     ...
;     const int c = lane & 7;
; #pragma unroll
;     for (int j = 0; j < 8; ++j) { const int n = (lane >> 3) + 8 * j; const float* sp = scr + (8 * c) * 65 + n;
;         u32x4 o; o.x = pk2w(sp[0 * 65], sp[1 * 65]); o.y = pk2w(sp[2 * 65], sp[3 * 65]); o.z = pk2w(sp[4 * 65], sp[5 * 65]); o.w = pk2w(sp[6 * 65], sp[7 * 65]);
;         *(u32x4*)(WT + (size_t)(drow0 + n) * K + k0 + 8 * c) = o; }
	v_bfe_u32 v2, v80, 16, 1
	v_add3_u32 v2, v80, v2, s54
	s_waitcnt lgkmcnt(2)
	v_bfe_u32 v47, v82, 16, 1
	ds_read2_b32 v[88:89], v45 offset0:134 offset1:142
	v_lshrrev_b32_e32 v2, 16, v2
	v_add3_u32 v47, v82, v47, s54
	ds_read2_b32 v[90:91], v45 offset0:199 offset1:207
	v_and_or_b32 v73, v47, s55, v2
	s_waitcnt lgkmcnt(3)
	v_bfe_u32 v2, v84, 16, 1
	v_add3_u32 v2, v84, v2, s54
	s_waitcnt lgkmcnt(2)
	v_bfe_u32 v47, v86, 16, 1
	v_lshrrev_b32_e32 v2, 16, v2
	v_add3_u32 v47, v86, v47, s54
	v_and_or_b32 v74, v47, s55, v2
	s_waitcnt lgkmcnt(1)
	v_bfe_u32 v2, v88, 16, 1
	v_add3_u32 v2, v88, v2, s54
	s_waitcnt lgkmcnt(0)
	v_bfe_u32 v47, v90, 16, 1
	v_lshrrev_b32_e32 v2, 16, v2
	v_add3_u32 v47, v90, v47, s54
	v_and_or_b32 v75, v47, s55, v2
	v_add_u32_e32 v2, s10, v61
	v_lshlrev_b64 v[92:93], 12, v[2:3]
	v_bfe_u32 v2, v77, 16, 1
	v_add3_u32 v2, v77, v2, s54
	v_bfe_u32 v47, v79, 16, 1
	v_lshl_add_u64 v[92:93], v[56:57], 0, v[92:93]
	v_lshrrev_b32_e32 v2, 16, v2
	v_add3_u32 v47, v79, v47, s54
	global_store_dwordx4 v[92:93], v[72:75], off
	ds_read2_b32 v[76:77], v62 offset0:16 offset1:24
	s_nop 0
	v_and_or_b32 v72, v47, s55, v2
	v_bfe_u32 v2, v81, 16, 1
	v_add3_u32 v2, v81, v2, s54
	v_bfe_u32 v47, v83, 16, 1
	v_lshrrev_b32_e32 v2, 16, v2
	v_add3_u32 v47, v83, v47, s54
	v_and_or_b32 v73, v47, s55, v2
	v_bfe_u32 v2, v85, 16, 1
	v_add3_u32 v2, v85, v2, s54
	v_bfe_u32 v47, v87, 16, 1
	v_lshrrev_b32_e32 v2, 16, v2
	v_add3_u32 v47, v87, v47, s54
	v_and_or_b32 v74, v47, s55, v2
	v_bfe_u32 v2, v89, 16, 1
	v_add3_u32 v2, v89, v2, s54
	v_bfe_u32 v47, v91, 16, 1
	v_lshrrev_b32_e32 v2, 16, v2
	v_add3_u32 v47, v91, v47, s54
	v_and_or_b32 v75, v47, s55, v2
	v_add_u32_e32 v2, s10, v63
	v_lshlrev_b64 v[78:79], 12, v[2:3]
	v_lshl_add_u64 v[78:79], v[56:57], 0, v[78:79]
	global_store_dwordx4 v[78:79], v[72:75], off
	ds_read2_b32 v[78:79], v62 offset0:81 offset1:89
	ds_read2_b32 v[80:81], v62 offset0:146 offset1:154
	ds_read2_b32 v[82:83], v62 offset0:211 offset1:219
	s_waitcnt lgkmcnt(3)
	v_bfe_u32 v2, v76, 16, 1
	v_add3_u32 v2, v76, v2, s54
	s_waitcnt lgkmcnt(2)
	v_bfe_u32 v47, v78, 16, 1
	ds_read2_b32 v[84:85], v45 offset0:20 offset1:28
	v_lshrrev_b32_e32 v2, 16, v2
	v_add3_u32 v47, v78, v47, s54
	ds_read2_b32 v[86:87], v45 offset0:85 offset1:93
	v_and_or_b32 v72, v47, s55, v2
	s_waitcnt lgkmcnt(3)
	v_bfe_u32 v2, v80, 16, 1
	v_add3_u32 v2, v80, v2, s54
	s_waitcnt lgkmcnt(2)
	v_bfe_u32 v47, v82, 16, 1
	ds_read2_b32 v[88:89], v45 offset0:150 offset1:158
	v_lshrrev_b32_e32 v2, 16, v2
	v_add3_u32 v47, v82, v47, s54
	ds_read2_b32 v[90:91], v45 offset0:215 offset1:223
	v_and_or_b32 v73, v47, s55, v2
	s_waitcnt lgkmcnt(3)
	v_bfe_u32 v2, v84, 16, 1
	v_add3_u32 v2, v84, v2, s54
	s_waitcnt lgkmcnt(2)
	v_bfe_u32 v47, v86, 16, 1
	v_lshrrev_b32_e32 v2, 16, v2
	v_add3_u32 v47, v86, v47, s54
	v_and_or_b32 v74, v47, s55, v2
	s_waitcnt lgkmcnt(1)
	v_bfe_u32 v2, v88, 16, 1
	v_add3_u32 v2, v88, v2, s54
	s_waitcnt lgkmcnt(0)
	v_bfe_u32 v47, v90, 16, 1
	v_lshrrev_b32_e32 v2, 16, v2
	v_add3_u32 v47, v90, v47, s54
	v_and_or_b32 v75, v47, s55, v2
	v_add_u32_e32 v2, s10, v64
	v_lshlrev_b64 v[92:93], 12, v[2:3]
	v_bfe_u32 v2, v77, 16, 1
	v_add3_u32 v2, v77, v2, s54
	v_bfe_u32 v47, v79, 16, 1
	v_lshl_add_u64 v[92:93], v[56:57], 0, v[92:93]
	v_lshrrev_b32_e32 v2, 16, v2
	v_add3_u32 v47, v79, v47, s54
	global_store_dwordx4 v[92:93], v[72:75], off
	ds_read2_b32 v[76:77], v62 offset0:32 offset1:40
	s_nop 0
	v_and_or_b32 v72, v47, s55, v2
	v_bfe_u32 v2, v81, 16, 1
	v_add3_u32 v2, v81, v2, s54
	v_bfe_u32 v47, v83, 16, 1
	v_lshrrev_b32_e32 v2, 16, v2
	v_add3_u32 v47, v83, v47, s54
	v_and_or_b32 v73, v47, s55, v2
	v_bfe_u32 v2, v85, 16, 1
	v_add3_u32 v2, v85, v2, s54
	v_bfe_u32 v47, v87, 16, 1
	v_lshrrev_b32_e32 v2, 16, v2
	v_add3_u32 v47, v87, v47, s54
	v_and_or_b32 v74, v47, s55, v2
	v_bfe_u32 v2, v89, 16, 1
	v_add3_u32 v2, v89, v2, s54
	v_bfe_u32 v47, v91, 16, 1
	v_lshrrev_b32_e32 v2, 16, v2
	v_add3_u32 v47, v91, v47, s54
	v_and_or_b32 v75, v47, s55, v2
	v_add_u32_e32 v2, s10, v65
	v_lshlrev_b64 v[78:79], 12, v[2:3]
	v_lshl_add_u64 v[78:79], v[56:57], 0, v[78:79]
	global_store_dwordx4 v[78:79], v[72:75], off
	ds_read2_b32 v[78:79], v62 offset0:97 offset1:105
	ds_read2_b32 v[80:81], v62 offset0:162 offset1:170
	ds_read2_b32 v[82:83], v62 offset0:227 offset1:235
	s_waitcnt lgkmcnt(3)
	v_bfe_u32 v2, v76, 16, 1
	v_add3_u32 v2, v76, v2, s54
	s_waitcnt lgkmcnt(2)
; DI unsigned pk2w(float lo, float hi) { return f2bfw(lo) | (f2bfw(hi) << 16); }
; DI void transpose_item(const float* W, int K, int N, bf16_t* WT, int mode, float* scr, int item, int lane) {
;     ...
;     const int c = lane & 7;
; #pragma unroll
;     for (int j = 0; j < 8; ++j) { const int n = (lane >> 3) + 8 * j; const float* sp = scr + (8 * c) * 65 + n;
;         u32x4 o; o.x = pk2w(sp[0 * 65], sp[1 * 65]); o.y = pk2w(sp[2 * 65], sp[3 * 65]); o.z = pk2w(sp[4 * 65], sp[5 * 65]); o.w = pk2w(sp[6 * 65], sp[7 * 65]);
;         *(u32x4*)(WT + (size_t)(drow0 + n) * K + k0 + 8 * c) = o; }
;     __builtin_amdgcn_s_waitcnt(0); __builtin_amdgcn_wave_barrier();
	v_bfe_u32 v47, v78, 16, 1
	ds_read2_b32 v[84:85], v45 offset0:36 offset1:44
	v_lshrrev_b32_e32 v2, 16, v2
	v_add3_u32 v47, v78, v47, s54
	ds_read2_b32 v[86:87], v45 offset0:101 offset1:109
	v_and_or_b32 v72, v47, s55, v2
	s_waitcnt lgkmcnt(3)
	v_bfe_u32 v2, v80, 16, 1
	v_add3_u32 v2, v80, v2, s54
	s_waitcnt lgkmcnt(2)
	v_bfe_u32 v47, v82, 16, 1
	ds_read2_b32 v[88:89], v45 offset0:166 offset1:174
	v_lshrrev_b32_e32 v2, 16, v2
	v_add3_u32 v47, v82, v47, s54
	ds_read2_b32 v[90:91], v45 offset0:231 offset1:239
	v_and_or_b32 v73, v47, s55, v2
	s_waitcnt lgkmcnt(3)
	v_bfe_u32 v2, v84, 16, 1
	v_add3_u32 v2, v84, v2, s54
	s_waitcnt lgkmcnt(2)
	v_bfe_u32 v47, v86, 16, 1
	v_lshrrev_b32_e32 v2, 16, v2
	v_add3_u32 v47, v86, v47, s54
	v_and_or_b32 v74, v47, s55, v2
	s_waitcnt lgkmcnt(1)
	v_bfe_u32 v2, v88, 16, 1
	v_add3_u32 v2, v88, v2, s54
	s_waitcnt lgkmcnt(0)
	v_bfe_u32 v47, v90, 16, 1
	v_lshrrev_b32_e32 v2, 16, v2
	v_add3_u32 v47, v90, v47, s54
	v_and_or_b32 v75, v47, s55, v2
	v_add_u32_e32 v2, s10, v67
	v_lshlrev_b64 v[92:93], 12, v[2:3]
	v_bfe_u32 v2, v77, 16, 1
	v_add3_u32 v2, v77, v2, s54
	v_bfe_u32 v47, v79, 16, 1
	v_lshl_add_u64 v[92:93], v[56:57], 0, v[92:93]
	v_lshrrev_b32_e32 v2, 16, v2
	v_add3_u32 v47, v79, v47, s54
	global_store_dwordx4 v[92:93], v[72:75], off
	ds_read2_b32 v[76:77], v62 offset0:48 offset1:56
	s_nop 0
	v_and_or_b32 v72, v47, s55, v2
	v_bfe_u32 v2, v81, 16, 1
	v_add3_u32 v2, v81, v2, s54
	v_bfe_u32 v47, v83, 16, 1
	v_lshrrev_b32_e32 v2, 16, v2
	v_add3_u32 v47, v83, v47, s54
	v_and_or_b32 v73, v47, s55, v2
	v_bfe_u32 v2, v85, 16, 1
	v_add3_u32 v2, v85, v2, s54
	v_bfe_u32 v47, v87, 16, 1
	v_lshrrev_b32_e32 v2, 16, v2
	v_add3_u32 v47, v87, v47, s54
	v_and_or_b32 v74, v47, s55, v2
	v_bfe_u32 v2, v89, 16, 1
	v_add3_u32 v2, v89, v2, s54
	v_bfe_u32 v47, v91, 16, 1
	v_lshrrev_b32_e32 v2, 16, v2
	v_add3_u32 v47, v91, v47, s54
	v_and_or_b32 v75, v47, s55, v2
	v_add_u32_e32 v2, s10, v68
	v_lshlrev_b64 v[78:79], 12, v[2:3]
	v_lshl_add_u64 v[78:79], v[56:57], 0, v[78:79]
	global_store_dwordx4 v[78:79], v[72:75], off
	ds_read2_b32 v[78:79], v62 offset0:113 offset1:121
	ds_read2_b32 v[80:81], v62 offset0:178 offset1:186
	ds_read2_b32 v[82:83], v62 offset0:243 offset1:251
	s_waitcnt lgkmcnt(3)
	v_bfe_u32 v2, v76, 16, 1
	v_add3_u32 v2, v76, v2, s54
	s_waitcnt lgkmcnt(2)
	v_bfe_u32 v47, v78, 16, 1
	ds_read2_b32 v[84:85], v45 offset0:52 offset1:60
	v_lshrrev_b32_e32 v2, 16, v2
	v_add3_u32 v47, v78, v47, s54
	ds_read2_b32 v[86:87], v45 offset0:117 offset1:125
	v_and_or_b32 v72, v47, s55, v2
	s_waitcnt lgkmcnt(3)
	v_bfe_u32 v2, v80, 16, 1
	v_add3_u32 v2, v80, v2, s54
	s_waitcnt lgkmcnt(2)
	v_bfe_u32 v47, v82, 16, 1
	ds_read2_b32 v[88:89], v45 offset0:182 offset1:190
	v_lshrrev_b32_e32 v2, 16, v2
	v_add3_u32 v47, v82, v47, s54
	ds_read2_b32 v[90:91], v45 offset0:247 offset1:255
	v_and_or_b32 v73, v47, s55, v2
	s_waitcnt lgkmcnt(3)
	v_bfe_u32 v2, v84, 16, 1
	v_add3_u32 v2, v84, v2, s54
	s_waitcnt lgkmcnt(2)
	v_bfe_u32 v47, v86, 16, 1
	v_lshrrev_b32_e32 v2, 16, v2
	v_add3_u32 v47, v86, v47, s54
	v_and_or_b32 v74, v47, s55, v2
	s_waitcnt lgkmcnt(1)
	v_bfe_u32 v2, v88, 16, 1
	v_add3_u32 v2, v88, v2, s54
	s_waitcnt lgkmcnt(0)
	v_bfe_u32 v45, v90, 16, 1
	v_lshrrev_b32_e32 v2, 16, v2
	v_add3_u32 v45, v90, v45, s54
	v_and_or_b32 v75, v45, s55, v2
	v_add_u32_e32 v2, s10, v69
	v_lshlrev_b64 v[92:93], 12, v[2:3]
	v_bfe_u32 v2, v77, 16, 1
	v_add3_u32 v2, v77, v2, s54
	v_bfe_u32 v45, v79, 16, 1
	v_lshl_add_u64 v[92:93], v[56:57], 0, v[92:93]
	v_lshrrev_b32_e32 v2, 16, v2
	v_add3_u32 v45, v79, v45, s54
	global_store_dwordx4 v[92:93], v[72:75], off
	s_nop 1
	v_and_or_b32 v72, v45, s55, v2
	v_bfe_u32 v2, v81, 16, 1
	v_add3_u32 v2, v81, v2, s54
	v_bfe_u32 v45, v83, 16, 1
	v_lshrrev_b32_e32 v2, 16, v2
	v_add3_u32 v45, v83, v45, s54
	v_and_or_b32 v73, v45, s55, v2
	v_bfe_u32 v2, v85, 16, 1
	v_add3_u32 v2, v85, v2, s54
	v_bfe_u32 v45, v87, 16, 1
	v_lshrrev_b32_e32 v2, 16, v2
	v_add3_u32 v45, v87, v45, s54
	v_and_or_b32 v74, v45, s55, v2
	v_bfe_u32 v2, v89, 16, 1
	v_add3_u32 v2, v89, v2, s54
	v_bfe_u32 v45, v91, 16, 1
	v_lshrrev_b32_e32 v2, 16, v2
	v_add3_u32 v45, v91, v45, s54
	v_and_or_b32 v75, v45, s55, v2
	v_add_u32_e32 v2, s10, v70
	v_lshlrev_b64 v[76:77], 12, v[2:3]
	v_lshl_add_u64 v[56:57], v[56:57], 0, v[76:77]
	global_store_dwordx4 v[56:57], v[72:75], off
	s_waitcnt lgkmcnt(0)

; DI void transpose_item(const float* W, int K, int N, bf16_t* WT, int mode, float* scr, int item, int lane) {
;     ...
;     f32x4 v[16];
; #pragma unroll
;     for (int i = 0; i < 16; ++i) v[i] = __builtin_nontemporal_load((const f32x4*)(W + (size_t)(k0 + 4 * i + (lane >> 4)) * N + n0 + 4 * (lane & 15)));
; #pragma unroll
;     for (int i = 0; i < 16; ++i) { float* d = scr + (4 * i + (lane >> 4)) * 65 + 4 * (lane & 15); d[0] = v[i][0]; d[1] = v[i][1]; d[2] = v[i][2]; d[3] = v[i][3]; }
;     __builtin_amdgcn_s_waitcnt(0); __builtin_amdgcn_wave_barrier();
;     const int c = lane & 7;
; #pragma unroll
;     for (int j = 0; j < 8; ++j) { const int n = (lane >> 3) + 8 * j; const float* sp = scr + (8 * c) * 65 + n;
.LBB0_60:
	s_andn2_b64 vcc, exec, s[8:9]
	s_cbranch_vccnz .LBB0_62
	s_add_i32 s9, s42, 0xb700
	s_and_b32 s8, s15, 0x7c0
	s_and_b32 s9, s9, 0x1ffc0
	v_or_b32_e32 v2, s9, v59
	s_lshl_b32 s40, s8, 2
	v_lshl_add_u64 v[56:57], v[16:17], 0, s[40:41]
	v_lshlrev_b32_e32 v2, 13, v2
	v_lshl_add_u64 v[56:57], v[56:57], 0, v[2:3]
	v_add_co_u32_e32 v76, vcc, 0x8000, v56
	v_add_u32_e32 v2, 0x410, v60
	s_nop 0
	v_addc_co_u32_e32 v77, vcc, 0, v57, vcc
	v_add_co_u32_e32 v80, vcc, 0x10000, v56
	global_load_dwordx4 v[72:75], v[56:57], off nt
	s_nop 0
	global_load_dwordx4 v[76:79], v[76:77], off nt
	v_addc_co_u32_e32 v81, vcc, 0, v57, vcc
	v_add_co_u32_e32 v84, vcc, 0x18000, v56
	s_lshl_b32 s40, s9, 1
	s_nop 0
	v_addc_co_u32_e32 v85, vcc, 0, v57, vcc
	global_load_dwordx4 v[80:83], v[80:81], off nt
	s_nop 0
	global_load_dwordx4 v[84:87], v[84:85], off nt
	v_add_co_u32_e32 v88, vcc, 0x20000, v56
	s_nop 1
	v_addc_co_u32_e32 v89, vcc, 0, v57, vcc
	v_add_co_u32_e32 v92, vcc, 0x28000, v56
	s_nop 1
	v_addc_co_u32_e32 v93, vcc, 0, v57, vcc
	global_load_dwordx4 v[88:91], v[88:89], off nt
	s_nop 0
	global_load_dwordx4 v[92:95], v[92:93], off nt
	v_add_co_u32_e32 v96, vcc, 0x30000, v56
	s_nop 1
	v_addc_co_u32_e32 v97, vcc, 0, v57, vcc
	v_add_co_u32_e32 v100, vcc, 0x38000, v56
	s_nop 1
	v_addc_co_u32_e32 v101, vcc, 0, v57, vcc
	global_load_dwordx4 v[96:99], v[96:97], off nt
	s_nop 0
	global_load_dwordx4 v[100:103], v[100:101], off nt
	v_add_co_u32_e32 v104, vcc, 0x40000, v56
	s_nop 1
	v_addc_co_u32_e32 v105, vcc, 0, v57, vcc
	v_add_co_u32_e32 v108, vcc, 0x48000, v56
	s_nop 1
	v_addc_co_u32_e32 v109, vcc, 0, v57, vcc
	global_load_dwordx4 v[104:107], v[104:105], off nt
	s_nop 0
	global_load_dwordx4 v[108:111], v[108:109], off nt
	v_add_co_u32_e32 v112, vcc, 0x50000, v56
	s_nop 1
	v_addc_co_u32_e32 v113, vcc, 0, v57, vcc
	v_add_co_u32_e32 v116, vcc, 0x58000, v56
	s_nop 1
	v_addc_co_u32_e32 v117, vcc, 0, v57, vcc
	global_load_dwordx4 v[112:115], v[112:113], off nt
	s_nop 0
	global_load_dwordx4 v[116:119], v[116:117], off nt
	v_add_co_u32_e32 v120, vcc, 0x60000, v56
	s_nop 1
	v_addc_co_u32_e32 v121, vcc, 0, v57, vcc
	v_add_co_u32_e32 v124, vcc, 0x68000, v56
	s_nop 1
	v_addc_co_u32_e32 v125, vcc, 0, v57, vcc
	global_load_dwordx4 v[120:123], v[120:121], off nt
	s_nop 0
	global_load_dwordx4 v[124:127], v[124:125], off nt
	v_add_co_u32_e32 v128, vcc, 0x70000, v56
	s_nop 1
	v_addc_co_u32_e32 v129, vcc, 0, v57, vcc
	global_load_dwordx4 v[128:131], v[128:129], off nt
	v_add_co_u32_e32 v56, vcc, 0x78000, v56
	s_nop 1
	v_addc_co_u32_e32 v57, vcc, 0, v57, vcc
	global_load_dwordx4 v[132:135], v[56:57], off nt
	s_waitcnt vmcnt(15)
	ds_write2_b32 v60, v72, v73 offset1:1
	ds_write2_b32 v60, v74, v75 offset0:2 offset1:3
	s_waitcnt vmcnt(14)
	ds_write2_b32 v2, v76, v77 offset1:1
	v_add_u32_e32 v2, 0x418, v60
	ds_write2_b32 v2, v78, v79 offset1:1
	v_add_u32_e32 v2, 0x820, v60
	v_lshl_add_u64 v[56:57], v[40:41], 0, s[40:41]
	s_waitcnt vmcnt(13)
	ds_write2_b32 v2, v80, v81 offset1:1
	v_add_u32_e32 v2, 0x828, v60
	ds_write2_b32 v2, v82, v83 offset1:1
	v_add_u32_e32 v2, 0xc30, v60
	s_waitcnt vmcnt(12)
	ds_write2_b32 v2, v84, v85 offset1:1
	v_add_u32_e32 v2, 0xc38, v60
	ds_write2_b32 v2, v86, v87 offset1:1
	v_add_u32_e32 v2, 0x1040, v60
	s_waitcnt vmcnt(11)
	ds_write2_b32 v2, v88, v89 offset1:1
	v_add_u32_e32 v2, 0x1048, v60
	ds_write2_b32 v2, v90, v91 offset1:1
	v_add_u32_e32 v2, 0x1450, v60
	s_waitcnt vmcnt(10)
	ds_write2_b32 v2, v92, v93 offset1:1
	v_add_u32_e32 v2, 0x1458, v60
	ds_write2_b32 v2, v94, v95 offset1:1
	v_add_u32_e32 v2, 0x1860, v60
	s_waitcnt vmcnt(9)
	ds_write2_b32 v2, v96, v97 offset1:1
	v_add_u32_e32 v2, 0x1868, v60
	ds_write2_b32 v2, v98, v99 offset1:1
	v_add_u32_e32 v2, 0x1c70, v60
	s_waitcnt vmcnt(8)
	ds_write2_b32 v2, v100, v101 offset1:1
	v_add_u32_e32 v2, 0x1c78, v60
	ds_write2_b32 v2, v102, v103 offset1:1
	v_add_u32_e32 v2, 0x2080, v60
	s_waitcnt vmcnt(7)
	ds_write2_b32 v2, v104, v105 offset1:1
	v_add_u32_e32 v2, 0x2088, v60
	ds_write2_b32 v2, v106, v107 offset1:1
	v_add_u32_e32 v2, 0x2490, v60
	s_waitcnt vmcnt(6)
	ds_write2_b32 v2, v108, v109 offset1:1
	v_add_u32_e32 v2, 0x2498, v60
	ds_write2_b32 v2, v110, v111 offset1:1
	v_add_u32_e32 v2, 0x28a0, v60
	s_waitcnt vmcnt(5)
	ds_write2_b32 v2, v112, v113 offset1:1
	v_add_u32_e32 v2, 0x28a8, v60
	ds_write2_b32 v2, v114, v115 offset1:1
	v_add_u32_e32 v2, 0x2cb0, v60
	s_waitcnt vmcnt(4)
	ds_write2_b32 v2, v116, v117 offset1:1
	v_add_u32_e32 v2, 0x2cb8, v60
	ds_write2_b32 v2, v118, v119 offset1:1
	v_add_u32_e32 v2, 0x30c0, v60
	s_waitcnt vmcnt(3)
	ds_write2_b32 v2, v120, v121 offset1:1
	v_add_u32_e32 v2, 0x30c8, v60
	ds_write2_b32 v2, v122, v123 offset1:1
	v_add_u32_e32 v2, 0x34d0, v60
	s_waitcnt vmcnt(2)
	ds_write2_b32 v2, v124, v125 offset1:1
	v_add_u32_e32 v2, 0x34d8, v60
	ds_write2_b32 v2, v126, v127 offset1:1
	v_add_u32_e32 v2, 0x38e0, v60
	s_waitcnt vmcnt(1)
	ds_write2_b32 v2, v128, v129 offset1:1
	v_add_u32_e32 v2, 0x38e8, v60
	ds_write2_b32 v2, v130, v131 offset1:1
	v_add_u32_e32 v2, 0x3cf0, v60
	s_waitcnt vmcnt(0)
	ds_write2_b32 v2, v132, v133 offset1:1
	v_add_u32_e32 v2, 0x3cf8, v60
	ds_write2_b32 v2, v134, v135 offset1:1
	s_waitcnt vmcnt(0) expcnt(0) lgkmcnt(0)
	ds_read2_b32 v[76:77], v62 offset1:8
	ds_read2_b32 v[78:79], v62 offset0:65 offset1:73
	ds_read2_b32 v[80:81], v62 offset0:130 offset1:138
	ds_read2_b32 v[82:83], v62 offset0:195 offset1:203
	s_waitcnt lgkmcnt(3)
	v_bfe_u32 v2, v76, 16, 1
	v_add3_u32 v2, v76, v2, s54
	s_waitcnt lgkmcnt(2)
	v_bfe_u32 v45, v78, 16, 1
	v_lshrrev_b32_e32 v2, 16, v2
	v_add3_u32 v45, v78, v45, s54
	v_and_or_b32 v72, v45, s55, v2
	v_add_u32_e32 v45, 0x400, v62
	ds_read2_b32 v[84:85], v45 offset0:4 offset1:12
	ds_read2_b32 v[86:87], v45 offset0:69 offset1:77
	s_waitcnt lgkmcnt(3)
; DI unsigned pk2w(float lo, float hi) { return f2bfw(lo) | (f2bfw(hi) << 16); }
; DI void transpose_item(const float* W, int K, int N, bf16_t* WT, int mode, float* scr, int item, int lane) {
;     ...
;     const int c = lane & 7;
; #pragma unroll
;     for (int j = 0; j < 8; ++j) { const int n = (lane >> 3) + 8 * j; const float* sp = scr + (8 * c) * 65 + n;
;         u32x4 o; o.x = pk2w(sp[0 * 65], sp[1 * 65]); o.y = pk2w(sp[2 * 65], sp[3 * 65]); o.z = pk2w(sp[4 * 65], sp[5 * 65]); o.w = pk2w(sp[6 * 65], sp[7 * 65]);
;         *(u32x4*)(WT + (size_t)(drow0 + n) * K + k0 + 8 * c) = o; }
;     __builtin_amdgcn_s_waitcnt(0); __builtin_amdgcn_wave_barrier();
	v_bfe_u32 v2, v80, 16, 1
	v_add3_u32 v2, v80, v2, s54
	s_waitcnt lgkmcnt(2)
	v_bfe_u32 v47, v82, 16, 1
	ds_read2_b32 v[88:89], v45 offset0:134 offset1:142
	v_lshrrev_b32_e32 v2, 16, v2
	v_add3_u32 v47, v82, v47, s54
	ds_read2_b32 v[90:91], v45 offset0:199 offset1:207
	v_and_or_b32 v73, v47, s55, v2
	s_waitcnt lgkmcnt(3)
	v_bfe_u32 v2, v84, 16, 1
	v_add3_u32 v2, v84, v2, s54
	s_waitcnt lgkmcnt(2)
	v_bfe_u32 v47, v86, 16, 1
	v_lshrrev_b32_e32 v2, 16, v2
	v_add3_u32 v47, v86, v47, s54
	v_and_or_b32 v74, v47, s55, v2
	s_waitcnt lgkmcnt(1)
	v_bfe_u32 v2, v88, 16, 1
	v_add3_u32 v2, v88, v2, s54
	s_waitcnt lgkmcnt(0)
	v_bfe_u32 v47, v90, 16, 1
	v_lshrrev_b32_e32 v2, 16, v2
	v_add3_u32 v47, v90, v47, s54
	v_and_or_b32 v75, v47, s55, v2
	v_or_b32_e32 v2, s8, v61
	v_lshlrev_b32_e32 v2, 12, v2
	v_lshl_add_u64 v[92:93], v[56:57], 0, v[2:3]
	v_bfe_u32 v2, v77, 16, 1
	v_add3_u32 v2, v77, v2, s54
	v_bfe_u32 v47, v79, 16, 1
	v_lshrrev_b32_e32 v2, 16, v2
	v_add3_u32 v47, v79, v47, s54
	global_store_dwordx4 v[92:93], v[72:75], off
	ds_read2_b32 v[76:77], v62 offset0:16 offset1:24
	s_nop 0
	v_and_or_b32 v72, v47, s55, v2
	v_bfe_u32 v2, v81, 16, 1
	v_add3_u32 v2, v81, v2, s54
	v_bfe_u32 v47, v83, 16, 1
	v_lshrrev_b32_e32 v2, 16, v2
	v_add3_u32 v47, v83, v47, s54
	v_and_or_b32 v73, v47, s55, v2
	v_bfe_u32 v2, v85, 16, 1
	v_add3_u32 v2, v85, v2, s54
	v_bfe_u32 v47, v87, 16, 1
	v_lshrrev_b32_e32 v2, 16, v2
	v_add3_u32 v47, v87, v47, s54
	v_and_or_b32 v74, v47, s55, v2
	v_bfe_u32 v2, v89, 16, 1
	v_add3_u32 v2, v89, v2, s54
	v_bfe_u32 v47, v91, 16, 1
	v_lshrrev_b32_e32 v2, 16, v2
	v_add3_u32 v47, v91, v47, s54
	v_and_or_b32 v75, v47, s55, v2
	v_or_b32_e32 v2, s8, v63
	v_lshlrev_b32_e32 v2, 12, v2
	v_lshl_add_u64 v[78:79], v[56:57], 0, v[2:3]
	global_store_dwordx4 v[78:79], v[72:75], off
	ds_read2_b32 v[78:79], v62 offset0:81 offset1:89
	ds_read2_b32 v[80:81], v62 offset0:146 offset1:154
	ds_read2_b32 v[82:83], v62 offset0:211 offset1:219
	s_waitcnt lgkmcnt(3)
	v_bfe_u32 v2, v76, 16, 1
	v_add3_u32 v2, v76, v2, s54
	s_waitcnt lgkmcnt(2)
	v_bfe_u32 v47, v78, 16, 1
	ds_read2_b32 v[84:85], v45 offset0:20 offset1:28
	v_lshrrev_b32_e32 v2, 16, v2
	v_add3_u32 v47, v78, v47, s54
	ds_read2_b32 v[86:87], v45 offset0:85 offset1:93
	v_and_or_b32 v72, v47, s55, v2
	s_waitcnt lgkmcnt(3)
	v_bfe_u32 v2, v80, 16, 1
	v_add3_u32 v2, v80, v2, s54
	s_waitcnt lgkmcnt(2)
	v_bfe_u32 v47, v82, 16, 1
	ds_read2_b32 v[88:89], v45 offset0:150 offset1:158
	v_lshrrev_b32_e32 v2, 16, v2
	v_add3_u32 v47, v82, v47, s54
	ds_read2_b32 v[90:91], v45 offset0:215 offset1:223
	v_and_or_b32 v73, v47, s55, v2
	s_waitcnt lgkmcnt(3)
	v_bfe_u32 v2, v84, 16, 1
	v_add3_u32 v2, v84, v2, s54
	s_waitcnt lgkmcnt(2)
	v_bfe_u32 v47, v86, 16, 1
	v_lshrrev_b32_e32 v2, 16, v2
	v_add3_u32 v47, v86, v47, s54
	v_and_or_b32 v74, v47, s55, v2
	s_waitcnt lgkmcnt(1)
	v_bfe_u32 v2, v88, 16, 1
	v_add3_u32 v2, v88, v2, s54
	s_waitcnt lgkmcnt(0)
	v_bfe_u32 v47, v90, 16, 1
	v_lshrrev_b32_e32 v2, 16, v2
	v_add3_u32 v47, v90, v47, s54
	v_and_or_b32 v75, v47, s55, v2
	v_or_b32_e32 v2, s8, v64
	v_lshlrev_b32_e32 v2, 12, v2
	v_lshl_add_u64 v[92:93], v[56:57], 0, v[2:3]
	v_bfe_u32 v2, v77, 16, 1
	v_add3_u32 v2, v77, v2, s54
	v_bfe_u32 v47, v79, 16, 1
	v_lshrrev_b32_e32 v2, 16, v2
	v_add3_u32 v47, v79, v47, s54
	global_store_dwordx4 v[92:93], v[72:75], off
	ds_read2_b32 v[76:77], v62 offset0:32 offset1:40
	s_nop 0
	v_and_or_b32 v72, v47, s55, v2
	v_bfe_u32 v2, v81, 16, 1
	v_add3_u32 v2, v81, v2, s54
	v_bfe_u32 v47, v83, 16, 1
	v_lshrrev_b32_e32 v2, 16, v2
	v_add3_u32 v47, v83, v47, s54
	v_and_or_b32 v73, v47, s55, v2
	v_bfe_u32 v2, v85, 16, 1
	v_add3_u32 v2, v85, v2, s54
	v_bfe_u32 v47, v87, 16, 1
	v_lshrrev_b32_e32 v2, 16, v2
	v_add3_u32 v47, v87, v47, s54
	v_and_or_b32 v74, v47, s55, v2
	v_bfe_u32 v2, v89, 16, 1
	v_add3_u32 v2, v89, v2, s54
	v_bfe_u32 v47, v91, 16, 1
	v_lshrrev_b32_e32 v2, 16, v2
	v_add3_u32 v47, v91, v47, s54
	v_and_or_b32 v75, v47, s55, v2
	v_or_b32_e32 v2, s8, v65
	v_lshlrev_b32_e32 v2, 12, v2
	v_lshl_add_u64 v[78:79], v[56:57], 0, v[2:3]
	global_store_dwordx4 v[78:79], v[72:75], off
	ds_read2_b32 v[78:79], v62 offset0:97 offset1:105
	ds_read2_b32 v[80:81], v62 offset0:162 offset1:170
	ds_read2_b32 v[82:83], v62 offset0:227 offset1:235
	s_waitcnt lgkmcnt(3)
	v_bfe_u32 v2, v76, 16, 1
	v_add3_u32 v2, v76, v2, s54
	s_waitcnt lgkmcnt(2)
; DI unsigned pk2w(float lo, float hi) { return f2bfw(lo) | (f2bfw(hi) << 16); }
; DI void transpose_item(const float* W, int K, int N, bf16_t* WT, int mode, float* scr, int item, int lane) {
;     ...
;     const int c = lane & 7;
; #pragma unroll
;     for (int j = 0; j < 8; ++j) { const int n = (lane >> 3) + 8 * j; const float* sp = scr + (8 * c) * 65 + n;
;         u32x4 o; o.x = pk2w(sp[0 * 65], sp[1 * 65]); o.y = pk2w(sp[2 * 65], sp[3 * 65]); o.z = pk2w(sp[4 * 65], sp[5 * 65]); o.w = pk2w(sp[6 * 65], sp[7 * 65]);
;         *(u32x4*)(WT + (size_t)(drow0 + n) * K + k0 + 8 * c) = o; }
;     __builtin_amdgcn_s_waitcnt(0); __builtin_amdgcn_wave_barrier();
	v_bfe_u32 v47, v78, 16, 1
	ds_read2_b32 v[84:85], v45 offset0:36 offset1:44
	v_lshrrev_b32_e32 v2, 16, v2
	v_add3_u32 v47, v78, v47, s54
	ds_read2_b32 v[86:87], v45 offset0:101 offset1:109
	v_and_or_b32 v72, v47, s55, v2
	s_waitcnt lgkmcnt(3)
	v_bfe_u32 v2, v80, 16, 1
	v_add3_u32 v2, v80, v2, s54
	s_waitcnt lgkmcnt(2)
	v_bfe_u32 v47, v82, 16, 1
	ds_read2_b32 v[88:89], v45 offset0:166 offset1:174
	v_lshrrev_b32_e32 v2, 16, v2
	v_add3_u32 v47, v82, v47, s54
	ds_read2_b32 v[90:91], v45 offset0:231 offset1:239
	v_and_or_b32 v73, v47, s55, v2
	s_waitcnt lgkmcnt(3)
	v_bfe_u32 v2, v84, 16, 1
	v_add3_u32 v2, v84, v2, s54
	s_waitcnt lgkmcnt(2)
	v_bfe_u32 v47, v86, 16, 1
	v_lshrrev_b32_e32 v2, 16, v2
	v_add3_u32 v47, v86, v47, s54
	v_and_or_b32 v74, v47, s55, v2
	s_waitcnt lgkmcnt(1)
	v_bfe_u32 v2, v88, 16, 1
	v_add3_u32 v2, v88, v2, s54
	s_waitcnt lgkmcnt(0)
	v_bfe_u32 v47, v90, 16, 1
	v_lshrrev_b32_e32 v2, 16, v2
	v_add3_u32 v47, v90, v47, s54
	v_and_or_b32 v75, v47, s55, v2
	v_or_b32_e32 v2, s8, v67
	v_lshlrev_b32_e32 v2, 12, v2
	v_lshl_add_u64 v[92:93], v[56:57], 0, v[2:3]
	v_bfe_u32 v2, v77, 16, 1
	v_add3_u32 v2, v77, v2, s54
	v_bfe_u32 v47, v79, 16, 1
	v_lshrrev_b32_e32 v2, 16, v2
	v_add3_u32 v47, v79, v47, s54
	global_store_dwordx4 v[92:93], v[72:75], off
	ds_read2_b32 v[76:77], v62 offset0:48 offset1:56
	s_nop 0
	v_and_or_b32 v72, v47, s55, v2
	v_bfe_u32 v2, v81, 16, 1
	v_add3_u32 v2, v81, v2, s54
	v_bfe_u32 v47, v83, 16, 1
	v_lshrrev_b32_e32 v2, 16, v2
	v_add3_u32 v47, v83, v47, s54
	v_and_or_b32 v73, v47, s55, v2
	v_bfe_u32 v2, v85, 16, 1
	v_add3_u32 v2, v85, v2, s54
	v_bfe_u32 v47, v87, 16, 1
	v_lshrrev_b32_e32 v2, 16, v2
	v_add3_u32 v47, v87, v47, s54
	v_and_or_b32 v74, v47, s55, v2
	v_bfe_u32 v2, v89, 16, 1
	v_add3_u32 v2, v89, v2, s54
	v_bfe_u32 v47, v91, 16, 1
	v_lshrrev_b32_e32 v2, 16, v2
	v_add3_u32 v47, v91, v47, s54
	v_and_or_b32 v75, v47, s55, v2
	v_or_b32_e32 v2, s8, v68
	v_lshlrev_b32_e32 v2, 12, v2
	v_lshl_add_u64 v[78:79], v[56:57], 0, v[2:3]
	global_store_dwordx4 v[78:79], v[72:75], off
	ds_read2_b32 v[78:79], v62 offset0:113 offset1:121
	ds_read2_b32 v[80:81], v62 offset0:178 offset1:186
	ds_read2_b32 v[82:83], v62 offset0:243 offset1:251
	s_waitcnt lgkmcnt(3)
	v_bfe_u32 v2, v76, 16, 1
	v_add3_u32 v2, v76, v2, s54
	s_waitcnt lgkmcnt(2)
	v_bfe_u32 v47, v78, 16, 1
	ds_read2_b32 v[84:85], v45 offset0:52 offset1:60
	v_lshrrev_b32_e32 v2, 16, v2
	v_add3_u32 v47, v78, v47, s54
	ds_read2_b32 v[86:87], v45 offset0:117 offset1:125
	v_and_or_b32 v72, v47, s55, v2
	s_waitcnt lgkmcnt(3)
	v_bfe_u32 v2, v80, 16, 1
	v_add3_u32 v2, v80, v2, s54
	s_waitcnt lgkmcnt(2)
	v_bfe_u32 v47, v82, 16, 1
	ds_read2_b32 v[88:89], v45 offset0:182 offset1:190
	v_lshrrev_b32_e32 v2, 16, v2
	v_add3_u32 v47, v82, v47, s54
	ds_read2_b32 v[90:91], v45 offset0:247 offset1:255
	v_and_or_b32 v73, v47, s55, v2
	s_waitcnt lgkmcnt(3)
	v_bfe_u32 v2, v84, 16, 1
	v_add3_u32 v2, v84, v2, s54
	s_waitcnt lgkmcnt(2)
	v_bfe_u32 v47, v86, 16, 1
	v_lshrrev_b32_e32 v2, 16, v2
	v_add3_u32 v47, v86, v47, s54
	v_and_or_b32 v74, v47, s55, v2
	s_waitcnt lgkmcnt(1)
	v_bfe_u32 v2, v88, 16, 1
	v_add3_u32 v2, v88, v2, s54
	s_waitcnt lgkmcnt(0)
	v_bfe_u32 v45, v90, 16, 1
	v_lshrrev_b32_e32 v2, 16, v2
	v_add3_u32 v45, v90, v45, s54
	v_and_or_b32 v75, v45, s55, v2
	v_or_b32_e32 v2, s8, v69
	v_lshlrev_b32_e32 v2, 12, v2
	v_lshl_add_u64 v[92:93], v[56:57], 0, v[2:3]
	v_bfe_u32 v2, v77, 16, 1
	v_add3_u32 v2, v77, v2, s54
	v_bfe_u32 v45, v79, 16, 1
	v_lshrrev_b32_e32 v2, 16, v2
	v_add3_u32 v45, v79, v45, s54
	global_store_dwordx4 v[92:93], v[72:75], off
	s_nop 1
	v_and_or_b32 v72, v45, s55, v2
	v_bfe_u32 v2, v81, 16, 1
	v_add3_u32 v2, v81, v2, s54
	v_bfe_u32 v45, v83, 16, 1
	v_lshrrev_b32_e32 v2, 16, v2
	v_add3_u32 v45, v83, v45, s54
	v_and_or_b32 v73, v45, s55, v2
	v_bfe_u32 v2, v85, 16, 1
	v_add3_u32 v2, v85, v2, s54
	v_bfe_u32 v45, v87, 16, 1
	v_lshrrev_b32_e32 v2, 16, v2
	v_add3_u32 v45, v87, v45, s54
	v_and_or_b32 v74, v45, s55, v2
	v_bfe_u32 v2, v89, 16, 1
	v_add3_u32 v2, v89, v2, s54
	v_bfe_u32 v45, v91, 16, 1
	v_lshrrev_b32_e32 v2, 16, v2
	v_add3_u32 v45, v91, v45, s54
	v_and_or_b32 v75, v45, s55, v2
	v_or_b32_e32 v2, s8, v70
	v_lshlrev_b32_e32 v2, 12, v2
	v_lshl_add_u64 v[56:57], v[56:57], 0, v[2:3]
	global_store_dwordx4 v[56:57], v[72:75], off
	s_waitcnt lgkmcnt(0)

; DI void transpose_item(const float* W, int K, int N, bf16_t* WT, int mode, float* scr, int item, int lane) {
;     const int nblk = N / 64, kb = item / nblk, nb = item % nblk, k0 = 64 * kb, n0 = 64 * nb;
;     int drow0 = n0;
;     if (mode == 1) { const int seg = n0 >> 10; const int dst = seg < 2 ? seg : (seg == 2 ? 6 : seg - 1); drow0 = dst * 1024 + (n0 & 1023); }
;     ...
;     f32x4 v[16];
; #pragma unroll
;     for (int i = 0; i < 16; ++i) v[i] = __builtin_nontemporal_load((const f32x4*)(W + (size_t)(k0 + 4 * i + (lane >> 4)) * N + n0 + 4 * (lane & 15)));
; #pragma unroll
;     for (int i = 0; i < 16; ++i) { float* d = scr + (4 * i + (lane >> 4)) * 65 + 4 * (lane & 15); d[0] = v[i][0]; d[1] = v[i][1]; d[2] = v[i][2]; d[3] = v[i][3]; }
;     __builtin_amdgcn_s_waitcnt(0); __builtin_amdgcn_wave_barrier();
.LBB0_63:
	s_andn2_b64 vcc, exec, s[8:9]
	s_cbranch_vccnz .LBB0_8
	s_mul_hi_i32 s8, s81, 0x92492493
	s_add_i32 s8, s8, s81
	s_lshr_b32 s9, s8, 31
	s_ashr_i32 s8, s8, 6
	s_add_i32 s8, s8, s9
	s_mul_i32 s9, s8, 0xffffff90
	s_add_i32 s9, s81, s9
	s_mul_i32 s10, s8, 0xffffe400
	s_ashr_i32 s9, s9, 4
	s_add_i32 s10, s15, s10
	s_add_i32 s11, s9, -1
	s_cmp_lg_u32 s9, 2
	s_cselect_b32 s11, s11, 6
	s_cmp_lt_i32 s9, 2
	s_cselect_b32 s9, s9, s11
	s_lshl_b32 s8, s8, 6
	v_or_b32_e32 v2, s8, v59
	s_ashr_i32 s11, s10, 31
	v_lshl_add_u64 v[56:57], s[10:11], 2, v[18:19]
	v_or_b32_e32 v45, 4, v2
	v_mad_i64_i32 v[72:73], s[72:73], v45, s48, v[56:57]
	v_or_b32_e32 v45, 8, v2
	v_mad_i64_i32 v[76:77], s[72:73], v45, s48, v[56:57]
	v_or_b32_e32 v45, 12, v2
	global_load_dwordx4 v[72:75], v[72:73], off nt
	v_mad_i64_i32 v[84:85], s[72:73], v45, s48, v[56:57]
	v_or_b32_e32 v45, 16, v2
	global_load_dwordx4 v[84:87], v[84:85], off nt
	v_mad_i64_i32 v[88:89], s[72:73], v45, s48, v[56:57]
	global_load_dwordx4 v[76:79], v[76:77], off nt
	v_or_b32_e32 v45, 20, v2
	global_load_dwordx4 v[88:91], v[88:89], off nt
	v_mad_i64_i32 v[80:81], s[72:73], v2, s48, v[56:57]
	v_mad_i64_i32 v[92:93], s[72:73], v45, s48, v[56:57]
	global_load_dwordx4 v[80:83], v[80:81], off nt
	v_or_b32_e32 v45, 24, v2
	global_load_dwordx4 v[92:95], v[92:93], off nt
	v_mad_i64_i32 v[96:97], s[72:73], v45, s48, v[56:57]
	global_load_dwordx4 v[96:99], v[96:97], off nt
	v_or_b32_e32 v45, 28, v2
	v_mad_i64_i32 v[100:101], s[72:73], v45, s48, v[56:57]
	global_load_dwordx4 v[100:103], v[100:101], off nt
	v_or_b32_e32 v45, 32, v2
	v_mad_i64_i32 v[104:105], s[72:73], v45, s48, v[56:57]
	global_load_dwordx4 v[104:107], v[104:105], off nt
	v_or_b32_e32 v45, 36, v2
	v_mad_i64_i32 v[108:109], s[72:73], v45, s48, v[56:57]
	global_load_dwordx4 v[108:111], v[108:109], off nt
	v_or_b32_e32 v45, 40, v2
	v_mad_i64_i32 v[112:113], s[72:73], v45, s48, v[56:57]
	global_load_dwordx4 v[112:115], v[112:113], off nt
	v_or_b32_e32 v45, 44, v2
	v_mad_i64_i32 v[116:117], s[72:73], v45, s48, v[56:57]
	global_load_dwordx4 v[116:119], v[116:117], off nt
	v_or_b32_e32 v45, 48, v2
	v_mad_i64_i32 v[120:121], s[72:73], v45, s48, v[56:57]
	global_load_dwordx4 v[120:123], v[120:121], off nt
	v_or_b32_e32 v45, 52, v2
	v_mad_i64_i32 v[124:125], s[72:73], v45, s48, v[56:57]
	global_load_dwordx4 v[124:127], v[124:125], off nt
	v_or_b32_e32 v45, 56, v2
	v_mad_i64_i32 v[128:129], s[72:73], v45, s48, v[56:57]
	global_load_dwordx4 v[128:131], v[128:129], off nt
	v_or_b32_e32 v2, 60, v2
	v_mad_i64_i32 v[56:57], s[72:73], v2, s48, v[56:57]
	global_load_dwordx4 v[132:135], v[56:57], off nt
	v_add_u32_e32 v2, 0x410, v60
	v_add_u32_e32 v45, 0x418, v60
	v_add_u32_e32 v47, 0x820, v60
	v_add_u32_e32 v56, 0x828, v60
	v_add_u32_e32 v57, 0xc30, v60
	s_and_b32 s10, s10, 0x3c0
	s_lshl_b32 s9, s9, 10
	s_or_b32 s10, s9, s10
	s_ashr_i32 s9, s8, 31
	s_waitcnt vmcnt(15)
	ds_write2_b32 v2, v72, v73 offset1:1
	ds_write2_b32 v45, v74, v75 offset1:1
	s_waitcnt vmcnt(13)
	ds_write2_b32 v47, v76, v77 offset1:1
	ds_write2_b32 v56, v78, v79 offset1:1
	s_waitcnt vmcnt(11)
	ds_write2_b32 v60, v80, v81 offset1:1
	ds_write2_b32 v60, v82, v83 offset0:2 offset1:3
	ds_write2_b32 v57, v84, v85 offset1:1
	v_add_u32_e32 v2, 0xc38, v60
	ds_write2_b32 v2, v86, v87 offset1:1
	v_add_u32_e32 v2, 0x1040, v60
	ds_write2_b32 v2, v88, v89 offset1:1
	v_add_u32_e32 v2, 0x1048, v60
	ds_write2_b32 v2, v90, v91 offset1:1
	v_add_u32_e32 v2, 0x1450, v60
	s_waitcnt vmcnt(10)
	ds_write2_b32 v2, v92, v93 offset1:1
	v_add_u32_e32 v2, 0x1458, v60
	ds_write2_b32 v2, v94, v95 offset1:1
	v_add_u32_e32 v2, 0x1860, v60
	s_waitcnt vmcnt(9)
	ds_write2_b32 v2, v96, v97 offset1:1
	v_add_u32_e32 v2, 0x1868, v60
	ds_write2_b32 v2, v98, v99 offset1:1
	v_add_u32_e32 v2, 0x1c70, v60
	s_waitcnt vmcnt(8)
	ds_write2_b32 v2, v100, v101 offset1:1
	v_add_u32_e32 v2, 0x1c78, v60
	ds_write2_b32 v2, v102, v103 offset1:1
	v_add_u32_e32 v2, 0x2080, v60
	s_waitcnt vmcnt(7)
	ds_write2_b32 v2, v104, v105 offset1:1
	v_add_u32_e32 v2, 0x2088, v60
	ds_write2_b32 v2, v106, v107 offset1:1
	v_add_u32_e32 v2, 0x2490, v60
	s_waitcnt vmcnt(6)
	ds_write2_b32 v2, v108, v109 offset1:1
	v_add_u32_e32 v2, 0x2498, v60
	ds_write2_b32 v2, v110, v111 offset1:1
	v_add_u32_e32 v2, 0x28a0, v60
	s_waitcnt vmcnt(5)
	ds_write2_b32 v2, v112, v113 offset1:1
	v_add_u32_e32 v2, 0x28a8, v60
	ds_write2_b32 v2, v114, v115 offset1:1
	v_add_u32_e32 v2, 0x2cb0, v60
	s_waitcnt vmcnt(4)
	ds_write2_b32 v2, v116, v117 offset1:1
	v_add_u32_e32 v2, 0x2cb8, v60
	ds_write2_b32 v2, v118, v119 offset1:1
	v_add_u32_e32 v2, 0x30c0, v60
	s_waitcnt vmcnt(3)
	ds_write2_b32 v2, v120, v121 offset1:1
	v_add_u32_e32 v2, 0x30c8, v60
	ds_write2_b32 v2, v122, v123 offset1:1
	v_add_u32_e32 v2, 0x34d0, v60
	s_waitcnt vmcnt(2)
	ds_write2_b32 v2, v124, v125 offset1:1
	v_add_u32_e32 v2, 0x34d8, v60
	ds_write2_b32 v2, v126, v127 offset1:1
	v_add_u32_e32 v2, 0x38e0, v60
	s_waitcnt vmcnt(1)
	ds_write2_b32 v2, v128, v129 offset1:1
	v_add_u32_e32 v2, 0x38e8, v60
	ds_write2_b32 v2, v130, v131 offset1:1
	v_add_u32_e32 v2, 0x3cf0, v60
	s_waitcnt vmcnt(0)
	ds_write2_b32 v2, v132, v133 offset1:1
	v_add_u32_e32 v2, 0x3cf8, v60
	ds_write2_b32 v2, v134, v135 offset1:1
	s_waitcnt vmcnt(0) expcnt(0) lgkmcnt(0)
	ds_read2_b32 v[76:77], v62 offset1:8
	ds_read2_b32 v[78:79], v62 offset0:65 offset1:73
	ds_read2_b32 v[80:81], v62 offset0:130 offset1:138
	ds_read2_b32 v[82:83], v62 offset0:195 offset1:203
	v_or_b32_e32 v92, s10, v61
	s_waitcnt lgkmcnt(3)
	v_bfe_u32 v2, v76, 16, 1
	v_add3_u32 v2, v76, v2, s54
	s_waitcnt lgkmcnt(2)
; DI unsigned pk2w(float lo, float hi) { return f2bfw(lo) | (f2bfw(hi) << 16); }
; DI void transpose_item(const float* W, int K, int N, bf16_t* WT, int mode, float* scr, int item, int lane) {
;     ...
;     const int c = lane & 7;
; #pragma unroll
;     for (int j = 0; j < 8; ++j) { const int n = (lane >> 3) + 8 * j; const float* sp = scr + (8 * c) * 65 + n;
;         u32x4 o; o.x = pk2w(sp[0 * 65], sp[1 * 65]); o.y = pk2w(sp[2 * 65], sp[3 * 65]); o.z = pk2w(sp[4 * 65], sp[5 * 65]); o.w = pk2w(sp[6 * 65], sp[7 * 65]);
;         *(u32x4*)(WT + (size_t)(drow0 + n) * K + k0 + 8 * c) = o; }
;     __builtin_amdgcn_s_waitcnt(0); __builtin_amdgcn_wave_barrier();
	v_bfe_u32 v45, v78, 16, 1
	v_lshrrev_b32_e32 v2, 16, v2
	v_add3_u32 v45, v78, v45, s54
	v_and_or_b32 v72, v45, s55, v2
	v_add_u32_e32 v45, 0x400, v62
	ds_read2_b32 v[84:85], v45 offset0:4 offset1:12
	ds_read2_b32 v[86:87], v45 offset0:69 offset1:77
	s_waitcnt lgkmcnt(3)
	v_bfe_u32 v2, v80, 16, 1
	v_add3_u32 v2, v80, v2, s54
	s_waitcnt lgkmcnt(2)
	v_bfe_u32 v47, v82, 16, 1
	ds_read2_b32 v[88:89], v45 offset0:134 offset1:142
	v_lshrrev_b32_e32 v2, 16, v2
	v_add3_u32 v47, v82, v47, s54
	ds_read2_b32 v[90:91], v45 offset0:199 offset1:207
	v_and_or_b32 v73, v47, s55, v2
	s_waitcnt lgkmcnt(3)
	v_bfe_u32 v2, v84, 16, 1
	v_add3_u32 v2, v84, v2, s54
	s_waitcnt lgkmcnt(2)
	v_bfe_u32 v47, v86, 16, 1
	v_lshrrev_b32_e32 v2, 16, v2
	v_add3_u32 v47, v86, v47, s54
	v_and_or_b32 v74, v47, s55, v2
	s_waitcnt lgkmcnt(1)
	v_bfe_u32 v2, v88, 16, 1
	v_add3_u32 v2, v88, v2, s54
	s_waitcnt lgkmcnt(0)
	v_bfe_u32 v47, v90, 16, 1
	v_lshrrev_b32_e32 v2, 16, v2
	v_add3_u32 v47, v90, v47, s54
	v_and_or_b32 v75, v47, s55, v2
	v_ashrrev_i32_e32 v93, 31, v92
	v_bfe_u32 v2, v77, 16, 1
	v_lshl_add_u64 v[56:57], s[8:9], 1, v[42:43]
	v_lshlrev_b64 v[92:93], 12, v[92:93]
	v_add3_u32 v2, v77, v2, s54
	v_bfe_u32 v47, v79, 16, 1
	v_lshl_add_u64 v[92:93], v[56:57], 0, v[92:93]
	v_lshrrev_b32_e32 v2, 16, v2
	v_add3_u32 v47, v79, v47, s54
	global_store_dwordx4 v[92:93], v[72:75], off
	v_or_b32_e32 v76, s10, v63
	v_ashrrev_i32_e32 v77, 31, v76
	v_and_or_b32 v72, v47, s55, v2
	v_bfe_u32 v2, v81, 16, 1
	v_add3_u32 v2, v81, v2, s54
	v_bfe_u32 v47, v83, 16, 1
	v_lshrrev_b32_e32 v2, 16, v2
	v_add3_u32 v47, v83, v47, s54
	v_and_or_b32 v73, v47, s55, v2
	v_bfe_u32 v2, v85, 16, 1
	v_add3_u32 v2, v85, v2, s54
	v_bfe_u32 v47, v87, 16, 1
	v_lshrrev_b32_e32 v2, 16, v2
	v_add3_u32 v47, v87, v47, s54
	v_and_or_b32 v74, v47, s55, v2
	v_bfe_u32 v2, v89, 16, 1
	v_add3_u32 v2, v89, v2, s54
	v_bfe_u32 v47, v91, 16, 1
	v_lshrrev_b32_e32 v2, 16, v2
	v_add3_u32 v47, v91, v47, s54
	v_lshlrev_b64 v[76:77], 12, v[76:77]
	v_and_or_b32 v75, v47, s55, v2
	ds_read2_b32 v[78:79], v62 offset0:16 offset1:24
	v_lshl_add_u64 v[76:77], v[56:57], 0, v[76:77]
	global_store_dwordx4 v[76:77], v[72:75], off
	ds_read2_b32 v[76:77], v62 offset0:81 offset1:89
	ds_read2_b32 v[80:81], v62 offset0:146 offset1:154
	ds_read2_b32 v[82:83], v62 offset0:211 offset1:219
	s_waitcnt lgkmcnt(3)
	v_bfe_u32 v2, v78, 16, 1
	v_add3_u32 v2, v78, v2, s54
	s_waitcnt lgkmcnt(2)
	v_bfe_u32 v47, v76, 16, 1
	ds_read2_b32 v[84:85], v45 offset0:20 offset1:28
	v_lshrrev_b32_e32 v2, 16, v2
	v_add3_u32 v47, v76, v47, s54
	ds_read2_b32 v[86:87], v45 offset0:85 offset1:93
	v_and_or_b32 v72, v47, s55, v2
	s_waitcnt lgkmcnt(3)
	v_bfe_u32 v2, v80, 16, 1
	v_add3_u32 v2, v80, v2, s54
	s_waitcnt lgkmcnt(2)
	v_bfe_u32 v47, v82, 16, 1
	ds_read2_b32 v[88:89], v45 offset0:150 offset1:158
	v_lshrrev_b32_e32 v2, 16, v2
	v_add3_u32 v47, v82, v47, s54
	ds_read2_b32 v[90:91], v45 offset0:215 offset1:223
	v_and_or_b32 v73, v47, s55, v2
	s_waitcnt lgkmcnt(3)
	v_bfe_u32 v2, v84, 16, 1
	v_add3_u32 v2, v84, v2, s54
	s_waitcnt lgkmcnt(2)
	v_bfe_u32 v47, v86, 16, 1
	v_lshrrev_b32_e32 v2, 16, v2
	v_add3_u32 v47, v86, v47, s54
	v_and_or_b32 v74, v47, s55, v2
	s_waitcnt lgkmcnt(1)
	v_bfe_u32 v2, v88, 16, 1
	v_add3_u32 v2, v88, v2, s54
	s_waitcnt lgkmcnt(0)
	v_bfe_u32 v47, v90, 16, 1
	v_lshrrev_b32_e32 v2, 16, v2
	v_add3_u32 v47, v90, v47, s54
	v_or_b32_e32 v92, s10, v64
	v_and_or_b32 v75, v47, s55, v2
	v_ashrrev_i32_e32 v93, 31, v92
	v_bfe_u32 v2, v79, 16, 1
	v_lshlrev_b64 v[92:93], 12, v[92:93]
	v_add3_u32 v2, v79, v2, s54
	v_bfe_u32 v47, v77, 16, 1
	v_lshl_add_u64 v[92:93], v[56:57], 0, v[92:93]
	v_lshrrev_b32_e32 v2, 16, v2
	v_add3_u32 v47, v77, v47, s54
	global_store_dwordx4 v[92:93], v[72:75], off
	v_or_b32_e32 v76, s10, v65
	v_ashrrev_i32_e32 v77, 31, v76
	v_and_or_b32 v72, v47, s55, v2
	v_bfe_u32 v2, v81, 16, 1
	v_add3_u32 v2, v81, v2, s54
	v_bfe_u32 v47, v83, 16, 1
	v_lshrrev_b32_e32 v2, 16, v2
	v_add3_u32 v47, v83, v47, s54
	v_and_or_b32 v73, v47, s55, v2
	v_bfe_u32 v2, v85, 16, 1
	v_add3_u32 v2, v85, v2, s54
	v_bfe_u32 v47, v87, 16, 1
	v_lshrrev_b32_e32 v2, 16, v2
	v_add3_u32 v47, v87, v47, s54
	v_and_or_b32 v74, v47, s55, v2
	v_bfe_u32 v2, v89, 16, 1
	v_add3_u32 v2, v89, v2, s54
	v_bfe_u32 v47, v91, 16, 1
	v_lshrrev_b32_e32 v2, 16, v2
	v_add3_u32 v47, v91, v47, s54
	v_lshlrev_b64 v[76:77], 12, v[76:77]
	v_and_or_b32 v75, v47, s55, v2
	ds_read2_b32 v[78:79], v62 offset0:32 offset1:40
	v_lshl_add_u64 v[76:77], v[56:57], 0, v[76:77]
	global_store_dwordx4 v[76:77], v[72:75], off
	ds_read2_b32 v[76:77], v62 offset0:97 offset1:105
	ds_read2_b32 v[80:81], v62 offset0:162 offset1:170
	ds_read2_b32 v[82:83], v62 offset0:227 offset1:235
	s_waitcnt lgkmcnt(3)
; DI unsigned pk2w(float lo, float hi) { return f2bfw(lo) | (f2bfw(hi) << 16); }
; DI void transpose_item(const float* W, int K, int N, bf16_t* WT, int mode, float* scr, int item, int lane) {
;     ...
;     const int c = lane & 7;
; #pragma unroll
;     for (int j = 0; j < 8; ++j) { const int n = (lane >> 3) + 8 * j; const float* sp = scr + (8 * c) * 65 + n;
;         u32x4 o; o.x = pk2w(sp[0 * 65], sp[1 * 65]); o.y = pk2w(sp[2 * 65], sp[3 * 65]); o.z = pk2w(sp[4 * 65], sp[5 * 65]); o.w = pk2w(sp[6 * 65], sp[7 * 65]);
;         *(u32x4*)(WT + (size_t)(drow0 + n) * K + k0 + 8 * c) = o; }
;     __builtin_amdgcn_s_waitcnt(0); __builtin_amdgcn_wave_barrier();
	v_bfe_u32 v2, v78, 16, 1
	v_add3_u32 v2, v78, v2, s54
	s_waitcnt lgkmcnt(2)
	v_bfe_u32 v47, v76, 16, 1
	ds_read2_b32 v[84:85], v45 offset0:36 offset1:44
	v_lshrrev_b32_e32 v2, 16, v2
	v_add3_u32 v47, v76, v47, s54
	ds_read2_b32 v[86:87], v45 offset0:101 offset1:109
	v_and_or_b32 v72, v47, s55, v2
	s_waitcnt lgkmcnt(3)
	v_bfe_u32 v2, v80, 16, 1
	v_add3_u32 v2, v80, v2, s54
	s_waitcnt lgkmcnt(2)
	v_bfe_u32 v47, v82, 16, 1
	ds_read2_b32 v[88:89], v45 offset0:166 offset1:174
	v_lshrrev_b32_e32 v2, 16, v2
	v_add3_u32 v47, v82, v47, s54
	ds_read2_b32 v[90:91], v45 offset0:231 offset1:239
	v_and_or_b32 v73, v47, s55, v2
	s_waitcnt lgkmcnt(3)
	v_bfe_u32 v2, v84, 16, 1
	v_add3_u32 v2, v84, v2, s54
	s_waitcnt lgkmcnt(2)
	v_bfe_u32 v47, v86, 16, 1
	v_lshrrev_b32_e32 v2, 16, v2
	v_add3_u32 v47, v86, v47, s54
	v_and_or_b32 v74, v47, s55, v2
	s_waitcnt lgkmcnt(1)
	v_bfe_u32 v2, v88, 16, 1
	v_add3_u32 v2, v88, v2, s54
	s_waitcnt lgkmcnt(0)
	v_bfe_u32 v47, v90, 16, 1
	v_lshrrev_b32_e32 v2, 16, v2
	v_add3_u32 v47, v90, v47, s54
	v_or_b32_e32 v92, s10, v67
	v_and_or_b32 v75, v47, s55, v2
	v_ashrrev_i32_e32 v93, 31, v92
	v_bfe_u32 v2, v79, 16, 1
	v_lshlrev_b64 v[92:93], 12, v[92:93]
	v_add3_u32 v2, v79, v2, s54
	v_bfe_u32 v47, v77, 16, 1
	v_lshl_add_u64 v[92:93], v[56:57], 0, v[92:93]
	v_lshrrev_b32_e32 v2, 16, v2
	v_add3_u32 v47, v77, v47, s54
	global_store_dwordx4 v[92:93], v[72:75], off
	v_or_b32_e32 v76, s10, v68
	v_ashrrev_i32_e32 v77, 31, v76
	v_and_or_b32 v72, v47, s55, v2
	v_bfe_u32 v2, v81, 16, 1
	v_add3_u32 v2, v81, v2, s54
	v_bfe_u32 v47, v83, 16, 1
	v_lshrrev_b32_e32 v2, 16, v2
	v_add3_u32 v47, v83, v47, s54
	v_and_or_b32 v73, v47, s55, v2
	v_bfe_u32 v2, v85, 16, 1
	v_add3_u32 v2, v85, v2, s54
	v_bfe_u32 v47, v87, 16, 1
	v_lshrrev_b32_e32 v2, 16, v2
	v_add3_u32 v47, v87, v47, s54
	v_and_or_b32 v74, v47, s55, v2
	v_bfe_u32 v2, v89, 16, 1
	v_add3_u32 v2, v89, v2, s54
	v_bfe_u32 v47, v91, 16, 1
	v_lshrrev_b32_e32 v2, 16, v2
	v_add3_u32 v47, v91, v47, s54
	v_lshlrev_b64 v[76:77], 12, v[76:77]
	v_and_or_b32 v75, v47, s55, v2
	ds_read2_b32 v[78:79], v62 offset0:48 offset1:56
	v_lshl_add_u64 v[76:77], v[56:57], 0, v[76:77]
	global_store_dwordx4 v[76:77], v[72:75], off
	ds_read2_b32 v[76:77], v62 offset0:113 offset1:121
	ds_read2_b32 v[80:81], v62 offset0:178 offset1:186
	ds_read2_b32 v[82:83], v62 offset0:243 offset1:251
	s_waitcnt lgkmcnt(3)
	v_bfe_u32 v2, v78, 16, 1
	v_add3_u32 v2, v78, v2, s54
	s_waitcnt lgkmcnt(2)
	v_bfe_u32 v47, v76, 16, 1
	ds_read2_b32 v[84:85], v45 offset0:52 offset1:60
	v_lshrrev_b32_e32 v2, 16, v2
	v_add3_u32 v47, v76, v47, s54
	ds_read2_b32 v[86:87], v45 offset0:117 offset1:125
	v_and_or_b32 v72, v47, s55, v2
	s_waitcnt lgkmcnt(3)
	v_bfe_u32 v2, v80, 16, 1
	v_add3_u32 v2, v80, v2, s54
	s_waitcnt lgkmcnt(2)
	v_bfe_u32 v47, v82, 16, 1
	ds_read2_b32 v[88:89], v45 offset0:182 offset1:190
	v_lshrrev_b32_e32 v2, 16, v2
	v_add3_u32 v47, v82, v47, s54
	ds_read2_b32 v[90:91], v45 offset0:247 offset1:255
	v_and_or_b32 v73, v47, s55, v2
	s_waitcnt lgkmcnt(3)
	v_bfe_u32 v2, v84, 16, 1
	v_add3_u32 v2, v84, v2, s54
	s_waitcnt lgkmcnt(2)
	v_bfe_u32 v47, v86, 16, 1
	v_lshrrev_b32_e32 v2, 16, v2
	v_add3_u32 v47, v86, v47, s54
	v_and_or_b32 v74, v47, s55, v2
	s_waitcnt lgkmcnt(1)
	v_bfe_u32 v2, v88, 16, 1
	v_add3_u32 v2, v88, v2, s54
	s_waitcnt lgkmcnt(0)
	v_bfe_u32 v45, v90, 16, 1
	v_lshrrev_b32_e32 v2, 16, v2
	v_add3_u32 v45, v90, v45, s54
	v_or_b32_e32 v92, s10, v69
	v_and_or_b32 v75, v45, s55, v2
	v_ashrrev_i32_e32 v93, 31, v92
	v_bfe_u32 v2, v79, 16, 1
	v_lshlrev_b64 v[92:93], 12, v[92:93]
	v_add3_u32 v2, v79, v2, s54
	v_bfe_u32 v45, v77, 16, 1
	v_lshl_add_u64 v[92:93], v[56:57], 0, v[92:93]
	v_lshrrev_b32_e32 v2, 16, v2
	v_add3_u32 v45, v77, v45, s54
	global_store_dwordx4 v[92:93], v[72:75], off
	v_or_b32_e32 v76, s10, v70
	v_ashrrev_i32_e32 v77, 31, v76
	v_and_or_b32 v72, v45, s55, v2
	v_bfe_u32 v2, v81, 16, 1
	v_add3_u32 v2, v81, v2, s54
	v_bfe_u32 v45, v83, 16, 1
	v_lshrrev_b32_e32 v2, 16, v2
	v_add3_u32 v45, v83, v45, s54
	v_and_or_b32 v73, v45, s55, v2
	v_bfe_u32 v2, v85, 16, 1
	v_add3_u32 v2, v85, v2, s54
	v_bfe_u32 v45, v87, 16, 1
	v_lshrrev_b32_e32 v2, 16, v2
	v_add3_u32 v45, v87, v45, s54
	v_and_or_b32 v74, v45, s55, v2
	v_bfe_u32 v2, v89, 16, 1
	v_add3_u32 v2, v89, v2, s54
	v_bfe_u32 v45, v91, 16, 1
	v_lshrrev_b32_e32 v2, 16, v2
	v_add3_u32 v45, v91, v45, s54
	v_lshlrev_b64 v[76:77], 12, v[76:77]
	v_and_or_b32 v75, v45, s55, v2
	v_lshl_add_u64 v[56:57], v[56:57], 0, v[76:77]
	global_store_dwordx4 v[56:57], v[72:75], off
	s_waitcnt lgkmcnt(0)
	s_branch .LBB0_8

; DI void transpose_item(const float* W, int K, int N, bf16_t* WT, int mode, float* scr, int item, int lane) {
;     ...
;     f32x4 v[16];
; #pragma unroll
;     for (int i = 0; i < 16; ++i) v[i] = __builtin_nontemporal_load((const f32x4*)(W + (size_t)(k0 + 4 * i + (lane >> 4)) * N + n0 + 4 * (lane & 15)));
; #pragma unroll
;     for (int i = 0; i < 16; ++i) { float* d = scr + (4 * i + (lane >> 4)) * 65 + 4 * (lane & 15); d[0] = v[i][0]; d[1] = v[i][1]; d[2] = v[i][2]; d[3] = v[i][3]; }
;     __builtin_amdgcn_s_waitcnt(0); __builtin_amdgcn_wave_barrier();
; DI void convert_item(const Args& a, float* scr, int it, int lane) {
;     ...
;     { const int mtx = r / I_RG, blk = mtx >> 1, which = mtx & 1;
;       transpose_item((which ? a.in[16] : a.in[14]) + (size_t)blk * 65536, 256, 256, (bf16_t*)(ws + WS_WRG) + (size_t)blk * 512 * 256, 3 + which, scr, r % I_RG, lane); }
.LBB0_253:
	s_add_i32 s46, s13, 0x3600
	s_add_i32 s47, s13, 0x6d80
	s_cmpk_gt_i32 s46, 0xd67f
	s_mov_b64 s[8:9], -1
	s_cbranch_scc0 .LBB0_307
	s_cmpk_gt_u32 s47, 0x11ff
	s_cbranch_scc0 .LBB0_304
	s_cmpk_gt_u32 s47, 0x27ff
	s_cbranch_scc0 .LBB0_297
	s_cmpk_gt_u32 s47, 0x32ff
	s_cbranch_scc0 .LBB0_294
	s_cmpk_gt_u32 s47, 0x337f
	s_cbranch_scc0 .LBB0_291
	s_cmp_lt_u32 s46, 0xffffc880
	s_cbranch_scc0 .LBB0_288
	s_cmpk_gt_u32 s47, 0x427f
	s_cbranch_scc0 .LBB0_285
	s_cmpk_gt_u32 s47, 0x47ff
	s_cbranch_scc0 .LBB0_282
	s_cmpk_gt_u32 s47, 0x5dff
	s_cbranch_scc0 .LBB0_275
	s_cmpk_gt_u32 s47, 0x68ff
	s_cbranch_scc0 .LBB0_272
	s_cmpk_gt_u32 s47, 0x697f
	s_cbranch_scc0 .LBB0_269
	s_cmpk_gt_u32 s47, 0x6d7f
	s_cbranch_scc0 .LBB0_266
	s_lshr_b32 s6, s13, 5
	s_and_b32 s48, s46, 16
	v_readlane_b32 s8, v254, 4
	v_readlane_b32 s50, v254, 6
	s_cmp_eq_u32 s48, 0
	v_readlane_b32 s9, v254, 5
	v_readlane_b32 s51, v254, 7
	s_cselect_b32 s49, s9, s51
	s_cselect_b32 s50, s8, s50
	s_lshl_b64 s[8:9], s[6:7], 18
	s_add_u32 s50, s50, s8
	s_addc_u32 s49, s49, s9
	s_add_u32 s51, s11, s8
	s_addc_u32 s52, s12, s9
	s_lshl_b32 s8, s48, 3
	s_and_b32 s6, s14, 0x100
	s_add_i32 s8, s8, s10
	s_add_i32 s6, s8, s6
	s_and_b32 s48, s15, 0xc0
	s_add_u32 s8, s50, s17
	v_or_b32_e32 v2, s48, v58
	s_addc_u32 s9, s49, 0
	v_mov_b32_e32 v53, v3
	v_lshl_add_u64 v[56:57], s[8:9], 0, v[52:53]
	v_lshlrev_b32_e32 v2, 10, v2
	v_lshl_add_u64 v[56:57], v[56:57], 0, v[2:3]
	v_add_co_u32_e32 v78, vcc, s18, v56
	global_load_dwordx4 v[70:73], v[56:57], off nt
	s_nop 0
	v_addc_co_u32_e32 v79, vcc, 0, v57, vcc
	v_add_co_u32_e32 v86, vcc, s19, v56
	global_load_dwordx4 v[74:77], v[78:79], off offset:-4096 nt
	s_nop 0
	global_load_dwordx4 v[78:81], v[78:79], off nt
	v_addc_co_u32_e32 v87, vcc, 0, v57, vcc
	v_add_co_u32_e32 v94, vcc, s20, v56
	global_load_dwordx4 v[82:85], v[86:87], off offset:-4096 nt
	s_nop 0
	global_load_dwordx4 v[86:89], v[86:87], off nt
	v_addc_co_u32_e32 v95, vcc, 0, v57, vcc
	global_load_dwordx4 v[90:93], v[94:95], off offset:-4096 nt
	s_nop 0
	global_load_dwordx4 v[94:97], v[94:95], off nt
	v_add_co_u32_e32 v102, vcc, s22, v56
	v_add_u32_e32 v2, 0x410, v59
	s_nop 0
	v_addc_co_u32_e32 v103, vcc, 0, v57, vcc
	global_load_dwordx4 v[98:101], v[102:103], off offset:-4096 nt
	s_nop 0
	global_load_dwordx4 v[102:105], v[102:103], off nt
	v_add_co_u32_e32 v110, vcc, s23, v56
	v_add_u32_e32 v53, 0x418, v59
	s_nop 0
	v_addc_co_u32_e32 v111, vcc, 0, v57, vcc
	global_load_dwordx4 v[106:109], v[110:111], off offset:-4096 nt
	s_nop 0
	global_load_dwordx4 v[110:113], v[110:111], off nt
	v_add_co_u32_e32 v118, vcc, s24, v56
	v_add_u32_e32 v55, 0x820, v59
	s_nop 0
	v_addc_co_u32_e32 v119, vcc, 0, v57, vcc
	global_load_dwordx4 v[114:117], v[118:119], off offset:-4096 nt
	s_nop 0
	global_load_dwordx4 v[118:121], v[118:119], off nt
	v_add_co_u32_e32 v126, vcc, s25, v56
	v_add_u32_e32 v69, 0xc38, v59
	s_nop 0
	v_addc_co_u32_e32 v127, vcc, 0, v57, vcc
	global_load_dwordx4 v[122:125], v[126:127], off offset:-4096 nt
	s_nop 0
	global_load_dwordx4 v[126:129], v[126:127], off nt
	v_add_co_u32_e32 v56, vcc, s26, v56
	v_add_u32_e32 v134, 0x1040, v59
	s_nop 0
	v_addc_co_u32_e32 v57, vcc, 0, v57, vcc
	global_load_dwordx4 v[130:133], v[56:57], off nt
	v_add_u32_e32 v56, 0x828, v59
	v_add_u32_e32 v57, 0xc30, v59
	v_add_u32_e32 v135, 0x1048, v59
	v_add_u32_e32 v136, 0x1450, v59
	v_add_u32_e32 v137, 0x1458, v59
	v_add_u32_e32 v138, 0x1860, v59
	v_add_u32_e32 v139, 0x1868, v59
	s_lshl_b32 s8, s48, 1
	s_add_u32 s8, s51, s8
	s_addc_u32 s9, s52, 0
	s_waitcnt vmcnt(0)
	ds_write2_b32 v59, v70, v71 offset1:1
	ds_write2_b32 v59, v72, v73 offset0:2 offset1:3
	ds_write2_b32 v2, v74, v75 offset1:1
	ds_write2_b32 v53, v76, v77 offset1:1
	ds_write2_b32 v55, v78, v79 offset1:1
	ds_write2_b32 v56, v80, v81 offset1:1
	ds_write2_b32 v57, v82, v83 offset1:1
	ds_write2_b32 v69, v84, v85 offset1:1
	ds_write2_b32 v134, v86, v87 offset1:1
	ds_write2_b32 v135, v88, v89 offset1:1
	ds_write2_b32 v136, v90, v91 offset1:1
	ds_write2_b32 v137, v92, v93 offset1:1
	ds_write2_b32 v138, v94, v95 offset1:1
	ds_write2_b32 v139, v96, v97 offset1:1
	v_add_u32_e32 v2, 0x1c70, v59
	v_mov_b32_e32 v55, v3
	v_lshl_add_u64 v[56:57], s[8:9], 0, v[54:55]
	v_or_b32_e32 v90, s6, v60
	ds_write2_b32 v2, v98, v99 offset1:1
	v_add_u32_e32 v2, 0x1c78, v59
	ds_write2_b32 v2, v100, v101 offset1:1
	v_add_u32_e32 v2, 0x2080, v59
	ds_write2_b32 v2, v102, v103 offset1:1
	v_add_u32_e32 v2, 0x2088, v59
	ds_write2_b32 v2, v104, v105 offset1:1
	v_add_u32_e32 v2, 0x2490, v59
	ds_write2_b32 v2, v106, v107 offset1:1
	v_add_u32_e32 v2, 0x2498, v59
	ds_write2_b32 v2, v108, v109 offset1:1
	v_add_u32_e32 v2, 0x28a0, v59
	ds_write2_b32 v2, v110, v111 offset1:1
	v_add_u32_e32 v2, 0x28a8, v59
	ds_write2_b32 v2, v112, v113 offset1:1
	v_add_u32_e32 v2, 0x2cb0, v59
	ds_write2_b32 v2, v114, v115 offset1:1
	v_add_u32_e32 v2, 0x2cb8, v59
	ds_write2_b32 v2, v116, v117 offset1:1
	v_add_u32_e32 v2, 0x30c0, v59
	ds_write2_b32 v2, v118, v119 offset1:1
	v_add_u32_e32 v2, 0x30c8, v59
	ds_write2_b32 v2, v120, v121 offset1:1
	v_add_u32_e32 v2, 0x34d0, v59
	ds_write2_b32 v2, v122, v123 offset1:1
	v_add_u32_e32 v2, 0x34d8, v59
	ds_write2_b32 v2, v124, v125 offset1:1
	v_add_u32_e32 v2, 0x38e0, v59
	ds_write2_b32 v2, v126, v127 offset1:1
	v_add_u32_e32 v2, 0x38e8, v59
	ds_write2_b32 v2, v128, v129 offset1:1
	v_add_u32_e32 v2, 0x3cf0, v59
	ds_write2_b32 v2, v130, v131 offset1:1
	v_add_u32_e32 v2, 0x3cf8, v59
	ds_write2_b32 v2, v132, v133 offset1:1
	s_waitcnt vmcnt(0) expcnt(0) lgkmcnt(0)
; DI unsigned pk2w(float lo, float hi) { return f2bfw(lo) | (f2bfw(hi) << 16); }
; DI void transpose_item(const float* W, int K, int N, bf16_t* WT, int mode, float* scr, int item, int lane) {
;     ...
;     const int c = lane & 7;
; #pragma unroll
;     for (int j = 0; j < 8; ++j) { const int n = (lane >> 3) + 8 * j; const float* sp = scr + (8 * c) * 65 + n;
;         u32x4 o; o.x = pk2w(sp[0 * 65], sp[1 * 65]); o.y = pk2w(sp[2 * 65], sp[3 * 65]); o.z = pk2w(sp[4 * 65], sp[5 * 65]); o.w = pk2w(sp[6 * 65], sp[7 * 65]);
;         *(u32x4*)(WT + (size_t)(drow0 + n) * K + k0 + 8 * c) = o; }
;     __builtin_amdgcn_s_waitcnt(0); __builtin_amdgcn_wave_barrier();
	ds_read2_b32 v[74:75], v61 offset1:8
	ds_read2_b32 v[76:77], v61 offset0:65 offset1:73
	ds_read2_b32 v[78:79], v61 offset0:130 offset1:138
	ds_read2_b32 v[80:81], v61 offset0:195 offset1:203
	v_ashrrev_i32_e32 v91, 31, v90
	s_waitcnt lgkmcnt(3)
	v_bfe_u32 v2, v74, 16, 1
	v_add3_u32 v2, v74, v2, s27
	s_waitcnt lgkmcnt(2)
	v_bfe_u32 v53, v76, 16, 1
	v_lshrrev_b32_e32 v2, 16, v2
	v_add3_u32 v53, v76, v53, s27
	v_and_or_b32 v70, v53, s28, v2
	v_add_u32_e32 v53, 0x400, v61
	ds_read2_b32 v[82:83], v53 offset0:4 offset1:12
	ds_read2_b32 v[84:85], v53 offset0:69 offset1:77
	s_waitcnt lgkmcnt(3)
	v_bfe_u32 v2, v78, 16, 1
	v_add3_u32 v2, v78, v2, s27
	s_waitcnt lgkmcnt(2)
	v_bfe_u32 v55, v80, 16, 1
	ds_read2_b32 v[86:87], v53 offset0:134 offset1:142
	v_lshrrev_b32_e32 v2, 16, v2
	v_add3_u32 v55, v80, v55, s27
	ds_read2_b32 v[88:89], v53 offset0:199 offset1:207
	v_and_or_b32 v71, v55, s28, v2
	s_waitcnt lgkmcnt(3)
	v_bfe_u32 v2, v82, 16, 1
	v_add3_u32 v2, v82, v2, s27
	s_waitcnt lgkmcnt(2)
	v_bfe_u32 v55, v84, 16, 1
	v_lshrrev_b32_e32 v2, 16, v2
	v_add3_u32 v55, v84, v55, s27
	v_and_or_b32 v72, v55, s28, v2
	s_waitcnt lgkmcnt(1)
	v_bfe_u32 v2, v86, 16, 1
	v_add3_u32 v2, v86, v2, s27
	s_waitcnt lgkmcnt(0)
	v_bfe_u32 v55, v88, 16, 1
	v_lshrrev_b32_e32 v2, 16, v2
	v_add3_u32 v55, v88, v55, s27
	v_and_or_b32 v73, v55, s28, v2
	v_bfe_u32 v2, v75, 16, 1
	v_lshlrev_b64 v[90:91], 9, v[90:91]
	v_add3_u32 v2, v75, v2, s27
	v_bfe_u32 v55, v77, 16, 1
	v_lshl_add_u64 v[90:91], v[56:57], 0, v[90:91]
	v_lshrrev_b32_e32 v2, 16, v2
	v_add3_u32 v55, v77, v55, s27
	global_store_dwordx4 v[90:91], v[70:73], off
	v_or_b32_e32 v74, s6, v62
	v_ashrrev_i32_e32 v75, 31, v74
	v_and_or_b32 v70, v55, s28, v2
	v_bfe_u32 v2, v79, 16, 1
	v_add3_u32 v2, v79, v2, s27
	v_bfe_u32 v55, v81, 16, 1
	v_lshrrev_b32_e32 v2, 16, v2
	v_add3_u32 v55, v81, v55, s27
	v_and_or_b32 v71, v55, s28, v2
	v_bfe_u32 v2, v83, 16, 1
	v_add3_u32 v2, v83, v2, s27
	v_bfe_u32 v55, v85, 16, 1
	v_lshrrev_b32_e32 v2, 16, v2
	v_add3_u32 v55, v85, v55, s27
	v_and_or_b32 v72, v55, s28, v2
	v_bfe_u32 v2, v87, 16, 1
	v_add3_u32 v2, v87, v2, s27
	v_bfe_u32 v55, v89, 16, 1
	v_lshrrev_b32_e32 v2, 16, v2
	v_add3_u32 v55, v89, v55, s27
	v_lshlrev_b64 v[74:75], 9, v[74:75]
	v_and_or_b32 v73, v55, s28, v2
	ds_read2_b32 v[76:77], v61 offset0:16 offset1:24
	v_lshl_add_u64 v[74:75], v[56:57], 0, v[74:75]
	global_store_dwordx4 v[74:75], v[70:73], off
	ds_read2_b32 v[74:75], v61 offset0:81 offset1:89
	ds_read2_b32 v[78:79], v61 offset0:146 offset1:154
	ds_read2_b32 v[80:81], v61 offset0:211 offset1:219
	s_waitcnt lgkmcnt(3)
	v_bfe_u32 v2, v76, 16, 1
	v_add3_u32 v2, v76, v2, s27
	s_waitcnt lgkmcnt(2)
	v_bfe_u32 v55, v74, 16, 1
	ds_read2_b32 v[82:83], v53 offset0:20 offset1:28
	v_lshrrev_b32_e32 v2, 16, v2
	v_add3_u32 v55, v74, v55, s27
	ds_read2_b32 v[84:85], v53 offset0:85 offset1:93
	v_and_or_b32 v70, v55, s28, v2
	s_waitcnt lgkmcnt(3)
	v_bfe_u32 v2, v78, 16, 1
	v_add3_u32 v2, v78, v2, s27
	s_waitcnt lgkmcnt(2)
	v_bfe_u32 v55, v80, 16, 1
	ds_read2_b32 v[86:87], v53 offset0:150 offset1:158
	v_lshrrev_b32_e32 v2, 16, v2
	v_add3_u32 v55, v80, v55, s27
	ds_read2_b32 v[88:89], v53 offset0:215 offset1:223
	v_and_or_b32 v71, v55, s28, v2
	s_waitcnt lgkmcnt(3)
	v_bfe_u32 v2, v82, 16, 1
	v_add3_u32 v2, v82, v2, s27
	s_waitcnt lgkmcnt(2)
	v_bfe_u32 v55, v84, 16, 1
	v_lshrrev_b32_e32 v2, 16, v2
	v_add3_u32 v55, v84, v55, s27
	v_and_or_b32 v72, v55, s28, v2
	s_waitcnt lgkmcnt(1)
	v_bfe_u32 v2, v86, 16, 1
	v_add3_u32 v2, v86, v2, s27
	s_waitcnt lgkmcnt(0)
	v_bfe_u32 v55, v88, 16, 1
	v_lshrrev_b32_e32 v2, 16, v2
	v_add3_u32 v55, v88, v55, s27
	v_or_b32_e32 v90, s6, v63
	v_and_or_b32 v73, v55, s28, v2
	v_ashrrev_i32_e32 v91, 31, v90
	v_bfe_u32 v2, v77, 16, 1
	v_lshlrev_b64 v[90:91], 9, v[90:91]
	v_add3_u32 v2, v77, v2, s27
	v_bfe_u32 v55, v75, 16, 1
	v_lshl_add_u64 v[90:91], v[56:57], 0, v[90:91]
	v_lshrrev_b32_e32 v2, 16, v2
	v_add3_u32 v55, v75, v55, s27
	global_store_dwordx4 v[90:91], v[70:73], off
	v_or_b32_e32 v74, s6, v64
	v_ashrrev_i32_e32 v75, 31, v74
	v_and_or_b32 v70, v55, s28, v2
	v_bfe_u32 v2, v79, 16, 1
	v_add3_u32 v2, v79, v2, s27
	v_bfe_u32 v55, v81, 16, 1
	v_lshrrev_b32_e32 v2, 16, v2
	v_add3_u32 v55, v81, v55, s27
	v_and_or_b32 v71, v55, s28, v2
	v_bfe_u32 v2, v83, 16, 1
	v_add3_u32 v2, v83, v2, s27
	v_bfe_u32 v55, v85, 16, 1
	v_lshrrev_b32_e32 v2, 16, v2
	v_add3_u32 v55, v85, v55, s27
	v_and_or_b32 v72, v55, s28, v2
	v_bfe_u32 v2, v87, 16, 1
	v_add3_u32 v2, v87, v2, s27
	v_bfe_u32 v55, v89, 16, 1
	v_lshrrev_b32_e32 v2, 16, v2
	v_add3_u32 v55, v89, v55, s27
	v_lshlrev_b64 v[74:75], 9, v[74:75]
	v_and_or_b32 v73, v55, s28, v2
	ds_read2_b32 v[76:77], v61 offset0:32 offset1:40
	v_lshl_add_u64 v[74:75], v[56:57], 0, v[74:75]
	global_store_dwordx4 v[74:75], v[70:73], off
	ds_read2_b32 v[74:75], v61 offset0:97 offset1:105
	ds_read2_b32 v[78:79], v61 offset0:162 offset1:170
	ds_read2_b32 v[80:81], v61 offset0:227 offset1:235
	s_waitcnt lgkmcnt(3)
	v_bfe_u32 v2, v76, 16, 1
	v_add3_u32 v2, v76, v2, s27
	s_waitcnt lgkmcnt(2)
	v_bfe_u32 v55, v74, 16, 1
	ds_read2_b32 v[82:83], v53 offset0:36 offset1:44
	v_lshrrev_b32_e32 v2, 16, v2
	v_add3_u32 v55, v74, v55, s27
	ds_read2_b32 v[84:85], v53 offset0:101 offset1:109
	v_and_or_b32 v70, v55, s28, v2
	s_waitcnt lgkmcnt(3)
	v_bfe_u32 v2, v78, 16, 1
	v_add3_u32 v2, v78, v2, s27
	s_waitcnt lgkmcnt(2)
	v_bfe_u32 v55, v80, 16, 1
	ds_read2_b32 v[86:87], v53 offset0:166 offset1:174
	v_lshrrev_b32_e32 v2, 16, v2
	v_add3_u32 v55, v80, v55, s27
	ds_read2_b32 v[88:89], v53 offset0:231 offset1:239
	v_and_or_b32 v71, v55, s28, v2
	s_waitcnt lgkmcnt(3)
	v_bfe_u32 v2, v82, 16, 1
	v_add3_u32 v2, v82, v2, s27
	s_waitcnt lgkmcnt(2)
; DI unsigned pk2w(float lo, float hi) { return f2bfw(lo) | (f2bfw(hi) << 16); }
; DI void transpose_item(const float* W, int K, int N, bf16_t* WT, int mode, float* scr, int item, int lane) {
;     ...
;     f32x4 v[16];
; #pragma unroll
;     for (int i = 0; i < 16; ++i) v[i] = __builtin_nontemporal_load((const f32x4*)(W + (size_t)(k0 + 4 * i + (lane >> 4)) * N + n0 + 4 * (lane & 15)));
; #pragma unroll
;     for (int i = 0; i < 16; ++i) { float* d = scr + (4 * i + (lane >> 4)) * 65 + 4 * (lane & 15); d[0] = v[i][0]; d[1] = v[i][1]; d[2] = v[i][2]; d[3] = v[i][3]; }
;     __builtin_amdgcn_s_waitcnt(0); __builtin_amdgcn_wave_barrier();
;     const int c = lane & 7;
; #pragma unroll
;     for (int j = 0; j < 8; ++j) { const int n = (lane >> 3) + 8 * j; const float* sp = scr + (8 * c) * 65 + n;
;         u32x4 o; o.x = pk2w(sp[0 * 65], sp[1 * 65]); o.y = pk2w(sp[2 * 65], sp[3 * 65]); o.z = pk2w(sp[4 * 65], sp[5 * 65]); o.w = pk2w(sp[6 * 65], sp[7 * 65]);
;         *(u32x4*)(WT + (size_t)(drow0 + n) * K + k0 + 8 * c) = o; }
;     __builtin_amdgcn_s_waitcnt(0); __builtin_amdgcn_wave_barrier();
	v_bfe_u32 v55, v84, 16, 1
	v_lshrrev_b32_e32 v2, 16, v2
	v_add3_u32 v55, v84, v55, s27
	v_and_or_b32 v72, v55, s28, v2
	s_waitcnt lgkmcnt(1)
	v_bfe_u32 v2, v86, 16, 1
	v_add3_u32 v2, v86, v2, s27
	s_waitcnt lgkmcnt(0)
	v_bfe_u32 v55, v88, 16, 1
	v_lshrrev_b32_e32 v2, 16, v2
	v_add3_u32 v55, v88, v55, s27
	v_or_b32_e32 v90, s6, v65
	v_and_or_b32 v73, v55, s28, v2
	v_ashrrev_i32_e32 v91, 31, v90
	v_bfe_u32 v2, v77, 16, 1
	v_lshlrev_b64 v[90:91], 9, v[90:91]
	v_add3_u32 v2, v77, v2, s27
	v_bfe_u32 v55, v75, 16, 1
	v_lshl_add_u64 v[90:91], v[56:57], 0, v[90:91]
	v_lshrrev_b32_e32 v2, 16, v2
	v_add3_u32 v55, v75, v55, s27
	global_store_dwordx4 v[90:91], v[70:73], off
	v_or_b32_e32 v74, s6, v66
	v_ashrrev_i32_e32 v75, 31, v74
	v_and_or_b32 v70, v55, s28, v2
	v_bfe_u32 v2, v79, 16, 1
	v_add3_u32 v2, v79, v2, s27
	v_bfe_u32 v55, v81, 16, 1
	v_lshrrev_b32_e32 v2, 16, v2
	v_add3_u32 v55, v81, v55, s27
	v_and_or_b32 v71, v55, s28, v2
	v_bfe_u32 v2, v83, 16, 1
	v_add3_u32 v2, v83, v2, s27
	v_bfe_u32 v55, v85, 16, 1
	v_lshrrev_b32_e32 v2, 16, v2
	v_add3_u32 v55, v85, v55, s27
	v_and_or_b32 v72, v55, s28, v2
	v_bfe_u32 v2, v87, 16, 1
	v_add3_u32 v2, v87, v2, s27
	v_bfe_u32 v55, v89, 16, 1
	v_lshrrev_b32_e32 v2, 16, v2
	v_add3_u32 v55, v89, v55, s27
	v_lshlrev_b64 v[74:75], 9, v[74:75]
	v_and_or_b32 v73, v55, s28, v2
	ds_read2_b32 v[76:77], v61 offset0:48 offset1:56
	v_lshl_add_u64 v[74:75], v[56:57], 0, v[74:75]
	global_store_dwordx4 v[74:75], v[70:73], off
	ds_read2_b32 v[74:75], v61 offset0:113 offset1:121
	ds_read2_b32 v[78:79], v61 offset0:178 offset1:186
	ds_read2_b32 v[80:81], v61 offset0:243 offset1:251
	s_waitcnt lgkmcnt(3)
	v_bfe_u32 v2, v76, 16, 1
	v_add3_u32 v2, v76, v2, s27
	s_waitcnt lgkmcnt(2)
	v_bfe_u32 v55, v74, 16, 1
	ds_read2_b32 v[82:83], v53 offset0:52 offset1:60
	v_lshrrev_b32_e32 v2, 16, v2
	v_add3_u32 v55, v74, v55, s27
	ds_read2_b32 v[84:85], v53 offset0:117 offset1:125
	v_and_or_b32 v70, v55, s28, v2
	s_waitcnt lgkmcnt(3)
	v_bfe_u32 v2, v78, 16, 1
	v_add3_u32 v2, v78, v2, s27
	s_waitcnt lgkmcnt(2)
	v_bfe_u32 v55, v80, 16, 1
	ds_read2_b32 v[86:87], v53 offset0:182 offset1:190
	v_lshrrev_b32_e32 v2, 16, v2
	v_add3_u32 v55, v80, v55, s27
	ds_read2_b32 v[88:89], v53 offset0:247 offset1:255
	v_and_or_b32 v71, v55, s28, v2
	s_waitcnt lgkmcnt(3)
	v_bfe_u32 v2, v82, 16, 1
	v_add3_u32 v2, v82, v2, s27
	s_waitcnt lgkmcnt(2)
	v_bfe_u32 v55, v84, 16, 1
	v_lshrrev_b32_e32 v2, 16, v2
	v_add3_u32 v55, v84, v55, s27
	v_and_or_b32 v72, v55, s28, v2
	s_waitcnt lgkmcnt(1)
	v_bfe_u32 v2, v86, 16, 1
	v_add3_u32 v2, v86, v2, s27
	s_waitcnt lgkmcnt(0)
	v_bfe_u32 v53, v88, 16, 1
	v_lshrrev_b32_e32 v2, 16, v2
	v_add3_u32 v53, v88, v53, s27
	v_or_b32_e32 v90, s6, v67
	v_and_or_b32 v73, v53, s28, v2
	v_ashrrev_i32_e32 v91, 31, v90
	v_bfe_u32 v2, v77, 16, 1
	v_lshlrev_b64 v[90:91], 9, v[90:91]
	v_add3_u32 v2, v77, v2, s27
	v_bfe_u32 v53, v75, 16, 1
	v_lshl_add_u64 v[90:91], v[56:57], 0, v[90:91]
	v_lshrrev_b32_e32 v2, 16, v2
	v_add3_u32 v53, v75, v53, s27
	global_store_dwordx4 v[90:91], v[70:73], off
	v_or_b32_e32 v74, s6, v68
	v_ashrrev_i32_e32 v75, 31, v74
	v_and_or_b32 v70, v53, s28, v2
	v_bfe_u32 v2, v79, 16, 1
	v_add3_u32 v2, v79, v2, s27
	v_bfe_u32 v53, v81, 16, 1
	v_lshrrev_b32_e32 v2, 16, v2
	v_add3_u32 v53, v81, v53, s27
	v_and_or_b32 v71, v53, s28, v2
	v_bfe_u32 v2, v83, 16, 1
	v_add3_u32 v2, v83, v2, s27
	v_bfe_u32 v53, v85, 16, 1
	v_lshrrev_b32_e32 v2, 16, v2
	v_add3_u32 v53, v85, v53, s27
	v_and_or_b32 v72, v53, s28, v2
	v_bfe_u32 v2, v87, 16, 1
	v_add3_u32 v2, v87, v2, s27
	v_bfe_u32 v53, v89, 16, 1
	v_lshrrev_b32_e32 v2, 16, v2
	v_add3_u32 v53, v89, v53, s27
	v_lshlrev_b64 v[74:75], 9, v[74:75]
	v_and_or_b32 v73, v53, s28, v2
	v_lshl_add_u64 v[56:57], v[56:57], 0, v[74:75]
	global_store_dwordx4 v[56:57], v[70:73], off
	s_waitcnt lgkmcnt(0)
	s_mov_b64 s[8:9], 0
.LBB0_266:
	s_andn2_b64 vcc, exec, s[8:9]
	s_cbranch_vccnz .LBB0_268
	s_and_b32 s8, s16, 0x7c0
	s_and_b32 s9, s3, 0x1ffc0
	v_or_b32_e32 v2, s9, v58
	s_lshl_b32 s6, s8, 2
	v_lshl_add_u64 v[56:57], v[20:21], 0, s[6:7]
	v_lshlrev_b32_e32 v2, 13, v2
	v_lshl_add_u64 v[56:57], v[56:57], 0, v[2:3]
	v_add_co_u32_e32 v74, vcc, 0x8000, v56
	v_add_u32_e32 v2, 0x410, v59
	s_nop 0
	v_addc_co_u32_e32 v75, vcc, 0, v57, vcc
	v_add_co_u32_e32 v78, vcc, 0x10000, v56
	global_load_dwordx4 v[70:73], v[56:57], off nt
	s_nop 0
	global_load_dwordx4 v[74:77], v[74:75], off nt
	v_addc_co_u32_e32 v79, vcc, 0, v57, vcc
	v_add_co_u32_e32 v82, vcc, 0x18000, v56
	s_lshl_b32 s6, s9, 1
	s_nop 0
	v_addc_co_u32_e32 v83, vcc, 0, v57, vcc
	global_load_dwordx4 v[78:81], v[78:79], off nt
	s_nop 0
	global_load_dwordx4 v[82:85], v[82:83], off nt
	v_add_co_u32_e32 v86, vcc, 0x20000, v56
	s_nop 1
	v_addc_co_u32_e32 v87, vcc, 0, v57, vcc
	v_add_co_u32_e32 v90, vcc, 0x28000, v56
	s_nop 1
	v_addc_co_u32_e32 v91, vcc, 0, v57, vcc
	global_load_dwordx4 v[86:89], v[86:87], off nt
	s_nop 0
	global_load_dwordx4 v[90:93], v[90:91], off nt
	v_add_co_u32_e32 v94, vcc, 0x30000, v56
	s_nop 1
	v_addc_co_u32_e32 v95, vcc, 0, v57, vcc
	v_add_co_u32_e32 v98, vcc, 0x38000, v56
	s_nop 1
	v_addc_co_u32_e32 v99, vcc, 0, v57, vcc
	global_load_dwordx4 v[94:97], v[94:95], off nt
	s_nop 0
	global_load_dwordx4 v[98:101], v[98:99], off nt
	v_add_co_u32_e32 v102, vcc, 0x40000, v56
	s_nop 1
	v_addc_co_u32_e32 v103, vcc, 0, v57, vcc
	v_add_co_u32_e32 v106, vcc, 0x48000, v56
	s_nop 1
	v_addc_co_u32_e32 v107, vcc, 0, v57, vcc
	global_load_dwordx4 v[102:105], v[102:103], off nt
	s_nop 0
	global_load_dwordx4 v[106:109], v[106:107], off nt
	v_add_co_u32_e32 v110, vcc, 0x50000, v56
	s_nop 1
	v_addc_co_u32_e32 v111, vcc, 0, v57, vcc
	v_add_co_u32_e32 v114, vcc, 0x58000, v56
	s_nop 1
	v_addc_co_u32_e32 v115, vcc, 0, v57, vcc
	global_load_dwordx4 v[110:113], v[110:111], off nt
	s_nop 0
	global_load_dwordx4 v[114:117], v[114:115], off nt
	v_add_co_u32_e32 v118, vcc, 0x60000, v56
	s_nop 1
	v_addc_co_u32_e32 v119, vcc, 0, v57, vcc
	v_add_co_u32_e32 v122, vcc, 0x68000, v56
	s_nop 1
	v_addc_co_u32_e32 v123, vcc, 0, v57, vcc
	global_load_dwordx4 v[118:121], v[118:119], off nt
	s_nop 0
	global_load_dwordx4 v[122:125], v[122:123], off nt
	v_add_co_u32_e32 v126, vcc, 0x70000, v56
	s_nop 1
	v_addc_co_u32_e32 v127, vcc, 0, v57, vcc
	global_load_dwordx4 v[126:129], v[126:127], off nt
	v_add_co_u32_e32 v56, vcc, 0x78000, v56
	s_nop 1
	v_addc_co_u32_e32 v57, vcc, 0, v57, vcc
	global_load_dwordx4 v[130:133], v[56:57], off nt
	s_waitcnt vmcnt(0)
; DI unsigned pk2w(float lo, float hi) { return f2bfw(lo) | (f2bfw(hi) << 16); }
; DI void transpose_item(const float* W, int K, int N, bf16_t* WT, int mode, float* scr, int item, int lane) {
;     ...
;     for (int i = 0; i < 16; ++i) { float* d = scr + (4 * i + (lane >> 4)) * 65 + 4 * (lane & 15); d[0] = v[i][0]; d[1] = v[i][1]; d[2] = v[i][2]; d[3] = v[i][3]; }
;     __builtin_amdgcn_s_waitcnt(0); __builtin_amdgcn_wave_barrier();
;     const int c = lane & 7;
; #pragma unroll
;     for (int j = 0; j < 8; ++j) { const int n = (lane >> 3) + 8 * j; const float* sp = scr + (8 * c) * 65 + n;
;         u32x4 o; o.x = pk2w(sp[0 * 65], sp[1 * 65]); o.y = pk2w(sp[2 * 65], sp[3 * 65]); o.z = pk2w(sp[4 * 65], sp[5 * 65]); o.w = pk2w(sp[6 * 65], sp[7 * 65]);
;         *(u32x4*)(WT + (size_t)(drow0 + n) * K + k0 + 8 * c) = o; }
;     __builtin_amdgcn_s_waitcnt(0); __builtin_amdgcn_wave_barrier();
	ds_write2_b32 v59, v70, v71 offset1:1
	ds_write2_b32 v59, v72, v73 offset0:2 offset1:3
	ds_write2_b32 v2, v74, v75 offset1:1
	v_add_u32_e32 v2, 0x418, v59
	ds_write2_b32 v2, v76, v77 offset1:1
	v_add_u32_e32 v2, 0x820, v59
	v_lshl_add_u64 v[56:57], v[22:23], 0, s[6:7]
	ds_write2_b32 v2, v78, v79 offset1:1
	v_add_u32_e32 v2, 0x828, v59
	ds_write2_b32 v2, v80, v81 offset1:1
	v_add_u32_e32 v2, 0xc30, v59
	ds_write2_b32 v2, v82, v83 offset1:1
	v_add_u32_e32 v2, 0xc38, v59
	ds_write2_b32 v2, v84, v85 offset1:1
	v_add_u32_e32 v2, 0x1040, v59
	ds_write2_b32 v2, v86, v87 offset1:1
	v_add_u32_e32 v2, 0x1048, v59
	ds_write2_b32 v2, v88, v89 offset1:1
	v_add_u32_e32 v2, 0x1450, v59
	ds_write2_b32 v2, v90, v91 offset1:1
	v_add_u32_e32 v2, 0x1458, v59
	ds_write2_b32 v2, v92, v93 offset1:1
	v_add_u32_e32 v2, 0x1860, v59
	ds_write2_b32 v2, v94, v95 offset1:1
	v_add_u32_e32 v2, 0x1868, v59
	ds_write2_b32 v2, v96, v97 offset1:1
	v_add_u32_e32 v2, 0x1c70, v59
	ds_write2_b32 v2, v98, v99 offset1:1
	v_add_u32_e32 v2, 0x1c78, v59
	ds_write2_b32 v2, v100, v101 offset1:1
	v_add_u32_e32 v2, 0x2080, v59
	ds_write2_b32 v2, v102, v103 offset1:1
	v_add_u32_e32 v2, 0x2088, v59
	ds_write2_b32 v2, v104, v105 offset1:1
	v_add_u32_e32 v2, 0x2490, v59
	ds_write2_b32 v2, v106, v107 offset1:1
	v_add_u32_e32 v2, 0x2498, v59
	ds_write2_b32 v2, v108, v109 offset1:1
	v_add_u32_e32 v2, 0x28a0, v59
	ds_write2_b32 v2, v110, v111 offset1:1
	v_add_u32_e32 v2, 0x28a8, v59
	ds_write2_b32 v2, v112, v113 offset1:1
	v_add_u32_e32 v2, 0x2cb0, v59
	ds_write2_b32 v2, v114, v115 offset1:1
	v_add_u32_e32 v2, 0x2cb8, v59
	ds_write2_b32 v2, v116, v117 offset1:1
	v_add_u32_e32 v2, 0x30c0, v59
	ds_write2_b32 v2, v118, v119 offset1:1
	v_add_u32_e32 v2, 0x30c8, v59
	ds_write2_b32 v2, v120, v121 offset1:1
	v_add_u32_e32 v2, 0x34d0, v59
	ds_write2_b32 v2, v122, v123 offset1:1
	v_add_u32_e32 v2, 0x34d8, v59
	ds_write2_b32 v2, v124, v125 offset1:1
	v_add_u32_e32 v2, 0x38e0, v59
	ds_write2_b32 v2, v126, v127 offset1:1
	v_add_u32_e32 v2, 0x38e8, v59
	ds_write2_b32 v2, v128, v129 offset1:1
	v_add_u32_e32 v2, 0x3cf0, v59
	ds_write2_b32 v2, v130, v131 offset1:1
	v_add_u32_e32 v2, 0x3cf8, v59
	ds_write2_b32 v2, v132, v133 offset1:1
	s_waitcnt vmcnt(0) expcnt(0) lgkmcnt(0)
	ds_read2_b32 v[74:75], v61 offset1:8
	ds_read2_b32 v[76:77], v61 offset0:65 offset1:73
	ds_read2_b32 v[78:79], v61 offset0:130 offset1:138
	ds_read2_b32 v[80:81], v61 offset0:195 offset1:203
	s_waitcnt lgkmcnt(3)
	v_bfe_u32 v2, v74, 16, 1
	v_add3_u32 v2, v74, v2, s27
	s_waitcnt lgkmcnt(2)
	v_bfe_u32 v53, v76, 16, 1
	v_lshrrev_b32_e32 v2, 16, v2
	v_add3_u32 v53, v76, v53, s27
	v_and_or_b32 v70, v53, s28, v2
	v_add_u32_e32 v53, 0x400, v61
	ds_read2_b32 v[82:83], v53 offset0:4 offset1:12
	ds_read2_b32 v[84:85], v53 offset0:69 offset1:77
	s_waitcnt lgkmcnt(3)
	v_bfe_u32 v2, v78, 16, 1
	v_add3_u32 v2, v78, v2, s27
	s_waitcnt lgkmcnt(2)
	v_bfe_u32 v55, v80, 16, 1
	ds_read2_b32 v[86:87], v53 offset0:134 offset1:142
	v_lshrrev_b32_e32 v2, 16, v2
	v_add3_u32 v55, v80, v55, s27
	ds_read2_b32 v[88:89], v53 offset0:199 offset1:207
	v_and_or_b32 v71, v55, s28, v2
	s_waitcnt lgkmcnt(3)
	v_bfe_u32 v2, v82, 16, 1
	v_add3_u32 v2, v82, v2, s27
	s_waitcnt lgkmcnt(2)
	v_bfe_u32 v55, v84, 16, 1
	v_lshrrev_b32_e32 v2, 16, v2
	v_add3_u32 v55, v84, v55, s27
	v_and_or_b32 v72, v55, s28, v2
	s_waitcnt lgkmcnt(1)
	v_bfe_u32 v2, v86, 16, 1
	v_add3_u32 v2, v86, v2, s27
	s_waitcnt lgkmcnt(0)
	v_bfe_u32 v55, v88, 16, 1
	v_lshrrev_b32_e32 v2, 16, v2
	v_add3_u32 v55, v88, v55, s27
	v_and_or_b32 v73, v55, s28, v2
	v_or_b32_e32 v2, s8, v60
	v_lshlrev_b32_e32 v2, 12, v2
	v_lshl_add_u64 v[90:91], v[56:57], 0, v[2:3]
	v_bfe_u32 v2, v75, 16, 1
	v_add3_u32 v2, v75, v2, s27
	v_bfe_u32 v55, v77, 16, 1
	v_lshrrev_b32_e32 v2, 16, v2
	v_add3_u32 v55, v77, v55, s27
	global_store_dwordx4 v[90:91], v[70:73], off
	ds_read2_b32 v[74:75], v61 offset0:16 offset1:24
	s_nop 0
	v_and_or_b32 v70, v55, s28, v2
	v_bfe_u32 v2, v79, 16, 1
	v_add3_u32 v2, v79, v2, s27
	v_bfe_u32 v55, v81, 16, 1
	v_lshrrev_b32_e32 v2, 16, v2
	v_add3_u32 v55, v81, v55, s27
	v_and_or_b32 v71, v55, s28, v2
	v_bfe_u32 v2, v83, 16, 1
	v_add3_u32 v2, v83, v2, s27
	v_bfe_u32 v55, v85, 16, 1
	v_lshrrev_b32_e32 v2, 16, v2
	v_add3_u32 v55, v85, v55, s27
	v_and_or_b32 v72, v55, s28, v2
	v_bfe_u32 v2, v87, 16, 1
	v_add3_u32 v2, v87, v2, s27
	v_bfe_u32 v55, v89, 16, 1
	v_lshrrev_b32_e32 v2, 16, v2
	v_add3_u32 v55, v89, v55, s27
	v_and_or_b32 v73, v55, s28, v2
	v_or_b32_e32 v2, s8, v62
	v_lshlrev_b32_e32 v2, 12, v2
	v_lshl_add_u64 v[76:77], v[56:57], 0, v[2:3]
	global_store_dwordx4 v[76:77], v[70:73], off
	ds_read2_b32 v[76:77], v61 offset0:81 offset1:89
	ds_read2_b32 v[78:79], v61 offset0:146 offset1:154
	ds_read2_b32 v[80:81], v61 offset0:211 offset1:219
	s_waitcnt lgkmcnt(3)
	v_bfe_u32 v2, v74, 16, 1
	v_add3_u32 v2, v74, v2, s27
	s_waitcnt lgkmcnt(2)
	v_bfe_u32 v55, v76, 16, 1
	ds_read2_b32 v[82:83], v53 offset0:20 offset1:28
	v_lshrrev_b32_e32 v2, 16, v2
	v_add3_u32 v55, v76, v55, s27
	ds_read2_b32 v[84:85], v53 offset0:85 offset1:93
	v_and_or_b32 v70, v55, s28, v2
	s_waitcnt lgkmcnt(3)
	v_bfe_u32 v2, v78, 16, 1
	v_add3_u32 v2, v78, v2, s27
	s_waitcnt lgkmcnt(2)
	v_bfe_u32 v55, v80, 16, 1
	ds_read2_b32 v[86:87], v53 offset0:150 offset1:158
	v_lshrrev_b32_e32 v2, 16, v2
	v_add3_u32 v55, v80, v55, s27
	ds_read2_b32 v[88:89], v53 offset0:215 offset1:223
	v_and_or_b32 v71, v55, s28, v2
	s_waitcnt lgkmcnt(3)
	v_bfe_u32 v2, v82, 16, 1
	v_add3_u32 v2, v82, v2, s27
	s_waitcnt lgkmcnt(2)
	v_bfe_u32 v55, v84, 16, 1
	v_lshrrev_b32_e32 v2, 16, v2
	v_add3_u32 v55, v84, v55, s27
	v_and_or_b32 v72, v55, s28, v2
	s_waitcnt lgkmcnt(1)
; DI unsigned pk2w(float lo, float hi) { return f2bfw(lo) | (f2bfw(hi) << 16); }
; DI void transpose_item(const float* W, int K, int N, bf16_t* WT, int mode, float* scr, int item, int lane) {
;     ...
;     const int c = lane & 7;
; #pragma unroll
;     for (int j = 0; j < 8; ++j) { const int n = (lane >> 3) + 8 * j; const float* sp = scr + (8 * c) * 65 + n;
;         u32x4 o; o.x = pk2w(sp[0 * 65], sp[1 * 65]); o.y = pk2w(sp[2 * 65], sp[3 * 65]); o.z = pk2w(sp[4 * 65], sp[5 * 65]); o.w = pk2w(sp[6 * 65], sp[7 * 65]);
;         *(u32x4*)(WT + (size_t)(drow0 + n) * K + k0 + 8 * c) = o; }
;     __builtin_amdgcn_s_waitcnt(0); __builtin_amdgcn_wave_barrier();
	v_bfe_u32 v2, v86, 16, 1
	v_add3_u32 v2, v86, v2, s27
	s_waitcnt lgkmcnt(0)
	v_bfe_u32 v55, v88, 16, 1
	v_lshrrev_b32_e32 v2, 16, v2
	v_add3_u32 v55, v88, v55, s27
	v_and_or_b32 v73, v55, s28, v2
	v_or_b32_e32 v2, s8, v63
	v_lshlrev_b32_e32 v2, 12, v2
	v_lshl_add_u64 v[90:91], v[56:57], 0, v[2:3]
	v_bfe_u32 v2, v75, 16, 1
	v_add3_u32 v2, v75, v2, s27
	v_bfe_u32 v55, v77, 16, 1
	v_lshrrev_b32_e32 v2, 16, v2
	v_add3_u32 v55, v77, v55, s27
	global_store_dwordx4 v[90:91], v[70:73], off
	ds_read2_b32 v[74:75], v61 offset0:32 offset1:40
	s_nop 0
	v_and_or_b32 v70, v55, s28, v2
	v_bfe_u32 v2, v79, 16, 1
	v_add3_u32 v2, v79, v2, s27
	v_bfe_u32 v55, v81, 16, 1
	v_lshrrev_b32_e32 v2, 16, v2
	v_add3_u32 v55, v81, v55, s27
	v_and_or_b32 v71, v55, s28, v2
	v_bfe_u32 v2, v83, 16, 1
	v_add3_u32 v2, v83, v2, s27
	v_bfe_u32 v55, v85, 16, 1
	v_lshrrev_b32_e32 v2, 16, v2
	v_add3_u32 v55, v85, v55, s27
	v_and_or_b32 v72, v55, s28, v2
	v_bfe_u32 v2, v87, 16, 1
	v_add3_u32 v2, v87, v2, s27
	v_bfe_u32 v55, v89, 16, 1
	v_lshrrev_b32_e32 v2, 16, v2
	v_add3_u32 v55, v89, v55, s27
	v_and_or_b32 v73, v55, s28, v2
	v_or_b32_e32 v2, s8, v64
	v_lshlrev_b32_e32 v2, 12, v2
	v_lshl_add_u64 v[76:77], v[56:57], 0, v[2:3]
	global_store_dwordx4 v[76:77], v[70:73], off
	ds_read2_b32 v[76:77], v61 offset0:97 offset1:105
	ds_read2_b32 v[78:79], v61 offset0:162 offset1:170
	ds_read2_b32 v[80:81], v61 offset0:227 offset1:235
	s_waitcnt lgkmcnt(3)
	v_bfe_u32 v2, v74, 16, 1
	v_add3_u32 v2, v74, v2, s27
	s_waitcnt lgkmcnt(2)
	v_bfe_u32 v55, v76, 16, 1
	ds_read2_b32 v[82:83], v53 offset0:36 offset1:44
	v_lshrrev_b32_e32 v2, 16, v2
	v_add3_u32 v55, v76, v55, s27
	ds_read2_b32 v[84:85], v53 offset0:101 offset1:109
	v_and_or_b32 v70, v55, s28, v2
	s_waitcnt lgkmcnt(3)
	v_bfe_u32 v2, v78, 16, 1
	v_add3_u32 v2, v78, v2, s27
	s_waitcnt lgkmcnt(2)
	v_bfe_u32 v55, v80, 16, 1
	ds_read2_b32 v[86:87], v53 offset0:166 offset1:174
	v_lshrrev_b32_e32 v2, 16, v2
	v_add3_u32 v55, v80, v55, s27
	ds_read2_b32 v[88:89], v53 offset0:231 offset1:239
	v_and_or_b32 v71, v55, s28, v2
	s_waitcnt lgkmcnt(3)
	v_bfe_u32 v2, v82, 16, 1
	v_add3_u32 v2, v82, v2, s27
	s_waitcnt lgkmcnt(2)
	v_bfe_u32 v55, v84, 16, 1
	v_lshrrev_b32_e32 v2, 16, v2
	v_add3_u32 v55, v84, v55, s27
	v_and_or_b32 v72, v55, s28, v2
	s_waitcnt lgkmcnt(1)
	v_bfe_u32 v2, v86, 16, 1
	v_add3_u32 v2, v86, v2, s27
	s_waitcnt lgkmcnt(0)
	v_bfe_u32 v55, v88, 16, 1
	v_lshrrev_b32_e32 v2, 16, v2
	v_add3_u32 v55, v88, v55, s27
	v_and_or_b32 v73, v55, s28, v2
	v_or_b32_e32 v2, s8, v65
	v_lshlrev_b32_e32 v2, 12, v2
	v_lshl_add_u64 v[90:91], v[56:57], 0, v[2:3]
	v_bfe_u32 v2, v75, 16, 1
	v_add3_u32 v2, v75, v2, s27
	v_bfe_u32 v55, v77, 16, 1
	v_lshrrev_b32_e32 v2, 16, v2
	v_add3_u32 v55, v77, v55, s27
	global_store_dwordx4 v[90:91], v[70:73], off
	ds_read2_b32 v[74:75], v61 offset0:48 offset1:56
	s_nop 0
	v_and_or_b32 v70, v55, s28, v2
	v_bfe_u32 v2, v79, 16, 1
	v_add3_u32 v2, v79, v2, s27
	v_bfe_u32 v55, v81, 16, 1
	v_lshrrev_b32_e32 v2, 16, v2
	v_add3_u32 v55, v81, v55, s27
	v_and_or_b32 v71, v55, s28, v2
	v_bfe_u32 v2, v83, 16, 1
	v_add3_u32 v2, v83, v2, s27
	v_bfe_u32 v55, v85, 16, 1
	v_lshrrev_b32_e32 v2, 16, v2
	v_add3_u32 v55, v85, v55, s27
	v_and_or_b32 v72, v55, s28, v2
	v_bfe_u32 v2, v87, 16, 1
	v_add3_u32 v2, v87, v2, s27
	v_bfe_u32 v55, v89, 16, 1
	v_lshrrev_b32_e32 v2, 16, v2
	v_add3_u32 v55, v89, v55, s27
	v_and_or_b32 v73, v55, s28, v2
	v_or_b32_e32 v2, s8, v66
	v_lshlrev_b32_e32 v2, 12, v2
	v_lshl_add_u64 v[76:77], v[56:57], 0, v[2:3]
	global_store_dwordx4 v[76:77], v[70:73], off
	ds_read2_b32 v[76:77], v61 offset0:113 offset1:121
	ds_read2_b32 v[78:79], v61 offset0:178 offset1:186
	ds_read2_b32 v[80:81], v61 offset0:243 offset1:251
	s_waitcnt lgkmcnt(3)
	v_bfe_u32 v2, v74, 16, 1
	v_add3_u32 v2, v74, v2, s27
	s_waitcnt lgkmcnt(2)
	v_bfe_u32 v55, v76, 16, 1
	ds_read2_b32 v[82:83], v53 offset0:52 offset1:60
	v_lshrrev_b32_e32 v2, 16, v2
	v_add3_u32 v55, v76, v55, s27
	ds_read2_b32 v[84:85], v53 offset0:117 offset1:125
	v_and_or_b32 v70, v55, s28, v2
	s_waitcnt lgkmcnt(3)
	v_bfe_u32 v2, v78, 16, 1
	v_add3_u32 v2, v78, v2, s27
	s_waitcnt lgkmcnt(2)
	v_bfe_u32 v55, v80, 16, 1
	ds_read2_b32 v[86:87], v53 offset0:182 offset1:190
	v_lshrrev_b32_e32 v2, 16, v2
	v_add3_u32 v55, v80, v55, s27
	ds_read2_b32 v[88:89], v53 offset0:247 offset1:255
	v_and_or_b32 v71, v55, s28, v2
	s_waitcnt lgkmcnt(3)
	v_bfe_u32 v2, v82, 16, 1
	v_add3_u32 v2, v82, v2, s27
	s_waitcnt lgkmcnt(2)
	v_bfe_u32 v55, v84, 16, 1
	v_lshrrev_b32_e32 v2, 16, v2
	v_add3_u32 v55, v84, v55, s27
	v_and_or_b32 v72, v55, s28, v2
	s_waitcnt lgkmcnt(1)
	v_bfe_u32 v2, v86, 16, 1
	v_add3_u32 v2, v86, v2, s27
	s_waitcnt lgkmcnt(0)
	v_bfe_u32 v53, v88, 16, 1
	v_lshrrev_b32_e32 v2, 16, v2
	v_add3_u32 v53, v88, v53, s27
	v_and_or_b32 v73, v53, s28, v2
	v_or_b32_e32 v2, s8, v67
	v_lshlrev_b32_e32 v2, 12, v2
	v_lshl_add_u64 v[90:91], v[56:57], 0, v[2:3]
	v_bfe_u32 v2, v75, 16, 1
	v_add3_u32 v2, v75, v2, s27
	v_bfe_u32 v53, v77, 16, 1
	v_lshrrev_b32_e32 v2, 16, v2
	v_add3_u32 v53, v77, v53, s27
	global_store_dwordx4 v[90:91], v[70:73], off
	s_nop 1
	v_and_or_b32 v70, v53, s28, v2
	v_bfe_u32 v2, v79, 16, 1
	v_add3_u32 v2, v79, v2, s27
	v_bfe_u32 v53, v81, 16, 1
	v_lshrrev_b32_e32 v2, 16, v2
	v_add3_u32 v53, v81, v53, s27
	v_and_or_b32 v71, v53, s28, v2
	v_bfe_u32 v2, v83, 16, 1
	v_add3_u32 v2, v83, v2, s27
	v_bfe_u32 v53, v85, 16, 1
	v_lshrrev_b32_e32 v2, 16, v2
	v_add3_u32 v53, v85, v53, s27
	v_and_or_b32 v72, v53, s28, v2
	v_bfe_u32 v2, v87, 16, 1
	v_add3_u32 v2, v87, v2, s27
	v_bfe_u32 v53, v89, 16, 1
	v_lshrrev_b32_e32 v2, 16, v2
	v_add3_u32 v53, v89, v53, s27
	v_and_or_b32 v73, v53, s28, v2
	v_or_b32_e32 v2, s8, v68
	v_lshlrev_b32_e32 v2, 12, v2
	v_lshl_add_u64 v[56:57], v[56:57], 0, v[2:3]
	global_store_dwordx4 v[56:57], v[70:73], off
	s_waitcnt lgkmcnt(0)

; DI void transpose_item(const float* W, int K, int N, bf16_t* WT, int mode, float* scr, int item, int lane) {
;     ...
;     f32x4 v[16];
; #pragma unroll
;     for (int i = 0; i < 16; ++i) v[i] = __builtin_nontemporal_load((const f32x4*)(W + (size_t)(k0 + 4 * i + (lane >> 4)) * N + n0 + 4 * (lane & 15)));
; #pragma unroll
;     for (int i = 0; i < 16; ++i) { float* d = scr + (4 * i + (lane >> 4)) * 65 + 4 * (lane & 15); d[0] = v[i][0]; d[1] = v[i][1]; d[2] = v[i][2]; d[3] = v[i][3]; }
;     __builtin_amdgcn_s_waitcnt(0); __builtin_amdgcn_wave_barrier();
;     const int c = lane & 7;
; #pragma unroll
;     for (int j = 0; j < 8; ++j) { const int n = (lane >> 3) + 8 * j; const float* sp = scr + (8 * c) * 65 + n;
.LBB0_269:
	s_andn2_b64 vcc, exec, s[8:9]
	s_cbranch_vccnz .LBB0_271
	s_add_i32 s6, s3, 0xfffed300
	s_and_b32 s8, s16, 0x7c0
	s_and_b32 s9, s6, 0x1c0
	v_or_b32_e32 v2, s9, v58
	s_lshl_b32 s6, s8, 2
	v_lshl_add_u64 v[56:57], v[24:25], 0, s[6:7]
	v_lshlrev_b32_e32 v2, 13, v2
	v_lshl_add_u64 v[56:57], v[56:57], 0, v[2:3]
	v_add_co_u32_e32 v74, vcc, 0x8000, v56
	v_add_u32_e32 v2, 0x410, v59
	s_nop 0
	v_addc_co_u32_e32 v75, vcc, 0, v57, vcc
	v_add_co_u32_e32 v78, vcc, 0x10000, v56
	global_load_dwordx4 v[70:73], v[56:57], off nt
	s_nop 0
	global_load_dwordx4 v[74:77], v[74:75], off nt
	v_addc_co_u32_e32 v79, vcc, 0, v57, vcc
	v_add_co_u32_e32 v82, vcc, 0x18000, v56
	s_lshl_b32 s6, s9, 1
	s_nop 0
	v_addc_co_u32_e32 v83, vcc, 0, v57, vcc
	global_load_dwordx4 v[78:81], v[78:79], off nt
	s_nop 0
	global_load_dwordx4 v[82:85], v[82:83], off nt
	v_add_co_u32_e32 v86, vcc, 0x20000, v56
	s_nop 1
	v_addc_co_u32_e32 v87, vcc, 0, v57, vcc
	v_add_co_u32_e32 v90, vcc, 0x28000, v56
	s_nop 1
	v_addc_co_u32_e32 v91, vcc, 0, v57, vcc
	global_load_dwordx4 v[86:89], v[86:87], off nt
	s_nop 0
	global_load_dwordx4 v[90:93], v[90:91], off nt
	v_add_co_u32_e32 v94, vcc, 0x30000, v56
	s_nop 1
	v_addc_co_u32_e32 v95, vcc, 0, v57, vcc
	v_add_co_u32_e32 v98, vcc, 0x38000, v56
	s_nop 1
	v_addc_co_u32_e32 v99, vcc, 0, v57, vcc
	global_load_dwordx4 v[94:97], v[94:95], off nt
	s_nop 0
	global_load_dwordx4 v[98:101], v[98:99], off nt
	v_add_co_u32_e32 v102, vcc, 0x40000, v56
	s_nop 1
	v_addc_co_u32_e32 v103, vcc, 0, v57, vcc
	v_add_co_u32_e32 v106, vcc, 0x48000, v56
	s_nop 1
	v_addc_co_u32_e32 v107, vcc, 0, v57, vcc
	global_load_dwordx4 v[102:105], v[102:103], off nt
	s_nop 0
	global_load_dwordx4 v[106:109], v[106:107], off nt
	v_add_co_u32_e32 v110, vcc, 0x50000, v56
	s_nop 1
	v_addc_co_u32_e32 v111, vcc, 0, v57, vcc
	v_add_co_u32_e32 v114, vcc, 0x58000, v56
	s_nop 1
	v_addc_co_u32_e32 v115, vcc, 0, v57, vcc
	global_load_dwordx4 v[110:113], v[110:111], off nt
	s_nop 0
	global_load_dwordx4 v[114:117], v[114:115], off nt
	v_add_co_u32_e32 v118, vcc, 0x60000, v56
	s_nop 1
	v_addc_co_u32_e32 v119, vcc, 0, v57, vcc
	v_add_co_u32_e32 v122, vcc, 0x68000, v56
	s_nop 1
	v_addc_co_u32_e32 v123, vcc, 0, v57, vcc
	global_load_dwordx4 v[118:121], v[118:119], off nt
	s_nop 0
	global_load_dwordx4 v[122:125], v[122:123], off nt
	v_add_co_u32_e32 v126, vcc, 0x70000, v56
	s_nop 1
	v_addc_co_u32_e32 v127, vcc, 0, v57, vcc
	global_load_dwordx4 v[126:129], v[126:127], off nt
	v_add_co_u32_e32 v56, vcc, 0x78000, v56
	s_nop 1
	v_addc_co_u32_e32 v57, vcc, 0, v57, vcc
	global_load_dwordx4 v[130:133], v[56:57], off nt
	s_waitcnt vmcnt(0)
	ds_write2_b32 v59, v70, v71 offset1:1
	ds_write2_b32 v59, v72, v73 offset0:2 offset1:3
	ds_write2_b32 v2, v74, v75 offset1:1
	v_add_u32_e32 v2, 0x418, v59
	ds_write2_b32 v2, v76, v77 offset1:1
	v_add_u32_e32 v2, 0x820, v59
	v_lshl_add_u64 v[56:57], v[26:27], 0, s[6:7]
	ds_write2_b32 v2, v78, v79 offset1:1
	v_add_u32_e32 v2, 0x828, v59
	ds_write2_b32 v2, v80, v81 offset1:1
	v_add_u32_e32 v2, 0xc30, v59
	ds_write2_b32 v2, v82, v83 offset1:1
	v_add_u32_e32 v2, 0xc38, v59
	ds_write2_b32 v2, v84, v85 offset1:1
	v_add_u32_e32 v2, 0x1040, v59
	ds_write2_b32 v2, v86, v87 offset1:1
	v_add_u32_e32 v2, 0x1048, v59
	ds_write2_b32 v2, v88, v89 offset1:1
	v_add_u32_e32 v2, 0x1450, v59
	ds_write2_b32 v2, v90, v91 offset1:1
	v_add_u32_e32 v2, 0x1458, v59
	ds_write2_b32 v2, v92, v93 offset1:1
	v_add_u32_e32 v2, 0x1860, v59
	ds_write2_b32 v2, v94, v95 offset1:1
	v_add_u32_e32 v2, 0x1868, v59
	ds_write2_b32 v2, v96, v97 offset1:1
	v_add_u32_e32 v2, 0x1c70, v59
	ds_write2_b32 v2, v98, v99 offset1:1
	v_add_u32_e32 v2, 0x1c78, v59
	ds_write2_b32 v2, v100, v101 offset1:1
	v_add_u32_e32 v2, 0x2080, v59
	ds_write2_b32 v2, v102, v103 offset1:1
	v_add_u32_e32 v2, 0x2088, v59
	ds_write2_b32 v2, v104, v105 offset1:1
	v_add_u32_e32 v2, 0x2490, v59
	ds_write2_b32 v2, v106, v107 offset1:1
	v_add_u32_e32 v2, 0x2498, v59
	ds_write2_b32 v2, v108, v109 offset1:1
	v_add_u32_e32 v2, 0x28a0, v59
	ds_write2_b32 v2, v110, v111 offset1:1
	v_add_u32_e32 v2, 0x28a8, v59
	ds_write2_b32 v2, v112, v113 offset1:1
	v_add_u32_e32 v2, 0x2cb0, v59
	ds_write2_b32 v2, v114, v115 offset1:1
	v_add_u32_e32 v2, 0x2cb8, v59
	ds_write2_b32 v2, v116, v117 offset1:1
	v_add_u32_e32 v2, 0x30c0, v59
	ds_write2_b32 v2, v118, v119 offset1:1
	v_add_u32_e32 v2, 0x30c8, v59
	ds_write2_b32 v2, v120, v121 offset1:1
	v_add_u32_e32 v2, 0x34d0, v59
	ds_write2_b32 v2, v122, v123 offset1:1
	v_add_u32_e32 v2, 0x34d8, v59
	ds_write2_b32 v2, v124, v125 offset1:1
	v_add_u32_e32 v2, 0x38e0, v59
	ds_write2_b32 v2, v126, v127 offset1:1
	v_add_u32_e32 v2, 0x38e8, v59
	ds_write2_b32 v2, v128, v129 offset1:1
	v_add_u32_e32 v2, 0x3cf0, v59
	ds_write2_b32 v2, v130, v131 offset1:1
	v_add_u32_e32 v2, 0x3cf8, v59
	ds_write2_b32 v2, v132, v133 offset1:1
	s_waitcnt vmcnt(0) expcnt(0) lgkmcnt(0)
	ds_read2_b32 v[74:75], v61 offset1:8
	ds_read2_b32 v[76:77], v61 offset0:65 offset1:73
	ds_read2_b32 v[78:79], v61 offset0:130 offset1:138
	ds_read2_b32 v[80:81], v61 offset0:195 offset1:203
	s_waitcnt lgkmcnt(3)
	v_bfe_u32 v2, v74, 16, 1
	v_add3_u32 v2, v74, v2, s27
	s_waitcnt lgkmcnt(2)
	v_bfe_u32 v53, v76, 16, 1
	v_lshrrev_b32_e32 v2, 16, v2
	v_add3_u32 v53, v76, v53, s27
	v_and_or_b32 v70, v53, s28, v2
	v_add_u32_e32 v53, 0x400, v61
	ds_read2_b32 v[82:83], v53 offset0:4 offset1:12
	ds_read2_b32 v[84:85], v53 offset0:69 offset1:77
	s_waitcnt lgkmcnt(3)
	v_bfe_u32 v2, v78, 16, 1
	v_add3_u32 v2, v78, v2, s27
	s_waitcnt lgkmcnt(2)
	v_bfe_u32 v55, v80, 16, 1
	ds_read2_b32 v[86:87], v53 offset0:134 offset1:142
	v_lshrrev_b32_e32 v2, 16, v2
	v_add3_u32 v55, v80, v55, s27
	ds_read2_b32 v[88:89], v53 offset0:199 offset1:207
	v_and_or_b32 v71, v55, s28, v2
	s_waitcnt lgkmcnt(3)
; DI unsigned pk2w(float lo, float hi) { return f2bfw(lo) | (f2bfw(hi) << 16); }
; DI void transpose_item(const float* W, int K, int N, bf16_t* WT, int mode, float* scr, int item, int lane) {
;     ...
;     const int c = lane & 7;
; #pragma unroll
;     for (int j = 0; j < 8; ++j) { const int n = (lane >> 3) + 8 * j; const float* sp = scr + (8 * c) * 65 + n;
;         u32x4 o; o.x = pk2w(sp[0 * 65], sp[1 * 65]); o.y = pk2w(sp[2 * 65], sp[3 * 65]); o.z = pk2w(sp[4 * 65], sp[5 * 65]); o.w = pk2w(sp[6 * 65], sp[7 * 65]);
;         *(u32x4*)(WT + (size_t)(drow0 + n) * K + k0 + 8 * c) = o; }
;     __builtin_amdgcn_s_waitcnt(0); __builtin_amdgcn_wave_barrier();
	v_bfe_u32 v2, v82, 16, 1
	v_add3_u32 v2, v82, v2, s27
	s_waitcnt lgkmcnt(2)
	v_bfe_u32 v55, v84, 16, 1
	v_lshrrev_b32_e32 v2, 16, v2
	v_add3_u32 v55, v84, v55, s27
	v_and_or_b32 v72, v55, s28, v2
	s_waitcnt lgkmcnt(1)
	v_bfe_u32 v2, v86, 16, 1
	v_add3_u32 v2, v86, v2, s27
	s_waitcnt lgkmcnt(0)
	v_bfe_u32 v55, v88, 16, 1
	v_lshrrev_b32_e32 v2, 16, v2
	v_add3_u32 v55, v88, v55, s27
	v_and_or_b32 v73, v55, s28, v2
	v_or_b32_e32 v2, s8, v60
	v_lshlrev_b32_e32 v2, 9, v2
	v_lshl_add_u64 v[90:91], v[56:57], 0, v[2:3]
	v_bfe_u32 v2, v75, 16, 1
	v_add3_u32 v2, v75, v2, s27
	v_bfe_u32 v55, v77, 16, 1
	v_lshrrev_b32_e32 v2, 16, v2
	v_add3_u32 v55, v77, v55, s27
	global_store_dwordx4 v[90:91], v[70:73], off
	ds_read2_b32 v[74:75], v61 offset0:16 offset1:24
	s_nop 0
	v_and_or_b32 v70, v55, s28, v2
	v_bfe_u32 v2, v79, 16, 1
	v_add3_u32 v2, v79, v2, s27
	v_bfe_u32 v55, v81, 16, 1
	v_lshrrev_b32_e32 v2, 16, v2
	v_add3_u32 v55, v81, v55, s27
	v_and_or_b32 v71, v55, s28, v2
	v_bfe_u32 v2, v83, 16, 1
	v_add3_u32 v2, v83, v2, s27
	v_bfe_u32 v55, v85, 16, 1
	v_lshrrev_b32_e32 v2, 16, v2
	v_add3_u32 v55, v85, v55, s27
	v_and_or_b32 v72, v55, s28, v2
	v_bfe_u32 v2, v87, 16, 1
	v_add3_u32 v2, v87, v2, s27
	v_bfe_u32 v55, v89, 16, 1
	v_lshrrev_b32_e32 v2, 16, v2
	v_add3_u32 v55, v89, v55, s27
	v_and_or_b32 v73, v55, s28, v2
	v_or_b32_e32 v2, s8, v62
	v_lshlrev_b32_e32 v2, 9, v2
	v_lshl_add_u64 v[76:77], v[56:57], 0, v[2:3]
	global_store_dwordx4 v[76:77], v[70:73], off
	ds_read2_b32 v[76:77], v61 offset0:81 offset1:89
	ds_read2_b32 v[78:79], v61 offset0:146 offset1:154
	ds_read2_b32 v[80:81], v61 offset0:211 offset1:219
	s_waitcnt lgkmcnt(3)
	v_bfe_u32 v2, v74, 16, 1
	v_add3_u32 v2, v74, v2, s27
	s_waitcnt lgkmcnt(2)
	v_bfe_u32 v55, v76, 16, 1
	ds_read2_b32 v[82:83], v53 offset0:20 offset1:28
	v_lshrrev_b32_e32 v2, 16, v2
	v_add3_u32 v55, v76, v55, s27
	ds_read2_b32 v[84:85], v53 offset0:85 offset1:93
	v_and_or_b32 v70, v55, s28, v2
	s_waitcnt lgkmcnt(3)
	v_bfe_u32 v2, v78, 16, 1
	v_add3_u32 v2, v78, v2, s27
	s_waitcnt lgkmcnt(2)
	v_bfe_u32 v55, v80, 16, 1
	ds_read2_b32 v[86:87], v53 offset0:150 offset1:158
	v_lshrrev_b32_e32 v2, 16, v2
	v_add3_u32 v55, v80, v55, s27
	ds_read2_b32 v[88:89], v53 offset0:215 offset1:223
	v_and_or_b32 v71, v55, s28, v2
	s_waitcnt lgkmcnt(3)
	v_bfe_u32 v2, v82, 16, 1
	v_add3_u32 v2, v82, v2, s27
	s_waitcnt lgkmcnt(2)
	v_bfe_u32 v55, v84, 16, 1
	v_lshrrev_b32_e32 v2, 16, v2
	v_add3_u32 v55, v84, v55, s27
	v_and_or_b32 v72, v55, s28, v2
	s_waitcnt lgkmcnt(1)
	v_bfe_u32 v2, v86, 16, 1
	v_add3_u32 v2, v86, v2, s27
	s_waitcnt lgkmcnt(0)
	v_bfe_u32 v55, v88, 16, 1
	v_lshrrev_b32_e32 v2, 16, v2
	v_add3_u32 v55, v88, v55, s27
	v_and_or_b32 v73, v55, s28, v2
	v_or_b32_e32 v2, s8, v63
	v_lshlrev_b32_e32 v2, 9, v2
	v_lshl_add_u64 v[90:91], v[56:57], 0, v[2:3]
	v_bfe_u32 v2, v75, 16, 1
	v_add3_u32 v2, v75, v2, s27
	v_bfe_u32 v55, v77, 16, 1
	v_lshrrev_b32_e32 v2, 16, v2
	v_add3_u32 v55, v77, v55, s27
	global_store_dwordx4 v[90:91], v[70:73], off
	ds_read2_b32 v[74:75], v61 offset0:32 offset1:40
	s_nop 0
	v_and_or_b32 v70, v55, s28, v2
	v_bfe_u32 v2, v79, 16, 1
	v_add3_u32 v2, v79, v2, s27
	v_bfe_u32 v55, v81, 16, 1
	v_lshrrev_b32_e32 v2, 16, v2
	v_add3_u32 v55, v81, v55, s27
	v_and_or_b32 v71, v55, s28, v2
	v_bfe_u32 v2, v83, 16, 1
	v_add3_u32 v2, v83, v2, s27
	v_bfe_u32 v55, v85, 16, 1
	v_lshrrev_b32_e32 v2, 16, v2
	v_add3_u32 v55, v85, v55, s27
	v_and_or_b32 v72, v55, s28, v2
	v_bfe_u32 v2, v87, 16, 1
	v_add3_u32 v2, v87, v2, s27
	v_bfe_u32 v55, v89, 16, 1
	v_lshrrev_b32_e32 v2, 16, v2
	v_add3_u32 v55, v89, v55, s27
	v_and_or_b32 v73, v55, s28, v2
	v_or_b32_e32 v2, s8, v64
	v_lshlrev_b32_e32 v2, 9, v2
	v_lshl_add_u64 v[76:77], v[56:57], 0, v[2:3]
	global_store_dwordx4 v[76:77], v[70:73], off
	ds_read2_b32 v[76:77], v61 offset0:97 offset1:105
	ds_read2_b32 v[78:79], v61 offset0:162 offset1:170
	ds_read2_b32 v[80:81], v61 offset0:227 offset1:235
	s_waitcnt lgkmcnt(3)
	v_bfe_u32 v2, v74, 16, 1
	v_add3_u32 v2, v74, v2, s27
	s_waitcnt lgkmcnt(2)
	v_bfe_u32 v55, v76, 16, 1
	ds_read2_b32 v[82:83], v53 offset0:36 offset1:44
	v_lshrrev_b32_e32 v2, 16, v2
	v_add3_u32 v55, v76, v55, s27
	ds_read2_b32 v[84:85], v53 offset0:101 offset1:109
	v_and_or_b32 v70, v55, s28, v2
	s_waitcnt lgkmcnt(3)
; DI unsigned pk2w(float lo, float hi) { return f2bfw(lo) | (f2bfw(hi) << 16); }
; DI void transpose_item(const float* W, int K, int N, bf16_t* WT, int mode, float* scr, int item, int lane) {
;     ...
;     const int c = lane & 7;
; #pragma unroll
;     for (int j = 0; j < 8; ++j) { const int n = (lane >> 3) + 8 * j; const float* sp = scr + (8 * c) * 65 + n;
;         u32x4 o; o.x = pk2w(sp[0 * 65], sp[1 * 65]); o.y = pk2w(sp[2 * 65], sp[3 * 65]); o.z = pk2w(sp[4 * 65], sp[5 * 65]); o.w = pk2w(sp[6 * 65], sp[7 * 65]);
;         *(u32x4*)(WT + (size_t)(drow0 + n) * K + k0 + 8 * c) = o; }
;     __builtin_amdgcn_s_waitcnt(0); __builtin_amdgcn_wave_barrier();
	v_bfe_u32 v2, v78, 16, 1
	v_add3_u32 v2, v78, v2, s27
	s_waitcnt lgkmcnt(2)
	v_bfe_u32 v55, v80, 16, 1
	ds_read2_b32 v[86:87], v53 offset0:166 offset1:174
	v_lshrrev_b32_e32 v2, 16, v2
	v_add3_u32 v55, v80, v55, s27
	ds_read2_b32 v[88:89], v53 offset0:231 offset1:239
	v_and_or_b32 v71, v55, s28, v2
	s_waitcnt lgkmcnt(3)
	v_bfe_u32 v2, v82, 16, 1
	v_add3_u32 v2, v82, v2, s27
	s_waitcnt lgkmcnt(2)
	v_bfe_u32 v55, v84, 16, 1
	v_lshrrev_b32_e32 v2, 16, v2
	v_add3_u32 v55, v84, v55, s27
	v_and_or_b32 v72, v55, s28, v2
	s_waitcnt lgkmcnt(1)
	v_bfe_u32 v2, v86, 16, 1
	v_add3_u32 v2, v86, v2, s27
	s_waitcnt lgkmcnt(0)
	v_bfe_u32 v55, v88, 16, 1
	v_lshrrev_b32_e32 v2, 16, v2
	v_add3_u32 v55, v88, v55, s27
	v_and_or_b32 v73, v55, s28, v2
	v_or_b32_e32 v2, s8, v65
	v_lshlrev_b32_e32 v2, 9, v2
	v_lshl_add_u64 v[90:91], v[56:57], 0, v[2:3]
	v_bfe_u32 v2, v75, 16, 1
	v_add3_u32 v2, v75, v2, s27
	v_bfe_u32 v55, v77, 16, 1
	v_lshrrev_b32_e32 v2, 16, v2
	v_add3_u32 v55, v77, v55, s27
	global_store_dwordx4 v[90:91], v[70:73], off
	ds_read2_b32 v[74:75], v61 offset0:48 offset1:56
	s_nop 0
	v_and_or_b32 v70, v55, s28, v2
	v_bfe_u32 v2, v79, 16, 1
	v_add3_u32 v2, v79, v2, s27
	v_bfe_u32 v55, v81, 16, 1
	v_lshrrev_b32_e32 v2, 16, v2
	v_add3_u32 v55, v81, v55, s27
	v_and_or_b32 v71, v55, s28, v2
	v_bfe_u32 v2, v83, 16, 1
	v_add3_u32 v2, v83, v2, s27
	v_bfe_u32 v55, v85, 16, 1
	v_lshrrev_b32_e32 v2, 16, v2
	v_add3_u32 v55, v85, v55, s27
	v_and_or_b32 v72, v55, s28, v2
	v_bfe_u32 v2, v87, 16, 1
	v_add3_u32 v2, v87, v2, s27
	v_bfe_u32 v55, v89, 16, 1
	v_lshrrev_b32_e32 v2, 16, v2
	v_add3_u32 v55, v89, v55, s27
	v_and_or_b32 v73, v55, s28, v2
	v_or_b32_e32 v2, s8, v66
	v_lshlrev_b32_e32 v2, 9, v2
	v_lshl_add_u64 v[76:77], v[56:57], 0, v[2:3]
	global_store_dwordx4 v[76:77], v[70:73], off
	ds_read2_b32 v[76:77], v61 offset0:113 offset1:121
	ds_read2_b32 v[78:79], v61 offset0:178 offset1:186
	ds_read2_b32 v[80:81], v61 offset0:243 offset1:251
	s_waitcnt lgkmcnt(3)
	v_bfe_u32 v2, v74, 16, 1
	v_add3_u32 v2, v74, v2, s27
	s_waitcnt lgkmcnt(2)
	v_bfe_u32 v55, v76, 16, 1
	ds_read2_b32 v[82:83], v53 offset0:52 offset1:60
	v_lshrrev_b32_e32 v2, 16, v2
	v_add3_u32 v55, v76, v55, s27
	ds_read2_b32 v[84:85], v53 offset0:117 offset1:125
	v_and_or_b32 v70, v55, s28, v2
	s_waitcnt lgkmcnt(3)
	v_bfe_u32 v2, v78, 16, 1
	v_add3_u32 v2, v78, v2, s27
	s_waitcnt lgkmcnt(2)
	v_bfe_u32 v55, v80, 16, 1
	ds_read2_b32 v[86:87], v53 offset0:182 offset1:190
	v_lshrrev_b32_e32 v2, 16, v2
	v_add3_u32 v55, v80, v55, s27
	ds_read2_b32 v[88:89], v53 offset0:247 offset1:255
	v_and_or_b32 v71, v55, s28, v2
	s_waitcnt lgkmcnt(3)
	v_bfe_u32 v2, v82, 16, 1
	v_add3_u32 v2, v82, v2, s27
	s_waitcnt lgkmcnt(2)
	v_bfe_u32 v55, v84, 16, 1
	v_lshrrev_b32_e32 v2, 16, v2
	v_add3_u32 v55, v84, v55, s27
	v_and_or_b32 v72, v55, s28, v2
	s_waitcnt lgkmcnt(1)
	v_bfe_u32 v2, v86, 16, 1
	v_add3_u32 v2, v86, v2, s27
	s_waitcnt lgkmcnt(0)
	v_bfe_u32 v53, v88, 16, 1
	v_lshrrev_b32_e32 v2, 16, v2
	v_add3_u32 v53, v88, v53, s27
	v_and_or_b32 v73, v53, s28, v2
	v_or_b32_e32 v2, s8, v67
	v_lshlrev_b32_e32 v2, 9, v2
	v_lshl_add_u64 v[90:91], v[56:57], 0, v[2:3]
	v_bfe_u32 v2, v75, 16, 1
	v_add3_u32 v2, v75, v2, s27
	v_bfe_u32 v53, v77, 16, 1
	v_lshrrev_b32_e32 v2, 16, v2
	v_add3_u32 v53, v77, v53, s27
	global_store_dwordx4 v[90:91], v[70:73], off
	s_nop 1
	v_and_or_b32 v70, v53, s28, v2
	v_bfe_u32 v2, v79, 16, 1
	v_add3_u32 v2, v79, v2, s27
	v_bfe_u32 v53, v81, 16, 1
	v_lshrrev_b32_e32 v2, 16, v2
	v_add3_u32 v53, v81, v53, s27
	v_and_or_b32 v71, v53, s28, v2
	v_bfe_u32 v2, v83, 16, 1
	v_add3_u32 v2, v83, v2, s27
	v_bfe_u32 v53, v85, 16, 1
	v_lshrrev_b32_e32 v2, 16, v2
	v_add3_u32 v53, v85, v53, s27
	v_and_or_b32 v72, v53, s28, v2
	v_bfe_u32 v2, v87, 16, 1
	v_add3_u32 v2, v87, v2, s27
	v_bfe_u32 v53, v89, 16, 1
	v_lshrrev_b32_e32 v2, 16, v2
	v_add3_u32 v53, v89, v53, s27
	v_and_or_b32 v73, v53, s28, v2
	v_or_b32_e32 v2, s8, v68
	v_lshlrev_b32_e32 v2, 9, v2
	v_lshl_add_u64 v[56:57], v[56:57], 0, v[2:3]
	global_store_dwordx4 v[56:57], v[70:73], off
	s_waitcnt lgkmcnt(0)

; DI void transpose_item(const float* W, int K, int N, bf16_t* WT, int mode, float* scr, int item, int lane) {
;     ...
;     f32x4 v[16];
; #pragma unroll
;     for (int i = 0; i < 16; ++i) v[i] = __builtin_nontemporal_load((const f32x4*)(W + (size_t)(k0 + 4 * i + (lane >> 4)) * N + n0 + 4 * (lane & 15)));
; #pragma unroll
;     for (int i = 0; i < 16; ++i) { float* d = scr + (4 * i + (lane >> 4)) * 65 + 4 * (lane & 15); d[0] = v[i][0]; d[1] = v[i][1]; d[2] = v[i][2]; d[3] = v[i][3]; }
;     __builtin_amdgcn_s_waitcnt(0); __builtin_amdgcn_wave_barrier();
;     const int c = lane & 7;
; #pragma unroll
;     for (int j = 0; j < 8; ++j) { const int n = (lane >> 3) + 8 * j; const float* sp = scr + (8 * c) * 65 + n;
.LBB0_272:
	s_andn2_b64 vcc, exec, s[8:9]
	s_cbranch_vccnz .LBB0_274
	s_add_i32 s6, s3, 0x1700
	s_and_b32 s8, s16, 0x7c0
	s_and_b32 s9, s6, 0x1ffc0
	v_or_b32_e32 v2, s9, v58
	s_lshl_b32 s6, s8, 2
	v_lshl_add_u64 v[56:57], v[28:29], 0, s[6:7]
	v_lshlrev_b32_e32 v2, 13, v2
	v_lshl_add_u64 v[56:57], v[56:57], 0, v[2:3]
	v_add_co_u32_e32 v74, vcc, 0x8000, v56
	v_add_u32_e32 v2, 0x410, v59
	s_nop 0
	v_addc_co_u32_e32 v75, vcc, 0, v57, vcc
	v_add_co_u32_e32 v78, vcc, 0x10000, v56
	global_load_dwordx4 v[70:73], v[56:57], off nt
	s_nop 0
	global_load_dwordx4 v[74:77], v[74:75], off nt
	v_addc_co_u32_e32 v79, vcc, 0, v57, vcc
	v_add_co_u32_e32 v82, vcc, 0x18000, v56
	s_lshl_b32 s6, s9, 1
	s_nop 0
	v_addc_co_u32_e32 v83, vcc, 0, v57, vcc
	global_load_dwordx4 v[78:81], v[78:79], off nt
	s_nop 0
	global_load_dwordx4 v[82:85], v[82:83], off nt
	v_add_co_u32_e32 v86, vcc, 0x20000, v56
	s_nop 1
	v_addc_co_u32_e32 v87, vcc, 0, v57, vcc
	v_add_co_u32_e32 v90, vcc, 0x28000, v56
	s_nop 1
	v_addc_co_u32_e32 v91, vcc, 0, v57, vcc
	global_load_dwordx4 v[86:89], v[86:87], off nt
	s_nop 0
	global_load_dwordx4 v[90:93], v[90:91], off nt
	v_add_co_u32_e32 v94, vcc, 0x30000, v56
	s_nop 1
	v_addc_co_u32_e32 v95, vcc, 0, v57, vcc
	v_add_co_u32_e32 v98, vcc, 0x38000, v56
	s_nop 1
	v_addc_co_u32_e32 v99, vcc, 0, v57, vcc
	global_load_dwordx4 v[94:97], v[94:95], off nt
	s_nop 0
	global_load_dwordx4 v[98:101], v[98:99], off nt
	v_add_co_u32_e32 v102, vcc, 0x40000, v56
	s_nop 1
	v_addc_co_u32_e32 v103, vcc, 0, v57, vcc
	v_add_co_u32_e32 v106, vcc, 0x48000, v56
	s_nop 1
	v_addc_co_u32_e32 v107, vcc, 0, v57, vcc
	global_load_dwordx4 v[102:105], v[102:103], off nt
	s_nop 0
	global_load_dwordx4 v[106:109], v[106:107], off nt
	v_add_co_u32_e32 v110, vcc, 0x50000, v56
	s_nop 1
	v_addc_co_u32_e32 v111, vcc, 0, v57, vcc
	v_add_co_u32_e32 v114, vcc, 0x58000, v56
	s_nop 1
	v_addc_co_u32_e32 v115, vcc, 0, v57, vcc
	global_load_dwordx4 v[110:113], v[110:111], off nt
	s_nop 0
	global_load_dwordx4 v[114:117], v[114:115], off nt
	v_add_co_u32_e32 v118, vcc, 0x60000, v56
	s_nop 1
	v_addc_co_u32_e32 v119, vcc, 0, v57, vcc
	v_add_co_u32_e32 v122, vcc, 0x68000, v56
	s_nop 1
	v_addc_co_u32_e32 v123, vcc, 0, v57, vcc
	global_load_dwordx4 v[118:121], v[118:119], off nt
	s_nop 0
	global_load_dwordx4 v[122:125], v[122:123], off nt
	v_add_co_u32_e32 v126, vcc, 0x70000, v56
	s_nop 1
	v_addc_co_u32_e32 v127, vcc, 0, v57, vcc
	global_load_dwordx4 v[126:129], v[126:127], off nt
	v_add_co_u32_e32 v56, vcc, 0x78000, v56
	s_nop 1
	v_addc_co_u32_e32 v57, vcc, 0, v57, vcc
	global_load_dwordx4 v[130:133], v[56:57], off nt
	s_waitcnt vmcnt(0)
	ds_write2_b32 v59, v70, v71 offset1:1
	ds_write2_b32 v59, v72, v73 offset0:2 offset1:3
	ds_write2_b32 v2, v74, v75 offset1:1
	v_add_u32_e32 v2, 0x418, v59
	ds_write2_b32 v2, v76, v77 offset1:1
	v_add_u32_e32 v2, 0x820, v59
	v_lshl_add_u64 v[56:57], v[30:31], 0, s[6:7]
	ds_write2_b32 v2, v78, v79 offset1:1
	v_add_u32_e32 v2, 0x828, v59
	ds_write2_b32 v2, v80, v81 offset1:1
	v_add_u32_e32 v2, 0xc30, v59
	ds_write2_b32 v2, v82, v83 offset1:1
	v_add_u32_e32 v2, 0xc38, v59
	ds_write2_b32 v2, v84, v85 offset1:1
	v_add_u32_e32 v2, 0x1040, v59
	ds_write2_b32 v2, v86, v87 offset1:1
	v_add_u32_e32 v2, 0x1048, v59
	ds_write2_b32 v2, v88, v89 offset1:1
	v_add_u32_e32 v2, 0x1450, v59
	ds_write2_b32 v2, v90, v91 offset1:1
	v_add_u32_e32 v2, 0x1458, v59
	ds_write2_b32 v2, v92, v93 offset1:1
	v_add_u32_e32 v2, 0x1860, v59
	ds_write2_b32 v2, v94, v95 offset1:1
	v_add_u32_e32 v2, 0x1868, v59
	ds_write2_b32 v2, v96, v97 offset1:1
	v_add_u32_e32 v2, 0x1c70, v59
	ds_write2_b32 v2, v98, v99 offset1:1
	v_add_u32_e32 v2, 0x1c78, v59
	ds_write2_b32 v2, v100, v101 offset1:1
	v_add_u32_e32 v2, 0x2080, v59
	ds_write2_b32 v2, v102, v103 offset1:1
	v_add_u32_e32 v2, 0x2088, v59
	ds_write2_b32 v2, v104, v105 offset1:1
	v_add_u32_e32 v2, 0x2490, v59
	ds_write2_b32 v2, v106, v107 offset1:1
	v_add_u32_e32 v2, 0x2498, v59
	ds_write2_b32 v2, v108, v109 offset1:1
	v_add_u32_e32 v2, 0x28a0, v59
	ds_write2_b32 v2, v110, v111 offset1:1
	v_add_u32_e32 v2, 0x28a8, v59
	ds_write2_b32 v2, v112, v113 offset1:1
	v_add_u32_e32 v2, 0x2cb0, v59
	ds_write2_b32 v2, v114, v115 offset1:1
	v_add_u32_e32 v2, 0x2cb8, v59
	ds_write2_b32 v2, v116, v117 offset1:1
	v_add_u32_e32 v2, 0x30c0, v59
	ds_write2_b32 v2, v118, v119 offset1:1
	v_add_u32_e32 v2, 0x30c8, v59
	ds_write2_b32 v2, v120, v121 offset1:1
	v_add_u32_e32 v2, 0x34d0, v59
	ds_write2_b32 v2, v122, v123 offset1:1
	v_add_u32_e32 v2, 0x34d8, v59
	ds_write2_b32 v2, v124, v125 offset1:1
	v_add_u32_e32 v2, 0x38e0, v59
	ds_write2_b32 v2, v126, v127 offset1:1
	v_add_u32_e32 v2, 0x38e8, v59
	ds_write2_b32 v2, v128, v129 offset1:1
	v_add_u32_e32 v2, 0x3cf0, v59
	ds_write2_b32 v2, v130, v131 offset1:1
	v_add_u32_e32 v2, 0x3cf8, v59
	ds_write2_b32 v2, v132, v133 offset1:1
	s_waitcnt vmcnt(0) expcnt(0) lgkmcnt(0)
	ds_read2_b32 v[74:75], v61 offset1:8
	ds_read2_b32 v[76:77], v61 offset0:65 offset1:73
	ds_read2_b32 v[78:79], v61 offset0:130 offset1:138
	ds_read2_b32 v[80:81], v61 offset0:195 offset1:203
	s_waitcnt lgkmcnt(3)
	v_bfe_u32 v2, v74, 16, 1
	v_add3_u32 v2, v74, v2, s27
	s_waitcnt lgkmcnt(2)
	v_bfe_u32 v53, v76, 16, 1
	v_lshrrev_b32_e32 v2, 16, v2
	v_add3_u32 v53, v76, v53, s27
	v_and_or_b32 v70, v53, s28, v2
	v_add_u32_e32 v53, 0x400, v61
	ds_read2_b32 v[82:83], v53 offset0:4 offset1:12
	ds_read2_b32 v[84:85], v53 offset0:69 offset1:77
	s_waitcnt lgkmcnt(3)
	v_bfe_u32 v2, v78, 16, 1
	v_add3_u32 v2, v78, v2, s27
	s_waitcnt lgkmcnt(2)
	v_bfe_u32 v55, v80, 16, 1
	ds_read2_b32 v[86:87], v53 offset0:134 offset1:142
	v_lshrrev_b32_e32 v2, 16, v2
	v_add3_u32 v55, v80, v55, s27
	ds_read2_b32 v[88:89], v53 offset0:199 offset1:207
	v_and_or_b32 v71, v55, s28, v2
	s_waitcnt lgkmcnt(3)
; DI unsigned pk2w(float lo, float hi) { return f2bfw(lo) | (f2bfw(hi) << 16); }
; DI void transpose_item(const float* W, int K, int N, bf16_t* WT, int mode, float* scr, int item, int lane) {
;     ...
;     const int c = lane & 7;
; #pragma unroll
;     for (int j = 0; j < 8; ++j) { const int n = (lane >> 3) + 8 * j; const float* sp = scr + (8 * c) * 65 + n;
;         u32x4 o; o.x = pk2w(sp[0 * 65], sp[1 * 65]); o.y = pk2w(sp[2 * 65], sp[3 * 65]); o.z = pk2w(sp[4 * 65], sp[5 * 65]); o.w = pk2w(sp[6 * 65], sp[7 * 65]);
;         *(u32x4*)(WT + (size_t)(drow0 + n) * K + k0 + 8 * c) = o; }
;     __builtin_amdgcn_s_waitcnt(0); __builtin_amdgcn_wave_barrier();
	v_bfe_u32 v2, v82, 16, 1
	v_add3_u32 v2, v82, v2, s27
	s_waitcnt lgkmcnt(2)
	v_bfe_u32 v55, v84, 16, 1
	v_lshrrev_b32_e32 v2, 16, v2
	v_add3_u32 v55, v84, v55, s27
	v_and_or_b32 v72, v55, s28, v2
	s_waitcnt lgkmcnt(1)
	v_bfe_u32 v2, v86, 16, 1
	v_add3_u32 v2, v86, v2, s27
	s_waitcnt lgkmcnt(0)
	v_bfe_u32 v55, v88, 16, 1
	v_lshrrev_b32_e32 v2, 16, v2
	v_add3_u32 v55, v88, v55, s27
	v_and_or_b32 v73, v55, s28, v2
	v_or_b32_e32 v2, s8, v60
	v_mul_u32_u24_e32 v2, 0x1600, v2
	v_lshlrev_b32_e32 v2, 1, v2
	v_lshl_add_u64 v[90:91], v[56:57], 0, v[2:3]
	v_bfe_u32 v2, v75, 16, 1
	v_add3_u32 v2, v75, v2, s27
	v_bfe_u32 v55, v77, 16, 1
	v_lshrrev_b32_e32 v2, 16, v2
	v_add3_u32 v55, v77, v55, s27
	global_store_dwordx4 v[90:91], v[70:73], off
	ds_read2_b32 v[74:75], v61 offset0:16 offset1:24
	s_nop 0
	v_and_or_b32 v70, v55, s28, v2
	v_bfe_u32 v2, v79, 16, 1
	v_add3_u32 v2, v79, v2, s27
	v_bfe_u32 v55, v81, 16, 1
	v_lshrrev_b32_e32 v2, 16, v2
	v_add3_u32 v55, v81, v55, s27
	v_and_or_b32 v71, v55, s28, v2
	v_bfe_u32 v2, v83, 16, 1
	v_add3_u32 v2, v83, v2, s27
	v_bfe_u32 v55, v85, 16, 1
	v_lshrrev_b32_e32 v2, 16, v2
	v_add3_u32 v55, v85, v55, s27
	v_and_or_b32 v72, v55, s28, v2
	v_bfe_u32 v2, v87, 16, 1
	v_add3_u32 v2, v87, v2, s27
	v_bfe_u32 v55, v89, 16, 1
	v_lshrrev_b32_e32 v2, 16, v2
	v_add3_u32 v55, v89, v55, s27
	v_and_or_b32 v73, v55, s28, v2
	v_or_b32_e32 v2, s8, v62
	v_mul_u32_u24_e32 v2, 0x1600, v2
	v_lshlrev_b32_e32 v2, 1, v2
	v_lshl_add_u64 v[76:77], v[56:57], 0, v[2:3]
	global_store_dwordx4 v[76:77], v[70:73], off
	ds_read2_b32 v[76:77], v61 offset0:81 offset1:89
	ds_read2_b32 v[78:79], v61 offset0:146 offset1:154
	ds_read2_b32 v[80:81], v61 offset0:211 offset1:219
	s_waitcnt lgkmcnt(3)
	v_bfe_u32 v2, v74, 16, 1
	v_add3_u32 v2, v74, v2, s27
	s_waitcnt lgkmcnt(2)
	v_bfe_u32 v55, v76, 16, 1
	ds_read2_b32 v[82:83], v53 offset0:20 offset1:28
	v_lshrrev_b32_e32 v2, 16, v2
	v_add3_u32 v55, v76, v55, s27
	ds_read2_b32 v[84:85], v53 offset0:85 offset1:93
	v_and_or_b32 v70, v55, s28, v2
	s_waitcnt lgkmcnt(3)
	v_bfe_u32 v2, v78, 16, 1
	v_add3_u32 v2, v78, v2, s27
	s_waitcnt lgkmcnt(2)
	v_bfe_u32 v55, v80, 16, 1
	ds_read2_b32 v[86:87], v53 offset0:150 offset1:158
	v_lshrrev_b32_e32 v2, 16, v2
	v_add3_u32 v55, v80, v55, s27
	ds_read2_b32 v[88:89], v53 offset0:215 offset1:223
	v_and_or_b32 v71, v55, s28, v2
	s_waitcnt lgkmcnt(3)
	v_bfe_u32 v2, v82, 16, 1
	v_add3_u32 v2, v82, v2, s27
	s_waitcnt lgkmcnt(2)
	v_bfe_u32 v55, v84, 16, 1
	v_lshrrev_b32_e32 v2, 16, v2
	v_add3_u32 v55, v84, v55, s27
	v_and_or_b32 v72, v55, s28, v2
	s_waitcnt lgkmcnt(1)
	v_bfe_u32 v2, v86, 16, 1
	v_add3_u32 v2, v86, v2, s27
	s_waitcnt lgkmcnt(0)
	v_bfe_u32 v55, v88, 16, 1
	v_lshrrev_b32_e32 v2, 16, v2
	v_add3_u32 v55, v88, v55, s27
	v_and_or_b32 v73, v55, s28, v2
	v_or_b32_e32 v2, s8, v63
	v_mul_u32_u24_e32 v2, 0x1600, v2
	v_lshlrev_b32_e32 v2, 1, v2
	v_lshl_add_u64 v[90:91], v[56:57], 0, v[2:3]
	v_bfe_u32 v2, v75, 16, 1
	v_add3_u32 v2, v75, v2, s27
	v_bfe_u32 v55, v77, 16, 1
	v_lshrrev_b32_e32 v2, 16, v2
	v_add3_u32 v55, v77, v55, s27
	global_store_dwordx4 v[90:91], v[70:73], off
	ds_read2_b32 v[74:75], v61 offset0:32 offset1:40
	s_nop 0
	v_and_or_b32 v70, v55, s28, v2
	v_bfe_u32 v2, v79, 16, 1
	v_add3_u32 v2, v79, v2, s27
	v_bfe_u32 v55, v81, 16, 1
	v_lshrrev_b32_e32 v2, 16, v2
	v_add3_u32 v55, v81, v55, s27
	v_and_or_b32 v71, v55, s28, v2
	v_bfe_u32 v2, v83, 16, 1
	v_add3_u32 v2, v83, v2, s27
	v_bfe_u32 v55, v85, 16, 1
	v_lshrrev_b32_e32 v2, 16, v2
	v_add3_u32 v55, v85, v55, s27
	v_and_or_b32 v72, v55, s28, v2
	v_bfe_u32 v2, v87, 16, 1
	v_add3_u32 v2, v87, v2, s27
	v_bfe_u32 v55, v89, 16, 1
	v_lshrrev_b32_e32 v2, 16, v2
	v_add3_u32 v55, v89, v55, s27
	v_and_or_b32 v73, v55, s28, v2
	v_or_b32_e32 v2, s8, v64
	v_mul_u32_u24_e32 v2, 0x1600, v2
	v_lshlrev_b32_e32 v2, 1, v2
	v_lshl_add_u64 v[76:77], v[56:57], 0, v[2:3]
	global_store_dwordx4 v[76:77], v[70:73], off
	ds_read2_b32 v[76:77], v61 offset0:97 offset1:105
	ds_read2_b32 v[78:79], v61 offset0:162 offset1:170
	ds_read2_b32 v[80:81], v61 offset0:227 offset1:235
	s_waitcnt lgkmcnt(3)
	v_bfe_u32 v2, v74, 16, 1
	v_add3_u32 v2, v74, v2, s27
	s_waitcnt lgkmcnt(2)
	v_bfe_u32 v55, v76, 16, 1
	ds_read2_b32 v[82:83], v53 offset0:36 offset1:44
	v_lshrrev_b32_e32 v2, 16, v2
	v_add3_u32 v55, v76, v55, s27
	ds_read2_b32 v[84:85], v53 offset0:101 offset1:109
	v_and_or_b32 v70, v55, s28, v2
	s_waitcnt lgkmcnt(3)
; DI unsigned pk2w(float lo, float hi) { return f2bfw(lo) | (f2bfw(hi) << 16); }
; DI void transpose_item(const float* W, int K, int N, bf16_t* WT, int mode, float* scr, int item, int lane) {
;     ...
;     const int c = lane & 7;
; #pragma unroll
;     for (int j = 0; j < 8; ++j) { const int n = (lane >> 3) + 8 * j; const float* sp = scr + (8 * c) * 65 + n;
;         u32x4 o; o.x = pk2w(sp[0 * 65], sp[1 * 65]); o.y = pk2w(sp[2 * 65], sp[3 * 65]); o.z = pk2w(sp[4 * 65], sp[5 * 65]); o.w = pk2w(sp[6 * 65], sp[7 * 65]);
;         *(u32x4*)(WT + (size_t)(drow0 + n) * K + k0 + 8 * c) = o; }
;     __builtin_amdgcn_s_waitcnt(0); __builtin_amdgcn_wave_barrier();
	v_bfe_u32 v2, v78, 16, 1
	v_add3_u32 v2, v78, v2, s27
	s_waitcnt lgkmcnt(2)
	v_bfe_u32 v55, v80, 16, 1
	ds_read2_b32 v[86:87], v53 offset0:166 offset1:174
	v_lshrrev_b32_e32 v2, 16, v2
	v_add3_u32 v55, v80, v55, s27
	ds_read2_b32 v[88:89], v53 offset0:231 offset1:239
	v_and_or_b32 v71, v55, s28, v2
	s_waitcnt lgkmcnt(3)
	v_bfe_u32 v2, v82, 16, 1
	v_add3_u32 v2, v82, v2, s27
	s_waitcnt lgkmcnt(2)
	v_bfe_u32 v55, v84, 16, 1
	v_lshrrev_b32_e32 v2, 16, v2
	v_add3_u32 v55, v84, v55, s27
	v_and_or_b32 v72, v55, s28, v2
	s_waitcnt lgkmcnt(1)
	v_bfe_u32 v2, v86, 16, 1
	v_add3_u32 v2, v86, v2, s27
	s_waitcnt lgkmcnt(0)
	v_bfe_u32 v55, v88, 16, 1
	v_lshrrev_b32_e32 v2, 16, v2
	v_add3_u32 v55, v88, v55, s27
	v_and_or_b32 v73, v55, s28, v2
	v_or_b32_e32 v2, s8, v65
	v_mul_u32_u24_e32 v2, 0x1600, v2
	v_lshlrev_b32_e32 v2, 1, v2
	v_lshl_add_u64 v[90:91], v[56:57], 0, v[2:3]
	v_bfe_u32 v2, v75, 16, 1
	v_add3_u32 v2, v75, v2, s27
	v_bfe_u32 v55, v77, 16, 1
	v_lshrrev_b32_e32 v2, 16, v2
	v_add3_u32 v55, v77, v55, s27
	global_store_dwordx4 v[90:91], v[70:73], off
	ds_read2_b32 v[74:75], v61 offset0:48 offset1:56
	s_nop 0
	v_and_or_b32 v70, v55, s28, v2
	v_bfe_u32 v2, v79, 16, 1
	v_add3_u32 v2, v79, v2, s27
	v_bfe_u32 v55, v81, 16, 1
	v_lshrrev_b32_e32 v2, 16, v2
	v_add3_u32 v55, v81, v55, s27
	v_and_or_b32 v71, v55, s28, v2
	v_bfe_u32 v2, v83, 16, 1
	v_add3_u32 v2, v83, v2, s27
	v_bfe_u32 v55, v85, 16, 1
	v_lshrrev_b32_e32 v2, 16, v2
	v_add3_u32 v55, v85, v55, s27
	v_and_or_b32 v72, v55, s28, v2
	v_bfe_u32 v2, v87, 16, 1
	v_add3_u32 v2, v87, v2, s27
	v_bfe_u32 v55, v89, 16, 1
	v_lshrrev_b32_e32 v2, 16, v2
	v_add3_u32 v55, v89, v55, s27
	v_and_or_b32 v73, v55, s28, v2
	v_or_b32_e32 v2, s8, v66
	v_mul_u32_u24_e32 v2, 0x1600, v2
	v_lshlrev_b32_e32 v2, 1, v2
	v_lshl_add_u64 v[76:77], v[56:57], 0, v[2:3]
	global_store_dwordx4 v[76:77], v[70:73], off
	ds_read2_b32 v[76:77], v61 offset0:113 offset1:121
	ds_read2_b32 v[78:79], v61 offset0:178 offset1:186
	ds_read2_b32 v[80:81], v61 offset0:243 offset1:251
	s_waitcnt lgkmcnt(3)
	v_bfe_u32 v2, v74, 16, 1
	v_add3_u32 v2, v74, v2, s27
	s_waitcnt lgkmcnt(2)
	v_bfe_u32 v55, v76, 16, 1
	ds_read2_b32 v[82:83], v53 offset0:52 offset1:60
	v_lshrrev_b32_e32 v2, 16, v2
	v_add3_u32 v55, v76, v55, s27
	ds_read2_b32 v[84:85], v53 offset0:117 offset1:125
	v_and_or_b32 v70, v55, s28, v2
	s_waitcnt lgkmcnt(3)
	v_bfe_u32 v2, v78, 16, 1
	v_add3_u32 v2, v78, v2, s27
	s_waitcnt lgkmcnt(2)
	v_bfe_u32 v55, v80, 16, 1
	ds_read2_b32 v[86:87], v53 offset0:182 offset1:190
	v_lshrrev_b32_e32 v2, 16, v2
	v_add3_u32 v55, v80, v55, s27
	ds_read2_b32 v[88:89], v53 offset0:247 offset1:255
	v_and_or_b32 v71, v55, s28, v2
	s_waitcnt lgkmcnt(3)
	v_bfe_u32 v2, v82, 16, 1
	v_add3_u32 v2, v82, v2, s27
	s_waitcnt lgkmcnt(2)
	v_bfe_u32 v55, v84, 16, 1
	v_lshrrev_b32_e32 v2, 16, v2
	v_add3_u32 v55, v84, v55, s27
	v_and_or_b32 v72, v55, s28, v2
	s_waitcnt lgkmcnt(1)
	v_bfe_u32 v2, v86, 16, 1
	v_add3_u32 v2, v86, v2, s27
	s_waitcnt lgkmcnt(0)
	v_bfe_u32 v53, v88, 16, 1
	v_lshrrev_b32_e32 v2, 16, v2
	v_add3_u32 v53, v88, v53, s27
	v_and_or_b32 v73, v53, s28, v2
	v_or_b32_e32 v2, s8, v67
	v_mul_u32_u24_e32 v2, 0x1600, v2
	v_lshlrev_b32_e32 v2, 1, v2
	v_lshl_add_u64 v[90:91], v[56:57], 0, v[2:3]
	v_bfe_u32 v2, v75, 16, 1
	v_add3_u32 v2, v75, v2, s27
	v_bfe_u32 v53, v77, 16, 1
	v_lshrrev_b32_e32 v2, 16, v2
	v_add3_u32 v53, v77, v53, s27
	global_store_dwordx4 v[90:91], v[70:73], off
	s_nop 1
	v_and_or_b32 v70, v53, s28, v2
	v_bfe_u32 v2, v79, 16, 1
	v_add3_u32 v2, v79, v2, s27
	v_bfe_u32 v53, v81, 16, 1
	v_lshrrev_b32_e32 v2, 16, v2
	v_add3_u32 v53, v81, v53, s27
	v_and_or_b32 v71, v53, s28, v2
	v_bfe_u32 v2, v83, 16, 1
	v_add3_u32 v2, v83, v2, s27
	v_bfe_u32 v53, v85, 16, 1
	v_lshrrev_b32_e32 v2, 16, v2
	v_add3_u32 v53, v85, v53, s27
	v_and_or_b32 v72, v53, s28, v2
	v_bfe_u32 v2, v87, 16, 1
	v_add3_u32 v2, v87, v2, s27
	v_bfe_u32 v53, v89, 16, 1
	v_lshrrev_b32_e32 v2, 16, v2
	v_add3_u32 v53, v89, v53, s27
	v_and_or_b32 v73, v53, s28, v2
	v_or_b32_e32 v2, s8, v68
	v_mul_u32_u24_e32 v2, 0x1600, v2
	v_lshlrev_b32_e32 v2, 1, v2
	v_lshl_add_u64 v[56:57], v[56:57], 0, v[2:3]
	global_store_dwordx4 v[56:57], v[70:73], off
	s_waitcnt lgkmcnt(0)

; DI void transpose_item(const float* W, int K, int N, bf16_t* WT, int mode, float* scr, int item, int lane) {
;     ...
;     else if (mode == 2) { drow0 = n0 < DFF ? (n0 / 128) * 256 + (n0 % 128) : ((n0 - DFF) / 128) * 256 + 128 + ((n0 - DFF) % 128); }
;     ...
;     f32x4 v[16];
; #pragma unroll
;     for (int i = 0; i < 16; ++i) v[i] = __builtin_nontemporal_load((const f32x4*)(W + (size_t)(k0 + 4 * i + (lane >> 4)) * N + n0 + 4 * (lane & 15)));
; #pragma unroll
;     for (int i = 0; i < 16; ++i) { float* d = scr + (4 * i + (lane >> 4)) * 65 + 4 * (lane & 15); d[0] = v[i][0]; d[1] = v[i][1]; d[2] = v[i][2]; d[3] = v[i][3]; }
;     __builtin_amdgcn_s_waitcnt(0); __builtin_amdgcn_wave_barrier();
;     const int c = lane & 7;
; #pragma unroll
;     for (int j = 0; j < 8; ++j) { const int n = (lane >> 3) + 8 * j; const float* sp = scr + (8 * c) * 65 + n;
.LBB0_280:
	s_lshl_b32 s6, s6, 6
	s_and_b32 s8, s6, 0x7fc0
	v_or_b32_e32 v2, s8, v58
	s_lshl_b32 s6, s49, 2
	v_mul_u32_u24_e32 v2, 0x2c00, v2
	v_lshl_add_u64 v[56:57], v[32:33], 0, s[6:7]
	v_lshlrev_b32_e32 v2, 2, v2
	v_lshl_add_u64 v[56:57], v[56:57], 0, v[2:3]
	v_add_co_u32_e32 v74, vcc, 0x2c000, v56
	v_add_u32_e32 v2, 0x410, v59
	s_nop 0
	v_addc_co_u32_e32 v75, vcc, 0, v57, vcc
	v_add_co_u32_e32 v78, vcc, s29, v56
	global_load_dwordx4 v[70:73], v[56:57], off nt
	s_nop 0
	global_load_dwordx4 v[74:77], v[74:75], off nt
	v_addc_co_u32_e32 v79, vcc, 0, v57, vcc
	v_add_co_u32_e32 v82, vcc, 0x84000, v56
	s_lshl_b32 s6, s8, 1
	s_nop 0
	v_addc_co_u32_e32 v83, vcc, 0, v57, vcc
	global_load_dwordx4 v[78:81], v[78:79], off nt
	s_nop 0
	global_load_dwordx4 v[82:85], v[82:83], off nt
	v_add_co_u32_e32 v86, vcc, 0xb0000, v56
	s_nop 1
	v_addc_co_u32_e32 v87, vcc, 0, v57, vcc
	v_add_co_u32_e32 v90, vcc, 0xdc000, v56
	s_nop 1
	v_addc_co_u32_e32 v91, vcc, 0, v57, vcc
	global_load_dwordx4 v[86:89], v[86:87], off nt
	s_nop 0
	global_load_dwordx4 v[90:93], v[90:91], off nt
	v_add_co_u32_e32 v94, vcc, 0x108000, v56
	s_nop 1
	v_addc_co_u32_e32 v95, vcc, 0, v57, vcc
	v_add_co_u32_e32 v98, vcc, 0x134000, v56
	s_nop 1
	v_addc_co_u32_e32 v99, vcc, 0, v57, vcc
	global_load_dwordx4 v[94:97], v[94:95], off nt
	s_nop 0
	global_load_dwordx4 v[98:101], v[98:99], off nt
	v_add_co_u32_e32 v102, vcc, 0x160000, v56
	s_nop 1
	v_addc_co_u32_e32 v103, vcc, 0, v57, vcc
	v_add_co_u32_e32 v106, vcc, 0x18c000, v56
	s_nop 1
	v_addc_co_u32_e32 v107, vcc, 0, v57, vcc
	global_load_dwordx4 v[102:105], v[102:103], off nt
	s_nop 0
	global_load_dwordx4 v[106:109], v[106:107], off nt
	v_add_co_u32_e32 v110, vcc, 0x1b8000, v56
	s_nop 1
	v_addc_co_u32_e32 v111, vcc, 0, v57, vcc
	v_add_co_u32_e32 v114, vcc, 0x1e4000, v56
	s_nop 1
	v_addc_co_u32_e32 v115, vcc, 0, v57, vcc
	global_load_dwordx4 v[110:113], v[110:111], off nt
	s_nop 0
	global_load_dwordx4 v[114:117], v[114:115], off nt
	v_add_co_u32_e32 v118, vcc, 0x210000, v56
	s_nop 1
	v_addc_co_u32_e32 v119, vcc, 0, v57, vcc
	v_add_co_u32_e32 v122, vcc, 0x23c000, v56
	s_nop 1
	v_addc_co_u32_e32 v123, vcc, 0, v57, vcc
	global_load_dwordx4 v[118:121], v[118:119], off nt
	s_nop 0
	global_load_dwordx4 v[122:125], v[122:123], off nt
	v_add_co_u32_e32 v126, vcc, 0x268000, v56
	s_nop 1
	v_addc_co_u32_e32 v127, vcc, 0, v57, vcc
	global_load_dwordx4 v[126:129], v[126:127], off nt
	v_add_co_u32_e32 v56, vcc, 0x294000, v56
	s_nop 1
	v_addc_co_u32_e32 v57, vcc, 0, v57, vcc
	global_load_dwordx4 v[130:133], v[56:57], off nt
	s_waitcnt vmcnt(0)
	ds_write2_b32 v59, v70, v71 offset1:1
	ds_write2_b32 v59, v72, v73 offset0:2 offset1:3
	ds_write2_b32 v2, v74, v75 offset1:1
	v_add_u32_e32 v2, 0x418, v59
	ds_write2_b32 v2, v76, v77 offset1:1
	v_add_u32_e32 v2, 0x820, v59
	v_lshl_add_u64 v[56:57], v[34:35], 0, s[6:7]
	ds_write2_b32 v2, v78, v79 offset1:1
	v_add_u32_e32 v2, 0x828, v59
	ds_write2_b32 v2, v80, v81 offset1:1
	v_add_u32_e32 v2, 0xc30, v59
	ds_write2_b32 v2, v82, v83 offset1:1
	v_add_u32_e32 v2, 0xc38, v59
	ds_write2_b32 v2, v84, v85 offset1:1
	v_add_u32_e32 v2, 0x1040, v59
	ds_write2_b32 v2, v86, v87 offset1:1
	v_add_u32_e32 v2, 0x1048, v59
	ds_write2_b32 v2, v88, v89 offset1:1
	v_add_u32_e32 v2, 0x1450, v59
	ds_write2_b32 v2, v90, v91 offset1:1
	v_add_u32_e32 v2, 0x1458, v59
	ds_write2_b32 v2, v92, v93 offset1:1
	v_add_u32_e32 v2, 0x1860, v59
	ds_write2_b32 v2, v94, v95 offset1:1
	v_add_u32_e32 v2, 0x1868, v59
	ds_write2_b32 v2, v96, v97 offset1:1
	v_add_u32_e32 v2, 0x1c70, v59
	ds_write2_b32 v2, v98, v99 offset1:1
	v_add_u32_e32 v2, 0x1c78, v59
	ds_write2_b32 v2, v100, v101 offset1:1
	v_add_u32_e32 v2, 0x2080, v59
	ds_write2_b32 v2, v102, v103 offset1:1
	v_add_u32_e32 v2, 0x2088, v59
	ds_write2_b32 v2, v104, v105 offset1:1
	v_add_u32_e32 v2, 0x2490, v59
	ds_write2_b32 v2, v106, v107 offset1:1
	v_add_u32_e32 v2, 0x2498, v59
	ds_write2_b32 v2, v108, v109 offset1:1
	v_add_u32_e32 v2, 0x28a0, v59
	ds_write2_b32 v2, v110, v111 offset1:1
	v_add_u32_e32 v2, 0x28a8, v59
	ds_write2_b32 v2, v112, v113 offset1:1
	v_add_u32_e32 v2, 0x2cb0, v59
	ds_write2_b32 v2, v114, v115 offset1:1
	v_add_u32_e32 v2, 0x2cb8, v59
	ds_write2_b32 v2, v116, v117 offset1:1
	v_add_u32_e32 v2, 0x30c0, v59
	ds_write2_b32 v2, v118, v119 offset1:1
	v_add_u32_e32 v2, 0x30c8, v59
	ds_write2_b32 v2, v120, v121 offset1:1
	v_add_u32_e32 v2, 0x34d0, v59
	ds_write2_b32 v2, v122, v123 offset1:1
	v_add_u32_e32 v2, 0x34d8, v59
	ds_write2_b32 v2, v124, v125 offset1:1
	v_add_u32_e32 v2, 0x38e0, v59
	ds_write2_b32 v2, v126, v127 offset1:1
	v_add_u32_e32 v2, 0x38e8, v59
	ds_write2_b32 v2, v128, v129 offset1:1
	v_add_u32_e32 v2, 0x3cf0, v59
	ds_write2_b32 v2, v130, v131 offset1:1
	v_add_u32_e32 v2, 0x3cf8, v59
	ds_write2_b32 v2, v132, v133 offset1:1
	s_waitcnt vmcnt(0) expcnt(0) lgkmcnt(0)
	ds_read2_b32 v[74:75], v61 offset1:8
	ds_read2_b32 v[76:77], v61 offset0:65 offset1:73
	ds_read2_b32 v[78:79], v61 offset0:130 offset1:138
	ds_read2_b32 v[80:81], v61 offset0:195 offset1:203
	s_waitcnt lgkmcnt(3)
	v_bfe_u32 v2, v74, 16, 1
	v_add3_u32 v2, v74, v2, s27
	s_waitcnt lgkmcnt(2)
	v_bfe_u32 v53, v76, 16, 1
	v_lshrrev_b32_e32 v2, 16, v2
	v_add3_u32 v53, v76, v53, s27
	v_and_or_b32 v70, v53, s28, v2
	v_add_u32_e32 v53, 0x400, v61
	ds_read2_b32 v[82:83], v53 offset0:4 offset1:12
	ds_read2_b32 v[84:85], v53 offset0:69 offset1:77
	s_waitcnt lgkmcnt(3)
	v_bfe_u32 v2, v78, 16, 1
	v_add3_u32 v2, v78, v2, s27
	s_waitcnt lgkmcnt(2)
	v_bfe_u32 v55, v80, 16, 1
	ds_read2_b32 v[86:87], v53 offset0:134 offset1:142
	v_lshrrev_b32_e32 v2, 16, v2
	v_add3_u32 v55, v80, v55, s27
	ds_read2_b32 v[88:89], v53 offset0:199 offset1:207
	v_and_or_b32 v71, v55, s28, v2
	s_waitcnt lgkmcnt(3)
; DI unsigned pk2w(float lo, float hi) { return f2bfw(lo) | (f2bfw(hi) << 16); }
; DI void transpose_item(const float* W, int K, int N, bf16_t* WT, int mode, float* scr, int item, int lane) {
;     ...
;     const int c = lane & 7;
; #pragma unroll
;     for (int j = 0; j < 8; ++j) { const int n = (lane >> 3) + 8 * j; const float* sp = scr + (8 * c) * 65 + n;
;         u32x4 o; o.x = pk2w(sp[0 * 65], sp[1 * 65]); o.y = pk2w(sp[2 * 65], sp[3 * 65]); o.z = pk2w(sp[4 * 65], sp[5 * 65]); o.w = pk2w(sp[6 * 65], sp[7 * 65]);
;         *(u32x4*)(WT + (size_t)(drow0 + n) * K + k0 + 8 * c) = o; }
;     __builtin_amdgcn_s_waitcnt(0); __builtin_amdgcn_wave_barrier();
	v_bfe_u32 v2, v82, 16, 1
	v_add3_u32 v2, v82, v2, s27
	s_waitcnt lgkmcnt(2)
	v_bfe_u32 v55, v84, 16, 1
	v_lshrrev_b32_e32 v2, 16, v2
	v_add3_u32 v55, v84, v55, s27
	v_and_or_b32 v72, v55, s28, v2
	s_waitcnt lgkmcnt(1)
	v_bfe_u32 v2, v86, 16, 1
	v_add3_u32 v2, v86, v2, s27
	s_waitcnt lgkmcnt(0)
	v_bfe_u32 v55, v88, 16, 1
	v_lshrrev_b32_e32 v2, 16, v2
	v_add3_u32 v55, v88, v55, s27
	v_and_or_b32 v73, v55, s28, v2
	v_add_u32_e32 v2, s48, v60
	v_lshlrev_b64 v[90:91], 12, v[2:3]
	v_bfe_u32 v2, v75, 16, 1
	v_add3_u32 v2, v75, v2, s27
	v_bfe_u32 v55, v77, 16, 1
	v_lshl_add_u64 v[90:91], v[56:57], 0, v[90:91]
	v_lshrrev_b32_e32 v2, 16, v2
	v_add3_u32 v55, v77, v55, s27
	global_store_dwordx4 v[90:91], v[70:73], off
	ds_read2_b32 v[74:75], v61 offset0:16 offset1:24
	s_nop 0
	v_and_or_b32 v70, v55, s28, v2
	v_bfe_u32 v2, v79, 16, 1
	v_add3_u32 v2, v79, v2, s27
	v_bfe_u32 v55, v81, 16, 1
	v_lshrrev_b32_e32 v2, 16, v2
	v_add3_u32 v55, v81, v55, s27
	v_and_or_b32 v71, v55, s28, v2
	v_bfe_u32 v2, v83, 16, 1
	v_add3_u32 v2, v83, v2, s27
	v_bfe_u32 v55, v85, 16, 1
	v_lshrrev_b32_e32 v2, 16, v2
	v_add3_u32 v55, v85, v55, s27
	v_and_or_b32 v72, v55, s28, v2
	v_bfe_u32 v2, v87, 16, 1
	v_add3_u32 v2, v87, v2, s27
	v_bfe_u32 v55, v89, 16, 1
	v_lshrrev_b32_e32 v2, 16, v2
	v_add3_u32 v55, v89, v55, s27
	v_and_or_b32 v73, v55, s28, v2
	v_add_u32_e32 v2, s48, v62
	v_lshlrev_b64 v[76:77], 12, v[2:3]
	v_lshl_add_u64 v[76:77], v[56:57], 0, v[76:77]
	global_store_dwordx4 v[76:77], v[70:73], off
	ds_read2_b32 v[76:77], v61 offset0:81 offset1:89
	ds_read2_b32 v[78:79], v61 offset0:146 offset1:154
	ds_read2_b32 v[80:81], v61 offset0:211 offset1:219
	s_waitcnt lgkmcnt(3)
	v_bfe_u32 v2, v74, 16, 1
	v_add3_u32 v2, v74, v2, s27
	s_waitcnt lgkmcnt(2)
	v_bfe_u32 v55, v76, 16, 1
	ds_read2_b32 v[82:83], v53 offset0:20 offset1:28
	v_lshrrev_b32_e32 v2, 16, v2
	v_add3_u32 v55, v76, v55, s27
	ds_read2_b32 v[84:85], v53 offset0:85 offset1:93
	v_and_or_b32 v70, v55, s28, v2
	s_waitcnt lgkmcnt(3)
	v_bfe_u32 v2, v78, 16, 1
	v_add3_u32 v2, v78, v2, s27
	s_waitcnt lgkmcnt(2)
	v_bfe_u32 v55, v80, 16, 1
	ds_read2_b32 v[86:87], v53 offset0:150 offset1:158
	v_lshrrev_b32_e32 v2, 16, v2
	v_add3_u32 v55, v80, v55, s27
	ds_read2_b32 v[88:89], v53 offset0:215 offset1:223
	v_and_or_b32 v71, v55, s28, v2
	s_waitcnt lgkmcnt(3)
	v_bfe_u32 v2, v82, 16, 1
	v_add3_u32 v2, v82, v2, s27
	s_waitcnt lgkmcnt(2)
	v_bfe_u32 v55, v84, 16, 1
	v_lshrrev_b32_e32 v2, 16, v2
	v_add3_u32 v55, v84, v55, s27
	v_and_or_b32 v72, v55, s28, v2
	s_waitcnt lgkmcnt(1)
	v_bfe_u32 v2, v86, 16, 1
	v_add3_u32 v2, v86, v2, s27
	s_waitcnt lgkmcnt(0)
	v_bfe_u32 v55, v88, 16, 1
	v_lshrrev_b32_e32 v2, 16, v2
	v_add3_u32 v55, v88, v55, s27
	v_and_or_b32 v73, v55, s28, v2
	v_add_u32_e32 v2, s48, v63
	v_lshlrev_b64 v[90:91], 12, v[2:3]
	v_bfe_u32 v2, v75, 16, 1
	v_add3_u32 v2, v75, v2, s27
	v_bfe_u32 v55, v77, 16, 1
	v_lshl_add_u64 v[90:91], v[56:57], 0, v[90:91]
	v_lshrrev_b32_e32 v2, 16, v2
	v_add3_u32 v55, v77, v55, s27
	global_store_dwordx4 v[90:91], v[70:73], off
	ds_read2_b32 v[74:75], v61 offset0:32 offset1:40
	s_nop 0
	v_and_or_b32 v70, v55, s28, v2
	v_bfe_u32 v2, v79, 16, 1
	v_add3_u32 v2, v79, v2, s27
	v_bfe_u32 v55, v81, 16, 1
	v_lshrrev_b32_e32 v2, 16, v2
	v_add3_u32 v55, v81, v55, s27
	v_and_or_b32 v71, v55, s28, v2
	v_bfe_u32 v2, v83, 16, 1
	v_add3_u32 v2, v83, v2, s27
	v_bfe_u32 v55, v85, 16, 1
	v_lshrrev_b32_e32 v2, 16, v2
	v_add3_u32 v55, v85, v55, s27
	v_and_or_b32 v72, v55, s28, v2
	v_bfe_u32 v2, v87, 16, 1
	v_add3_u32 v2, v87, v2, s27
	v_bfe_u32 v55, v89, 16, 1
	v_lshrrev_b32_e32 v2, 16, v2
	v_add3_u32 v55, v89, v55, s27
	v_and_or_b32 v73, v55, s28, v2
	v_add_u32_e32 v2, s48, v64
	v_lshlrev_b64 v[76:77], 12, v[2:3]
	v_lshl_add_u64 v[76:77], v[56:57], 0, v[76:77]
	global_store_dwordx4 v[76:77], v[70:73], off
	ds_read2_b32 v[76:77], v61 offset0:97 offset1:105
	ds_read2_b32 v[78:79], v61 offset0:162 offset1:170
	ds_read2_b32 v[80:81], v61 offset0:227 offset1:235
	s_waitcnt lgkmcnt(3)
	v_bfe_u32 v2, v74, 16, 1
	v_add3_u32 v2, v74, v2, s27
	s_waitcnt lgkmcnt(2)
	v_bfe_u32 v55, v76, 16, 1
	ds_read2_b32 v[82:83], v53 offset0:36 offset1:44
	v_lshrrev_b32_e32 v2, 16, v2
	v_add3_u32 v55, v76, v55, s27
	ds_read2_b32 v[84:85], v53 offset0:101 offset1:109
	v_and_or_b32 v70, v55, s28, v2
	s_waitcnt lgkmcnt(3)
; DI unsigned pk2w(float lo, float hi) { return f2bfw(lo) | (f2bfw(hi) << 16); }
; DI void transpose_item(const float* W, int K, int N, bf16_t* WT, int mode, float* scr, int item, int lane) {
;     ...
;     const int c = lane & 7;
; #pragma unroll
;     for (int j = 0; j < 8; ++j) { const int n = (lane >> 3) + 8 * j; const float* sp = scr + (8 * c) * 65 + n;
;         u32x4 o; o.x = pk2w(sp[0 * 65], sp[1 * 65]); o.y = pk2w(sp[2 * 65], sp[3 * 65]); o.z = pk2w(sp[4 * 65], sp[5 * 65]); o.w = pk2w(sp[6 * 65], sp[7 * 65]);
;         *(u32x4*)(WT + (size_t)(drow0 + n) * K + k0 + 8 * c) = o; }
;     __builtin_amdgcn_s_waitcnt(0); __builtin_amdgcn_wave_barrier();
	v_bfe_u32 v2, v78, 16, 1
	v_add3_u32 v2, v78, v2, s27
	s_waitcnt lgkmcnt(2)
	v_bfe_u32 v55, v80, 16, 1
	ds_read2_b32 v[86:87], v53 offset0:166 offset1:174
	v_lshrrev_b32_e32 v2, 16, v2
	v_add3_u32 v55, v80, v55, s27
	ds_read2_b32 v[88:89], v53 offset0:231 offset1:239
	v_and_or_b32 v71, v55, s28, v2
	s_waitcnt lgkmcnt(3)
	v_bfe_u32 v2, v82, 16, 1
	v_add3_u32 v2, v82, v2, s27
	s_waitcnt lgkmcnt(2)
	v_bfe_u32 v55, v84, 16, 1
	v_lshrrev_b32_e32 v2, 16, v2
	v_add3_u32 v55, v84, v55, s27
	v_and_or_b32 v72, v55, s28, v2
	s_waitcnt lgkmcnt(1)
	v_bfe_u32 v2, v86, 16, 1
	v_add3_u32 v2, v86, v2, s27
	s_waitcnt lgkmcnt(0)
	v_bfe_u32 v55, v88, 16, 1
	v_lshrrev_b32_e32 v2, 16, v2
	v_add3_u32 v55, v88, v55, s27
	v_and_or_b32 v73, v55, s28, v2
	v_add_u32_e32 v2, s48, v65
	v_lshlrev_b64 v[90:91], 12, v[2:3]
	v_bfe_u32 v2, v75, 16, 1
	v_add3_u32 v2, v75, v2, s27
	v_bfe_u32 v55, v77, 16, 1
	v_lshl_add_u64 v[90:91], v[56:57], 0, v[90:91]
	v_lshrrev_b32_e32 v2, 16, v2
	v_add3_u32 v55, v77, v55, s27
	global_store_dwordx4 v[90:91], v[70:73], off
	ds_read2_b32 v[74:75], v61 offset0:48 offset1:56
	s_nop 0
	v_and_or_b32 v70, v55, s28, v2
	v_bfe_u32 v2, v79, 16, 1
	v_add3_u32 v2, v79, v2, s27
	v_bfe_u32 v55, v81, 16, 1
	v_lshrrev_b32_e32 v2, 16, v2
	v_add3_u32 v55, v81, v55, s27
	v_and_or_b32 v71, v55, s28, v2
	v_bfe_u32 v2, v83, 16, 1
	v_add3_u32 v2, v83, v2, s27
	v_bfe_u32 v55, v85, 16, 1
	v_lshrrev_b32_e32 v2, 16, v2
	v_add3_u32 v55, v85, v55, s27
	v_and_or_b32 v72, v55, s28, v2
	v_bfe_u32 v2, v87, 16, 1
	v_add3_u32 v2, v87, v2, s27
	v_bfe_u32 v55, v89, 16, 1
	v_lshrrev_b32_e32 v2, 16, v2
	v_add3_u32 v55, v89, v55, s27
	v_and_or_b32 v73, v55, s28, v2
	v_add_u32_e32 v2, s48, v66
	v_lshlrev_b64 v[76:77], 12, v[2:3]
	v_lshl_add_u64 v[76:77], v[56:57], 0, v[76:77]
	global_store_dwordx4 v[76:77], v[70:73], off
	ds_read2_b32 v[76:77], v61 offset0:113 offset1:121
	ds_read2_b32 v[78:79], v61 offset0:178 offset1:186
	ds_read2_b32 v[80:81], v61 offset0:243 offset1:251
	s_waitcnt lgkmcnt(3)
	v_bfe_u32 v2, v74, 16, 1
	v_add3_u32 v2, v74, v2, s27
	s_waitcnt lgkmcnt(2)
	v_bfe_u32 v55, v76, 16, 1
	ds_read2_b32 v[82:83], v53 offset0:52 offset1:60
	v_lshrrev_b32_e32 v2, 16, v2
	v_add3_u32 v55, v76, v55, s27
	ds_read2_b32 v[84:85], v53 offset0:117 offset1:125
	v_and_or_b32 v70, v55, s28, v2
	s_waitcnt lgkmcnt(3)
	v_bfe_u32 v2, v78, 16, 1
	v_add3_u32 v2, v78, v2, s27
	s_waitcnt lgkmcnt(2)
	v_bfe_u32 v55, v80, 16, 1
	ds_read2_b32 v[86:87], v53 offset0:182 offset1:190
	v_lshrrev_b32_e32 v2, 16, v2
	v_add3_u32 v55, v80, v55, s27
	ds_read2_b32 v[88:89], v53 offset0:247 offset1:255
	v_and_or_b32 v71, v55, s28, v2
	s_waitcnt lgkmcnt(3)
	v_bfe_u32 v2, v82, 16, 1
	v_add3_u32 v2, v82, v2, s27
	s_waitcnt lgkmcnt(2)
	v_bfe_u32 v55, v84, 16, 1
	v_lshrrev_b32_e32 v2, 16, v2
	v_add3_u32 v55, v84, v55, s27
	v_and_or_b32 v72, v55, s28, v2
	s_waitcnt lgkmcnt(1)
	v_bfe_u32 v2, v86, 16, 1
	v_add3_u32 v2, v86, v2, s27
	s_waitcnt lgkmcnt(0)
	v_bfe_u32 v53, v88, 16, 1
	v_lshrrev_b32_e32 v2, 16, v2
	v_add3_u32 v53, v88, v53, s27
	v_and_or_b32 v73, v53, s28, v2
	v_add_u32_e32 v2, s48, v67
	v_lshlrev_b64 v[90:91], 12, v[2:3]
	v_bfe_u32 v2, v75, 16, 1
	v_add3_u32 v2, v75, v2, s27
	v_bfe_u32 v53, v77, 16, 1
	v_lshl_add_u64 v[90:91], v[56:57], 0, v[90:91]
	v_lshrrev_b32_e32 v2, 16, v2
	v_add3_u32 v53, v77, v53, s27
	global_store_dwordx4 v[90:91], v[70:73], off
	s_nop 1
	v_and_or_b32 v70, v53, s28, v2
	v_bfe_u32 v2, v79, 16, 1
	v_add3_u32 v2, v79, v2, s27
	v_bfe_u32 v53, v81, 16, 1
	v_lshrrev_b32_e32 v2, 16, v2
	v_add3_u32 v53, v81, v53, s27
	v_and_or_b32 v71, v53, s28, v2
	v_bfe_u32 v2, v83, 16, 1
	v_add3_u32 v2, v83, v2, s27
	v_bfe_u32 v53, v85, 16, 1
	v_lshrrev_b32_e32 v2, 16, v2
	v_add3_u32 v53, v85, v53, s27
	v_and_or_b32 v72, v53, s28, v2
	v_bfe_u32 v2, v87, 16, 1
	v_add3_u32 v2, v87, v2, s27
	v_bfe_u32 v53, v89, 16, 1
	v_lshrrev_b32_e32 v2, 16, v2
	v_add3_u32 v53, v89, v53, s27
	v_and_or_b32 v73, v53, s28, v2
	v_add_u32_e32 v2, s48, v68
	v_lshlrev_b64 v[74:75], 12, v[2:3]
	v_lshl_add_u64 v[56:57], v[56:57], 0, v[74:75]
	global_store_dwordx4 v[56:57], v[70:73], off
	s_waitcnt lgkmcnt(0)

; DI void transpose_item(const float* W, int K, int N, bf16_t* WT, int mode, float* scr, int item, int lane) {
;     ...
;     f32x4 v[16];
; #pragma unroll
;     for (int i = 0; i < 16; ++i) v[i] = __builtin_nontemporal_load((const f32x4*)(W + (size_t)(k0 + 4 * i + (lane >> 4)) * N + n0 + 4 * (lane & 15)));
; #pragma unroll
;     for (int i = 0; i < 16; ++i) { float* d = scr + (4 * i + (lane >> 4)) * 65 + 4 * (lane & 15); d[0] = v[i][0]; d[1] = v[i][1]; d[2] = v[i][2]; d[3] = v[i][3]; }
;     __builtin_amdgcn_s_waitcnt(0); __builtin_amdgcn_wave_barrier();
;     const int c = lane & 7;
; #pragma unroll
;     for (int j = 0; j < 8; ++j) { const int n = (lane >> 3) + 8 * j; const float* sp = scr + (8 * c) * 65 + n;
.LBB0_282:
	s_andn2_b64 vcc, exec, s[8:9]
	s_cbranch_vccnz .LBB0_284
	s_add_i32 s6, s3, 0x4e00
	s_and_b32 s8, s16, 0x7c0
	s_and_b32 s9, s6, 0x1ffc0
	v_or_b32_e32 v2, s9, v58
	s_lshl_b32 s6, s8, 2
	v_lshl_add_u64 v[56:57], v[4:5], 0, s[6:7]
	v_lshlrev_b32_e32 v2, 13, v2
	v_lshl_add_u64 v[56:57], v[56:57], 0, v[2:3]
	v_add_co_u32_e32 v74, vcc, 0x8000, v56
	v_add_u32_e32 v2, 0x410, v59
	s_nop 0
	v_addc_co_u32_e32 v75, vcc, 0, v57, vcc
	v_add_co_u32_e32 v78, vcc, 0x10000, v56
	global_load_dwordx4 v[70:73], v[56:57], off nt
	s_nop 0
	global_load_dwordx4 v[74:77], v[74:75], off nt
	v_addc_co_u32_e32 v79, vcc, 0, v57, vcc
	v_add_co_u32_e32 v82, vcc, 0x18000, v56
	s_lshl_b32 s6, s9, 1
	s_nop 0
	v_addc_co_u32_e32 v83, vcc, 0, v57, vcc
	global_load_dwordx4 v[78:81], v[78:79], off nt
	s_nop 0
	global_load_dwordx4 v[82:85], v[82:83], off nt
	v_add_co_u32_e32 v86, vcc, 0x20000, v56
	s_nop 1
	v_addc_co_u32_e32 v87, vcc, 0, v57, vcc
	v_add_co_u32_e32 v90, vcc, 0x28000, v56
	s_nop 1
	v_addc_co_u32_e32 v91, vcc, 0, v57, vcc
	global_load_dwordx4 v[86:89], v[86:87], off nt
	s_nop 0
	global_load_dwordx4 v[90:93], v[90:91], off nt
	v_add_co_u32_e32 v94, vcc, 0x30000, v56
	s_nop 1
	v_addc_co_u32_e32 v95, vcc, 0, v57, vcc
	v_add_co_u32_e32 v98, vcc, 0x38000, v56
	s_nop 1
	v_addc_co_u32_e32 v99, vcc, 0, v57, vcc
	global_load_dwordx4 v[94:97], v[94:95], off nt
	s_nop 0
	global_load_dwordx4 v[98:101], v[98:99], off nt
	v_add_co_u32_e32 v102, vcc, 0x40000, v56
	s_nop 1
	v_addc_co_u32_e32 v103, vcc, 0, v57, vcc
	v_add_co_u32_e32 v106, vcc, 0x48000, v56
	s_nop 1
	v_addc_co_u32_e32 v107, vcc, 0, v57, vcc
	global_load_dwordx4 v[102:105], v[102:103], off nt
	s_nop 0
	global_load_dwordx4 v[106:109], v[106:107], off nt
	v_add_co_u32_e32 v110, vcc, 0x50000, v56
	s_nop 1
	v_addc_co_u32_e32 v111, vcc, 0, v57, vcc
	v_add_co_u32_e32 v114, vcc, 0x58000, v56
	s_nop 1
	v_addc_co_u32_e32 v115, vcc, 0, v57, vcc
	global_load_dwordx4 v[110:113], v[110:111], off nt
	s_nop 0
	global_load_dwordx4 v[114:117], v[114:115], off nt
	v_add_co_u32_e32 v118, vcc, 0x60000, v56
	s_nop 1
	v_addc_co_u32_e32 v119, vcc, 0, v57, vcc
	v_add_co_u32_e32 v122, vcc, 0x68000, v56
	s_nop 1
	v_addc_co_u32_e32 v123, vcc, 0, v57, vcc
	global_load_dwordx4 v[118:121], v[118:119], off nt
	s_nop 0
	global_load_dwordx4 v[122:125], v[122:123], off nt
	v_add_co_u32_e32 v126, vcc, 0x70000, v56
	s_nop 1
	v_addc_co_u32_e32 v127, vcc, 0, v57, vcc
	global_load_dwordx4 v[126:129], v[126:127], off nt
	v_add_co_u32_e32 v56, vcc, 0x78000, v56
	s_nop 1
	v_addc_co_u32_e32 v57, vcc, 0, v57, vcc
	global_load_dwordx4 v[130:133], v[56:57], off nt
	s_waitcnt vmcnt(0)
	ds_write2_b32 v59, v70, v71 offset1:1
	ds_write2_b32 v59, v72, v73 offset0:2 offset1:3
	ds_write2_b32 v2, v74, v75 offset1:1
	v_add_u32_e32 v2, 0x418, v59
	ds_write2_b32 v2, v76, v77 offset1:1
	v_add_u32_e32 v2, 0x820, v59
	v_lshl_add_u64 v[56:57], v[36:37], 0, s[6:7]
	ds_write2_b32 v2, v78, v79 offset1:1
	v_add_u32_e32 v2, 0x828, v59
	ds_write2_b32 v2, v80, v81 offset1:1
	v_add_u32_e32 v2, 0xc30, v59
	ds_write2_b32 v2, v82, v83 offset1:1
	v_add_u32_e32 v2, 0xc38, v59
	ds_write2_b32 v2, v84, v85 offset1:1
	v_add_u32_e32 v2, 0x1040, v59
	ds_write2_b32 v2, v86, v87 offset1:1
	v_add_u32_e32 v2, 0x1048, v59
	ds_write2_b32 v2, v88, v89 offset1:1
	v_add_u32_e32 v2, 0x1450, v59
	ds_write2_b32 v2, v90, v91 offset1:1
	v_add_u32_e32 v2, 0x1458, v59
	ds_write2_b32 v2, v92, v93 offset1:1
	v_add_u32_e32 v2, 0x1860, v59
	ds_write2_b32 v2, v94, v95 offset1:1
	v_add_u32_e32 v2, 0x1868, v59
	ds_write2_b32 v2, v96, v97 offset1:1
	v_add_u32_e32 v2, 0x1c70, v59
	ds_write2_b32 v2, v98, v99 offset1:1
	v_add_u32_e32 v2, 0x1c78, v59
	ds_write2_b32 v2, v100, v101 offset1:1
	v_add_u32_e32 v2, 0x2080, v59
	ds_write2_b32 v2, v102, v103 offset1:1
	v_add_u32_e32 v2, 0x2088, v59
	ds_write2_b32 v2, v104, v105 offset1:1
	v_add_u32_e32 v2, 0x2490, v59
	ds_write2_b32 v2, v106, v107 offset1:1
	v_add_u32_e32 v2, 0x2498, v59
	ds_write2_b32 v2, v108, v109 offset1:1
	v_add_u32_e32 v2, 0x28a0, v59
	ds_write2_b32 v2, v110, v111 offset1:1
	v_add_u32_e32 v2, 0x28a8, v59
	ds_write2_b32 v2, v112, v113 offset1:1
	v_add_u32_e32 v2, 0x2cb0, v59
	ds_write2_b32 v2, v114, v115 offset1:1
	v_add_u32_e32 v2, 0x2cb8, v59
	ds_write2_b32 v2, v116, v117 offset1:1
	v_add_u32_e32 v2, 0x30c0, v59
	ds_write2_b32 v2, v118, v119 offset1:1
	v_add_u32_e32 v2, 0x30c8, v59
	ds_write2_b32 v2, v120, v121 offset1:1
	v_add_u32_e32 v2, 0x34d0, v59
	ds_write2_b32 v2, v122, v123 offset1:1
	v_add_u32_e32 v2, 0x34d8, v59
	ds_write2_b32 v2, v124, v125 offset1:1
	v_add_u32_e32 v2, 0x38e0, v59
	ds_write2_b32 v2, v126, v127 offset1:1
	v_add_u32_e32 v2, 0x38e8, v59
	ds_write2_b32 v2, v128, v129 offset1:1
	v_add_u32_e32 v2, 0x3cf0, v59
	ds_write2_b32 v2, v130, v131 offset1:1
	v_add_u32_e32 v2, 0x3cf8, v59
	ds_write2_b32 v2, v132, v133 offset1:1
	s_waitcnt vmcnt(0) expcnt(0) lgkmcnt(0)
	ds_read2_b32 v[74:75], v61 offset1:8
	ds_read2_b32 v[76:77], v61 offset0:65 offset1:73
	ds_read2_b32 v[78:79], v61 offset0:130 offset1:138
	ds_read2_b32 v[80:81], v61 offset0:195 offset1:203
	s_waitcnt lgkmcnt(3)
	v_bfe_u32 v2, v74, 16, 1
	v_add3_u32 v2, v74, v2, s27
	s_waitcnt lgkmcnt(2)
	v_bfe_u32 v53, v76, 16, 1
	v_lshrrev_b32_e32 v2, 16, v2
	v_add3_u32 v53, v76, v53, s27
	v_and_or_b32 v70, v53, s28, v2
	v_add_u32_e32 v53, 0x400, v61
	ds_read2_b32 v[82:83], v53 offset0:4 offset1:12
	ds_read2_b32 v[84:85], v53 offset0:69 offset1:77
	s_waitcnt lgkmcnt(3)
	v_bfe_u32 v2, v78, 16, 1
	v_add3_u32 v2, v78, v2, s27
	s_waitcnt lgkmcnt(2)
	v_bfe_u32 v55, v80, 16, 1
	ds_read2_b32 v[86:87], v53 offset0:134 offset1:142
	v_lshrrev_b32_e32 v2, 16, v2
	v_add3_u32 v55, v80, v55, s27
	ds_read2_b32 v[88:89], v53 offset0:199 offset1:207
	v_and_or_b32 v71, v55, s28, v2
	s_waitcnt lgkmcnt(3)
; DI unsigned pk2w(float lo, float hi) { return f2bfw(lo) | (f2bfw(hi) << 16); }
; DI void transpose_item(const float* W, int K, int N, bf16_t* WT, int mode, float* scr, int item, int lane) {
;     ...
;     const int c = lane & 7;
; #pragma unroll
;     for (int j = 0; j < 8; ++j) { const int n = (lane >> 3) + 8 * j; const float* sp = scr + (8 * c) * 65 + n;
;         u32x4 o; o.x = pk2w(sp[0 * 65], sp[1 * 65]); o.y = pk2w(sp[2 * 65], sp[3 * 65]); o.z = pk2w(sp[4 * 65], sp[5 * 65]); o.w = pk2w(sp[6 * 65], sp[7 * 65]);
;         *(u32x4*)(WT + (size_t)(drow0 + n) * K + k0 + 8 * c) = o; }
;     __builtin_amdgcn_s_waitcnt(0); __builtin_amdgcn_wave_barrier();
	v_bfe_u32 v2, v82, 16, 1
	v_add3_u32 v2, v82, v2, s27
	s_waitcnt lgkmcnt(2)
	v_bfe_u32 v55, v84, 16, 1
	v_lshrrev_b32_e32 v2, 16, v2
	v_add3_u32 v55, v84, v55, s27
	v_and_or_b32 v72, v55, s28, v2
	s_waitcnt lgkmcnt(1)
	v_bfe_u32 v2, v86, 16, 1
	v_add3_u32 v2, v86, v2, s27
	s_waitcnt lgkmcnt(0)
	v_bfe_u32 v55, v88, 16, 1
	v_lshrrev_b32_e32 v2, 16, v2
	v_add3_u32 v55, v88, v55, s27
	v_and_or_b32 v73, v55, s28, v2
	v_or_b32_e32 v2, s8, v60
	v_mul_u32_u24_e32 v2, 0xb00, v2
	v_lshlrev_b32_e32 v2, 1, v2
	v_lshl_add_u64 v[90:91], v[56:57], 0, v[2:3]
	v_bfe_u32 v2, v75, 16, 1
	v_add3_u32 v2, v75, v2, s27
	v_bfe_u32 v55, v77, 16, 1
	v_lshrrev_b32_e32 v2, 16, v2
	v_add3_u32 v55, v77, v55, s27
	global_store_dwordx4 v[90:91], v[70:73], off
	ds_read2_b32 v[74:75], v61 offset0:16 offset1:24
	s_nop 0
	v_and_or_b32 v70, v55, s28, v2
	v_bfe_u32 v2, v79, 16, 1
	v_add3_u32 v2, v79, v2, s27
	v_bfe_u32 v55, v81, 16, 1
	v_lshrrev_b32_e32 v2, 16, v2
	v_add3_u32 v55, v81, v55, s27
	v_and_or_b32 v71, v55, s28, v2
	v_bfe_u32 v2, v83, 16, 1
	v_add3_u32 v2, v83, v2, s27
	v_bfe_u32 v55, v85, 16, 1
	v_lshrrev_b32_e32 v2, 16, v2
	v_add3_u32 v55, v85, v55, s27
	v_and_or_b32 v72, v55, s28, v2
	v_bfe_u32 v2, v87, 16, 1
	v_add3_u32 v2, v87, v2, s27
	v_bfe_u32 v55, v89, 16, 1
	v_lshrrev_b32_e32 v2, 16, v2
	v_add3_u32 v55, v89, v55, s27
	v_and_or_b32 v73, v55, s28, v2
	v_or_b32_e32 v2, s8, v62
	v_mul_u32_u24_e32 v2, 0xb00, v2
	v_lshlrev_b32_e32 v2, 1, v2
	v_lshl_add_u64 v[76:77], v[56:57], 0, v[2:3]
	global_store_dwordx4 v[76:77], v[70:73], off
	ds_read2_b32 v[76:77], v61 offset0:81 offset1:89
	ds_read2_b32 v[78:79], v61 offset0:146 offset1:154
	ds_read2_b32 v[80:81], v61 offset0:211 offset1:219
	s_waitcnt lgkmcnt(3)
	v_bfe_u32 v2, v74, 16, 1
	v_add3_u32 v2, v74, v2, s27
	s_waitcnt lgkmcnt(2)
	v_bfe_u32 v55, v76, 16, 1
	ds_read2_b32 v[82:83], v53 offset0:20 offset1:28
	v_lshrrev_b32_e32 v2, 16, v2
	v_add3_u32 v55, v76, v55, s27
	ds_read2_b32 v[84:85], v53 offset0:85 offset1:93
	v_and_or_b32 v70, v55, s28, v2
	s_waitcnt lgkmcnt(3)
	v_bfe_u32 v2, v78, 16, 1
	v_add3_u32 v2, v78, v2, s27
	s_waitcnt lgkmcnt(2)
	v_bfe_u32 v55, v80, 16, 1
	ds_read2_b32 v[86:87], v53 offset0:150 offset1:158
	v_lshrrev_b32_e32 v2, 16, v2
	v_add3_u32 v55, v80, v55, s27
	ds_read2_b32 v[88:89], v53 offset0:215 offset1:223
	v_and_or_b32 v71, v55, s28, v2
	s_waitcnt lgkmcnt(3)
	v_bfe_u32 v2, v82, 16, 1
	v_add3_u32 v2, v82, v2, s27
	s_waitcnt lgkmcnt(2)
	v_bfe_u32 v55, v84, 16, 1
	v_lshrrev_b32_e32 v2, 16, v2
	v_add3_u32 v55, v84, v55, s27
	v_and_or_b32 v72, v55, s28, v2
	s_waitcnt lgkmcnt(1)
	v_bfe_u32 v2, v86, 16, 1
	v_add3_u32 v2, v86, v2, s27
	s_waitcnt lgkmcnt(0)
	v_bfe_u32 v55, v88, 16, 1
	v_lshrrev_b32_e32 v2, 16, v2
	v_add3_u32 v55, v88, v55, s27
	v_and_or_b32 v73, v55, s28, v2
	v_or_b32_e32 v2, s8, v63
	v_mul_u32_u24_e32 v2, 0xb00, v2
	v_lshlrev_b32_e32 v2, 1, v2
	v_lshl_add_u64 v[90:91], v[56:57], 0, v[2:3]
	v_bfe_u32 v2, v75, 16, 1
	v_add3_u32 v2, v75, v2, s27
	v_bfe_u32 v55, v77, 16, 1
	v_lshrrev_b32_e32 v2, 16, v2
	v_add3_u32 v55, v77, v55, s27
	global_store_dwordx4 v[90:91], v[70:73], off
	ds_read2_b32 v[74:75], v61 offset0:32 offset1:40
	s_nop 0
	v_and_or_b32 v70, v55, s28, v2
	v_bfe_u32 v2, v79, 16, 1
	v_add3_u32 v2, v79, v2, s27
	v_bfe_u32 v55, v81, 16, 1
	v_lshrrev_b32_e32 v2, 16, v2
	v_add3_u32 v55, v81, v55, s27
	v_and_or_b32 v71, v55, s28, v2
	v_bfe_u32 v2, v83, 16, 1
	v_add3_u32 v2, v83, v2, s27
	v_bfe_u32 v55, v85, 16, 1
	v_lshrrev_b32_e32 v2, 16, v2
	v_add3_u32 v55, v85, v55, s27
	v_and_or_b32 v72, v55, s28, v2
	v_bfe_u32 v2, v87, 16, 1
	v_add3_u32 v2, v87, v2, s27
	v_bfe_u32 v55, v89, 16, 1
	v_lshrrev_b32_e32 v2, 16, v2
	v_add3_u32 v55, v89, v55, s27
	v_and_or_b32 v73, v55, s28, v2
	v_or_b32_e32 v2, s8, v64
	v_mul_u32_u24_e32 v2, 0xb00, v2
	v_lshlrev_b32_e32 v2, 1, v2
	v_lshl_add_u64 v[76:77], v[56:57], 0, v[2:3]
	global_store_dwordx4 v[76:77], v[70:73], off
	ds_read2_b32 v[76:77], v61 offset0:97 offset1:105
	ds_read2_b32 v[78:79], v61 offset0:162 offset1:170
	ds_read2_b32 v[80:81], v61 offset0:227 offset1:235
	s_waitcnt lgkmcnt(3)
	v_bfe_u32 v2, v74, 16, 1
	v_add3_u32 v2, v74, v2, s27
	s_waitcnt lgkmcnt(2)
	v_bfe_u32 v55, v76, 16, 1
	ds_read2_b32 v[82:83], v53 offset0:36 offset1:44
	v_lshrrev_b32_e32 v2, 16, v2
	v_add3_u32 v55, v76, v55, s27
	ds_read2_b32 v[84:85], v53 offset0:101 offset1:109
	v_and_or_b32 v70, v55, s28, v2
	s_waitcnt lgkmcnt(3)
; DI unsigned pk2w(float lo, float hi) { return f2bfw(lo) | (f2bfw(hi) << 16); }
; DI void transpose_item(const float* W, int K, int N, bf16_t* WT, int mode, float* scr, int item, int lane) {
;     ...
;     const int c = lane & 7;
; #pragma unroll
;     for (int j = 0; j < 8; ++j) { const int n = (lane >> 3) + 8 * j; const float* sp = scr + (8 * c) * 65 + n;
;         u32x4 o; o.x = pk2w(sp[0 * 65], sp[1 * 65]); o.y = pk2w(sp[2 * 65], sp[3 * 65]); o.z = pk2w(sp[4 * 65], sp[5 * 65]); o.w = pk2w(sp[6 * 65], sp[7 * 65]);
;         *(u32x4*)(WT + (size_t)(drow0 + n) * K + k0 + 8 * c) = o; }
;     __builtin_amdgcn_s_waitcnt(0); __builtin_amdgcn_wave_barrier();
	v_bfe_u32 v2, v78, 16, 1
	v_add3_u32 v2, v78, v2, s27
	s_waitcnt lgkmcnt(2)
	v_bfe_u32 v55, v80, 16, 1
	ds_read2_b32 v[86:87], v53 offset0:166 offset1:174
	v_lshrrev_b32_e32 v2, 16, v2
	v_add3_u32 v55, v80, v55, s27
	ds_read2_b32 v[88:89], v53 offset0:231 offset1:239
	v_and_or_b32 v71, v55, s28, v2
	s_waitcnt lgkmcnt(3)
	v_bfe_u32 v2, v82, 16, 1
	v_add3_u32 v2, v82, v2, s27
	s_waitcnt lgkmcnt(2)
	v_bfe_u32 v55, v84, 16, 1
	v_lshrrev_b32_e32 v2, 16, v2
	v_add3_u32 v55, v84, v55, s27
	v_and_or_b32 v72, v55, s28, v2
	s_waitcnt lgkmcnt(1)
	v_bfe_u32 v2, v86, 16, 1
	v_add3_u32 v2, v86, v2, s27
	s_waitcnt lgkmcnt(0)
	v_bfe_u32 v55, v88, 16, 1
	v_lshrrev_b32_e32 v2, 16, v2
	v_add3_u32 v55, v88, v55, s27
	v_and_or_b32 v73, v55, s28, v2
	v_or_b32_e32 v2, s8, v65
	v_mul_u32_u24_e32 v2, 0xb00, v2
	v_lshlrev_b32_e32 v2, 1, v2
	v_lshl_add_u64 v[90:91], v[56:57], 0, v[2:3]
	v_bfe_u32 v2, v75, 16, 1
	v_add3_u32 v2, v75, v2, s27
	v_bfe_u32 v55, v77, 16, 1
	v_lshrrev_b32_e32 v2, 16, v2
	v_add3_u32 v55, v77, v55, s27
	global_store_dwordx4 v[90:91], v[70:73], off
	ds_read2_b32 v[74:75], v61 offset0:48 offset1:56
	s_nop 0
	v_and_or_b32 v70, v55, s28, v2
	v_bfe_u32 v2, v79, 16, 1
	v_add3_u32 v2, v79, v2, s27
	v_bfe_u32 v55, v81, 16, 1
	v_lshrrev_b32_e32 v2, 16, v2
	v_add3_u32 v55, v81, v55, s27
	v_and_or_b32 v71, v55, s28, v2
	v_bfe_u32 v2, v83, 16, 1
	v_add3_u32 v2, v83, v2, s27
	v_bfe_u32 v55, v85, 16, 1
	v_lshrrev_b32_e32 v2, 16, v2
	v_add3_u32 v55, v85, v55, s27
	v_and_or_b32 v72, v55, s28, v2
	v_bfe_u32 v2, v87, 16, 1
	v_add3_u32 v2, v87, v2, s27
	v_bfe_u32 v55, v89, 16, 1
	v_lshrrev_b32_e32 v2, 16, v2
	v_add3_u32 v55, v89, v55, s27
	v_and_or_b32 v73, v55, s28, v2
	v_or_b32_e32 v2, s8, v66
	v_mul_u32_u24_e32 v2, 0xb00, v2
	v_lshlrev_b32_e32 v2, 1, v2
	v_lshl_add_u64 v[76:77], v[56:57], 0, v[2:3]
	global_store_dwordx4 v[76:77], v[70:73], off
	ds_read2_b32 v[76:77], v61 offset0:113 offset1:121
	ds_read2_b32 v[78:79], v61 offset0:178 offset1:186
	ds_read2_b32 v[80:81], v61 offset0:243 offset1:251
	s_waitcnt lgkmcnt(3)
	v_bfe_u32 v2, v74, 16, 1
	v_add3_u32 v2, v74, v2, s27
	s_waitcnt lgkmcnt(2)
	v_bfe_u32 v55, v76, 16, 1
	ds_read2_b32 v[82:83], v53 offset0:52 offset1:60
	v_lshrrev_b32_e32 v2, 16, v2
	v_add3_u32 v55, v76, v55, s27
	ds_read2_b32 v[84:85], v53 offset0:117 offset1:125
	v_and_or_b32 v70, v55, s28, v2
	s_waitcnt lgkmcnt(3)
	v_bfe_u32 v2, v78, 16, 1
	v_add3_u32 v2, v78, v2, s27
	s_waitcnt lgkmcnt(2)
	v_bfe_u32 v55, v80, 16, 1
	ds_read2_b32 v[86:87], v53 offset0:182 offset1:190
	v_lshrrev_b32_e32 v2, 16, v2
	v_add3_u32 v55, v80, v55, s27
	ds_read2_b32 v[88:89], v53 offset0:247 offset1:255
	v_and_or_b32 v71, v55, s28, v2
	s_waitcnt lgkmcnt(3)
	v_bfe_u32 v2, v82, 16, 1
	v_add3_u32 v2, v82, v2, s27
	s_waitcnt lgkmcnt(2)
	v_bfe_u32 v55, v84, 16, 1
	v_lshrrev_b32_e32 v2, 16, v2
	v_add3_u32 v55, v84, v55, s27
	v_and_or_b32 v72, v55, s28, v2
	s_waitcnt lgkmcnt(1)
	v_bfe_u32 v2, v86, 16, 1
	v_add3_u32 v2, v86, v2, s27
	s_waitcnt lgkmcnt(0)
	v_bfe_u32 v53, v88, 16, 1
	v_lshrrev_b32_e32 v2, 16, v2
	v_add3_u32 v53, v88, v53, s27
	v_and_or_b32 v73, v53, s28, v2
	v_or_b32_e32 v2, s8, v67
	v_mul_u32_u24_e32 v2, 0xb00, v2
	v_lshlrev_b32_e32 v2, 1, v2
	v_lshl_add_u64 v[90:91], v[56:57], 0, v[2:3]
	v_bfe_u32 v2, v75, 16, 1
	v_add3_u32 v2, v75, v2, s27
	v_bfe_u32 v53, v77, 16, 1
	v_lshrrev_b32_e32 v2, 16, v2
	v_add3_u32 v53, v77, v53, s27
	global_store_dwordx4 v[90:91], v[70:73], off
	s_nop 1
	v_and_or_b32 v70, v53, s28, v2
	v_bfe_u32 v2, v79, 16, 1
	v_add3_u32 v2, v79, v2, s27
	v_bfe_u32 v53, v81, 16, 1
	v_lshrrev_b32_e32 v2, 16, v2
	v_add3_u32 v53, v81, v53, s27
	v_and_or_b32 v71, v53, s28, v2
	v_bfe_u32 v2, v83, 16, 1
	v_add3_u32 v2, v83, v2, s27
	v_bfe_u32 v53, v85, 16, 1
	v_lshrrev_b32_e32 v2, 16, v2
	v_add3_u32 v53, v85, v53, s27
	v_and_or_b32 v72, v53, s28, v2
	v_bfe_u32 v2, v87, 16, 1
	v_add3_u32 v2, v87, v2, s27
	v_bfe_u32 v53, v89, 16, 1
	v_lshrrev_b32_e32 v2, 16, v2
	v_add3_u32 v53, v89, v53, s27
	v_and_or_b32 v73, v53, s28, v2
	v_or_b32_e32 v2, s8, v68
	v_mul_u32_u24_e32 v2, 0xb00, v2
	v_lshlrev_b32_e32 v2, 1, v2
	v_lshl_add_u64 v[56:57], v[56:57], 0, v[2:3]
	global_store_dwordx4 v[56:57], v[70:73], off
	s_waitcnt lgkmcnt(0)

; DI unsigned pk2w(float lo, float hi) { return f2bfw(lo) | (f2bfw(hi) << 16); }
; DI void transpose_item(const float* W, int K, int N, bf16_t* WT, int mode, float* scr, int item, int lane) {
;     const int nblk = N / 64, kb = item / nblk, nb = item % nblk, k0 = 64 * kb, n0 = 64 * nb;
;     int drow0 = n0;
;     if (mode == 1) { const int seg = n0 >> 10; const int dst = seg < 2 ? seg : (seg == 2 ? 6 : seg - 1); drow0 = dst * 1024 + (n0 & 1023); }
;     else if (mode == 2) { drow0 = n0 < DFF ? (n0 / 128) * 256 + (n0 % 128) : ((n0 - DFF) / 128) * 256 + 128 + ((n0 - DFF) % 128); }
;     else if (mode == 3) { drow0 = (n0 / 128) * 256 + (n0 % 128); }
;     else if (mode == 4) { drow0 = (n0 / 128) * 256 + 128 + (n0 % 128); }
;     f32x4 v[16];
; #pragma unroll
;     for (int i = 0; i < 16; ++i) v[i] = __builtin_nontemporal_load((const f32x4*)(W + (size_t)(k0 + 4 * i + (lane >> 4)) * N + n0 + 4 * (lane & 15)));
; #pragma unroll
;     for (int i = 0; i < 16; ++i) { float* d = scr + (4 * i + (lane >> 4)) * 65 + 4 * (lane & 15); d[0] = v[i][0]; d[1] = v[i][1]; d[2] = v[i][2]; d[3] = v[i][3]; }
;     __builtin_amdgcn_s_waitcnt(0); __builtin_amdgcn_wave_barrier();
;     const int c = lane & 7;
; #pragma unroll
;     for (int j = 0; j < 8; ++j) { const int n = (lane >> 3) + 8 * j; const float* sp = scr + (8 * c) * 65 + n;
;         u32x4 o; o.x = pk2w(sp[0 * 65], sp[1 * 65]); o.y = pk2w(sp[2 * 65], sp[3 * 65]); o.z = pk2w(sp[4 * 65], sp[5 * 65]); o.w = pk2w(sp[6 * 65], sp[7 * 65]);
.LBB0_285:
	s_andn2_b64 vcc, exec, s[8:9]
	s_cbranch_vccnz .LBB0_287
	s_add_i32 s6, s47, 0xc880
	s_and_b32 s8, s6, 0xffff
	s_mul_i32 s8, s8, 0xba2f
	s_lshr_b32 s9, s8, 16
	s_lshr_b32 s8, s8, 22
	s_mulk_i32 s8, 0x58
	s_sub_i32 s6, s6, s8
	s_lshl_b32 s6, s6, 6
	s_and_b32 s9, s9, 0xffc0
	s_and_b32 s8, s6, 0xffc0
	v_or_b32_e32 v2, s9, v58
	s_lshl_b32 s6, s8, 2
	v_mul_u32_u24_e32 v2, 0x1600, v2
	v_lshl_add_u64 v[56:57], v[6:7], 0, s[6:7]
	v_lshlrev_b32_e32 v2, 2, v2
	v_lshl_add_u64 v[56:57], v[56:57], 0, v[2:3]
	v_add_co_u32_e32 v74, vcc, s38, v56
	v_add_u32_e32 v2, 0x410, v59
	s_nop 0
	v_addc_co_u32_e32 v75, vcc, 0, v57, vcc
	v_add_co_u32_e32 v78, vcc, s30, v56
	global_load_dwordx4 v[70:73], v[56:57], off nt
	s_nop 0
	global_load_dwordx4 v[74:77], v[74:75], off nt
	v_addc_co_u32_e32 v79, vcc, 0, v57, vcc
	v_add_co_u32_e32 v82, vcc, s39, v56
	s_lshl_b32 s6, s9, 1
	s_nop 0
	v_addc_co_u32_e32 v83, vcc, 0, v57, vcc
	global_load_dwordx4 v[78:81], v[78:79], off nt
	s_nop 0
	global_load_dwordx4 v[82:85], v[82:83], off nt
	v_add_co_u32_e32 v86, vcc, s29, v56
	s_nop 1
	v_addc_co_u32_e32 v87, vcc, 0, v57, vcc
	v_add_co_u32_e32 v90, vcc, s40, v56
	s_nop 1
	v_addc_co_u32_e32 v91, vcc, 0, v57, vcc
	global_load_dwordx4 v[86:89], v[86:87], off nt
	s_nop 0
	global_load_dwordx4 v[90:93], v[90:91], off nt
	v_add_co_u32_e32 v94, vcc, s31, v56
	s_nop 1
	v_addc_co_u32_e32 v95, vcc, 0, v57, vcc
	v_add_co_u32_e32 v98, vcc, s41, v56
	s_nop 1
	v_addc_co_u32_e32 v99, vcc, 0, v57, vcc
	global_load_dwordx4 v[94:97], v[94:95], off nt
	s_nop 0
	global_load_dwordx4 v[98:101], v[98:99], off nt
	v_add_co_u32_e32 v102, vcc, s34, v56
	s_nop 1
	v_addc_co_u32_e32 v103, vcc, 0, v57, vcc
	v_add_co_u32_e32 v106, vcc, s42, v56
	s_nop 1
	v_addc_co_u32_e32 v107, vcc, 0, v57, vcc
	global_load_dwordx4 v[102:105], v[102:103], off nt
	s_nop 0
	global_load_dwordx4 v[106:109], v[106:107], off nt
	v_add_co_u32_e32 v110, vcc, s35, v56
	s_nop 1
	v_addc_co_u32_e32 v111, vcc, 0, v57, vcc
	v_add_co_u32_e32 v114, vcc, s43, v56
	s_nop 1
	v_addc_co_u32_e32 v115, vcc, 0, v57, vcc
	global_load_dwordx4 v[110:113], v[110:111], off nt
	s_nop 0
	global_load_dwordx4 v[114:117], v[114:115], off nt
	v_add_co_u32_e32 v118, vcc, s36, v56
	s_nop 1
	v_addc_co_u32_e32 v119, vcc, 0, v57, vcc
	global_load_dwordx4 v[118:121], v[118:119], off nt
	v_add_co_u32_e32 v122, vcc, s44, v56
	s_nop 1
	v_addc_co_u32_e32 v123, vcc, 0, v57, vcc
	global_load_dwordx4 v[122:125], v[122:123], off nt
	v_add_co_u32_e32 v126, vcc, s37, v56
	s_nop 1
	v_addc_co_u32_e32 v127, vcc, 0, v57, vcc
	global_load_dwordx4 v[126:129], v[126:127], off nt
	v_add_co_u32_e32 v56, vcc, s45, v56
	s_nop 1
	v_addc_co_u32_e32 v57, vcc, 0, v57, vcc
	global_load_dwordx4 v[130:133], v[56:57], off nt
	s_waitcnt vmcnt(0)
	ds_write2_b32 v59, v70, v71 offset1:1
	ds_write2_b32 v59, v72, v73 offset0:2 offset1:3
	ds_write2_b32 v2, v74, v75 offset1:1
	v_add_u32_e32 v2, 0x418, v59
	ds_write2_b32 v2, v76, v77 offset1:1
	v_add_u32_e32 v2, 0x820, v59
	v_lshl_add_u64 v[56:57], v[38:39], 0, s[6:7]
	ds_write2_b32 v2, v78, v79 offset1:1
	v_add_u32_e32 v2, 0x828, v59
	ds_write2_b32 v2, v80, v81 offset1:1
	v_add_u32_e32 v2, 0xc30, v59
	ds_write2_b32 v2, v82, v83 offset1:1
	v_add_u32_e32 v2, 0xc38, v59
	ds_write2_b32 v2, v84, v85 offset1:1
	v_add_u32_e32 v2, 0x1040, v59
	ds_write2_b32 v2, v86, v87 offset1:1
	v_add_u32_e32 v2, 0x1048, v59
	ds_write2_b32 v2, v88, v89 offset1:1
	v_add_u32_e32 v2, 0x1450, v59
	ds_write2_b32 v2, v90, v91 offset1:1
	v_add_u32_e32 v2, 0x1458, v59
	ds_write2_b32 v2, v92, v93 offset1:1
	v_add_u32_e32 v2, 0x1860, v59
	ds_write2_b32 v2, v94, v95 offset1:1
	v_add_u32_e32 v2, 0x1868, v59
	ds_write2_b32 v2, v96, v97 offset1:1
	v_add_u32_e32 v2, 0x1c70, v59
	ds_write2_b32 v2, v98, v99 offset1:1
	v_add_u32_e32 v2, 0x1c78, v59
	ds_write2_b32 v2, v100, v101 offset1:1
	v_add_u32_e32 v2, 0x2080, v59
	ds_write2_b32 v2, v102, v103 offset1:1
	v_add_u32_e32 v2, 0x2088, v59
	ds_write2_b32 v2, v104, v105 offset1:1
	v_add_u32_e32 v2, 0x2490, v59
	ds_write2_b32 v2, v106, v107 offset1:1
	v_add_u32_e32 v2, 0x2498, v59
	ds_write2_b32 v2, v108, v109 offset1:1
	v_add_u32_e32 v2, 0x28a0, v59
	ds_write2_b32 v2, v110, v111 offset1:1
	v_add_u32_e32 v2, 0x28a8, v59
	ds_write2_b32 v2, v112, v113 offset1:1
	v_add_u32_e32 v2, 0x2cb0, v59
	ds_write2_b32 v2, v114, v115 offset1:1
	v_add_u32_e32 v2, 0x2cb8, v59
	ds_write2_b32 v2, v116, v117 offset1:1
	v_add_u32_e32 v2, 0x30c0, v59
	ds_write2_b32 v2, v118, v119 offset1:1
	v_add_u32_e32 v2, 0x30c8, v59
	ds_write2_b32 v2, v120, v121 offset1:1
	v_add_u32_e32 v2, 0x34d0, v59
	ds_write2_b32 v2, v122, v123 offset1:1
	v_add_u32_e32 v2, 0x34d8, v59
	ds_write2_b32 v2, v124, v125 offset1:1
	v_add_u32_e32 v2, 0x38e0, v59
	ds_write2_b32 v2, v126, v127 offset1:1
	v_add_u32_e32 v2, 0x38e8, v59
	ds_write2_b32 v2, v128, v129 offset1:1
	v_add_u32_e32 v2, 0x3cf0, v59
	ds_write2_b32 v2, v130, v131 offset1:1
	v_add_u32_e32 v2, 0x3cf8, v59
	ds_write2_b32 v2, v132, v133 offset1:1
	s_waitcnt vmcnt(0) expcnt(0) lgkmcnt(0)
	ds_read2_b32 v[74:75], v61 offset1:8
	ds_read2_b32 v[76:77], v61 offset0:65 offset1:73
	ds_read2_b32 v[78:79], v61 offset0:130 offset1:138
	ds_read2_b32 v[80:81], v61 offset0:195 offset1:203
	s_waitcnt lgkmcnt(3)
	v_bfe_u32 v2, v74, 16, 1
	v_add3_u32 v2, v74, v2, s27
	s_waitcnt lgkmcnt(2)
	v_bfe_u32 v53, v76, 16, 1
	v_lshrrev_b32_e32 v2, 16, v2
	v_add3_u32 v53, v76, v53, s27
	v_and_or_b32 v70, v53, s28, v2
	v_add_u32_e32 v53, 0x400, v61
	ds_read2_b32 v[82:83], v53 offset0:4 offset1:12
	ds_read2_b32 v[84:85], v53 offset0:69 offset1:77
	s_waitcnt lgkmcnt(3)
	v_bfe_u32 v2, v78, 16, 1
	v_add3_u32 v2, v78, v2, s27
	s_waitcnt lgkmcnt(2)
; DI unsigned pk2w(float lo, float hi) { return f2bfw(lo) | (f2bfw(hi) << 16); }
; DI void transpose_item(const float* W, int K, int N, bf16_t* WT, int mode, float* scr, int item, int lane) {
;     ...
;     const int c = lane & 7;
; #pragma unroll
;     for (int j = 0; j < 8; ++j) { const int n = (lane >> 3) + 8 * j; const float* sp = scr + (8 * c) * 65 + n;
;         u32x4 o; o.x = pk2w(sp[0 * 65], sp[1 * 65]); o.y = pk2w(sp[2 * 65], sp[3 * 65]); o.z = pk2w(sp[4 * 65], sp[5 * 65]); o.w = pk2w(sp[6 * 65], sp[7 * 65]);
;         *(u32x4*)(WT + (size_t)(drow0 + n) * K + k0 + 8 * c) = o; }
	v_bfe_u32 v55, v80, 16, 1
	ds_read2_b32 v[86:87], v53 offset0:134 offset1:142
	v_lshrrev_b32_e32 v2, 16, v2
	v_add3_u32 v55, v80, v55, s27
	ds_read2_b32 v[88:89], v53 offset0:199 offset1:207
	v_and_or_b32 v71, v55, s28, v2
	s_waitcnt lgkmcnt(3)
	v_bfe_u32 v2, v82, 16, 1
	v_add3_u32 v2, v82, v2, s27
	s_waitcnt lgkmcnt(2)
	v_bfe_u32 v55, v84, 16, 1
	v_lshrrev_b32_e32 v2, 16, v2
	v_add3_u32 v55, v84, v55, s27
	v_and_or_b32 v72, v55, s28, v2
	s_waitcnt lgkmcnt(1)
	v_bfe_u32 v2, v86, 16, 1
	v_add3_u32 v2, v86, v2, s27
	s_waitcnt lgkmcnt(0)
	v_bfe_u32 v55, v88, 16, 1
	v_lshrrev_b32_e32 v2, 16, v2
	v_add3_u32 v55, v88, v55, s27
	v_and_or_b32 v73, v55, s28, v2
	v_or_b32_e32 v2, s8, v60
	v_lshlrev_b32_e32 v2, 12, v2
	v_lshl_add_u64 v[90:91], v[56:57], 0, v[2:3]
	v_bfe_u32 v2, v75, 16, 1
	v_add3_u32 v2, v75, v2, s27
	v_bfe_u32 v55, v77, 16, 1
	v_lshrrev_b32_e32 v2, 16, v2
	v_add3_u32 v55, v77, v55, s27
	global_store_dwordx4 v[90:91], v[70:73], off
	ds_read2_b32 v[74:75], v61 offset0:16 offset1:24
	s_nop 0
	v_and_or_b32 v70, v55, s28, v2
	v_bfe_u32 v2, v79, 16, 1
	v_add3_u32 v2, v79, v2, s27
	v_bfe_u32 v55, v81, 16, 1
	v_lshrrev_b32_e32 v2, 16, v2
	v_add3_u32 v55, v81, v55, s27
	v_and_or_b32 v71, v55, s28, v2
	v_bfe_u32 v2, v83, 16, 1
	v_add3_u32 v2, v83, v2, s27
	v_bfe_u32 v55, v85, 16, 1
	v_lshrrev_b32_e32 v2, 16, v2
	v_add3_u32 v55, v85, v55, s27
	v_and_or_b32 v72, v55, s28, v2
	v_bfe_u32 v2, v87, 16, 1
	v_add3_u32 v2, v87, v2, s27
	v_bfe_u32 v55, v89, 16, 1
	v_lshrrev_b32_e32 v2, 16, v2
	v_add3_u32 v55, v89, v55, s27
	v_and_or_b32 v73, v55, s28, v2
	v_or_b32_e32 v2, s8, v62
	v_lshlrev_b32_e32 v2, 12, v2
	v_lshl_add_u64 v[76:77], v[56:57], 0, v[2:3]
	global_store_dwordx4 v[76:77], v[70:73], off
	ds_read2_b32 v[76:77], v61 offset0:81 offset1:89
	ds_read2_b32 v[78:79], v61 offset0:146 offset1:154
	ds_read2_b32 v[80:81], v61 offset0:211 offset1:219
	s_waitcnt lgkmcnt(3)
	v_bfe_u32 v2, v74, 16, 1
	v_add3_u32 v2, v74, v2, s27
	s_waitcnt lgkmcnt(2)
	v_bfe_u32 v55, v76, 16, 1
	ds_read2_b32 v[82:83], v53 offset0:20 offset1:28
	v_lshrrev_b32_e32 v2, 16, v2
	v_add3_u32 v55, v76, v55, s27
	ds_read2_b32 v[84:85], v53 offset0:85 offset1:93
	v_and_or_b32 v70, v55, s28, v2
	s_waitcnt lgkmcnt(3)
	v_bfe_u32 v2, v78, 16, 1
	v_add3_u32 v2, v78, v2, s27
	s_waitcnt lgkmcnt(2)
	v_bfe_u32 v55, v80, 16, 1
	ds_read2_b32 v[86:87], v53 offset0:150 offset1:158
	v_lshrrev_b32_e32 v2, 16, v2
	v_add3_u32 v55, v80, v55, s27
	ds_read2_b32 v[88:89], v53 offset0:215 offset1:223
	v_and_or_b32 v71, v55, s28, v2
	s_waitcnt lgkmcnt(3)
	v_bfe_u32 v2, v82, 16, 1
	v_add3_u32 v2, v82, v2, s27
	s_waitcnt lgkmcnt(2)
	v_bfe_u32 v55, v84, 16, 1
	v_lshrrev_b32_e32 v2, 16, v2
	v_add3_u32 v55, v84, v55, s27
	v_and_or_b32 v72, v55, s28, v2
	s_waitcnt lgkmcnt(1)
	v_bfe_u32 v2, v86, 16, 1
	v_add3_u32 v2, v86, v2, s27
	s_waitcnt lgkmcnt(0)
	v_bfe_u32 v55, v88, 16, 1
	v_lshrrev_b32_e32 v2, 16, v2
	v_add3_u32 v55, v88, v55, s27
	v_and_or_b32 v73, v55, s28, v2
	v_or_b32_e32 v2, s8, v63
	v_lshlrev_b32_e32 v2, 12, v2
	v_lshl_add_u64 v[90:91], v[56:57], 0, v[2:3]
	v_bfe_u32 v2, v75, 16, 1
	v_add3_u32 v2, v75, v2, s27
	v_bfe_u32 v55, v77, 16, 1
	v_lshrrev_b32_e32 v2, 16, v2
	v_add3_u32 v55, v77, v55, s27
	global_store_dwordx4 v[90:91], v[70:73], off
	ds_read2_b32 v[74:75], v61 offset0:32 offset1:40
	s_nop 0
	v_and_or_b32 v70, v55, s28, v2
	v_bfe_u32 v2, v79, 16, 1
	v_add3_u32 v2, v79, v2, s27
	v_bfe_u32 v55, v81, 16, 1
	v_lshrrev_b32_e32 v2, 16, v2
	v_add3_u32 v55, v81, v55, s27
	v_and_or_b32 v71, v55, s28, v2
	v_bfe_u32 v2, v83, 16, 1
	v_add3_u32 v2, v83, v2, s27
	v_bfe_u32 v55, v85, 16, 1
	v_lshrrev_b32_e32 v2, 16, v2
	v_add3_u32 v55, v85, v55, s27
	v_and_or_b32 v72, v55, s28, v2
	v_bfe_u32 v2, v87, 16, 1
	v_add3_u32 v2, v87, v2, s27
	v_bfe_u32 v55, v89, 16, 1
	v_lshrrev_b32_e32 v2, 16, v2
	v_add3_u32 v55, v89, v55, s27
	v_and_or_b32 v73, v55, s28, v2
	v_or_b32_e32 v2, s8, v64
	v_lshlrev_b32_e32 v2, 12, v2
	v_lshl_add_u64 v[76:77], v[56:57], 0, v[2:3]
	global_store_dwordx4 v[76:77], v[70:73], off
	ds_read2_b32 v[76:77], v61 offset0:97 offset1:105
	ds_read2_b32 v[78:79], v61 offset0:162 offset1:170
	ds_read2_b32 v[80:81], v61 offset0:227 offset1:235
	s_waitcnt lgkmcnt(3)
	v_bfe_u32 v2, v74, 16, 1
	v_add3_u32 v2, v74, v2, s27
	s_waitcnt lgkmcnt(2)
; DI unsigned pk2w(float lo, float hi) { return f2bfw(lo) | (f2bfw(hi) << 16); }
; DI void transpose_item(const float* W, int K, int N, bf16_t* WT, int mode, float* scr, int item, int lane) {
;     ...
;     const int c = lane & 7;
; #pragma unroll
;     for (int j = 0; j < 8; ++j) { const int n = (lane >> 3) + 8 * j; const float* sp = scr + (8 * c) * 65 + n;
;         u32x4 o; o.x = pk2w(sp[0 * 65], sp[1 * 65]); o.y = pk2w(sp[2 * 65], sp[3 * 65]); o.z = pk2w(sp[4 * 65], sp[5 * 65]); o.w = pk2w(sp[6 * 65], sp[7 * 65]);
;         *(u32x4*)(WT + (size_t)(drow0 + n) * K + k0 + 8 * c) = o; }
;     __builtin_amdgcn_s_waitcnt(0); __builtin_amdgcn_wave_barrier();
	v_bfe_u32 v55, v76, 16, 1
	ds_read2_b32 v[82:83], v53 offset0:36 offset1:44
	v_lshrrev_b32_e32 v2, 16, v2
	v_add3_u32 v55, v76, v55, s27
	ds_read2_b32 v[84:85], v53 offset0:101 offset1:109
	v_and_or_b32 v70, v55, s28, v2
	s_waitcnt lgkmcnt(3)
	v_bfe_u32 v2, v78, 16, 1
	v_add3_u32 v2, v78, v2, s27
	s_waitcnt lgkmcnt(2)
	v_bfe_u32 v55, v80, 16, 1
	ds_read2_b32 v[86:87], v53 offset0:166 offset1:174
	v_lshrrev_b32_e32 v2, 16, v2
	v_add3_u32 v55, v80, v55, s27
	ds_read2_b32 v[88:89], v53 offset0:231 offset1:239
	v_and_or_b32 v71, v55, s28, v2
	s_waitcnt lgkmcnt(3)
	v_bfe_u32 v2, v82, 16, 1
	v_add3_u32 v2, v82, v2, s27
	s_waitcnt lgkmcnt(2)
	v_bfe_u32 v55, v84, 16, 1
	v_lshrrev_b32_e32 v2, 16, v2
	v_add3_u32 v55, v84, v55, s27
	v_and_or_b32 v72, v55, s28, v2
	s_waitcnt lgkmcnt(1)
	v_bfe_u32 v2, v86, 16, 1
	v_add3_u32 v2, v86, v2, s27
	s_waitcnt lgkmcnt(0)
	v_bfe_u32 v55, v88, 16, 1
	v_lshrrev_b32_e32 v2, 16, v2
	v_add3_u32 v55, v88, v55, s27
	v_and_or_b32 v73, v55, s28, v2
	v_or_b32_e32 v2, s8, v65
	v_lshlrev_b32_e32 v2, 12, v2
	v_lshl_add_u64 v[90:91], v[56:57], 0, v[2:3]
	v_bfe_u32 v2, v75, 16, 1
	v_add3_u32 v2, v75, v2, s27
	v_bfe_u32 v55, v77, 16, 1
	v_lshrrev_b32_e32 v2, 16, v2
	v_add3_u32 v55, v77, v55, s27
	global_store_dwordx4 v[90:91], v[70:73], off
	ds_read2_b32 v[74:75], v61 offset0:48 offset1:56
	s_nop 0
	v_and_or_b32 v70, v55, s28, v2
	v_bfe_u32 v2, v79, 16, 1
	v_add3_u32 v2, v79, v2, s27
	v_bfe_u32 v55, v81, 16, 1
	v_lshrrev_b32_e32 v2, 16, v2
	v_add3_u32 v55, v81, v55, s27
	v_and_or_b32 v71, v55, s28, v2
	v_bfe_u32 v2, v83, 16, 1
	v_add3_u32 v2, v83, v2, s27
	v_bfe_u32 v55, v85, 16, 1
	v_lshrrev_b32_e32 v2, 16, v2
	v_add3_u32 v55, v85, v55, s27
	v_and_or_b32 v72, v55, s28, v2
	v_bfe_u32 v2, v87, 16, 1
	v_add3_u32 v2, v87, v2, s27
	v_bfe_u32 v55, v89, 16, 1
	v_lshrrev_b32_e32 v2, 16, v2
	v_add3_u32 v55, v89, v55, s27
	v_and_or_b32 v73, v55, s28, v2
	v_or_b32_e32 v2, s8, v66
	v_lshlrev_b32_e32 v2, 12, v2
	v_lshl_add_u64 v[76:77], v[56:57], 0, v[2:3]
	global_store_dwordx4 v[76:77], v[70:73], off
	ds_read2_b32 v[76:77], v61 offset0:113 offset1:121
	ds_read2_b32 v[78:79], v61 offset0:178 offset1:186
	ds_read2_b32 v[80:81], v61 offset0:243 offset1:251
	s_waitcnt lgkmcnt(3)
	v_bfe_u32 v2, v74, 16, 1
	v_add3_u32 v2, v74, v2, s27
	s_waitcnt lgkmcnt(2)
	v_bfe_u32 v55, v76, 16, 1
	ds_read2_b32 v[82:83], v53 offset0:52 offset1:60
	v_lshrrev_b32_e32 v2, 16, v2
	v_add3_u32 v55, v76, v55, s27
	ds_read2_b32 v[84:85], v53 offset0:117 offset1:125
	v_and_or_b32 v70, v55, s28, v2
	s_waitcnt lgkmcnt(3)
	v_bfe_u32 v2, v78, 16, 1
	v_add3_u32 v2, v78, v2, s27
	s_waitcnt lgkmcnt(2)
	v_bfe_u32 v55, v80, 16, 1
	ds_read2_b32 v[86:87], v53 offset0:182 offset1:190
	v_lshrrev_b32_e32 v2, 16, v2
	v_add3_u32 v55, v80, v55, s27
	ds_read2_b32 v[88:89], v53 offset0:247 offset1:255
	v_and_or_b32 v71, v55, s28, v2
	s_waitcnt lgkmcnt(3)
	v_bfe_u32 v2, v82, 16, 1
	v_add3_u32 v2, v82, v2, s27
	s_waitcnt lgkmcnt(2)
	v_bfe_u32 v55, v84, 16, 1
	v_lshrrev_b32_e32 v2, 16, v2
	v_add3_u32 v55, v84, v55, s27
	v_and_or_b32 v72, v55, s28, v2
	s_waitcnt lgkmcnt(1)
	v_bfe_u32 v2, v86, 16, 1
	v_add3_u32 v2, v86, v2, s27
	s_waitcnt lgkmcnt(0)
	v_bfe_u32 v53, v88, 16, 1
	v_lshrrev_b32_e32 v2, 16, v2
	v_add3_u32 v53, v88, v53, s27
	v_and_or_b32 v73, v53, s28, v2
	v_or_b32_e32 v2, s8, v67
	v_lshlrev_b32_e32 v2, 12, v2
	v_lshl_add_u64 v[90:91], v[56:57], 0, v[2:3]
	v_bfe_u32 v2, v75, 16, 1
	v_add3_u32 v2, v75, v2, s27
	v_bfe_u32 v53, v77, 16, 1
	v_lshrrev_b32_e32 v2, 16, v2
	v_add3_u32 v53, v77, v53, s27
	global_store_dwordx4 v[90:91], v[70:73], off
	s_nop 1
	v_and_or_b32 v70, v53, s28, v2
	v_bfe_u32 v2, v79, 16, 1
	v_add3_u32 v2, v79, v2, s27
	v_bfe_u32 v53, v81, 16, 1
	v_lshrrev_b32_e32 v2, 16, v2
	v_add3_u32 v53, v81, v53, s27
	v_and_or_b32 v71, v53, s28, v2
	v_bfe_u32 v2, v83, 16, 1
	v_add3_u32 v2, v83, v2, s27
	v_bfe_u32 v53, v85, 16, 1
	v_lshrrev_b32_e32 v2, 16, v2
	v_add3_u32 v53, v85, v53, s27
	v_and_or_b32 v72, v53, s28, v2
	v_bfe_u32 v2, v87, 16, 1
	v_add3_u32 v2, v87, v2, s27
	v_bfe_u32 v53, v89, 16, 1
	v_lshrrev_b32_e32 v2, 16, v2
	v_add3_u32 v53, v89, v53, s27
	v_and_or_b32 v73, v53, s28, v2
	v_or_b32_e32 v2, s8, v68
	v_lshlrev_b32_e32 v2, 12, v2
	v_lshl_add_u64 v[56:57], v[56:57], 0, v[2:3]
	global_store_dwordx4 v[56:57], v[70:73], off
	s_waitcnt lgkmcnt(0)

; DI unsigned pk2w(float lo, float hi) { return f2bfw(lo) | (f2bfw(hi) << 16); }
; DI void transpose_item(const float* W, int K, int N, bf16_t* WT, int mode, float* scr, int item, int lane) {
;     const int nblk = N / 64, kb = item / nblk, nb = item % nblk, k0 = 64 * kb, n0 = 64 * nb;
;     int drow0 = n0;
;     if (mode == 1) { const int seg = n0 >> 10; const int dst = seg < 2 ? seg : (seg == 2 ? 6 : seg - 1); drow0 = dst * 1024 + (n0 & 1023); }
;     else if (mode == 2) { drow0 = n0 < DFF ? (n0 / 128) * 256 + (n0 % 128) : ((n0 - DFF) / 128) * 256 + 128 + ((n0 - DFF) % 128); }
;     else if (mode == 3) { drow0 = (n0 / 128) * 256 + (n0 % 128); }
;     else if (mode == 4) { drow0 = (n0 / 128) * 256 + 128 + (n0 % 128); }
;     f32x4 v[16];
; #pragma unroll
;     for (int i = 0; i < 16; ++i) v[i] = __builtin_nontemporal_load((const f32x4*)(W + (size_t)(k0 + 4 * i + (lane >> 4)) * N + n0 + 4 * (lane & 15)));
; #pragma unroll
;     for (int i = 0; i < 16; ++i) { float* d = scr + (4 * i + (lane >> 4)) * 65 + 4 * (lane & 15); d[0] = v[i][0]; d[1] = v[i][1]; d[2] = v[i][2]; d[3] = v[i][3]; }
;     __builtin_amdgcn_s_waitcnt(0); __builtin_amdgcn_wave_barrier();
;     const int c = lane & 7;
; #pragma unroll
;     for (int j = 0; j < 8; ++j) { const int n = (lane >> 3) + 8 * j; const float* sp = scr + (8 * c) * 65 + n;
;         u32x4 o; o.x = pk2w(sp[0 * 65], sp[1 * 65]); o.y = pk2w(sp[2 * 65], sp[3 * 65]); o.z = pk2w(sp[4 * 65], sp[5 * 65]); o.w = pk2w(sp[6 * 65], sp[7 * 65]);
.LBB0_288:
	s_andn2_b64 vcc, exec, s[8:9]
	s_cbranch_vccnz .LBB0_290
	s_add_i32 s6, s3, 0x6c00
	s_and_b32 s8, s16, 0x7c0
	s_and_b32 s9, s6, 0x1ffc0
	v_or_b32_e32 v2, s9, v58
	s_lshl_b32 s6, s8, 2
	v_lshl_add_u64 v[56:57], v[8:9], 0, s[6:7]
	v_lshlrev_b32_e32 v2, 13, v2
	v_lshl_add_u64 v[56:57], v[56:57], 0, v[2:3]
	v_add_co_u32_e32 v74, vcc, 0x8000, v56
	v_add_u32_e32 v2, 0x410, v59
	s_nop 0
	v_addc_co_u32_e32 v75, vcc, 0, v57, vcc
	v_add_co_u32_e32 v78, vcc, 0x10000, v56
	global_load_dwordx4 v[70:73], v[56:57], off nt
	s_nop 0
	global_load_dwordx4 v[74:77], v[74:75], off nt
	v_addc_co_u32_e32 v79, vcc, 0, v57, vcc
	v_add_co_u32_e32 v82, vcc, 0x18000, v56
	s_lshl_b32 s6, s9, 1
	s_nop 0
	v_addc_co_u32_e32 v83, vcc, 0, v57, vcc
	global_load_dwordx4 v[78:81], v[78:79], off nt
	s_nop 0
	global_load_dwordx4 v[82:85], v[82:83], off nt
	v_add_co_u32_e32 v86, vcc, 0x20000, v56
	s_nop 1
	v_addc_co_u32_e32 v87, vcc, 0, v57, vcc
	v_add_co_u32_e32 v90, vcc, 0x28000, v56
	s_nop 1
	v_addc_co_u32_e32 v91, vcc, 0, v57, vcc
	global_load_dwordx4 v[86:89], v[86:87], off nt
	s_nop 0
	global_load_dwordx4 v[90:93], v[90:91], off nt
	v_add_co_u32_e32 v94, vcc, 0x30000, v56
	s_nop 1
	v_addc_co_u32_e32 v95, vcc, 0, v57, vcc
	v_add_co_u32_e32 v98, vcc, 0x38000, v56
	s_nop 1
	v_addc_co_u32_e32 v99, vcc, 0, v57, vcc
	global_load_dwordx4 v[94:97], v[94:95], off nt
	s_nop 0
	global_load_dwordx4 v[98:101], v[98:99], off nt
	v_add_co_u32_e32 v102, vcc, 0x40000, v56
	s_nop 1
	v_addc_co_u32_e32 v103, vcc, 0, v57, vcc
	v_add_co_u32_e32 v106, vcc, 0x48000, v56
	s_nop 1
	v_addc_co_u32_e32 v107, vcc, 0, v57, vcc
	global_load_dwordx4 v[102:105], v[102:103], off nt
	s_nop 0
	global_load_dwordx4 v[106:109], v[106:107], off nt
	v_add_co_u32_e32 v110, vcc, 0x50000, v56
	s_nop 1
	v_addc_co_u32_e32 v111, vcc, 0, v57, vcc
	v_add_co_u32_e32 v114, vcc, 0x58000, v56
	s_nop 1
	v_addc_co_u32_e32 v115, vcc, 0, v57, vcc
	global_load_dwordx4 v[110:113], v[110:111], off nt
	s_nop 0
	global_load_dwordx4 v[114:117], v[114:115], off nt
	v_add_co_u32_e32 v118, vcc, 0x60000, v56
	s_nop 1
	v_addc_co_u32_e32 v119, vcc, 0, v57, vcc
	v_add_co_u32_e32 v122, vcc, 0x68000, v56
	s_nop 1
	v_addc_co_u32_e32 v123, vcc, 0, v57, vcc
	global_load_dwordx4 v[118:121], v[118:119], off nt
	s_nop 0
	global_load_dwordx4 v[122:125], v[122:123], off nt
	v_add_co_u32_e32 v126, vcc, 0x70000, v56
	s_nop 1
	v_addc_co_u32_e32 v127, vcc, 0, v57, vcc
	global_load_dwordx4 v[126:129], v[126:127], off nt
	v_add_co_u32_e32 v56, vcc, 0x78000, v56
	s_nop 1
	v_addc_co_u32_e32 v57, vcc, 0, v57, vcc
	global_load_dwordx4 v[130:133], v[56:57], off nt
	s_waitcnt vmcnt(0)
	ds_write2_b32 v59, v70, v71 offset1:1
	ds_write2_b32 v59, v72, v73 offset0:2 offset1:3
	ds_write2_b32 v2, v74, v75 offset1:1
	v_add_u32_e32 v2, 0x418, v59
	ds_write2_b32 v2, v76, v77 offset1:1
	v_add_u32_e32 v2, 0x820, v59
	v_lshl_add_u64 v[56:57], v[40:41], 0, s[6:7]
	ds_write2_b32 v2, v78, v79 offset1:1
	v_add_u32_e32 v2, 0x828, v59
	ds_write2_b32 v2, v80, v81 offset1:1
	v_add_u32_e32 v2, 0xc30, v59
	ds_write2_b32 v2, v82, v83 offset1:1
	v_add_u32_e32 v2, 0xc38, v59
	ds_write2_b32 v2, v84, v85 offset1:1
	v_add_u32_e32 v2, 0x1040, v59
	ds_write2_b32 v2, v86, v87 offset1:1
	v_add_u32_e32 v2, 0x1048, v59
	ds_write2_b32 v2, v88, v89 offset1:1
	v_add_u32_e32 v2, 0x1450, v59
	ds_write2_b32 v2, v90, v91 offset1:1
	v_add_u32_e32 v2, 0x1458, v59
	ds_write2_b32 v2, v92, v93 offset1:1
	v_add_u32_e32 v2, 0x1860, v59
	ds_write2_b32 v2, v94, v95 offset1:1
	v_add_u32_e32 v2, 0x1868, v59
	ds_write2_b32 v2, v96, v97 offset1:1
	v_add_u32_e32 v2, 0x1c70, v59
	ds_write2_b32 v2, v98, v99 offset1:1
	v_add_u32_e32 v2, 0x1c78, v59
	ds_write2_b32 v2, v100, v101 offset1:1
	v_add_u32_e32 v2, 0x2080, v59
	ds_write2_b32 v2, v102, v103 offset1:1
	v_add_u32_e32 v2, 0x2088, v59
	ds_write2_b32 v2, v104, v105 offset1:1
	v_add_u32_e32 v2, 0x2490, v59
	ds_write2_b32 v2, v106, v107 offset1:1
	v_add_u32_e32 v2, 0x2498, v59
	ds_write2_b32 v2, v108, v109 offset1:1
	v_add_u32_e32 v2, 0x28a0, v59
	ds_write2_b32 v2, v110, v111 offset1:1
	v_add_u32_e32 v2, 0x28a8, v59
	ds_write2_b32 v2, v112, v113 offset1:1
	v_add_u32_e32 v2, 0x2cb0, v59
	ds_write2_b32 v2, v114, v115 offset1:1
	v_add_u32_e32 v2, 0x2cb8, v59
	ds_write2_b32 v2, v116, v117 offset1:1
	v_add_u32_e32 v2, 0x30c0, v59
	ds_write2_b32 v2, v118, v119 offset1:1
	v_add_u32_e32 v2, 0x30c8, v59
	ds_write2_b32 v2, v120, v121 offset1:1
	v_add_u32_e32 v2, 0x34d0, v59
	ds_write2_b32 v2, v122, v123 offset1:1
	v_add_u32_e32 v2, 0x34d8, v59
	ds_write2_b32 v2, v124, v125 offset1:1
	v_add_u32_e32 v2, 0x38e0, v59
	ds_write2_b32 v2, v126, v127 offset1:1
	v_add_u32_e32 v2, 0x38e8, v59
	ds_write2_b32 v2, v128, v129 offset1:1
	v_add_u32_e32 v2, 0x3cf0, v59
	ds_write2_b32 v2, v130, v131 offset1:1
	v_add_u32_e32 v2, 0x3cf8, v59
	ds_write2_b32 v2, v132, v133 offset1:1
	s_waitcnt vmcnt(0) expcnt(0) lgkmcnt(0)
	ds_read2_b32 v[74:75], v61 offset1:8
	ds_read2_b32 v[76:77], v61 offset0:65 offset1:73
	ds_read2_b32 v[78:79], v61 offset0:130 offset1:138
	ds_read2_b32 v[80:81], v61 offset0:195 offset1:203
	s_waitcnt lgkmcnt(3)
	v_bfe_u32 v2, v74, 16, 1
	v_add3_u32 v2, v74, v2, s27
	s_waitcnt lgkmcnt(2)
	v_bfe_u32 v53, v76, 16, 1
	v_lshrrev_b32_e32 v2, 16, v2
	v_add3_u32 v53, v76, v53, s27
	v_and_or_b32 v70, v53, s28, v2
	v_add_u32_e32 v53, 0x400, v61
	ds_read2_b32 v[82:83], v53 offset0:4 offset1:12
	ds_read2_b32 v[84:85], v53 offset0:69 offset1:77
	s_waitcnt lgkmcnt(3)
	v_bfe_u32 v2, v78, 16, 1
	v_add3_u32 v2, v78, v2, s27
	s_waitcnt lgkmcnt(2)
	v_bfe_u32 v55, v80, 16, 1
	ds_read2_b32 v[86:87], v53 offset0:134 offset1:142
	v_lshrrev_b32_e32 v2, 16, v2
	v_add3_u32 v55, v80, v55, s27
	ds_read2_b32 v[88:89], v53 offset0:199 offset1:207
	v_and_or_b32 v71, v55, s28, v2
	s_waitcnt lgkmcnt(3)
; DI unsigned pk2w(float lo, float hi) { return f2bfw(lo) | (f2bfw(hi) << 16); }
; DI void transpose_item(const float* W, int K, int N, bf16_t* WT, int mode, float* scr, int item, int lane) {
;     ...
;     const int c = lane & 7;
; #pragma unroll
;     for (int j = 0; j < 8; ++j) { const int n = (lane >> 3) + 8 * j; const float* sp = scr + (8 * c) * 65 + n;
;         u32x4 o; o.x = pk2w(sp[0 * 65], sp[1 * 65]); o.y = pk2w(sp[2 * 65], sp[3 * 65]); o.z = pk2w(sp[4 * 65], sp[5 * 65]); o.w = pk2w(sp[6 * 65], sp[7 * 65]);
;         *(u32x4*)(WT + (size_t)(drow0 + n) * K + k0 + 8 * c) = o; }
	v_bfe_u32 v2, v82, 16, 1
	v_add3_u32 v2, v82, v2, s27
	s_waitcnt lgkmcnt(2)
	v_bfe_u32 v55, v84, 16, 1
	v_lshrrev_b32_e32 v2, 16, v2
	v_add3_u32 v55, v84, v55, s27
	v_and_or_b32 v72, v55, s28, v2
	s_waitcnt lgkmcnt(1)
	v_bfe_u32 v2, v86, 16, 1
	v_add3_u32 v2, v86, v2, s27
	s_waitcnt lgkmcnt(0)
	v_bfe_u32 v55, v88, 16, 1
	v_lshrrev_b32_e32 v2, 16, v2
	v_add3_u32 v55, v88, v55, s27
	v_and_or_b32 v73, v55, s28, v2
	v_or_b32_e32 v2, s8, v60
	v_lshlrev_b32_e32 v2, 12, v2
	v_lshl_add_u64 v[90:91], v[56:57], 0, v[2:3]
	v_bfe_u32 v2, v75, 16, 1
	v_add3_u32 v2, v75, v2, s27
	v_bfe_u32 v55, v77, 16, 1
	v_lshrrev_b32_e32 v2, 16, v2
	v_add3_u32 v55, v77, v55, s27
	global_store_dwordx4 v[90:91], v[70:73], off
	ds_read2_b32 v[74:75], v61 offset0:16 offset1:24
	s_nop 0
	v_and_or_b32 v70, v55, s28, v2
	v_bfe_u32 v2, v79, 16, 1
	v_add3_u32 v2, v79, v2, s27
	v_bfe_u32 v55, v81, 16, 1
	v_lshrrev_b32_e32 v2, 16, v2
	v_add3_u32 v55, v81, v55, s27
	v_and_or_b32 v71, v55, s28, v2
	v_bfe_u32 v2, v83, 16, 1
	v_add3_u32 v2, v83, v2, s27
	v_bfe_u32 v55, v85, 16, 1
	v_lshrrev_b32_e32 v2, 16, v2
	v_add3_u32 v55, v85, v55, s27
	v_and_or_b32 v72, v55, s28, v2
	v_bfe_u32 v2, v87, 16, 1
	v_add3_u32 v2, v87, v2, s27
	v_bfe_u32 v55, v89, 16, 1
	v_lshrrev_b32_e32 v2, 16, v2
	v_add3_u32 v55, v89, v55, s27
	v_and_or_b32 v73, v55, s28, v2
	v_or_b32_e32 v2, s8, v62
	v_lshlrev_b32_e32 v2, 12, v2
	v_lshl_add_u64 v[76:77], v[56:57], 0, v[2:3]
	global_store_dwordx4 v[76:77], v[70:73], off
	ds_read2_b32 v[76:77], v61 offset0:81 offset1:89
	ds_read2_b32 v[78:79], v61 offset0:146 offset1:154
	ds_read2_b32 v[80:81], v61 offset0:211 offset1:219
	s_waitcnt lgkmcnt(3)
	v_bfe_u32 v2, v74, 16, 1
	v_add3_u32 v2, v74, v2, s27
	s_waitcnt lgkmcnt(2)
	v_bfe_u32 v55, v76, 16, 1
	ds_read2_b32 v[82:83], v53 offset0:20 offset1:28
	v_lshrrev_b32_e32 v2, 16, v2
	v_add3_u32 v55, v76, v55, s27
	ds_read2_b32 v[84:85], v53 offset0:85 offset1:93
	v_and_or_b32 v70, v55, s28, v2
	s_waitcnt lgkmcnt(3)
	v_bfe_u32 v2, v78, 16, 1
	v_add3_u32 v2, v78, v2, s27
	s_waitcnt lgkmcnt(2)
	v_bfe_u32 v55, v80, 16, 1
	ds_read2_b32 v[86:87], v53 offset0:150 offset1:158
	v_lshrrev_b32_e32 v2, 16, v2
	v_add3_u32 v55, v80, v55, s27
	ds_read2_b32 v[88:89], v53 offset0:215 offset1:223
	v_and_or_b32 v71, v55, s28, v2
	s_waitcnt lgkmcnt(3)
	v_bfe_u32 v2, v82, 16, 1
	v_add3_u32 v2, v82, v2, s27
	s_waitcnt lgkmcnt(2)
	v_bfe_u32 v55, v84, 16, 1
	v_lshrrev_b32_e32 v2, 16, v2
	v_add3_u32 v55, v84, v55, s27
	v_and_or_b32 v72, v55, s28, v2
	s_waitcnt lgkmcnt(1)
	v_bfe_u32 v2, v86, 16, 1
	v_add3_u32 v2, v86, v2, s27
	s_waitcnt lgkmcnt(0)
	v_bfe_u32 v55, v88, 16, 1
	v_lshrrev_b32_e32 v2, 16, v2
	v_add3_u32 v55, v88, v55, s27
	v_and_or_b32 v73, v55, s28, v2
	v_or_b32_e32 v2, s8, v63
	v_lshlrev_b32_e32 v2, 12, v2
	v_lshl_add_u64 v[90:91], v[56:57], 0, v[2:3]
	v_bfe_u32 v2, v75, 16, 1
	v_add3_u32 v2, v75, v2, s27
	v_bfe_u32 v55, v77, 16, 1
	v_lshrrev_b32_e32 v2, 16, v2
	v_add3_u32 v55, v77, v55, s27
	global_store_dwordx4 v[90:91], v[70:73], off
	ds_read2_b32 v[74:75], v61 offset0:32 offset1:40
	s_nop 0
	v_and_or_b32 v70, v55, s28, v2
	v_bfe_u32 v2, v79, 16, 1
	v_add3_u32 v2, v79, v2, s27
	v_bfe_u32 v55, v81, 16, 1
	v_lshrrev_b32_e32 v2, 16, v2
	v_add3_u32 v55, v81, v55, s27
	v_and_or_b32 v71, v55, s28, v2
	v_bfe_u32 v2, v83, 16, 1
	v_add3_u32 v2, v83, v2, s27
	v_bfe_u32 v55, v85, 16, 1
	v_lshrrev_b32_e32 v2, 16, v2
	v_add3_u32 v55, v85, v55, s27
	v_and_or_b32 v72, v55, s28, v2
	v_bfe_u32 v2, v87, 16, 1
	v_add3_u32 v2, v87, v2, s27
	v_bfe_u32 v55, v89, 16, 1
	v_lshrrev_b32_e32 v2, 16, v2
	v_add3_u32 v55, v89, v55, s27
	v_and_or_b32 v73, v55, s28, v2
	v_or_b32_e32 v2, s8, v64
	v_lshlrev_b32_e32 v2, 12, v2
	v_lshl_add_u64 v[76:77], v[56:57], 0, v[2:3]
	global_store_dwordx4 v[76:77], v[70:73], off
	ds_read2_b32 v[76:77], v61 offset0:97 offset1:105
	ds_read2_b32 v[78:79], v61 offset0:162 offset1:170
	ds_read2_b32 v[80:81], v61 offset0:227 offset1:235
	s_waitcnt lgkmcnt(3)
	v_bfe_u32 v2, v74, 16, 1
	v_add3_u32 v2, v74, v2, s27
	s_waitcnt lgkmcnt(2)
	v_bfe_u32 v55, v76, 16, 1
	ds_read2_b32 v[82:83], v53 offset0:36 offset1:44
	v_lshrrev_b32_e32 v2, 16, v2
	v_add3_u32 v55, v76, v55, s27
	ds_read2_b32 v[84:85], v53 offset0:101 offset1:109
	v_and_or_b32 v70, v55, s28, v2
	s_waitcnt lgkmcnt(3)
; DI unsigned pk2w(float lo, float hi) { return f2bfw(lo) | (f2bfw(hi) << 16); }
; DI void transpose_item(const float* W, int K, int N, bf16_t* WT, int mode, float* scr, int item, int lane) {
;     ...
;     const int c = lane & 7;
; #pragma unroll
;     for (int j = 0; j < 8; ++j) { const int n = (lane >> 3) + 8 * j; const float* sp = scr + (8 * c) * 65 + n;
;         u32x4 o; o.x = pk2w(sp[0 * 65], sp[1 * 65]); o.y = pk2w(sp[2 * 65], sp[3 * 65]); o.z = pk2w(sp[4 * 65], sp[5 * 65]); o.w = pk2w(sp[6 * 65], sp[7 * 65]);
;         *(u32x4*)(WT + (size_t)(drow0 + n) * K + k0 + 8 * c) = o; }
;     __builtin_amdgcn_s_waitcnt(0); __builtin_amdgcn_wave_barrier();
	v_bfe_u32 v2, v78, 16, 1
	v_add3_u32 v2, v78, v2, s27
	s_waitcnt lgkmcnt(2)
	v_bfe_u32 v55, v80, 16, 1
	ds_read2_b32 v[86:87], v53 offset0:166 offset1:174
	v_lshrrev_b32_e32 v2, 16, v2
	v_add3_u32 v55, v80, v55, s27
	ds_read2_b32 v[88:89], v53 offset0:231 offset1:239
	v_and_or_b32 v71, v55, s28, v2
	s_waitcnt lgkmcnt(3)
	v_bfe_u32 v2, v82, 16, 1
	v_add3_u32 v2, v82, v2, s27
	s_waitcnt lgkmcnt(2)
	v_bfe_u32 v55, v84, 16, 1
	v_lshrrev_b32_e32 v2, 16, v2
	v_add3_u32 v55, v84, v55, s27
	v_and_or_b32 v72, v55, s28, v2
	s_waitcnt lgkmcnt(1)
	v_bfe_u32 v2, v86, 16, 1
	v_add3_u32 v2, v86, v2, s27
	s_waitcnt lgkmcnt(0)
	v_bfe_u32 v55, v88, 16, 1
	v_lshrrev_b32_e32 v2, 16, v2
	v_add3_u32 v55, v88, v55, s27
	v_and_or_b32 v73, v55, s28, v2
	v_or_b32_e32 v2, s8, v65
	v_lshlrev_b32_e32 v2, 12, v2
	v_lshl_add_u64 v[90:91], v[56:57], 0, v[2:3]
	v_bfe_u32 v2, v75, 16, 1
	v_add3_u32 v2, v75, v2, s27
	v_bfe_u32 v55, v77, 16, 1
	v_lshrrev_b32_e32 v2, 16, v2
	v_add3_u32 v55, v77, v55, s27
	global_store_dwordx4 v[90:91], v[70:73], off
	ds_read2_b32 v[74:75], v61 offset0:48 offset1:56
	s_nop 0
	v_and_or_b32 v70, v55, s28, v2
	v_bfe_u32 v2, v79, 16, 1
	v_add3_u32 v2, v79, v2, s27
	v_bfe_u32 v55, v81, 16, 1
	v_lshrrev_b32_e32 v2, 16, v2
	v_add3_u32 v55, v81, v55, s27
	v_and_or_b32 v71, v55, s28, v2
	v_bfe_u32 v2, v83, 16, 1
	v_add3_u32 v2, v83, v2, s27
	v_bfe_u32 v55, v85, 16, 1
	v_lshrrev_b32_e32 v2, 16, v2
	v_add3_u32 v55, v85, v55, s27
	v_and_or_b32 v72, v55, s28, v2
	v_bfe_u32 v2, v87, 16, 1
	v_add3_u32 v2, v87, v2, s27
	v_bfe_u32 v55, v89, 16, 1
	v_lshrrev_b32_e32 v2, 16, v2
	v_add3_u32 v55, v89, v55, s27
	v_and_or_b32 v73, v55, s28, v2
	v_or_b32_e32 v2, s8, v66
	v_lshlrev_b32_e32 v2, 12, v2
	v_lshl_add_u64 v[76:77], v[56:57], 0, v[2:3]
	global_store_dwordx4 v[76:77], v[70:73], off
	ds_read2_b32 v[76:77], v61 offset0:113 offset1:121
	ds_read2_b32 v[78:79], v61 offset0:178 offset1:186
	ds_read2_b32 v[80:81], v61 offset0:243 offset1:251
	s_waitcnt lgkmcnt(3)
	v_bfe_u32 v2, v74, 16, 1
	v_add3_u32 v2, v74, v2, s27
	s_waitcnt lgkmcnt(2)
	v_bfe_u32 v55, v76, 16, 1
	ds_read2_b32 v[82:83], v53 offset0:52 offset1:60
	v_lshrrev_b32_e32 v2, 16, v2
	v_add3_u32 v55, v76, v55, s27
	ds_read2_b32 v[84:85], v53 offset0:117 offset1:125
	v_and_or_b32 v70, v55, s28, v2
	s_waitcnt lgkmcnt(3)
	v_bfe_u32 v2, v78, 16, 1
	v_add3_u32 v2, v78, v2, s27
	s_waitcnt lgkmcnt(2)
	v_bfe_u32 v55, v80, 16, 1
	ds_read2_b32 v[86:87], v53 offset0:182 offset1:190
	v_lshrrev_b32_e32 v2, 16, v2
	v_add3_u32 v55, v80, v55, s27
	ds_read2_b32 v[88:89], v53 offset0:247 offset1:255
	v_and_or_b32 v71, v55, s28, v2
	s_waitcnt lgkmcnt(3)
	v_bfe_u32 v2, v82, 16, 1
	v_add3_u32 v2, v82, v2, s27
	s_waitcnt lgkmcnt(2)
	v_bfe_u32 v55, v84, 16, 1
	v_lshrrev_b32_e32 v2, 16, v2
	v_add3_u32 v55, v84, v55, s27
	v_and_or_b32 v72, v55, s28, v2
	s_waitcnt lgkmcnt(1)
	v_bfe_u32 v2, v86, 16, 1
	v_add3_u32 v2, v86, v2, s27
	s_waitcnt lgkmcnt(0)
	v_bfe_u32 v53, v88, 16, 1
	v_lshrrev_b32_e32 v2, 16, v2
	v_add3_u32 v53, v88, v53, s27
	v_and_or_b32 v73, v53, s28, v2
	v_or_b32_e32 v2, s8, v67
	v_lshlrev_b32_e32 v2, 12, v2
	v_lshl_add_u64 v[90:91], v[56:57], 0, v[2:3]
	v_bfe_u32 v2, v75, 16, 1
	v_add3_u32 v2, v75, v2, s27
	v_bfe_u32 v53, v77, 16, 1
	v_lshrrev_b32_e32 v2, 16, v2
	v_add3_u32 v53, v77, v53, s27
	global_store_dwordx4 v[90:91], v[70:73], off
	s_nop 1
	v_and_or_b32 v70, v53, s28, v2
	v_bfe_u32 v2, v79, 16, 1
	v_add3_u32 v2, v79, v2, s27
	v_bfe_u32 v53, v81, 16, 1
	v_lshrrev_b32_e32 v2, 16, v2
	v_add3_u32 v53, v81, v53, s27
	v_and_or_b32 v71, v53, s28, v2
	v_bfe_u32 v2, v83, 16, 1
	v_add3_u32 v2, v83, v2, s27
	v_bfe_u32 v53, v85, 16, 1
	v_lshrrev_b32_e32 v2, 16, v2
	v_add3_u32 v53, v85, v53, s27
	v_and_or_b32 v72, v53, s28, v2
	v_bfe_u32 v2, v87, 16, 1
	v_add3_u32 v2, v87, v2, s27
	v_bfe_u32 v53, v89, 16, 1
	v_lshrrev_b32_e32 v2, 16, v2
	v_add3_u32 v53, v89, v53, s27
	v_and_or_b32 v73, v53, s28, v2
	v_or_b32_e32 v2, s8, v68
	v_lshlrev_b32_e32 v2, 12, v2
	v_lshl_add_u64 v[56:57], v[56:57], 0, v[2:3]
	global_store_dwordx4 v[56:57], v[70:73], off
	s_waitcnt lgkmcnt(0)

; DI unsigned pk2w(float lo, float hi) { return f2bfw(lo) | (f2bfw(hi) << 16); }
; DI void transpose_item(const float* W, int K, int N, bf16_t* WT, int mode, float* scr, int item, int lane) {
;     const int nblk = N / 64, kb = item / nblk, nb = item % nblk, k0 = 64 * kb, n0 = 64 * nb;
;     int drow0 = n0;
;     if (mode == 1) { const int seg = n0 >> 10; const int dst = seg < 2 ? seg : (seg == 2 ? 6 : seg - 1); drow0 = dst * 1024 + (n0 & 1023); }
;     else if (mode == 2) { drow0 = n0 < DFF ? (n0 / 128) * 256 + (n0 % 128) : ((n0 - DFF) / 128) * 256 + 128 + ((n0 - DFF) % 128); }
;     else if (mode == 3) { drow0 = (n0 / 128) * 256 + (n0 % 128); }
;     else if (mode == 4) { drow0 = (n0 / 128) * 256 + 128 + (n0 % 128); }
;     f32x4 v[16];
; #pragma unroll
;     for (int i = 0; i < 16; ++i) v[i] = __builtin_nontemporal_load((const f32x4*)(W + (size_t)(k0 + 4 * i + (lane >> 4)) * N + n0 + 4 * (lane & 15)));
; #pragma unroll
;     for (int i = 0; i < 16; ++i) { float* d = scr + (4 * i + (lane >> 4)) * 65 + 4 * (lane & 15); d[0] = v[i][0]; d[1] = v[i][1]; d[2] = v[i][2]; d[3] = v[i][3]; }
;     __builtin_amdgcn_s_waitcnt(0); __builtin_amdgcn_wave_barrier();
;     const int c = lane & 7;
; #pragma unroll
;     for (int j = 0; j < 8; ++j) { const int n = (lane >> 3) + 8 * j; const float* sp = scr + (8 * c) * 65 + n;
;         u32x4 o; o.x = pk2w(sp[0 * 65], sp[1 * 65]); o.y = pk2w(sp[2 * 65], sp[3 * 65]); o.z = pk2w(sp[4 * 65], sp[5 * 65]); o.w = pk2w(sp[6 * 65], sp[7 * 65]);
.LBB0_291:
	s_andn2_b64 vcc, exec, s[8:9]
	s_cbranch_vccnz .LBB0_293
	s_add_i32 s6, s3, 0xfffed300
	s_and_b32 s8, s16, 0x7c0
	s_and_b32 s9, s6, 0x1c0
	v_or_b32_e32 v2, s9, v58
	s_lshl_b32 s6, s8, 2
	v_lshl_add_u64 v[56:57], v[10:11], 0, s[6:7]
	v_lshlrev_b32_e32 v2, 13, v2
	v_lshl_add_u64 v[56:57], v[56:57], 0, v[2:3]
	v_add_co_u32_e32 v74, vcc, 0x8000, v56
	v_add_u32_e32 v2, 0x410, v59
	s_nop 0
	v_addc_co_u32_e32 v75, vcc, 0, v57, vcc
	v_add_co_u32_e32 v78, vcc, 0x10000, v56
	global_load_dwordx4 v[70:73], v[56:57], off nt
	s_nop 0
	global_load_dwordx4 v[74:77], v[74:75], off nt
	v_addc_co_u32_e32 v79, vcc, 0, v57, vcc
	v_add_co_u32_e32 v82, vcc, 0x18000, v56
	s_lshl_b32 s6, s9, 1
	s_nop 0
	v_addc_co_u32_e32 v83, vcc, 0, v57, vcc
	global_load_dwordx4 v[78:81], v[78:79], off nt
	s_nop 0
	global_load_dwordx4 v[82:85], v[82:83], off nt
	v_add_co_u32_e32 v86, vcc, 0x20000, v56
	s_nop 1
	v_addc_co_u32_e32 v87, vcc, 0, v57, vcc
	v_add_co_u32_e32 v90, vcc, 0x28000, v56
	s_nop 1
	v_addc_co_u32_e32 v91, vcc, 0, v57, vcc
	global_load_dwordx4 v[86:89], v[86:87], off nt
	s_nop 0
	global_load_dwordx4 v[90:93], v[90:91], off nt
	v_add_co_u32_e32 v94, vcc, 0x30000, v56
	s_nop 1
	v_addc_co_u32_e32 v95, vcc, 0, v57, vcc
	v_add_co_u32_e32 v98, vcc, 0x38000, v56
	s_nop 1
	v_addc_co_u32_e32 v99, vcc, 0, v57, vcc
	global_load_dwordx4 v[94:97], v[94:95], off nt
	s_nop 0
	global_load_dwordx4 v[98:101], v[98:99], off nt
	v_add_co_u32_e32 v102, vcc, 0x40000, v56
	s_nop 1
	v_addc_co_u32_e32 v103, vcc, 0, v57, vcc
	v_add_co_u32_e32 v106, vcc, 0x48000, v56
	s_nop 1
	v_addc_co_u32_e32 v107, vcc, 0, v57, vcc
	global_load_dwordx4 v[102:105], v[102:103], off nt
	s_nop 0
	global_load_dwordx4 v[106:109], v[106:107], off nt
	v_add_co_u32_e32 v110, vcc, 0x50000, v56
	s_nop 1
	v_addc_co_u32_e32 v111, vcc, 0, v57, vcc
	v_add_co_u32_e32 v114, vcc, 0x58000, v56
	s_nop 1
	v_addc_co_u32_e32 v115, vcc, 0, v57, vcc
	global_load_dwordx4 v[110:113], v[110:111], off nt
	s_nop 0
	global_load_dwordx4 v[114:117], v[114:115], off nt
	v_add_co_u32_e32 v118, vcc, 0x60000, v56
	s_nop 1
	v_addc_co_u32_e32 v119, vcc, 0, v57, vcc
	v_add_co_u32_e32 v122, vcc, 0x68000, v56
	s_nop 1
	v_addc_co_u32_e32 v123, vcc, 0, v57, vcc
	global_load_dwordx4 v[118:121], v[118:119], off nt
	s_nop 0
	global_load_dwordx4 v[122:125], v[122:123], off nt
	v_add_co_u32_e32 v126, vcc, 0x70000, v56
	s_nop 1
	v_addc_co_u32_e32 v127, vcc, 0, v57, vcc
	global_load_dwordx4 v[126:129], v[126:127], off nt
	v_add_co_u32_e32 v56, vcc, 0x78000, v56
	s_nop 1
	v_addc_co_u32_e32 v57, vcc, 0, v57, vcc
	global_load_dwordx4 v[130:133], v[56:57], off nt
	s_waitcnt vmcnt(0)
	ds_write2_b32 v59, v70, v71 offset1:1
	ds_write2_b32 v59, v72, v73 offset0:2 offset1:3
	ds_write2_b32 v2, v74, v75 offset1:1
	v_add_u32_e32 v2, 0x418, v59
	ds_write2_b32 v2, v76, v77 offset1:1
	v_add_u32_e32 v2, 0x820, v59
	v_lshl_add_u64 v[56:57], v[42:43], 0, s[6:7]
	ds_write2_b32 v2, v78, v79 offset1:1
	v_add_u32_e32 v2, 0x828, v59
	ds_write2_b32 v2, v80, v81 offset1:1
	v_add_u32_e32 v2, 0xc30, v59
	ds_write2_b32 v2, v82, v83 offset1:1
	v_add_u32_e32 v2, 0xc38, v59
	ds_write2_b32 v2, v84, v85 offset1:1
	v_add_u32_e32 v2, 0x1040, v59
	ds_write2_b32 v2, v86, v87 offset1:1
	v_add_u32_e32 v2, 0x1048, v59
	ds_write2_b32 v2, v88, v89 offset1:1
	v_add_u32_e32 v2, 0x1450, v59
	ds_write2_b32 v2, v90, v91 offset1:1
	v_add_u32_e32 v2, 0x1458, v59
	ds_write2_b32 v2, v92, v93 offset1:1
	v_add_u32_e32 v2, 0x1860, v59
	ds_write2_b32 v2, v94, v95 offset1:1
	v_add_u32_e32 v2, 0x1868, v59
	ds_write2_b32 v2, v96, v97 offset1:1
	v_add_u32_e32 v2, 0x1c70, v59
	ds_write2_b32 v2, v98, v99 offset1:1
	v_add_u32_e32 v2, 0x1c78, v59
	ds_write2_b32 v2, v100, v101 offset1:1
	v_add_u32_e32 v2, 0x2080, v59
	ds_write2_b32 v2, v102, v103 offset1:1
	v_add_u32_e32 v2, 0x2088, v59
	ds_write2_b32 v2, v104, v105 offset1:1
	v_add_u32_e32 v2, 0x2490, v59
	ds_write2_b32 v2, v106, v107 offset1:1
	v_add_u32_e32 v2, 0x2498, v59
	ds_write2_b32 v2, v108, v109 offset1:1
	v_add_u32_e32 v2, 0x28a0, v59
	ds_write2_b32 v2, v110, v111 offset1:1
	v_add_u32_e32 v2, 0x28a8, v59
	ds_write2_b32 v2, v112, v113 offset1:1
	v_add_u32_e32 v2, 0x2cb0, v59
	ds_write2_b32 v2, v114, v115 offset1:1
	v_add_u32_e32 v2, 0x2cb8, v59
	ds_write2_b32 v2, v116, v117 offset1:1
	v_add_u32_e32 v2, 0x30c0, v59
	ds_write2_b32 v2, v118, v119 offset1:1
	v_add_u32_e32 v2, 0x30c8, v59
	ds_write2_b32 v2, v120, v121 offset1:1
	v_add_u32_e32 v2, 0x34d0, v59
	ds_write2_b32 v2, v122, v123 offset1:1
	v_add_u32_e32 v2, 0x34d8, v59
	ds_write2_b32 v2, v124, v125 offset1:1
	v_add_u32_e32 v2, 0x38e0, v59
	ds_write2_b32 v2, v126, v127 offset1:1
	v_add_u32_e32 v2, 0x38e8, v59
	ds_write2_b32 v2, v128, v129 offset1:1
	v_add_u32_e32 v2, 0x3cf0, v59
	ds_write2_b32 v2, v130, v131 offset1:1
	v_add_u32_e32 v2, 0x3cf8, v59
	ds_write2_b32 v2, v132, v133 offset1:1
	s_waitcnt vmcnt(0) expcnt(0) lgkmcnt(0)
	ds_read2_b32 v[74:75], v61 offset1:8
	ds_read2_b32 v[76:77], v61 offset0:65 offset1:73
	ds_read2_b32 v[78:79], v61 offset0:130 offset1:138
	ds_read2_b32 v[80:81], v61 offset0:195 offset1:203
	s_waitcnt lgkmcnt(3)
	v_bfe_u32 v2, v74, 16, 1
	v_add3_u32 v2, v74, v2, s27
	s_waitcnt lgkmcnt(2)
	v_bfe_u32 v53, v76, 16, 1
	v_lshrrev_b32_e32 v2, 16, v2
	v_add3_u32 v53, v76, v53, s27
	v_and_or_b32 v70, v53, s28, v2
	v_add_u32_e32 v53, 0x400, v61
	ds_read2_b32 v[82:83], v53 offset0:4 offset1:12
	ds_read2_b32 v[84:85], v53 offset0:69 offset1:77
	s_waitcnt lgkmcnt(3)
	v_bfe_u32 v2, v78, 16, 1
	v_add3_u32 v2, v78, v2, s27
	s_waitcnt lgkmcnt(2)
	v_bfe_u32 v55, v80, 16, 1
	ds_read2_b32 v[86:87], v53 offset0:134 offset1:142
	v_lshrrev_b32_e32 v2, 16, v2
	v_add3_u32 v55, v80, v55, s27
	ds_read2_b32 v[88:89], v53 offset0:199 offset1:207
	v_and_or_b32 v71, v55, s28, v2
	s_waitcnt lgkmcnt(3)
; DI unsigned pk2w(float lo, float hi) { return f2bfw(lo) | (f2bfw(hi) << 16); }
; DI void transpose_item(const float* W, int K, int N, bf16_t* WT, int mode, float* scr, int item, int lane) {
;     ...
;     const int c = lane & 7;
; #pragma unroll
;     for (int j = 0; j < 8; ++j) { const int n = (lane >> 3) + 8 * j; const float* sp = scr + (8 * c) * 65 + n;
;         u32x4 o; o.x = pk2w(sp[0 * 65], sp[1 * 65]); o.y = pk2w(sp[2 * 65], sp[3 * 65]); o.z = pk2w(sp[4 * 65], sp[5 * 65]); o.w = pk2w(sp[6 * 65], sp[7 * 65]);
;         *(u32x4*)(WT + (size_t)(drow0 + n) * K + k0 + 8 * c) = o; }
	v_bfe_u32 v2, v82, 16, 1
	v_add3_u32 v2, v82, v2, s27
	s_waitcnt lgkmcnt(2)
	v_bfe_u32 v55, v84, 16, 1
	v_lshrrev_b32_e32 v2, 16, v2
	v_add3_u32 v55, v84, v55, s27
	v_and_or_b32 v72, v55, s28, v2
	s_waitcnt lgkmcnt(1)
	v_bfe_u32 v2, v86, 16, 1
	v_add3_u32 v2, v86, v2, s27
	s_waitcnt lgkmcnt(0)
	v_bfe_u32 v55, v88, 16, 1
	v_lshrrev_b32_e32 v2, 16, v2
	v_add3_u32 v55, v88, v55, s27
	v_and_or_b32 v73, v55, s28, v2
	v_or_b32_e32 v2, s8, v60
	v_lshlrev_b32_e32 v2, 9, v2
	v_lshl_add_u64 v[90:91], v[56:57], 0, v[2:3]
	v_bfe_u32 v2, v75, 16, 1
	v_add3_u32 v2, v75, v2, s27
	v_bfe_u32 v55, v77, 16, 1
	v_lshrrev_b32_e32 v2, 16, v2
	v_add3_u32 v55, v77, v55, s27
	global_store_dwordx4 v[90:91], v[70:73], off
	ds_read2_b32 v[74:75], v61 offset0:16 offset1:24
	s_nop 0
	v_and_or_b32 v70, v55, s28, v2
	v_bfe_u32 v2, v79, 16, 1
	v_add3_u32 v2, v79, v2, s27
	v_bfe_u32 v55, v81, 16, 1
	v_lshrrev_b32_e32 v2, 16, v2
	v_add3_u32 v55, v81, v55, s27
	v_and_or_b32 v71, v55, s28, v2
	v_bfe_u32 v2, v83, 16, 1
	v_add3_u32 v2, v83, v2, s27
	v_bfe_u32 v55, v85, 16, 1
	v_lshrrev_b32_e32 v2, 16, v2
	v_add3_u32 v55, v85, v55, s27
	v_and_or_b32 v72, v55, s28, v2
	v_bfe_u32 v2, v87, 16, 1
	v_add3_u32 v2, v87, v2, s27
	v_bfe_u32 v55, v89, 16, 1
	v_lshrrev_b32_e32 v2, 16, v2
	v_add3_u32 v55, v89, v55, s27
	v_and_or_b32 v73, v55, s28, v2
	v_or_b32_e32 v2, s8, v62
	v_lshlrev_b32_e32 v2, 9, v2
	v_lshl_add_u64 v[76:77], v[56:57], 0, v[2:3]
	global_store_dwordx4 v[76:77], v[70:73], off
	ds_read2_b32 v[76:77], v61 offset0:81 offset1:89
	ds_read2_b32 v[78:79], v61 offset0:146 offset1:154
	ds_read2_b32 v[80:81], v61 offset0:211 offset1:219
	s_waitcnt lgkmcnt(3)
	v_bfe_u32 v2, v74, 16, 1
	v_add3_u32 v2, v74, v2, s27
	s_waitcnt lgkmcnt(2)
	v_bfe_u32 v55, v76, 16, 1
	ds_read2_b32 v[82:83], v53 offset0:20 offset1:28
	v_lshrrev_b32_e32 v2, 16, v2
	v_add3_u32 v55, v76, v55, s27
	ds_read2_b32 v[84:85], v53 offset0:85 offset1:93
	v_and_or_b32 v70, v55, s28, v2
	s_waitcnt lgkmcnt(3)
	v_bfe_u32 v2, v78, 16, 1
	v_add3_u32 v2, v78, v2, s27
	s_waitcnt lgkmcnt(2)
	v_bfe_u32 v55, v80, 16, 1
	ds_read2_b32 v[86:87], v53 offset0:150 offset1:158
	v_lshrrev_b32_e32 v2, 16, v2
	v_add3_u32 v55, v80, v55, s27
	ds_read2_b32 v[88:89], v53 offset0:215 offset1:223
	v_and_or_b32 v71, v55, s28, v2
	s_waitcnt lgkmcnt(3)
	v_bfe_u32 v2, v82, 16, 1
	v_add3_u32 v2, v82, v2, s27
	s_waitcnt lgkmcnt(2)
	v_bfe_u32 v55, v84, 16, 1
	v_lshrrev_b32_e32 v2, 16, v2
	v_add3_u32 v55, v84, v55, s27
	v_and_or_b32 v72, v55, s28, v2
	s_waitcnt lgkmcnt(1)
	v_bfe_u32 v2, v86, 16, 1
	v_add3_u32 v2, v86, v2, s27
	s_waitcnt lgkmcnt(0)
	v_bfe_u32 v55, v88, 16, 1
	v_lshrrev_b32_e32 v2, 16, v2
	v_add3_u32 v55, v88, v55, s27
	v_and_or_b32 v73, v55, s28, v2
	v_or_b32_e32 v2, s8, v63
	v_lshlrev_b32_e32 v2, 9, v2
	v_lshl_add_u64 v[90:91], v[56:57], 0, v[2:3]
	v_bfe_u32 v2, v75, 16, 1
	v_add3_u32 v2, v75, v2, s27
	v_bfe_u32 v55, v77, 16, 1
	v_lshrrev_b32_e32 v2, 16, v2
	v_add3_u32 v55, v77, v55, s27
	global_store_dwordx4 v[90:91], v[70:73], off
	ds_read2_b32 v[74:75], v61 offset0:32 offset1:40
	s_nop 0
	v_and_or_b32 v70, v55, s28, v2
	v_bfe_u32 v2, v79, 16, 1
	v_add3_u32 v2, v79, v2, s27
	v_bfe_u32 v55, v81, 16, 1
	v_lshrrev_b32_e32 v2, 16, v2
	v_add3_u32 v55, v81, v55, s27
	v_and_or_b32 v71, v55, s28, v2
	v_bfe_u32 v2, v83, 16, 1
	v_add3_u32 v2, v83, v2, s27
	v_bfe_u32 v55, v85, 16, 1
	v_lshrrev_b32_e32 v2, 16, v2
	v_add3_u32 v55, v85, v55, s27
	v_and_or_b32 v72, v55, s28, v2
	v_bfe_u32 v2, v87, 16, 1
	v_add3_u32 v2, v87, v2, s27
	v_bfe_u32 v55, v89, 16, 1
	v_lshrrev_b32_e32 v2, 16, v2
	v_add3_u32 v55, v89, v55, s27
	v_and_or_b32 v73, v55, s28, v2
	v_or_b32_e32 v2, s8, v64
	v_lshlrev_b32_e32 v2, 9, v2
	v_lshl_add_u64 v[76:77], v[56:57], 0, v[2:3]
	global_store_dwordx4 v[76:77], v[70:73], off
	ds_read2_b32 v[76:77], v61 offset0:97 offset1:105
	ds_read2_b32 v[78:79], v61 offset0:162 offset1:170
	ds_read2_b32 v[80:81], v61 offset0:227 offset1:235
	s_waitcnt lgkmcnt(3)
	v_bfe_u32 v2, v74, 16, 1
	v_add3_u32 v2, v74, v2, s27
	s_waitcnt lgkmcnt(2)
	v_bfe_u32 v55, v76, 16, 1
	ds_read2_b32 v[82:83], v53 offset0:36 offset1:44
	v_lshrrev_b32_e32 v2, 16, v2
	v_add3_u32 v55, v76, v55, s27
	ds_read2_b32 v[84:85], v53 offset0:101 offset1:109
	v_and_or_b32 v70, v55, s28, v2
	s_waitcnt lgkmcnt(3)
; DI unsigned pk2w(float lo, float hi) { return f2bfw(lo) | (f2bfw(hi) << 16); }
; DI void transpose_item(const float* W, int K, int N, bf16_t* WT, int mode, float* scr, int item, int lane) {
;     ...
;     const int c = lane & 7;
; #pragma unroll
;     for (int j = 0; j < 8; ++j) { const int n = (lane >> 3) + 8 * j; const float* sp = scr + (8 * c) * 65 + n;
;         u32x4 o; o.x = pk2w(sp[0 * 65], sp[1 * 65]); o.y = pk2w(sp[2 * 65], sp[3 * 65]); o.z = pk2w(sp[4 * 65], sp[5 * 65]); o.w = pk2w(sp[6 * 65], sp[7 * 65]);
;         *(u32x4*)(WT + (size_t)(drow0 + n) * K + k0 + 8 * c) = o; }
;     __builtin_amdgcn_s_waitcnt(0); __builtin_amdgcn_wave_barrier();
	v_bfe_u32 v2, v78, 16, 1
	v_add3_u32 v2, v78, v2, s27
	s_waitcnt lgkmcnt(2)
	v_bfe_u32 v55, v80, 16, 1
	ds_read2_b32 v[86:87], v53 offset0:166 offset1:174
	v_lshrrev_b32_e32 v2, 16, v2
	v_add3_u32 v55, v80, v55, s27
	ds_read2_b32 v[88:89], v53 offset0:231 offset1:239
	v_and_or_b32 v71, v55, s28, v2
	s_waitcnt lgkmcnt(3)
	v_bfe_u32 v2, v82, 16, 1
	v_add3_u32 v2, v82, v2, s27
	s_waitcnt lgkmcnt(2)
	v_bfe_u32 v55, v84, 16, 1
	v_lshrrev_b32_e32 v2, 16, v2
	v_add3_u32 v55, v84, v55, s27
	v_and_or_b32 v72, v55, s28, v2
	s_waitcnt lgkmcnt(1)
	v_bfe_u32 v2, v86, 16, 1
	v_add3_u32 v2, v86, v2, s27
	s_waitcnt lgkmcnt(0)
	v_bfe_u32 v55, v88, 16, 1
	v_lshrrev_b32_e32 v2, 16, v2
	v_add3_u32 v55, v88, v55, s27
	v_and_or_b32 v73, v55, s28, v2
	v_or_b32_e32 v2, s8, v65
	v_lshlrev_b32_e32 v2, 9, v2
	v_lshl_add_u64 v[90:91], v[56:57], 0, v[2:3]
	v_bfe_u32 v2, v75, 16, 1
	v_add3_u32 v2, v75, v2, s27
	v_bfe_u32 v55, v77, 16, 1
	v_lshrrev_b32_e32 v2, 16, v2
	v_add3_u32 v55, v77, v55, s27
	global_store_dwordx4 v[90:91], v[70:73], off
	ds_read2_b32 v[74:75], v61 offset0:48 offset1:56
	s_nop 0
	v_and_or_b32 v70, v55, s28, v2
	v_bfe_u32 v2, v79, 16, 1
	v_add3_u32 v2, v79, v2, s27
	v_bfe_u32 v55, v81, 16, 1
	v_lshrrev_b32_e32 v2, 16, v2
	v_add3_u32 v55, v81, v55, s27
	v_and_or_b32 v71, v55, s28, v2
	v_bfe_u32 v2, v83, 16, 1
	v_add3_u32 v2, v83, v2, s27
	v_bfe_u32 v55, v85, 16, 1
	v_lshrrev_b32_e32 v2, 16, v2
	v_add3_u32 v55, v85, v55, s27
	v_and_or_b32 v72, v55, s28, v2
	v_bfe_u32 v2, v87, 16, 1
	v_add3_u32 v2, v87, v2, s27
	v_bfe_u32 v55, v89, 16, 1
	v_lshrrev_b32_e32 v2, 16, v2
	v_add3_u32 v55, v89, v55, s27
	v_and_or_b32 v73, v55, s28, v2
	v_or_b32_e32 v2, s8, v66
	v_lshlrev_b32_e32 v2, 9, v2
	v_lshl_add_u64 v[76:77], v[56:57], 0, v[2:3]
	global_store_dwordx4 v[76:77], v[70:73], off
	ds_read2_b32 v[76:77], v61 offset0:113 offset1:121
	ds_read2_b32 v[78:79], v61 offset0:178 offset1:186
	ds_read2_b32 v[80:81], v61 offset0:243 offset1:251
	s_waitcnt lgkmcnt(3)
	v_bfe_u32 v2, v74, 16, 1
	v_add3_u32 v2, v74, v2, s27
	s_waitcnt lgkmcnt(2)
	v_bfe_u32 v55, v76, 16, 1
	ds_read2_b32 v[82:83], v53 offset0:52 offset1:60
	v_lshrrev_b32_e32 v2, 16, v2
	v_add3_u32 v55, v76, v55, s27
	ds_read2_b32 v[84:85], v53 offset0:117 offset1:125
	v_and_or_b32 v70, v55, s28, v2
	s_waitcnt lgkmcnt(3)
	v_bfe_u32 v2, v78, 16, 1
	v_add3_u32 v2, v78, v2, s27
	s_waitcnt lgkmcnt(2)
	v_bfe_u32 v55, v80, 16, 1
	ds_read2_b32 v[86:87], v53 offset0:182 offset1:190
	v_lshrrev_b32_e32 v2, 16, v2
	v_add3_u32 v55, v80, v55, s27
	ds_read2_b32 v[88:89], v53 offset0:247 offset1:255
	v_and_or_b32 v71, v55, s28, v2
	s_waitcnt lgkmcnt(3)
	v_bfe_u32 v2, v82, 16, 1
	v_add3_u32 v2, v82, v2, s27
	s_waitcnt lgkmcnt(2)
	v_bfe_u32 v55, v84, 16, 1
	v_lshrrev_b32_e32 v2, 16, v2
	v_add3_u32 v55, v84, v55, s27
	v_and_or_b32 v72, v55, s28, v2
	s_waitcnt lgkmcnt(1)
	v_bfe_u32 v2, v86, 16, 1
	v_add3_u32 v2, v86, v2, s27
	s_waitcnt lgkmcnt(0)
	v_bfe_u32 v53, v88, 16, 1
	v_lshrrev_b32_e32 v2, 16, v2
	v_add3_u32 v53, v88, v53, s27
	v_and_or_b32 v73, v53, s28, v2
	v_or_b32_e32 v2, s8, v67
	v_lshlrev_b32_e32 v2, 9, v2
	v_lshl_add_u64 v[90:91], v[56:57], 0, v[2:3]
	v_bfe_u32 v2, v75, 16, 1
	v_add3_u32 v2, v75, v2, s27
	v_bfe_u32 v53, v77, 16, 1
	v_lshrrev_b32_e32 v2, 16, v2
	v_add3_u32 v53, v77, v53, s27
	global_store_dwordx4 v[90:91], v[70:73], off
	s_nop 1
	v_and_or_b32 v70, v53, s28, v2
	v_bfe_u32 v2, v79, 16, 1
	v_add3_u32 v2, v79, v2, s27
	v_bfe_u32 v53, v81, 16, 1
	v_lshrrev_b32_e32 v2, 16, v2
	v_add3_u32 v53, v81, v53, s27
	v_and_or_b32 v71, v53, s28, v2
	v_bfe_u32 v2, v83, 16, 1
	v_add3_u32 v2, v83, v2, s27
	v_bfe_u32 v53, v85, 16, 1
	v_lshrrev_b32_e32 v2, 16, v2
	v_add3_u32 v53, v85, v53, s27
	v_and_or_b32 v72, v53, s28, v2
	v_bfe_u32 v2, v87, 16, 1
	v_add3_u32 v2, v87, v2, s27
	v_bfe_u32 v53, v89, 16, 1
	v_lshrrev_b32_e32 v2, 16, v2
	v_add3_u32 v53, v89, v53, s27
	v_and_or_b32 v73, v53, s28, v2
	v_or_b32_e32 v2, s8, v68
	v_lshlrev_b32_e32 v2, 9, v2
	v_lshl_add_u64 v[56:57], v[56:57], 0, v[2:3]
	global_store_dwordx4 v[56:57], v[70:73], off
	s_waitcnt lgkmcnt(0)

; DI unsigned pk2w(float lo, float hi) { return f2bfw(lo) | (f2bfw(hi) << 16); }
; DI void transpose_item(const float* W, int K, int N, bf16_t* WT, int mode, float* scr, int item, int lane) {
;     const int nblk = N / 64, kb = item / nblk, nb = item % nblk, k0 = 64 * kb, n0 = 64 * nb;
;     int drow0 = n0;
;     if (mode == 1) { const int seg = n0 >> 10; const int dst = seg < 2 ? seg : (seg == 2 ? 6 : seg - 1); drow0 = dst * 1024 + (n0 & 1023); }
;     else if (mode == 2) { drow0 = n0 < DFF ? (n0 / 128) * 256 + (n0 % 128) : ((n0 - DFF) / 128) * 256 + 128 + ((n0 - DFF) % 128); }
;     else if (mode == 3) { drow0 = (n0 / 128) * 256 + (n0 % 128); }
;     else if (mode == 4) { drow0 = (n0 / 128) * 256 + 128 + (n0 % 128); }
;     f32x4 v[16];
; #pragma unroll
;     for (int i = 0; i < 16; ++i) v[i] = __builtin_nontemporal_load((const f32x4*)(W + (size_t)(k0 + 4 * i + (lane >> 4)) * N + n0 + 4 * (lane & 15)));
; #pragma unroll
;     for (int i = 0; i < 16; ++i) { float* d = scr + (4 * i + (lane >> 4)) * 65 + 4 * (lane & 15); d[0] = v[i][0]; d[1] = v[i][1]; d[2] = v[i][2]; d[3] = v[i][3]; }
;     __builtin_amdgcn_s_waitcnt(0); __builtin_amdgcn_wave_barrier();
;     const int c = lane & 7;
; #pragma unroll
;     for (int j = 0; j < 8; ++j) { const int n = (lane >> 3) + 8 * j; const float* sp = scr + (8 * c) * 65 + n;
;         u32x4 o; o.x = pk2w(sp[0 * 65], sp[1 * 65]); o.y = pk2w(sp[2 * 65], sp[3 * 65]); o.z = pk2w(sp[4 * 65], sp[5 * 65]); o.w = pk2w(sp[6 * 65], sp[7 * 65]);
.LBB0_294:
	s_andn2_b64 vcc, exec, s[8:9]
	s_cbranch_vccnz .LBB0_296
	s_add_i32 s6, s3, 0x8300
	s_and_b32 s8, s16, 0x7c0
	s_and_b32 s9, s6, 0x1ffc0
	v_or_b32_e32 v2, s9, v58
	s_lshl_b32 s6, s8, 2
	v_lshl_add_u64 v[56:57], v[12:13], 0, s[6:7]
	v_lshlrev_b32_e32 v2, 13, v2
	v_lshl_add_u64 v[56:57], v[56:57], 0, v[2:3]
	v_add_co_u32_e32 v74, vcc, 0x8000, v56
	v_add_u32_e32 v2, 0x410, v59
	s_nop 0
	v_addc_co_u32_e32 v75, vcc, 0, v57, vcc
	v_add_co_u32_e32 v78, vcc, 0x10000, v56
	global_load_dwordx4 v[70:73], v[56:57], off nt
	s_nop 0
	global_load_dwordx4 v[74:77], v[74:75], off nt
	v_addc_co_u32_e32 v79, vcc, 0, v57, vcc
	v_add_co_u32_e32 v82, vcc, 0x18000, v56
	s_lshl_b32 s6, s9, 1
	s_nop 0
	v_addc_co_u32_e32 v83, vcc, 0, v57, vcc
	global_load_dwordx4 v[78:81], v[78:79], off nt
	s_nop 0
	global_load_dwordx4 v[82:85], v[82:83], off nt
	v_add_co_u32_e32 v86, vcc, 0x20000, v56
	s_nop 1
	v_addc_co_u32_e32 v87, vcc, 0, v57, vcc
	v_add_co_u32_e32 v90, vcc, 0x28000, v56
	s_nop 1
	v_addc_co_u32_e32 v91, vcc, 0, v57, vcc
	global_load_dwordx4 v[86:89], v[86:87], off nt
	s_nop 0
	global_load_dwordx4 v[90:93], v[90:91], off nt
	v_add_co_u32_e32 v94, vcc, 0x30000, v56
	s_nop 1
	v_addc_co_u32_e32 v95, vcc, 0, v57, vcc
	v_add_co_u32_e32 v98, vcc, 0x38000, v56
	s_nop 1
	v_addc_co_u32_e32 v99, vcc, 0, v57, vcc
	global_load_dwordx4 v[94:97], v[94:95], off nt
	s_nop 0
	global_load_dwordx4 v[98:101], v[98:99], off nt
	v_add_co_u32_e32 v102, vcc, 0x40000, v56
	s_nop 1
	v_addc_co_u32_e32 v103, vcc, 0, v57, vcc
	v_add_co_u32_e32 v106, vcc, 0x48000, v56
	s_nop 1
	v_addc_co_u32_e32 v107, vcc, 0, v57, vcc
	global_load_dwordx4 v[102:105], v[102:103], off nt
	s_nop 0
	global_load_dwordx4 v[106:109], v[106:107], off nt
	v_add_co_u32_e32 v110, vcc, 0x50000, v56
	s_nop 1
	v_addc_co_u32_e32 v111, vcc, 0, v57, vcc
	v_add_co_u32_e32 v114, vcc, 0x58000, v56
	s_nop 1
	v_addc_co_u32_e32 v115, vcc, 0, v57, vcc
	global_load_dwordx4 v[110:113], v[110:111], off nt
	s_nop 0
	global_load_dwordx4 v[114:117], v[114:115], off nt
	v_add_co_u32_e32 v118, vcc, 0x60000, v56
	s_nop 1
	v_addc_co_u32_e32 v119, vcc, 0, v57, vcc
	v_add_co_u32_e32 v122, vcc, 0x68000, v56
	s_nop 1
	v_addc_co_u32_e32 v123, vcc, 0, v57, vcc
	global_load_dwordx4 v[118:121], v[118:119], off nt
	s_nop 0
	global_load_dwordx4 v[122:125], v[122:123], off nt
	v_add_co_u32_e32 v126, vcc, 0x70000, v56
	s_nop 1
	v_addc_co_u32_e32 v127, vcc, 0, v57, vcc
	global_load_dwordx4 v[126:129], v[126:127], off nt
	v_add_co_u32_e32 v56, vcc, 0x78000, v56
	s_nop 1
	v_addc_co_u32_e32 v57, vcc, 0, v57, vcc
	global_load_dwordx4 v[130:133], v[56:57], off nt
	s_waitcnt vmcnt(0)
	ds_write2_b32 v59, v70, v71 offset1:1
	ds_write2_b32 v59, v72, v73 offset0:2 offset1:3
	ds_write2_b32 v2, v74, v75 offset1:1
	v_add_u32_e32 v2, 0x418, v59
	ds_write2_b32 v2, v76, v77 offset1:1
	v_add_u32_e32 v2, 0x820, v59
	v_lshl_add_u64 v[56:57], v[44:45], 0, s[6:7]
	ds_write2_b32 v2, v78, v79 offset1:1
	v_add_u32_e32 v2, 0x828, v59
	ds_write2_b32 v2, v80, v81 offset1:1
	v_add_u32_e32 v2, 0xc30, v59
	ds_write2_b32 v2, v82, v83 offset1:1
	v_add_u32_e32 v2, 0xc38, v59
	ds_write2_b32 v2, v84, v85 offset1:1
	v_add_u32_e32 v2, 0x1040, v59
	ds_write2_b32 v2, v86, v87 offset1:1
	v_add_u32_e32 v2, 0x1048, v59
	ds_write2_b32 v2, v88, v89 offset1:1
	v_add_u32_e32 v2, 0x1450, v59
	ds_write2_b32 v2, v90, v91 offset1:1
	v_add_u32_e32 v2, 0x1458, v59
	ds_write2_b32 v2, v92, v93 offset1:1
	v_add_u32_e32 v2, 0x1860, v59
	ds_write2_b32 v2, v94, v95 offset1:1
	v_add_u32_e32 v2, 0x1868, v59
	ds_write2_b32 v2, v96, v97 offset1:1
	v_add_u32_e32 v2, 0x1c70, v59
	ds_write2_b32 v2, v98, v99 offset1:1
	v_add_u32_e32 v2, 0x1c78, v59
	ds_write2_b32 v2, v100, v101 offset1:1
	v_add_u32_e32 v2, 0x2080, v59
	ds_write2_b32 v2, v102, v103 offset1:1
	v_add_u32_e32 v2, 0x2088, v59
	ds_write2_b32 v2, v104, v105 offset1:1
	v_add_u32_e32 v2, 0x2490, v59
	ds_write2_b32 v2, v106, v107 offset1:1
	v_add_u32_e32 v2, 0x2498, v59
	ds_write2_b32 v2, v108, v109 offset1:1
	v_add_u32_e32 v2, 0x28a0, v59
	ds_write2_b32 v2, v110, v111 offset1:1
	v_add_u32_e32 v2, 0x28a8, v59
	ds_write2_b32 v2, v112, v113 offset1:1
	v_add_u32_e32 v2, 0x2cb0, v59
	ds_write2_b32 v2, v114, v115 offset1:1
	v_add_u32_e32 v2, 0x2cb8, v59
	ds_write2_b32 v2, v116, v117 offset1:1
	v_add_u32_e32 v2, 0x30c0, v59
	ds_write2_b32 v2, v118, v119 offset1:1
	v_add_u32_e32 v2, 0x30c8, v59
	ds_write2_b32 v2, v120, v121 offset1:1
	v_add_u32_e32 v2, 0x34d0, v59
	ds_write2_b32 v2, v122, v123 offset1:1
	v_add_u32_e32 v2, 0x34d8, v59
	ds_write2_b32 v2, v124, v125 offset1:1
	v_add_u32_e32 v2, 0x38e0, v59
	ds_write2_b32 v2, v126, v127 offset1:1
	v_add_u32_e32 v2, 0x38e8, v59
	ds_write2_b32 v2, v128, v129 offset1:1
	v_add_u32_e32 v2, 0x3cf0, v59
	ds_write2_b32 v2, v130, v131 offset1:1
	v_add_u32_e32 v2, 0x3cf8, v59
	ds_write2_b32 v2, v132, v133 offset1:1
	s_waitcnt vmcnt(0) expcnt(0) lgkmcnt(0)
	ds_read2_b32 v[74:75], v61 offset1:8
	ds_read2_b32 v[76:77], v61 offset0:65 offset1:73
	ds_read2_b32 v[78:79], v61 offset0:130 offset1:138
	ds_read2_b32 v[80:81], v61 offset0:195 offset1:203
	s_waitcnt lgkmcnt(3)
	v_bfe_u32 v2, v74, 16, 1
	v_add3_u32 v2, v74, v2, s27
	s_waitcnt lgkmcnt(2)
	v_bfe_u32 v53, v76, 16, 1
	v_lshrrev_b32_e32 v2, 16, v2
	v_add3_u32 v53, v76, v53, s27
	v_and_or_b32 v70, v53, s28, v2
	v_add_u32_e32 v53, 0x400, v61
	ds_read2_b32 v[82:83], v53 offset0:4 offset1:12
	ds_read2_b32 v[84:85], v53 offset0:69 offset1:77
	s_waitcnt lgkmcnt(3)
	v_bfe_u32 v2, v78, 16, 1
	v_add3_u32 v2, v78, v2, s27
	s_waitcnt lgkmcnt(2)
	v_bfe_u32 v55, v80, 16, 1
	ds_read2_b32 v[86:87], v53 offset0:134 offset1:142
	v_lshrrev_b32_e32 v2, 16, v2
	v_add3_u32 v55, v80, v55, s27
	ds_read2_b32 v[88:89], v53 offset0:199 offset1:207
	v_and_or_b32 v71, v55, s28, v2
	s_waitcnt lgkmcnt(3)
; DI unsigned pk2w(float lo, float hi) { return f2bfw(lo) | (f2bfw(hi) << 16); }
; DI void transpose_item(const float* W, int K, int N, bf16_t* WT, int mode, float* scr, int item, int lane) {
;     ...
;     const int c = lane & 7;
; #pragma unroll
;     for (int j = 0; j < 8; ++j) { const int n = (lane >> 3) + 8 * j; const float* sp = scr + (8 * c) * 65 + n;
;         u32x4 o; o.x = pk2w(sp[0 * 65], sp[1 * 65]); o.y = pk2w(sp[2 * 65], sp[3 * 65]); o.z = pk2w(sp[4 * 65], sp[5 * 65]); o.w = pk2w(sp[6 * 65], sp[7 * 65]);
;         *(u32x4*)(WT + (size_t)(drow0 + n) * K + k0 + 8 * c) = o; }
	v_bfe_u32 v2, v82, 16, 1
	v_add3_u32 v2, v82, v2, s27
	s_waitcnt lgkmcnt(2)
	v_bfe_u32 v55, v84, 16, 1
	v_lshrrev_b32_e32 v2, 16, v2
	v_add3_u32 v55, v84, v55, s27
	v_and_or_b32 v72, v55, s28, v2
	s_waitcnt lgkmcnt(1)
	v_bfe_u32 v2, v86, 16, 1
	v_add3_u32 v2, v86, v2, s27
	s_waitcnt lgkmcnt(0)
	v_bfe_u32 v55, v88, 16, 1
	v_lshrrev_b32_e32 v2, 16, v2
	v_add3_u32 v55, v88, v55, s27
	v_and_or_b32 v73, v55, s28, v2
	v_or_b32_e32 v2, s8, v60
	v_mul_u32_u24_e32 v2, 0x1600, v2
	v_lshlrev_b32_e32 v2, 1, v2
	v_lshl_add_u64 v[90:91], v[56:57], 0, v[2:3]
	v_bfe_u32 v2, v75, 16, 1
	v_add3_u32 v2, v75, v2, s27
	v_bfe_u32 v55, v77, 16, 1
	v_lshrrev_b32_e32 v2, 16, v2
	v_add3_u32 v55, v77, v55, s27
	global_store_dwordx4 v[90:91], v[70:73], off
	ds_read2_b32 v[74:75], v61 offset0:16 offset1:24
	s_nop 0
	v_and_or_b32 v70, v55, s28, v2
	v_bfe_u32 v2, v79, 16, 1
	v_add3_u32 v2, v79, v2, s27
	v_bfe_u32 v55, v81, 16, 1
	v_lshrrev_b32_e32 v2, 16, v2
	v_add3_u32 v55, v81, v55, s27
	v_and_or_b32 v71, v55, s28, v2
	v_bfe_u32 v2, v83, 16, 1
	v_add3_u32 v2, v83, v2, s27
	v_bfe_u32 v55, v85, 16, 1
	v_lshrrev_b32_e32 v2, 16, v2
	v_add3_u32 v55, v85, v55, s27
	v_and_or_b32 v72, v55, s28, v2
	v_bfe_u32 v2, v87, 16, 1
	v_add3_u32 v2, v87, v2, s27
	v_bfe_u32 v55, v89, 16, 1
	v_lshrrev_b32_e32 v2, 16, v2
	v_add3_u32 v55, v89, v55, s27
	v_and_or_b32 v73, v55, s28, v2
	v_or_b32_e32 v2, s8, v62
	v_mul_u32_u24_e32 v2, 0x1600, v2
	v_lshlrev_b32_e32 v2, 1, v2
	v_lshl_add_u64 v[76:77], v[56:57], 0, v[2:3]
	global_store_dwordx4 v[76:77], v[70:73], off
	ds_read2_b32 v[76:77], v61 offset0:81 offset1:89
	ds_read2_b32 v[78:79], v61 offset0:146 offset1:154
	ds_read2_b32 v[80:81], v61 offset0:211 offset1:219
	s_waitcnt lgkmcnt(3)
	v_bfe_u32 v2, v74, 16, 1
	v_add3_u32 v2, v74, v2, s27
	s_waitcnt lgkmcnt(2)
	v_bfe_u32 v55, v76, 16, 1
	ds_read2_b32 v[82:83], v53 offset0:20 offset1:28
	v_lshrrev_b32_e32 v2, 16, v2
	v_add3_u32 v55, v76, v55, s27
	ds_read2_b32 v[84:85], v53 offset0:85 offset1:93
	v_and_or_b32 v70, v55, s28, v2
	s_waitcnt lgkmcnt(3)
	v_bfe_u32 v2, v78, 16, 1
	v_add3_u32 v2, v78, v2, s27
	s_waitcnt lgkmcnt(2)
	v_bfe_u32 v55, v80, 16, 1
	ds_read2_b32 v[86:87], v53 offset0:150 offset1:158
	v_lshrrev_b32_e32 v2, 16, v2
	v_add3_u32 v55, v80, v55, s27
	ds_read2_b32 v[88:89], v53 offset0:215 offset1:223
	v_and_or_b32 v71, v55, s28, v2
	s_waitcnt lgkmcnt(3)
	v_bfe_u32 v2, v82, 16, 1
	v_add3_u32 v2, v82, v2, s27
	s_waitcnt lgkmcnt(2)
	v_bfe_u32 v55, v84, 16, 1
	v_lshrrev_b32_e32 v2, 16, v2
	v_add3_u32 v55, v84, v55, s27
	v_and_or_b32 v72, v55, s28, v2
	s_waitcnt lgkmcnt(1)
	v_bfe_u32 v2, v86, 16, 1
	v_add3_u32 v2, v86, v2, s27
	s_waitcnt lgkmcnt(0)
	v_bfe_u32 v55, v88, 16, 1
	v_lshrrev_b32_e32 v2, 16, v2
	v_add3_u32 v55, v88, v55, s27
	v_and_or_b32 v73, v55, s28, v2
	v_or_b32_e32 v2, s8, v63
	v_mul_u32_u24_e32 v2, 0x1600, v2
	v_lshlrev_b32_e32 v2, 1, v2
	v_lshl_add_u64 v[90:91], v[56:57], 0, v[2:3]
	v_bfe_u32 v2, v75, 16, 1
	v_add3_u32 v2, v75, v2, s27
	v_bfe_u32 v55, v77, 16, 1
	v_lshrrev_b32_e32 v2, 16, v2
	v_add3_u32 v55, v77, v55, s27
	global_store_dwordx4 v[90:91], v[70:73], off
	ds_read2_b32 v[74:75], v61 offset0:32 offset1:40
	s_nop 0
	v_and_or_b32 v70, v55, s28, v2
	v_bfe_u32 v2, v79, 16, 1
	v_add3_u32 v2, v79, v2, s27
	v_bfe_u32 v55, v81, 16, 1
	v_lshrrev_b32_e32 v2, 16, v2
	v_add3_u32 v55, v81, v55, s27
	v_and_or_b32 v71, v55, s28, v2
	v_bfe_u32 v2, v83, 16, 1
	v_add3_u32 v2, v83, v2, s27
	v_bfe_u32 v55, v85, 16, 1
	v_lshrrev_b32_e32 v2, 16, v2
	v_add3_u32 v55, v85, v55, s27
	v_and_or_b32 v72, v55, s28, v2
	v_bfe_u32 v2, v87, 16, 1
	v_add3_u32 v2, v87, v2, s27
	v_bfe_u32 v55, v89, 16, 1
	v_lshrrev_b32_e32 v2, 16, v2
	v_add3_u32 v55, v89, v55, s27
	v_and_or_b32 v73, v55, s28, v2
	v_or_b32_e32 v2, s8, v64
	v_mul_u32_u24_e32 v2, 0x1600, v2
	v_lshlrev_b32_e32 v2, 1, v2
	v_lshl_add_u64 v[76:77], v[56:57], 0, v[2:3]
	global_store_dwordx4 v[76:77], v[70:73], off
	ds_read2_b32 v[76:77], v61 offset0:97 offset1:105
	ds_read2_b32 v[78:79], v61 offset0:162 offset1:170
	ds_read2_b32 v[80:81], v61 offset0:227 offset1:235
	s_waitcnt lgkmcnt(3)
	v_bfe_u32 v2, v74, 16, 1
	v_add3_u32 v2, v74, v2, s27
	s_waitcnt lgkmcnt(2)
	v_bfe_u32 v55, v76, 16, 1
	ds_read2_b32 v[82:83], v53 offset0:36 offset1:44
	v_lshrrev_b32_e32 v2, 16, v2
	v_add3_u32 v55, v76, v55, s27
	ds_read2_b32 v[84:85], v53 offset0:101 offset1:109
	v_and_or_b32 v70, v55, s28, v2
	s_waitcnt lgkmcnt(3)
; DI unsigned pk2w(float lo, float hi) { return f2bfw(lo) | (f2bfw(hi) << 16); }
; DI void transpose_item(const float* W, int K, int N, bf16_t* WT, int mode, float* scr, int item, int lane) {
;     ...
;     const int c = lane & 7;
; #pragma unroll
;     for (int j = 0; j < 8; ++j) { const int n = (lane >> 3) + 8 * j; const float* sp = scr + (8 * c) * 65 + n;
;         u32x4 o; o.x = pk2w(sp[0 * 65], sp[1 * 65]); o.y = pk2w(sp[2 * 65], sp[3 * 65]); o.z = pk2w(sp[4 * 65], sp[5 * 65]); o.w = pk2w(sp[6 * 65], sp[7 * 65]);
;         *(u32x4*)(WT + (size_t)(drow0 + n) * K + k0 + 8 * c) = o; }
;     __builtin_amdgcn_s_waitcnt(0); __builtin_amdgcn_wave_barrier();
	v_bfe_u32 v2, v78, 16, 1
	v_add3_u32 v2, v78, v2, s27
	s_waitcnt lgkmcnt(2)
	v_bfe_u32 v55, v80, 16, 1
	ds_read2_b32 v[86:87], v53 offset0:166 offset1:174
	v_lshrrev_b32_e32 v2, 16, v2
	v_add3_u32 v55, v80, v55, s27
	ds_read2_b32 v[88:89], v53 offset0:231 offset1:239
	v_and_or_b32 v71, v55, s28, v2
	s_waitcnt lgkmcnt(3)
	v_bfe_u32 v2, v82, 16, 1
	v_add3_u32 v2, v82, v2, s27
	s_waitcnt lgkmcnt(2)
	v_bfe_u32 v55, v84, 16, 1
	v_lshrrev_b32_e32 v2, 16, v2
	v_add3_u32 v55, v84, v55, s27
	v_and_or_b32 v72, v55, s28, v2
	s_waitcnt lgkmcnt(1)
	v_bfe_u32 v2, v86, 16, 1
	v_add3_u32 v2, v86, v2, s27
	s_waitcnt lgkmcnt(0)
	v_bfe_u32 v55, v88, 16, 1
	v_lshrrev_b32_e32 v2, 16, v2
	v_add3_u32 v55, v88, v55, s27
	v_and_or_b32 v73, v55, s28, v2
	v_or_b32_e32 v2, s8, v65
	v_mul_u32_u24_e32 v2, 0x1600, v2
	v_lshlrev_b32_e32 v2, 1, v2
	v_lshl_add_u64 v[90:91], v[56:57], 0, v[2:3]
	v_bfe_u32 v2, v75, 16, 1
	v_add3_u32 v2, v75, v2, s27
	v_bfe_u32 v55, v77, 16, 1
	v_lshrrev_b32_e32 v2, 16, v2
	v_add3_u32 v55, v77, v55, s27
	global_store_dwordx4 v[90:91], v[70:73], off
	ds_read2_b32 v[74:75], v61 offset0:48 offset1:56
	s_nop 0
	v_and_or_b32 v70, v55, s28, v2
	v_bfe_u32 v2, v79, 16, 1
	v_add3_u32 v2, v79, v2, s27
	v_bfe_u32 v55, v81, 16, 1
	v_lshrrev_b32_e32 v2, 16, v2
	v_add3_u32 v55, v81, v55, s27
	v_and_or_b32 v71, v55, s28, v2
	v_bfe_u32 v2, v83, 16, 1
	v_add3_u32 v2, v83, v2, s27
	v_bfe_u32 v55, v85, 16, 1
	v_lshrrev_b32_e32 v2, 16, v2
	v_add3_u32 v55, v85, v55, s27
	v_and_or_b32 v72, v55, s28, v2
	v_bfe_u32 v2, v87, 16, 1
	v_add3_u32 v2, v87, v2, s27
	v_bfe_u32 v55, v89, 16, 1
	v_lshrrev_b32_e32 v2, 16, v2
	v_add3_u32 v55, v89, v55, s27
	v_and_or_b32 v73, v55, s28, v2
	v_or_b32_e32 v2, s8, v66
	v_mul_u32_u24_e32 v2, 0x1600, v2
	v_lshlrev_b32_e32 v2, 1, v2
	v_lshl_add_u64 v[76:77], v[56:57], 0, v[2:3]
	global_store_dwordx4 v[76:77], v[70:73], off
	ds_read2_b32 v[76:77], v61 offset0:113 offset1:121
	ds_read2_b32 v[78:79], v61 offset0:178 offset1:186
	ds_read2_b32 v[80:81], v61 offset0:243 offset1:251
	s_waitcnt lgkmcnt(3)
	v_bfe_u32 v2, v74, 16, 1
	v_add3_u32 v2, v74, v2, s27
	s_waitcnt lgkmcnt(2)
	v_bfe_u32 v55, v76, 16, 1
	ds_read2_b32 v[82:83], v53 offset0:52 offset1:60
	v_lshrrev_b32_e32 v2, 16, v2
	v_add3_u32 v55, v76, v55, s27
	ds_read2_b32 v[84:85], v53 offset0:117 offset1:125
	v_and_or_b32 v70, v55, s28, v2
	s_waitcnt lgkmcnt(3)
	v_bfe_u32 v2, v78, 16, 1
	v_add3_u32 v2, v78, v2, s27
	s_waitcnt lgkmcnt(2)
	v_bfe_u32 v55, v80, 16, 1
	ds_read2_b32 v[86:87], v53 offset0:182 offset1:190
	v_lshrrev_b32_e32 v2, 16, v2
	v_add3_u32 v55, v80, v55, s27
	ds_read2_b32 v[88:89], v53 offset0:247 offset1:255
	v_and_or_b32 v71, v55, s28, v2
	s_waitcnt lgkmcnt(3)
	v_bfe_u32 v2, v82, 16, 1
	v_add3_u32 v2, v82, v2, s27
	s_waitcnt lgkmcnt(2)
	v_bfe_u32 v55, v84, 16, 1
	v_lshrrev_b32_e32 v2, 16, v2
	v_add3_u32 v55, v84, v55, s27
	v_and_or_b32 v72, v55, s28, v2
	s_waitcnt lgkmcnt(1)
	v_bfe_u32 v2, v86, 16, 1
	v_add3_u32 v2, v86, v2, s27
	s_waitcnt lgkmcnt(0)
	v_bfe_u32 v53, v88, 16, 1
	v_lshrrev_b32_e32 v2, 16, v2
	v_add3_u32 v53, v88, v53, s27
	v_and_or_b32 v73, v53, s28, v2
	v_or_b32_e32 v2, s8, v67
	v_mul_u32_u24_e32 v2, 0x1600, v2
	v_lshlrev_b32_e32 v2, 1, v2
	v_lshl_add_u64 v[90:91], v[56:57], 0, v[2:3]
	v_bfe_u32 v2, v75, 16, 1
	v_add3_u32 v2, v75, v2, s27
	v_bfe_u32 v53, v77, 16, 1
	v_lshrrev_b32_e32 v2, 16, v2
	v_add3_u32 v53, v77, v53, s27
	global_store_dwordx4 v[90:91], v[70:73], off
	s_nop 1
	v_and_or_b32 v70, v53, s28, v2
	v_bfe_u32 v2, v79, 16, 1
	v_add3_u32 v2, v79, v2, s27
	v_bfe_u32 v53, v81, 16, 1
	v_lshrrev_b32_e32 v2, 16, v2
	v_add3_u32 v53, v81, v53, s27
	v_and_or_b32 v71, v53, s28, v2
	v_bfe_u32 v2, v83, 16, 1
	v_add3_u32 v2, v83, v2, s27
	v_bfe_u32 v53, v85, 16, 1
	v_lshrrev_b32_e32 v2, 16, v2
	v_add3_u32 v53, v85, v53, s27
	v_and_or_b32 v72, v53, s28, v2
	v_bfe_u32 v2, v87, 16, 1
	v_add3_u32 v2, v87, v2, s27
	v_bfe_u32 v53, v89, 16, 1
	v_lshrrev_b32_e32 v2, 16, v2
	v_add3_u32 v53, v89, v53, s27
	v_and_or_b32 v73, v53, s28, v2
	v_or_b32_e32 v2, s8, v68
	v_mul_u32_u24_e32 v2, 0x1600, v2
	v_lshlrev_b32_e32 v2, 1, v2
	v_lshl_add_u64 v[56:57], v[56:57], 0, v[2:3]
	global_store_dwordx4 v[56:57], v[70:73], off
	s_waitcnt lgkmcnt(0)

; DI unsigned pk2w(float lo, float hi) { return f2bfw(lo) | (f2bfw(hi) << 16); }
; DI void transpose_item(const float* W, int K, int N, bf16_t* WT, int mode, float* scr, int item, int lane) {
;     const int nblk = N / 64, kb = item / nblk, nb = item % nblk, k0 = 64 * kb, n0 = 64 * nb;
;     int drow0 = n0;
;     if (mode == 1) { const int seg = n0 >> 10; const int dst = seg < 2 ? seg : (seg == 2 ? 6 : seg - 1); drow0 = dst * 1024 + (n0 & 1023); }
;     else if (mode == 2) { drow0 = n0 < DFF ? (n0 / 128) * 256 + (n0 % 128) : ((n0 - DFF) / 128) * 256 + 128 + ((n0 - DFF) % 128); }
;     else if (mode == 3) { drow0 = (n0 / 128) * 256 + (n0 % 128); }
;     else if (mode == 4) { drow0 = (n0 / 128) * 256 + 128 + (n0 % 128); }
;     f32x4 v[16];
; #pragma unroll
;     for (int i = 0; i < 16; ++i) v[i] = __builtin_nontemporal_load((const f32x4*)(W + (size_t)(k0 + 4 * i + (lane >> 4)) * N + n0 + 4 * (lane & 15)));
; #pragma unroll
;     for (int i = 0; i < 16; ++i) { float* d = scr + (4 * i + (lane >> 4)) * 65 + 4 * (lane & 15); d[0] = v[i][0]; d[1] = v[i][1]; d[2] = v[i][2]; d[3] = v[i][3]; }
;     __builtin_amdgcn_s_waitcnt(0); __builtin_amdgcn_wave_barrier();
;     const int c = lane & 7;
; #pragma unroll
;     for (int j = 0; j < 8; ++j) { const int n = (lane >> 3) + 8 * j; const float* sp = scr + (8 * c) * 65 + n;
;         u32x4 o; o.x = pk2w(sp[0 * 65], sp[1 * 65]); o.y = pk2w(sp[2 * 65], sp[3 * 65]); o.z = pk2w(sp[4 * 65], sp[5 * 65]); o.w = pk2w(sp[6 * 65], sp[7 * 65]);
.LBB0_302:
	s_lshl_b32 s6, s6, 6
	s_and_b32 s8, s6, 0x7fc0
	v_or_b32_e32 v2, s8, v58
	s_lshl_b32 s6, s49, 2
	v_mul_u32_u24_e32 v2, 0x2c00, v2
	v_lshl_add_u64 v[56:57], v[14:15], 0, s[6:7]
	v_lshlrev_b32_e32 v2, 2, v2
	v_lshl_add_u64 v[56:57], v[56:57], 0, v[2:3]
	v_add_co_u32_e32 v74, vcc, 0x2c000, v56
	v_add_u32_e32 v2, 0x410, v59
	s_nop 0
	v_addc_co_u32_e32 v75, vcc, 0, v57, vcc
	v_add_co_u32_e32 v78, vcc, s29, v56
	global_load_dwordx4 v[70:73], v[56:57], off nt
	s_nop 0
	global_load_dwordx4 v[74:77], v[74:75], off nt
	v_addc_co_u32_e32 v79, vcc, 0, v57, vcc
	v_add_co_u32_e32 v82, vcc, 0x84000, v56
	s_lshl_b32 s6, s8, 1
	s_nop 0
	v_addc_co_u32_e32 v83, vcc, 0, v57, vcc
	global_load_dwordx4 v[78:81], v[78:79], off nt
	s_nop 0
	global_load_dwordx4 v[82:85], v[82:83], off nt
	v_add_co_u32_e32 v86, vcc, 0xb0000, v56
	s_nop 1
	v_addc_co_u32_e32 v87, vcc, 0, v57, vcc
	v_add_co_u32_e32 v90, vcc, 0xdc000, v56
	s_nop 1
	v_addc_co_u32_e32 v91, vcc, 0, v57, vcc
	global_load_dwordx4 v[86:89], v[86:87], off nt
	s_nop 0
	global_load_dwordx4 v[90:93], v[90:91], off nt
	v_add_co_u32_e32 v94, vcc, 0x108000, v56
	s_nop 1
	v_addc_co_u32_e32 v95, vcc, 0, v57, vcc
	v_add_co_u32_e32 v98, vcc, 0x134000, v56
	s_nop 1
	v_addc_co_u32_e32 v99, vcc, 0, v57, vcc
	global_load_dwordx4 v[94:97], v[94:95], off nt
	s_nop 0
	global_load_dwordx4 v[98:101], v[98:99], off nt
	v_add_co_u32_e32 v102, vcc, 0x160000, v56
	s_nop 1
	v_addc_co_u32_e32 v103, vcc, 0, v57, vcc
	v_add_co_u32_e32 v106, vcc, 0x18c000, v56
	s_nop 1
	v_addc_co_u32_e32 v107, vcc, 0, v57, vcc
	global_load_dwordx4 v[102:105], v[102:103], off nt
	s_nop 0
	global_load_dwordx4 v[106:109], v[106:107], off nt
	v_add_co_u32_e32 v110, vcc, 0x1b8000, v56
	s_nop 1
	v_addc_co_u32_e32 v111, vcc, 0, v57, vcc
	v_add_co_u32_e32 v114, vcc, 0x1e4000, v56
	s_nop 1
	v_addc_co_u32_e32 v115, vcc, 0, v57, vcc
	global_load_dwordx4 v[110:113], v[110:111], off nt
	s_nop 0
	global_load_dwordx4 v[114:117], v[114:115], off nt
	v_add_co_u32_e32 v118, vcc, 0x210000, v56
	s_nop 1
	v_addc_co_u32_e32 v119, vcc, 0, v57, vcc
	v_add_co_u32_e32 v122, vcc, 0x23c000, v56
	s_nop 1
	v_addc_co_u32_e32 v123, vcc, 0, v57, vcc
	global_load_dwordx4 v[118:121], v[118:119], off nt
	s_nop 0
	global_load_dwordx4 v[122:125], v[122:123], off nt
	v_add_co_u32_e32 v126, vcc, 0x268000, v56
	s_nop 1
	v_addc_co_u32_e32 v127, vcc, 0, v57, vcc
	global_load_dwordx4 v[126:129], v[126:127], off nt
	v_add_co_u32_e32 v56, vcc, 0x294000, v56
	s_nop 1
	v_addc_co_u32_e32 v57, vcc, 0, v57, vcc
	global_load_dwordx4 v[130:133], v[56:57], off nt
	s_waitcnt vmcnt(0)
	ds_write2_b32 v59, v70, v71 offset1:1
	ds_write2_b32 v59, v72, v73 offset0:2 offset1:3
	ds_write2_b32 v2, v74, v75 offset1:1
	v_add_u32_e32 v2, 0x418, v59
	ds_write2_b32 v2, v76, v77 offset1:1
	v_add_u32_e32 v2, 0x820, v59
	v_lshl_add_u64 v[56:57], v[46:47], 0, s[6:7]
	ds_write2_b32 v2, v78, v79 offset1:1
	v_add_u32_e32 v2, 0x828, v59
	ds_write2_b32 v2, v80, v81 offset1:1
	v_add_u32_e32 v2, 0xc30, v59
	ds_write2_b32 v2, v82, v83 offset1:1
	v_add_u32_e32 v2, 0xc38, v59
	ds_write2_b32 v2, v84, v85 offset1:1
	v_add_u32_e32 v2, 0x1040, v59
	ds_write2_b32 v2, v86, v87 offset1:1
	v_add_u32_e32 v2, 0x1048, v59
	ds_write2_b32 v2, v88, v89 offset1:1
	v_add_u32_e32 v2, 0x1450, v59
	ds_write2_b32 v2, v90, v91 offset1:1
	v_add_u32_e32 v2, 0x1458, v59
	ds_write2_b32 v2, v92, v93 offset1:1
	v_add_u32_e32 v2, 0x1860, v59
	ds_write2_b32 v2, v94, v95 offset1:1
	v_add_u32_e32 v2, 0x1868, v59
	ds_write2_b32 v2, v96, v97 offset1:1
	v_add_u32_e32 v2, 0x1c70, v59
	ds_write2_b32 v2, v98, v99 offset1:1
	v_add_u32_e32 v2, 0x1c78, v59
	ds_write2_b32 v2, v100, v101 offset1:1
	v_add_u32_e32 v2, 0x2080, v59
	ds_write2_b32 v2, v102, v103 offset1:1
	v_add_u32_e32 v2, 0x2088, v59
	ds_write2_b32 v2, v104, v105 offset1:1
	v_add_u32_e32 v2, 0x2490, v59
	ds_write2_b32 v2, v106, v107 offset1:1
	v_add_u32_e32 v2, 0x2498, v59
	ds_write2_b32 v2, v108, v109 offset1:1
	v_add_u32_e32 v2, 0x28a0, v59
	ds_write2_b32 v2, v110, v111 offset1:1
	v_add_u32_e32 v2, 0x28a8, v59
	ds_write2_b32 v2, v112, v113 offset1:1
	v_add_u32_e32 v2, 0x2cb0, v59
	ds_write2_b32 v2, v114, v115 offset1:1
	v_add_u32_e32 v2, 0x2cb8, v59
	ds_write2_b32 v2, v116, v117 offset1:1
	v_add_u32_e32 v2, 0x30c0, v59
	ds_write2_b32 v2, v118, v119 offset1:1
	v_add_u32_e32 v2, 0x30c8, v59
	ds_write2_b32 v2, v120, v121 offset1:1
	v_add_u32_e32 v2, 0x34d0, v59
	ds_write2_b32 v2, v122, v123 offset1:1
	v_add_u32_e32 v2, 0x34d8, v59
	ds_write2_b32 v2, v124, v125 offset1:1
	v_add_u32_e32 v2, 0x38e0, v59
	ds_write2_b32 v2, v126, v127 offset1:1
	v_add_u32_e32 v2, 0x38e8, v59
	ds_write2_b32 v2, v128, v129 offset1:1
	v_add_u32_e32 v2, 0x3cf0, v59
	ds_write2_b32 v2, v130, v131 offset1:1
	v_add_u32_e32 v2, 0x3cf8, v59
	ds_write2_b32 v2, v132, v133 offset1:1
	s_waitcnt vmcnt(0) expcnt(0) lgkmcnt(0)
	ds_read2_b32 v[74:75], v61 offset1:8
	ds_read2_b32 v[76:77], v61 offset0:65 offset1:73
	ds_read2_b32 v[78:79], v61 offset0:130 offset1:138
	ds_read2_b32 v[80:81], v61 offset0:195 offset1:203
	s_waitcnt lgkmcnt(3)
	v_bfe_u32 v2, v74, 16, 1
	v_add3_u32 v2, v74, v2, s27
	s_waitcnt lgkmcnt(2)
	v_bfe_u32 v53, v76, 16, 1
	v_lshrrev_b32_e32 v2, 16, v2
	v_add3_u32 v53, v76, v53, s27
	v_and_or_b32 v70, v53, s28, v2
	v_add_u32_e32 v53, 0x400, v61
	ds_read2_b32 v[82:83], v53 offset0:4 offset1:12
	ds_read2_b32 v[84:85], v53 offset0:69 offset1:77
	s_waitcnt lgkmcnt(3)
	v_bfe_u32 v2, v78, 16, 1
	v_add3_u32 v2, v78, v2, s27
	s_waitcnt lgkmcnt(2)
	v_bfe_u32 v55, v80, 16, 1
	ds_read2_b32 v[86:87], v53 offset0:134 offset1:142
	v_lshrrev_b32_e32 v2, 16, v2
	v_add3_u32 v55, v80, v55, s27
	ds_read2_b32 v[88:89], v53 offset0:199 offset1:207
	v_and_or_b32 v71, v55, s28, v2
	s_waitcnt lgkmcnt(3)
; DI unsigned pk2w(float lo, float hi) { return f2bfw(lo) | (f2bfw(hi) << 16); }
; DI void transpose_item(const float* W, int K, int N, bf16_t* WT, int mode, float* scr, int item, int lane) {
;     ...
;     const int c = lane & 7;
; #pragma unroll
;     for (int j = 0; j < 8; ++j) { const int n = (lane >> 3) + 8 * j; const float* sp = scr + (8 * c) * 65 + n;
;         u32x4 o; o.x = pk2w(sp[0 * 65], sp[1 * 65]); o.y = pk2w(sp[2 * 65], sp[3 * 65]); o.z = pk2w(sp[4 * 65], sp[5 * 65]); o.w = pk2w(sp[6 * 65], sp[7 * 65]);
;         *(u32x4*)(WT + (size_t)(drow0 + n) * K + k0 + 8 * c) = o; }
	v_bfe_u32 v2, v82, 16, 1
	v_add3_u32 v2, v82, v2, s27
	s_waitcnt lgkmcnt(2)
	v_bfe_u32 v55, v84, 16, 1
	v_lshrrev_b32_e32 v2, 16, v2
	v_add3_u32 v55, v84, v55, s27
	v_and_or_b32 v72, v55, s28, v2
	s_waitcnt lgkmcnt(1)
	v_bfe_u32 v2, v86, 16, 1
	v_add3_u32 v2, v86, v2, s27
	s_waitcnt lgkmcnt(0)
	v_bfe_u32 v55, v88, 16, 1
	v_lshrrev_b32_e32 v2, 16, v2
	v_add3_u32 v55, v88, v55, s27
	v_and_or_b32 v73, v55, s28, v2
	v_add_u32_e32 v2, s48, v60
	v_lshlrev_b64 v[90:91], 12, v[2:3]
	v_bfe_u32 v2, v75, 16, 1
	v_add3_u32 v2, v75, v2, s27
	v_bfe_u32 v55, v77, 16, 1
	v_lshl_add_u64 v[90:91], v[56:57], 0, v[90:91]
	v_lshrrev_b32_e32 v2, 16, v2
	v_add3_u32 v55, v77, v55, s27
	global_store_dwordx4 v[90:91], v[70:73], off
	ds_read2_b32 v[74:75], v61 offset0:16 offset1:24
	s_nop 0
	v_and_or_b32 v70, v55, s28, v2
	v_bfe_u32 v2, v79, 16, 1
	v_add3_u32 v2, v79, v2, s27
	v_bfe_u32 v55, v81, 16, 1
	v_lshrrev_b32_e32 v2, 16, v2
	v_add3_u32 v55, v81, v55, s27
	v_and_or_b32 v71, v55, s28, v2
	v_bfe_u32 v2, v83, 16, 1
	v_add3_u32 v2, v83, v2, s27
	v_bfe_u32 v55, v85, 16, 1
	v_lshrrev_b32_e32 v2, 16, v2
	v_add3_u32 v55, v85, v55, s27
	v_and_or_b32 v72, v55, s28, v2
	v_bfe_u32 v2, v87, 16, 1
	v_add3_u32 v2, v87, v2, s27
	v_bfe_u32 v55, v89, 16, 1
	v_lshrrev_b32_e32 v2, 16, v2
	v_add3_u32 v55, v89, v55, s27
	v_and_or_b32 v73, v55, s28, v2
	v_add_u32_e32 v2, s48, v62
	v_lshlrev_b64 v[76:77], 12, v[2:3]
	v_lshl_add_u64 v[76:77], v[56:57], 0, v[76:77]
	global_store_dwordx4 v[76:77], v[70:73], off
	ds_read2_b32 v[76:77], v61 offset0:81 offset1:89
	ds_read2_b32 v[78:79], v61 offset0:146 offset1:154
	ds_read2_b32 v[80:81], v61 offset0:211 offset1:219
	s_waitcnt lgkmcnt(3)
	v_bfe_u32 v2, v74, 16, 1
	v_add3_u32 v2, v74, v2, s27
	s_waitcnt lgkmcnt(2)
	v_bfe_u32 v55, v76, 16, 1
	ds_read2_b32 v[82:83], v53 offset0:20 offset1:28
	v_lshrrev_b32_e32 v2, 16, v2
	v_add3_u32 v55, v76, v55, s27
	ds_read2_b32 v[84:85], v53 offset0:85 offset1:93
	v_and_or_b32 v70, v55, s28, v2
	s_waitcnt lgkmcnt(3)
	v_bfe_u32 v2, v78, 16, 1
	v_add3_u32 v2, v78, v2, s27
	s_waitcnt lgkmcnt(2)
	v_bfe_u32 v55, v80, 16, 1
	ds_read2_b32 v[86:87], v53 offset0:150 offset1:158
	v_lshrrev_b32_e32 v2, 16, v2
	v_add3_u32 v55, v80, v55, s27
	ds_read2_b32 v[88:89], v53 offset0:215 offset1:223
	v_and_or_b32 v71, v55, s28, v2
	s_waitcnt lgkmcnt(3)
	v_bfe_u32 v2, v82, 16, 1
	v_add3_u32 v2, v82, v2, s27
	s_waitcnt lgkmcnt(2)
	v_bfe_u32 v55, v84, 16, 1
	v_lshrrev_b32_e32 v2, 16, v2
	v_add3_u32 v55, v84, v55, s27
	v_and_or_b32 v72, v55, s28, v2
	s_waitcnt lgkmcnt(1)
	v_bfe_u32 v2, v86, 16, 1
	v_add3_u32 v2, v86, v2, s27
	s_waitcnt lgkmcnt(0)
	v_bfe_u32 v55, v88, 16, 1
	v_lshrrev_b32_e32 v2, 16, v2
	v_add3_u32 v55, v88, v55, s27
	v_and_or_b32 v73, v55, s28, v2
	v_add_u32_e32 v2, s48, v63
	v_lshlrev_b64 v[90:91], 12, v[2:3]
	v_bfe_u32 v2, v75, 16, 1
	v_add3_u32 v2, v75, v2, s27
	v_bfe_u32 v55, v77, 16, 1
	v_lshl_add_u64 v[90:91], v[56:57], 0, v[90:91]
	v_lshrrev_b32_e32 v2, 16, v2
	v_add3_u32 v55, v77, v55, s27
	global_store_dwordx4 v[90:91], v[70:73], off
	ds_read2_b32 v[74:75], v61 offset0:32 offset1:40
	s_nop 0
	v_and_or_b32 v70, v55, s28, v2
	v_bfe_u32 v2, v79, 16, 1
	v_add3_u32 v2, v79, v2, s27
	v_bfe_u32 v55, v81, 16, 1
	v_lshrrev_b32_e32 v2, 16, v2
	v_add3_u32 v55, v81, v55, s27
	v_and_or_b32 v71, v55, s28, v2
	v_bfe_u32 v2, v83, 16, 1
	v_add3_u32 v2, v83, v2, s27
	v_bfe_u32 v55, v85, 16, 1
	v_lshrrev_b32_e32 v2, 16, v2
	v_add3_u32 v55, v85, v55, s27
	v_and_or_b32 v72, v55, s28, v2
	v_bfe_u32 v2, v87, 16, 1
	v_add3_u32 v2, v87, v2, s27
	v_bfe_u32 v55, v89, 16, 1
	v_lshrrev_b32_e32 v2, 16, v2
	v_add3_u32 v55, v89, v55, s27
	v_and_or_b32 v73, v55, s28, v2
	v_add_u32_e32 v2, s48, v64
	v_lshlrev_b64 v[76:77], 12, v[2:3]
	v_lshl_add_u64 v[76:77], v[56:57], 0, v[76:77]
	global_store_dwordx4 v[76:77], v[70:73], off
	ds_read2_b32 v[76:77], v61 offset0:97 offset1:105
	ds_read2_b32 v[78:79], v61 offset0:162 offset1:170
	ds_read2_b32 v[80:81], v61 offset0:227 offset1:235
	s_waitcnt lgkmcnt(3)
	v_bfe_u32 v2, v74, 16, 1
	v_add3_u32 v2, v74, v2, s27
	s_waitcnt lgkmcnt(2)
	v_bfe_u32 v55, v76, 16, 1
	ds_read2_b32 v[82:83], v53 offset0:36 offset1:44
	v_lshrrev_b32_e32 v2, 16, v2
	v_add3_u32 v55, v76, v55, s27
	ds_read2_b32 v[84:85], v53 offset0:101 offset1:109
	v_and_or_b32 v70, v55, s28, v2
	s_waitcnt lgkmcnt(3)
; DI unsigned pk2w(float lo, float hi) { return f2bfw(lo) | (f2bfw(hi) << 16); }
; DI void transpose_item(const float* W, int K, int N, bf16_t* WT, int mode, float* scr, int item, int lane) {
;     ...
;     const int c = lane & 7;
; #pragma unroll
;     for (int j = 0; j < 8; ++j) { const int n = (lane >> 3) + 8 * j; const float* sp = scr + (8 * c) * 65 + n;
;         u32x4 o; o.x = pk2w(sp[0 * 65], sp[1 * 65]); o.y = pk2w(sp[2 * 65], sp[3 * 65]); o.z = pk2w(sp[4 * 65], sp[5 * 65]); o.w = pk2w(sp[6 * 65], sp[7 * 65]);
;         *(u32x4*)(WT + (size_t)(drow0 + n) * K + k0 + 8 * c) = o; }
;     __builtin_amdgcn_s_waitcnt(0); __builtin_amdgcn_wave_barrier();
	v_bfe_u32 v2, v78, 16, 1
	v_add3_u32 v2, v78, v2, s27
	s_waitcnt lgkmcnt(2)
	v_bfe_u32 v55, v80, 16, 1
	ds_read2_b32 v[86:87], v53 offset0:166 offset1:174
	v_lshrrev_b32_e32 v2, 16, v2
	v_add3_u32 v55, v80, v55, s27
	ds_read2_b32 v[88:89], v53 offset0:231 offset1:239
	v_and_or_b32 v71, v55, s28, v2
	s_waitcnt lgkmcnt(3)
	v_bfe_u32 v2, v82, 16, 1
	v_add3_u32 v2, v82, v2, s27
	s_waitcnt lgkmcnt(2)
	v_bfe_u32 v55, v84, 16, 1
	v_lshrrev_b32_e32 v2, 16, v2
	v_add3_u32 v55, v84, v55, s27
	v_and_or_b32 v72, v55, s28, v2
	s_waitcnt lgkmcnt(1)
	v_bfe_u32 v2, v86, 16, 1
	v_add3_u32 v2, v86, v2, s27
	s_waitcnt lgkmcnt(0)
	v_bfe_u32 v55, v88, 16, 1
	v_lshrrev_b32_e32 v2, 16, v2
	v_add3_u32 v55, v88, v55, s27
	v_and_or_b32 v73, v55, s28, v2
	v_add_u32_e32 v2, s48, v65
	v_lshlrev_b64 v[90:91], 12, v[2:3]
	v_bfe_u32 v2, v75, 16, 1
	v_add3_u32 v2, v75, v2, s27
	v_bfe_u32 v55, v77, 16, 1
	v_lshl_add_u64 v[90:91], v[56:57], 0, v[90:91]
	v_lshrrev_b32_e32 v2, 16, v2
	v_add3_u32 v55, v77, v55, s27
	global_store_dwordx4 v[90:91], v[70:73], off
	ds_read2_b32 v[74:75], v61 offset0:48 offset1:56
	s_nop 0
	v_and_or_b32 v70, v55, s28, v2
	v_bfe_u32 v2, v79, 16, 1
	v_add3_u32 v2, v79, v2, s27
	v_bfe_u32 v55, v81, 16, 1
	v_lshrrev_b32_e32 v2, 16, v2
	v_add3_u32 v55, v81, v55, s27
	v_and_or_b32 v71, v55, s28, v2
	v_bfe_u32 v2, v83, 16, 1
	v_add3_u32 v2, v83, v2, s27
	v_bfe_u32 v55, v85, 16, 1
	v_lshrrev_b32_e32 v2, 16, v2
	v_add3_u32 v55, v85, v55, s27
	v_and_or_b32 v72, v55, s28, v2
	v_bfe_u32 v2, v87, 16, 1
	v_add3_u32 v2, v87, v2, s27
	v_bfe_u32 v55, v89, 16, 1
	v_lshrrev_b32_e32 v2, 16, v2
	v_add3_u32 v55, v89, v55, s27
	v_and_or_b32 v73, v55, s28, v2
	v_add_u32_e32 v2, s48, v66
	v_lshlrev_b64 v[76:77], 12, v[2:3]
	v_lshl_add_u64 v[76:77], v[56:57], 0, v[76:77]
	global_store_dwordx4 v[76:77], v[70:73], off
	ds_read2_b32 v[76:77], v61 offset0:113 offset1:121
	ds_read2_b32 v[78:79], v61 offset0:178 offset1:186
	ds_read2_b32 v[80:81], v61 offset0:243 offset1:251
	s_waitcnt lgkmcnt(3)
	v_bfe_u32 v2, v74, 16, 1
	v_add3_u32 v2, v74, v2, s27
	s_waitcnt lgkmcnt(2)
	v_bfe_u32 v55, v76, 16, 1
	ds_read2_b32 v[82:83], v53 offset0:52 offset1:60
	v_lshrrev_b32_e32 v2, 16, v2
	v_add3_u32 v55, v76, v55, s27
	ds_read2_b32 v[84:85], v53 offset0:117 offset1:125
	v_and_or_b32 v70, v55, s28, v2
	s_waitcnt lgkmcnt(3)
	v_bfe_u32 v2, v78, 16, 1
	v_add3_u32 v2, v78, v2, s27
	s_waitcnt lgkmcnt(2)
	v_bfe_u32 v55, v80, 16, 1
	ds_read2_b32 v[86:87], v53 offset0:182 offset1:190
	v_lshrrev_b32_e32 v2, 16, v2
	v_add3_u32 v55, v80, v55, s27
	ds_read2_b32 v[88:89], v53 offset0:247 offset1:255
	v_and_or_b32 v71, v55, s28, v2
	s_waitcnt lgkmcnt(3)
	v_bfe_u32 v2, v82, 16, 1
	v_add3_u32 v2, v82, v2, s27
	s_waitcnt lgkmcnt(2)
	v_bfe_u32 v55, v84, 16, 1
	v_lshrrev_b32_e32 v2, 16, v2
	v_add3_u32 v55, v84, v55, s27
	v_and_or_b32 v72, v55, s28, v2
	s_waitcnt lgkmcnt(1)
	v_bfe_u32 v2, v86, 16, 1
	v_add3_u32 v2, v86, v2, s27
	s_waitcnt lgkmcnt(0)
	v_bfe_u32 v53, v88, 16, 1
	v_lshrrev_b32_e32 v2, 16, v2
	v_add3_u32 v53, v88, v53, s27
	v_and_or_b32 v73, v53, s28, v2
	v_add_u32_e32 v2, s48, v67
	v_lshlrev_b64 v[90:91], 12, v[2:3]
	v_bfe_u32 v2, v75, 16, 1
	v_add3_u32 v2, v75, v2, s27
	v_bfe_u32 v53, v77, 16, 1
	v_lshl_add_u64 v[90:91], v[56:57], 0, v[90:91]
	v_lshrrev_b32_e32 v2, 16, v2
	v_add3_u32 v53, v77, v53, s27
	global_store_dwordx4 v[90:91], v[70:73], off
	s_nop 1
	v_and_or_b32 v70, v53, s28, v2
	v_bfe_u32 v2, v79, 16, 1
	v_add3_u32 v2, v79, v2, s27
	v_bfe_u32 v53, v81, 16, 1
	v_lshrrev_b32_e32 v2, 16, v2
	v_add3_u32 v53, v81, v53, s27
	v_and_or_b32 v71, v53, s28, v2
	v_bfe_u32 v2, v83, 16, 1
	v_add3_u32 v2, v83, v2, s27
	v_bfe_u32 v53, v85, 16, 1
	v_lshrrev_b32_e32 v2, 16, v2
	v_add3_u32 v53, v85, v53, s27
	v_and_or_b32 v72, v53, s28, v2
	v_bfe_u32 v2, v87, 16, 1
	v_add3_u32 v2, v87, v2, s27
	v_bfe_u32 v53, v89, 16, 1
	v_lshrrev_b32_e32 v2, 16, v2
	v_add3_u32 v53, v89, v53, s27
	v_and_or_b32 v73, v53, s28, v2
	v_add_u32_e32 v2, s48, v68
	v_lshlrev_b64 v[74:75], 12, v[2:3]
	v_lshl_add_u64 v[56:57], v[56:57], 0, v[74:75]
	global_store_dwordx4 v[56:57], v[70:73], off
	s_waitcnt lgkmcnt(0)

; DI unsigned pk2w(float lo, float hi) { return f2bfw(lo) | (f2bfw(hi) << 16); }
; DI void transpose_item(const float* W, int K, int N, bf16_t* WT, int mode, float* scr, int item, int lane) {
;     const int nblk = N / 64, kb = item / nblk, nb = item % nblk, k0 = 64 * kb, n0 = 64 * nb;
;     int drow0 = n0;
;     if (mode == 1) { const int seg = n0 >> 10; const int dst = seg < 2 ? seg : (seg == 2 ? 6 : seg - 1); drow0 = dst * 1024 + (n0 & 1023); }
;     else if (mode == 2) { drow0 = n0 < DFF ? (n0 / 128) * 256 + (n0 % 128) : ((n0 - DFF) / 128) * 256 + 128 + ((n0 - DFF) % 128); }
;     else if (mode == 3) { drow0 = (n0 / 128) * 256 + (n0 % 128); }
;     else if (mode == 4) { drow0 = (n0 / 128) * 256 + 128 + (n0 % 128); }
;     f32x4 v[16];
; #pragma unroll
;     for (int i = 0; i < 16; ++i) v[i] = __builtin_nontemporal_load((const f32x4*)(W + (size_t)(k0 + 4 * i + (lane >> 4)) * N + n0 + 4 * (lane & 15)));
; #pragma unroll
;     for (int i = 0; i < 16; ++i) { float* d = scr + (4 * i + (lane >> 4)) * 65 + 4 * (lane & 15); d[0] = v[i][0]; d[1] = v[i][1]; d[2] = v[i][2]; d[3] = v[i][3]; }
;     __builtin_amdgcn_s_waitcnt(0); __builtin_amdgcn_wave_barrier();
;     const int c = lane & 7;
; #pragma unroll
;     for (int j = 0; j < 8; ++j) { const int n = (lane >> 3) + 8 * j; const float* sp = scr + (8 * c) * 65 + n;
;         u32x4 o; o.x = pk2w(sp[0 * 65], sp[1 * 65]); o.y = pk2w(sp[2 * 65], sp[3 * 65]); o.z = pk2w(sp[4 * 65], sp[5 * 65]); o.w = pk2w(sp[6 * 65], sp[7 * 65]);
.LBB0_304:
	s_andn2_b64 vcc, exec, s[8:9]
	s_cbranch_vccnz .LBB0_306
	s_add_i32 s6, s3, 0xb700
	s_and_b32 s8, s16, 0x7c0
	s_and_b32 s9, s6, 0x1ffc0
	v_or_b32_e32 v2, s9, v58
	s_lshl_b32 s6, s8, 2
	v_lshl_add_u64 v[56:57], v[16:17], 0, s[6:7]
	v_lshlrev_b32_e32 v2, 13, v2
	v_lshl_add_u64 v[56:57], v[56:57], 0, v[2:3]
	v_add_co_u32_e32 v74, vcc, 0x8000, v56
	v_add_u32_e32 v2, 0x410, v59
	s_nop 0
	v_addc_co_u32_e32 v75, vcc, 0, v57, vcc
	v_add_co_u32_e32 v78, vcc, 0x10000, v56
	global_load_dwordx4 v[70:73], v[56:57], off nt
	s_nop 0
	global_load_dwordx4 v[74:77], v[74:75], off nt
	v_addc_co_u32_e32 v79, vcc, 0, v57, vcc
	v_add_co_u32_e32 v82, vcc, 0x18000, v56
	s_lshl_b32 s6, s9, 1
	s_nop 0
	v_addc_co_u32_e32 v83, vcc, 0, v57, vcc
	global_load_dwordx4 v[78:81], v[78:79], off nt
	s_nop 0
	global_load_dwordx4 v[82:85], v[82:83], off nt
	v_add_co_u32_e32 v86, vcc, 0x20000, v56
	s_nop 1
	v_addc_co_u32_e32 v87, vcc, 0, v57, vcc
	v_add_co_u32_e32 v90, vcc, 0x28000, v56
	s_nop 1
	v_addc_co_u32_e32 v91, vcc, 0, v57, vcc
	global_load_dwordx4 v[86:89], v[86:87], off nt
	s_nop 0
	global_load_dwordx4 v[90:93], v[90:91], off nt
	v_add_co_u32_e32 v94, vcc, 0x30000, v56
	s_nop 1
	v_addc_co_u32_e32 v95, vcc, 0, v57, vcc
	v_add_co_u32_e32 v98, vcc, 0x38000, v56
	s_nop 1
	v_addc_co_u32_e32 v99, vcc, 0, v57, vcc
	global_load_dwordx4 v[94:97], v[94:95], off nt
	s_nop 0
	global_load_dwordx4 v[98:101], v[98:99], off nt
	v_add_co_u32_e32 v102, vcc, 0x40000, v56
	s_nop 1
	v_addc_co_u32_e32 v103, vcc, 0, v57, vcc
	v_add_co_u32_e32 v106, vcc, 0x48000, v56
	s_nop 1
	v_addc_co_u32_e32 v107, vcc, 0, v57, vcc
	global_load_dwordx4 v[102:105], v[102:103], off nt
	s_nop 0
	global_load_dwordx4 v[106:109], v[106:107], off nt
	v_add_co_u32_e32 v110, vcc, 0x50000, v56
	s_nop 1
	v_addc_co_u32_e32 v111, vcc, 0, v57, vcc
	v_add_co_u32_e32 v114, vcc, 0x58000, v56
	s_nop 1
	v_addc_co_u32_e32 v115, vcc, 0, v57, vcc
	global_load_dwordx4 v[110:113], v[110:111], off nt
	s_nop 0
	global_load_dwordx4 v[114:117], v[114:115], off nt
	v_add_co_u32_e32 v118, vcc, 0x60000, v56
	s_nop 1
	v_addc_co_u32_e32 v119, vcc, 0, v57, vcc
	v_add_co_u32_e32 v122, vcc, 0x68000, v56
	s_nop 1
	v_addc_co_u32_e32 v123, vcc, 0, v57, vcc
	global_load_dwordx4 v[118:121], v[118:119], off nt
	s_nop 0
	global_load_dwordx4 v[122:125], v[122:123], off nt
	v_add_co_u32_e32 v126, vcc, 0x70000, v56
	s_nop 1
	v_addc_co_u32_e32 v127, vcc, 0, v57, vcc
	global_load_dwordx4 v[126:129], v[126:127], off nt
	v_add_co_u32_e32 v56, vcc, 0x78000, v56
	s_nop 1
	v_addc_co_u32_e32 v57, vcc, 0, v57, vcc
	global_load_dwordx4 v[130:133], v[56:57], off nt
	s_waitcnt vmcnt(0)
	ds_write2_b32 v59, v70, v71 offset1:1
	ds_write2_b32 v59, v72, v73 offset0:2 offset1:3
	ds_write2_b32 v2, v74, v75 offset1:1
	v_add_u32_e32 v2, 0x418, v59
	ds_write2_b32 v2, v76, v77 offset1:1
	v_add_u32_e32 v2, 0x820, v59
	v_lshl_add_u64 v[56:57], v[48:49], 0, s[6:7]
	ds_write2_b32 v2, v78, v79 offset1:1
	v_add_u32_e32 v2, 0x828, v59
	ds_write2_b32 v2, v80, v81 offset1:1
	v_add_u32_e32 v2, 0xc30, v59
	ds_write2_b32 v2, v82, v83 offset1:1
	v_add_u32_e32 v2, 0xc38, v59
	ds_write2_b32 v2, v84, v85 offset1:1
	v_add_u32_e32 v2, 0x1040, v59
	ds_write2_b32 v2, v86, v87 offset1:1
	v_add_u32_e32 v2, 0x1048, v59
	ds_write2_b32 v2, v88, v89 offset1:1
	v_add_u32_e32 v2, 0x1450, v59
	ds_write2_b32 v2, v90, v91 offset1:1
	v_add_u32_e32 v2, 0x1458, v59
	ds_write2_b32 v2, v92, v93 offset1:1
	v_add_u32_e32 v2, 0x1860, v59
	ds_write2_b32 v2, v94, v95 offset1:1
	v_add_u32_e32 v2, 0x1868, v59
	ds_write2_b32 v2, v96, v97 offset1:1
	v_add_u32_e32 v2, 0x1c70, v59
	ds_write2_b32 v2, v98, v99 offset1:1
	v_add_u32_e32 v2, 0x1c78, v59
	ds_write2_b32 v2, v100, v101 offset1:1
	v_add_u32_e32 v2, 0x2080, v59
	ds_write2_b32 v2, v102, v103 offset1:1
	v_add_u32_e32 v2, 0x2088, v59
	ds_write2_b32 v2, v104, v105 offset1:1
	v_add_u32_e32 v2, 0x2490, v59
	ds_write2_b32 v2, v106, v107 offset1:1
	v_add_u32_e32 v2, 0x2498, v59
	ds_write2_b32 v2, v108, v109 offset1:1
	v_add_u32_e32 v2, 0x28a0, v59
	ds_write2_b32 v2, v110, v111 offset1:1
	v_add_u32_e32 v2, 0x28a8, v59
	ds_write2_b32 v2, v112, v113 offset1:1
	v_add_u32_e32 v2, 0x2cb0, v59
	ds_write2_b32 v2, v114, v115 offset1:1
	v_add_u32_e32 v2, 0x2cb8, v59
	ds_write2_b32 v2, v116, v117 offset1:1
	v_add_u32_e32 v2, 0x30c0, v59
	ds_write2_b32 v2, v118, v119 offset1:1
	v_add_u32_e32 v2, 0x30c8, v59
	ds_write2_b32 v2, v120, v121 offset1:1
	v_add_u32_e32 v2, 0x34d0, v59
	ds_write2_b32 v2, v122, v123 offset1:1
	v_add_u32_e32 v2, 0x34d8, v59
	ds_write2_b32 v2, v124, v125 offset1:1
	v_add_u32_e32 v2, 0x38e0, v59
	ds_write2_b32 v2, v126, v127 offset1:1
	v_add_u32_e32 v2, 0x38e8, v59
	ds_write2_b32 v2, v128, v129 offset1:1
	v_add_u32_e32 v2, 0x3cf0, v59
	ds_write2_b32 v2, v130, v131 offset1:1
	v_add_u32_e32 v2, 0x3cf8, v59
	ds_write2_b32 v2, v132, v133 offset1:1
	s_waitcnt vmcnt(0) expcnt(0) lgkmcnt(0)
	ds_read2_b32 v[74:75], v61 offset1:8
	ds_read2_b32 v[76:77], v61 offset0:65 offset1:73
	ds_read2_b32 v[78:79], v61 offset0:130 offset1:138
	ds_read2_b32 v[80:81], v61 offset0:195 offset1:203
	s_waitcnt lgkmcnt(3)
	v_bfe_u32 v2, v74, 16, 1
	v_add3_u32 v2, v74, v2, s27
	s_waitcnt lgkmcnt(2)
	v_bfe_u32 v53, v76, 16, 1
	v_lshrrev_b32_e32 v2, 16, v2
	v_add3_u32 v53, v76, v53, s27
	v_and_or_b32 v70, v53, s28, v2
	v_add_u32_e32 v53, 0x400, v61
	ds_read2_b32 v[82:83], v53 offset0:4 offset1:12
	ds_read2_b32 v[84:85], v53 offset0:69 offset1:77
	s_waitcnt lgkmcnt(3)
	v_bfe_u32 v2, v78, 16, 1
	v_add3_u32 v2, v78, v2, s27
	s_waitcnt lgkmcnt(2)
	v_bfe_u32 v55, v80, 16, 1
	ds_read2_b32 v[86:87], v53 offset0:134 offset1:142
	v_lshrrev_b32_e32 v2, 16, v2
	v_add3_u32 v55, v80, v55, s27
	ds_read2_b32 v[88:89], v53 offset0:199 offset1:207
	v_and_or_b32 v71, v55, s28, v2
	s_waitcnt lgkmcnt(3)
; DI unsigned pk2w(float lo, float hi) { return f2bfw(lo) | (f2bfw(hi) << 16); }
; DI void transpose_item(const float* W, int K, int N, bf16_t* WT, int mode, float* scr, int item, int lane) {
;     ...
;     const int c = lane & 7;
; #pragma unroll
;     for (int j = 0; j < 8; ++j) { const int n = (lane >> 3) + 8 * j; const float* sp = scr + (8 * c) * 65 + n;
;         u32x4 o; o.x = pk2w(sp[0 * 65], sp[1 * 65]); o.y = pk2w(sp[2 * 65], sp[3 * 65]); o.z = pk2w(sp[4 * 65], sp[5 * 65]); o.w = pk2w(sp[6 * 65], sp[7 * 65]);
;         *(u32x4*)(WT + (size_t)(drow0 + n) * K + k0 + 8 * c) = o; }
	v_bfe_u32 v2, v82, 16, 1
	v_add3_u32 v2, v82, v2, s27
	s_waitcnt lgkmcnt(2)
	v_bfe_u32 v55, v84, 16, 1
	v_lshrrev_b32_e32 v2, 16, v2
	v_add3_u32 v55, v84, v55, s27
	v_and_or_b32 v72, v55, s28, v2
	s_waitcnt lgkmcnt(1)
	v_bfe_u32 v2, v86, 16, 1
	v_add3_u32 v2, v86, v2, s27
	s_waitcnt lgkmcnt(0)
	v_bfe_u32 v55, v88, 16, 1
	v_lshrrev_b32_e32 v2, 16, v2
	v_add3_u32 v55, v88, v55, s27
	v_and_or_b32 v73, v55, s28, v2
	v_or_b32_e32 v2, s8, v60
	v_lshlrev_b32_e32 v2, 12, v2
	v_lshl_add_u64 v[90:91], v[56:57], 0, v[2:3]
	v_bfe_u32 v2, v75, 16, 1
	v_add3_u32 v2, v75, v2, s27
	v_bfe_u32 v55, v77, 16, 1
	v_lshrrev_b32_e32 v2, 16, v2
	v_add3_u32 v55, v77, v55, s27
	global_store_dwordx4 v[90:91], v[70:73], off
	ds_read2_b32 v[74:75], v61 offset0:16 offset1:24
	s_nop 0
	v_and_or_b32 v70, v55, s28, v2
	v_bfe_u32 v2, v79, 16, 1
	v_add3_u32 v2, v79, v2, s27
	v_bfe_u32 v55, v81, 16, 1
	v_lshrrev_b32_e32 v2, 16, v2
	v_add3_u32 v55, v81, v55, s27
	v_and_or_b32 v71, v55, s28, v2
	v_bfe_u32 v2, v83, 16, 1
	v_add3_u32 v2, v83, v2, s27
	v_bfe_u32 v55, v85, 16, 1
	v_lshrrev_b32_e32 v2, 16, v2
	v_add3_u32 v55, v85, v55, s27
	v_and_or_b32 v72, v55, s28, v2
	v_bfe_u32 v2, v87, 16, 1
	v_add3_u32 v2, v87, v2, s27
	v_bfe_u32 v55, v89, 16, 1
	v_lshrrev_b32_e32 v2, 16, v2
	v_add3_u32 v55, v89, v55, s27
	v_and_or_b32 v73, v55, s28, v2
	v_or_b32_e32 v2, s8, v62
	v_lshlrev_b32_e32 v2, 12, v2
	v_lshl_add_u64 v[76:77], v[56:57], 0, v[2:3]
	global_store_dwordx4 v[76:77], v[70:73], off
	ds_read2_b32 v[76:77], v61 offset0:81 offset1:89
	ds_read2_b32 v[78:79], v61 offset0:146 offset1:154
	ds_read2_b32 v[80:81], v61 offset0:211 offset1:219
	s_waitcnt lgkmcnt(3)
	v_bfe_u32 v2, v74, 16, 1
	v_add3_u32 v2, v74, v2, s27
	s_waitcnt lgkmcnt(2)
	v_bfe_u32 v55, v76, 16, 1
	ds_read2_b32 v[82:83], v53 offset0:20 offset1:28
	v_lshrrev_b32_e32 v2, 16, v2
	v_add3_u32 v55, v76, v55, s27
	ds_read2_b32 v[84:85], v53 offset0:85 offset1:93
	v_and_or_b32 v70, v55, s28, v2
	s_waitcnt lgkmcnt(3)
	v_bfe_u32 v2, v78, 16, 1
	v_add3_u32 v2, v78, v2, s27
	s_waitcnt lgkmcnt(2)
	v_bfe_u32 v55, v80, 16, 1
	ds_read2_b32 v[86:87], v53 offset0:150 offset1:158
	v_lshrrev_b32_e32 v2, 16, v2
	v_add3_u32 v55, v80, v55, s27
	ds_read2_b32 v[88:89], v53 offset0:215 offset1:223
	v_and_or_b32 v71, v55, s28, v2
	s_waitcnt lgkmcnt(3)
	v_bfe_u32 v2, v82, 16, 1
	v_add3_u32 v2, v82, v2, s27
	s_waitcnt lgkmcnt(2)
	v_bfe_u32 v55, v84, 16, 1
	v_lshrrev_b32_e32 v2, 16, v2
	v_add3_u32 v55, v84, v55, s27
	v_and_or_b32 v72, v55, s28, v2
	s_waitcnt lgkmcnt(1)
	v_bfe_u32 v2, v86, 16, 1
	v_add3_u32 v2, v86, v2, s27
	s_waitcnt lgkmcnt(0)
	v_bfe_u32 v55, v88, 16, 1
	v_lshrrev_b32_e32 v2, 16, v2
	v_add3_u32 v55, v88, v55, s27
	v_and_or_b32 v73, v55, s28, v2
	v_or_b32_e32 v2, s8, v63
	v_lshlrev_b32_e32 v2, 12, v2
	v_lshl_add_u64 v[90:91], v[56:57], 0, v[2:3]
	v_bfe_u32 v2, v75, 16, 1
	v_add3_u32 v2, v75, v2, s27
	v_bfe_u32 v55, v77, 16, 1
	v_lshrrev_b32_e32 v2, 16, v2
	v_add3_u32 v55, v77, v55, s27
	global_store_dwordx4 v[90:91], v[70:73], off
	ds_read2_b32 v[74:75], v61 offset0:32 offset1:40
	s_nop 0
	v_and_or_b32 v70, v55, s28, v2
	v_bfe_u32 v2, v79, 16, 1
	v_add3_u32 v2, v79, v2, s27
	v_bfe_u32 v55, v81, 16, 1
	v_lshrrev_b32_e32 v2, 16, v2
	v_add3_u32 v55, v81, v55, s27
	v_and_or_b32 v71, v55, s28, v2
	v_bfe_u32 v2, v83, 16, 1
	v_add3_u32 v2, v83, v2, s27
	v_bfe_u32 v55, v85, 16, 1
	v_lshrrev_b32_e32 v2, 16, v2
	v_add3_u32 v55, v85, v55, s27
	v_and_or_b32 v72, v55, s28, v2
	v_bfe_u32 v2, v87, 16, 1
	v_add3_u32 v2, v87, v2, s27
	v_bfe_u32 v55, v89, 16, 1
	v_lshrrev_b32_e32 v2, 16, v2
	v_add3_u32 v55, v89, v55, s27
	v_and_or_b32 v73, v55, s28, v2
	v_or_b32_e32 v2, s8, v64
	v_lshlrev_b32_e32 v2, 12, v2
	v_lshl_add_u64 v[76:77], v[56:57], 0, v[2:3]
	global_store_dwordx4 v[76:77], v[70:73], off
	ds_read2_b32 v[76:77], v61 offset0:97 offset1:105
	ds_read2_b32 v[78:79], v61 offset0:162 offset1:170
	ds_read2_b32 v[80:81], v61 offset0:227 offset1:235
	s_waitcnt lgkmcnt(3)
	v_bfe_u32 v2, v74, 16, 1
	v_add3_u32 v2, v74, v2, s27
	s_waitcnt lgkmcnt(2)
	v_bfe_u32 v55, v76, 16, 1
	ds_read2_b32 v[82:83], v53 offset0:36 offset1:44
	v_lshrrev_b32_e32 v2, 16, v2
	v_add3_u32 v55, v76, v55, s27
	ds_read2_b32 v[84:85], v53 offset0:101 offset1:109
	v_and_or_b32 v70, v55, s28, v2
	s_waitcnt lgkmcnt(3)
; DI unsigned pk2w(float lo, float hi) { return f2bfw(lo) | (f2bfw(hi) << 16); }
; DI void transpose_item(const float* W, int K, int N, bf16_t* WT, int mode, float* scr, int item, int lane) {
;     ...
;     const int c = lane & 7;
; #pragma unroll
;     for (int j = 0; j < 8; ++j) { const int n = (lane >> 3) + 8 * j; const float* sp = scr + (8 * c) * 65 + n;
;         u32x4 o; o.x = pk2w(sp[0 * 65], sp[1 * 65]); o.y = pk2w(sp[2 * 65], sp[3 * 65]); o.z = pk2w(sp[4 * 65], sp[5 * 65]); o.w = pk2w(sp[6 * 65], sp[7 * 65]);
;         *(u32x4*)(WT + (size_t)(drow0 + n) * K + k0 + 8 * c) = o; }
;     __builtin_amdgcn_s_waitcnt(0); __builtin_amdgcn_wave_barrier();
	v_bfe_u32 v2, v78, 16, 1
	v_add3_u32 v2, v78, v2, s27
	s_waitcnt lgkmcnt(2)
	v_bfe_u32 v55, v80, 16, 1
	ds_read2_b32 v[86:87], v53 offset0:166 offset1:174
	v_lshrrev_b32_e32 v2, 16, v2
	v_add3_u32 v55, v80, v55, s27
	ds_read2_b32 v[88:89], v53 offset0:231 offset1:239
	v_and_or_b32 v71, v55, s28, v2
	s_waitcnt lgkmcnt(3)
	v_bfe_u32 v2, v82, 16, 1
	v_add3_u32 v2, v82, v2, s27
	s_waitcnt lgkmcnt(2)
	v_bfe_u32 v55, v84, 16, 1
	v_lshrrev_b32_e32 v2, 16, v2
	v_add3_u32 v55, v84, v55, s27
	v_and_or_b32 v72, v55, s28, v2
	s_waitcnt lgkmcnt(1)
	v_bfe_u32 v2, v86, 16, 1
	v_add3_u32 v2, v86, v2, s27
	s_waitcnt lgkmcnt(0)
	v_bfe_u32 v55, v88, 16, 1
	v_lshrrev_b32_e32 v2, 16, v2
	v_add3_u32 v55, v88, v55, s27
	v_and_or_b32 v73, v55, s28, v2
	v_or_b32_e32 v2, s8, v65
	v_lshlrev_b32_e32 v2, 12, v2
	v_lshl_add_u64 v[90:91], v[56:57], 0, v[2:3]
	v_bfe_u32 v2, v75, 16, 1
	v_add3_u32 v2, v75, v2, s27
	v_bfe_u32 v55, v77, 16, 1
	v_lshrrev_b32_e32 v2, 16, v2
	v_add3_u32 v55, v77, v55, s27
	global_store_dwordx4 v[90:91], v[70:73], off
	ds_read2_b32 v[74:75], v61 offset0:48 offset1:56
	s_nop 0
	v_and_or_b32 v70, v55, s28, v2
	v_bfe_u32 v2, v79, 16, 1
	v_add3_u32 v2, v79, v2, s27
	v_bfe_u32 v55, v81, 16, 1
	v_lshrrev_b32_e32 v2, 16, v2
	v_add3_u32 v55, v81, v55, s27
	v_and_or_b32 v71, v55, s28, v2
	v_bfe_u32 v2, v83, 16, 1
	v_add3_u32 v2, v83, v2, s27
	v_bfe_u32 v55, v85, 16, 1
	v_lshrrev_b32_e32 v2, 16, v2
	v_add3_u32 v55, v85, v55, s27
	v_and_or_b32 v72, v55, s28, v2
	v_bfe_u32 v2, v87, 16, 1
	v_add3_u32 v2, v87, v2, s27
	v_bfe_u32 v55, v89, 16, 1
	v_lshrrev_b32_e32 v2, 16, v2
	v_add3_u32 v55, v89, v55, s27
	v_and_or_b32 v73, v55, s28, v2
	v_or_b32_e32 v2, s8, v66
	v_lshlrev_b32_e32 v2, 12, v2
	v_lshl_add_u64 v[76:77], v[56:57], 0, v[2:3]
	global_store_dwordx4 v[76:77], v[70:73], off
	ds_read2_b32 v[76:77], v61 offset0:113 offset1:121
	ds_read2_b32 v[78:79], v61 offset0:178 offset1:186
	ds_read2_b32 v[80:81], v61 offset0:243 offset1:251
	s_waitcnt lgkmcnt(3)
	v_bfe_u32 v2, v74, 16, 1
	v_add3_u32 v2, v74, v2, s27
	s_waitcnt lgkmcnt(2)
	v_bfe_u32 v55, v76, 16, 1
	ds_read2_b32 v[82:83], v53 offset0:52 offset1:60
	v_lshrrev_b32_e32 v2, 16, v2
	v_add3_u32 v55, v76, v55, s27
	ds_read2_b32 v[84:85], v53 offset0:117 offset1:125
	v_and_or_b32 v70, v55, s28, v2
	s_waitcnt lgkmcnt(3)
	v_bfe_u32 v2, v78, 16, 1
	v_add3_u32 v2, v78, v2, s27
	s_waitcnt lgkmcnt(2)
	v_bfe_u32 v55, v80, 16, 1
	ds_read2_b32 v[86:87], v53 offset0:182 offset1:190
	v_lshrrev_b32_e32 v2, 16, v2
	v_add3_u32 v55, v80, v55, s27
	ds_read2_b32 v[88:89], v53 offset0:247 offset1:255
	v_and_or_b32 v71, v55, s28, v2
	s_waitcnt lgkmcnt(3)
	v_bfe_u32 v2, v82, 16, 1
	v_add3_u32 v2, v82, v2, s27
	s_waitcnt lgkmcnt(2)
	v_bfe_u32 v55, v84, 16, 1
	v_lshrrev_b32_e32 v2, 16, v2
	v_add3_u32 v55, v84, v55, s27
	v_and_or_b32 v72, v55, s28, v2
	s_waitcnt lgkmcnt(1)
	v_bfe_u32 v2, v86, 16, 1
	v_add3_u32 v2, v86, v2, s27
	s_waitcnt lgkmcnt(0)
	v_bfe_u32 v53, v88, 16, 1
	v_lshrrev_b32_e32 v2, 16, v2
	v_add3_u32 v53, v88, v53, s27
	v_and_or_b32 v73, v53, s28, v2
	v_or_b32_e32 v2, s8, v67
	v_lshlrev_b32_e32 v2, 12, v2
	v_lshl_add_u64 v[90:91], v[56:57], 0, v[2:3]
	v_bfe_u32 v2, v75, 16, 1
	v_add3_u32 v2, v75, v2, s27
	v_bfe_u32 v53, v77, 16, 1
	v_lshrrev_b32_e32 v2, 16, v2
	v_add3_u32 v53, v77, v53, s27
	global_store_dwordx4 v[90:91], v[70:73], off
	s_nop 1
	v_and_or_b32 v70, v53, s28, v2
	v_bfe_u32 v2, v79, 16, 1
	v_add3_u32 v2, v79, v2, s27
	v_bfe_u32 v53, v81, 16, 1
	v_lshrrev_b32_e32 v2, 16, v2
	v_add3_u32 v53, v81, v53, s27
	v_and_or_b32 v71, v53, s28, v2
	v_bfe_u32 v2, v83, 16, 1
	v_add3_u32 v2, v83, v2, s27
	v_bfe_u32 v53, v85, 16, 1
	v_lshrrev_b32_e32 v2, 16, v2
	v_add3_u32 v53, v85, v53, s27
	v_and_or_b32 v72, v53, s28, v2
	v_bfe_u32 v2, v87, 16, 1
	v_add3_u32 v2, v87, v2, s27
	v_bfe_u32 v53, v89, 16, 1
	v_lshrrev_b32_e32 v2, 16, v2
	v_add3_u32 v53, v89, v53, s27
	v_and_or_b32 v73, v53, s28, v2
	v_or_b32_e32 v2, s8, v68
	v_lshlrev_b32_e32 v2, 12, v2
	v_lshl_add_u64 v[56:57], v[56:57], 0, v[2:3]
	global_store_dwordx4 v[56:57], v[70:73], off
	s_waitcnt lgkmcnt(0)

; DI unsigned pk2w(float lo, float hi) { return f2bfw(lo) | (f2bfw(hi) << 16); }
; DI void transpose_item(const float* W, int K, int N, bf16_t* WT, int mode, float* scr, int item, int lane) {
;     const int nblk = N / 64, kb = item / nblk, nb = item % nblk, k0 = 64 * kb, n0 = 64 * nb;
;     int drow0 = n0;
;     if (mode == 1) { const int seg = n0 >> 10; const int dst = seg < 2 ? seg : (seg == 2 ? 6 : seg - 1); drow0 = dst * 1024 + (n0 & 1023); }
;     else if (mode == 2) { drow0 = n0 < DFF ? (n0 / 128) * 256 + (n0 % 128) : ((n0 - DFF) / 128) * 256 + 128 + ((n0 - DFF) % 128); }
;     else if (mode == 3) { drow0 = (n0 / 128) * 256 + (n0 % 128); }
;     else if (mode == 4) { drow0 = (n0 / 128) * 256 + 128 + (n0 % 128); }
;     f32x4 v[16];
; #pragma unroll
;     for (int i = 0; i < 16; ++i) v[i] = __builtin_nontemporal_load((const f32x4*)(W + (size_t)(k0 + 4 * i + (lane >> 4)) * N + n0 + 4 * (lane & 15)));
; #pragma unroll
;     for (int i = 0; i < 16; ++i) { float* d = scr + (4 * i + (lane >> 4)) * 65 + 4 * (lane & 15); d[0] = v[i][0]; d[1] = v[i][1]; d[2] = v[i][2]; d[3] = v[i][3]; }
;     __builtin_amdgcn_s_waitcnt(0); __builtin_amdgcn_wave_barrier();
;     const int c = lane & 7;
; #pragma unroll
;     for (int j = 0; j < 8; ++j) { const int n = (lane >> 3) + 8 * j; const float* sp = scr + (8 * c) * 65 + n;
;         u32x4 o; o.x = pk2w(sp[0 * 65], sp[1 * 65]); o.y = pk2w(sp[2 * 65], sp[3 * 65]); o.z = pk2w(sp[4 * 65], sp[5 * 65]); o.w = pk2w(sp[6 * 65], sp[7 * 65]);
.LBB0_307:
	s_andn2_b64 vcc, exec, s[8:9]
	s_cbranch_vccnz .LBB0_252
	s_mul_hi_i32 s6, s47, 0x92492493
	s_add_i32 s6, s6, s47
	s_lshr_b32 s8, s6, 31
	s_ashr_i32 s6, s6, 6
	s_add_i32 s6, s6, s8
	s_mul_i32 s8, s6, 0x70
	s_sub_i32 s8, s47, s8
	s_lshl_b32 s48, s8, 6
	s_ashr_i32 s8, s8, 4
	s_add_i32 s9, s8, -1
	s_cmp_lg_u32 s8, 2
	s_cselect_b32 s9, s9, 6
	s_cmp_lt_i32 s8, 2
	s_cselect_b32 s9, s8, s9
	s_lshl_b32 s8, s6, 6
	v_or_b32_e32 v2, s8, v58
	s_ashr_i32 s49, s48, 31
	v_lshl_add_u64 v[56:57], s[48:49], 2, v[18:19]
	v_or_b32_e32 v53, 4, v2
	v_mad_i64_i32 v[74:75], s[50:51], v53, s21, v[56:57]
	v_or_b32_e32 v53, 8, v2
	v_mad_i64_i32 v[70:71], s[50:51], v2, s21, v[56:57]
	v_mad_i64_i32 v[78:79], s[50:51], v53, s21, v[56:57]
	v_or_b32_e32 v53, 12, v2
	global_load_dwordx4 v[70:73], v[70:71], off nt
	s_nop 0
	global_load_dwordx4 v[74:77], v[74:75], off nt
	v_mad_i64_i32 v[82:83], s[50:51], v53, s21, v[56:57]
	v_or_b32_e32 v53, 16, v2
	global_load_dwordx4 v[82:85], v[82:83], off nt
	v_mad_i64_i32 v[86:87], s[50:51], v53, s21, v[56:57]
	global_load_dwordx4 v[86:89], v[86:87], off nt
	v_or_b32_e32 v53, 20, v2
	v_mad_i64_i32 v[90:91], s[50:51], v53, s21, v[56:57]
	global_load_dwordx4 v[78:81], v[78:79], off nt
	v_or_b32_e32 v53, 24, v2
	global_load_dwordx4 v[90:93], v[90:91], off nt
	v_mad_i64_i32 v[94:95], s[50:51], v53, s21, v[56:57]
	global_load_dwordx4 v[94:97], v[94:95], off nt
	v_or_b32_e32 v53, 28, v2
	v_mad_i64_i32 v[98:99], s[50:51], v53, s21, v[56:57]
	global_load_dwordx4 v[98:101], v[98:99], off nt
	v_or_b32_e32 v53, 32, v2
	v_mad_i64_i32 v[102:103], s[50:51], v53, s21, v[56:57]
	global_load_dwordx4 v[102:105], v[102:103], off nt
	v_or_b32_e32 v53, 36, v2
	v_mad_i64_i32 v[106:107], s[50:51], v53, s21, v[56:57]
	global_load_dwordx4 v[106:109], v[106:107], off nt
	v_or_b32_e32 v53, 40, v2
	v_mad_i64_i32 v[110:111], s[50:51], v53, s21, v[56:57]
	global_load_dwordx4 v[110:113], v[110:111], off nt
	v_or_b32_e32 v53, 44, v2
	v_mad_i64_i32 v[114:115], s[50:51], v53, s21, v[56:57]
	global_load_dwordx4 v[114:117], v[114:115], off nt
	v_or_b32_e32 v53, 48, v2
	v_mad_i64_i32 v[118:119], s[50:51], v53, s21, v[56:57]
	global_load_dwordx4 v[118:121], v[118:119], off nt
	v_or_b32_e32 v53, 52, v2
	v_mad_i64_i32 v[122:123], s[50:51], v53, s21, v[56:57]
	global_load_dwordx4 v[122:125], v[122:123], off nt
	v_or_b32_e32 v53, 56, v2
	v_mad_i64_i32 v[126:127], s[50:51], v53, s21, v[56:57]
	global_load_dwordx4 v[126:129], v[126:127], off nt
	v_or_b32_e32 v2, 60, v2
	v_mad_i64_i32 v[56:57], s[50:51], v2, s21, v[56:57]
	global_load_dwordx4 v[130:133], v[56:57], off nt
	v_add_u32_e32 v2, 0x410, v59
	v_add_u32_e32 v53, 0x418, v59
	v_add_u32_e32 v55, 0x820, v59
	v_add_u32_e32 v56, 0x828, v59
	v_add_u32_e32 v57, 0xc30, v59
	s_and_b32 s6, s48, 0x3c0
	s_lshl_b32 s9, s9, 10
	s_or_b32 s6, s9, s6
	s_ashr_i32 s9, s8, 31
	s_waitcnt vmcnt(0)
	ds_write2_b32 v59, v70, v71 offset1:1
	ds_write2_b32 v59, v72, v73 offset0:2 offset1:3
	ds_write2_b32 v2, v74, v75 offset1:1
	ds_write2_b32 v53, v76, v77 offset1:1
	ds_write2_b32 v55, v78, v79 offset1:1
	ds_write2_b32 v56, v80, v81 offset1:1
	ds_write2_b32 v57, v82, v83 offset1:1
	v_add_u32_e32 v2, 0xc38, v59
	ds_write2_b32 v2, v84, v85 offset1:1
	v_add_u32_e32 v2, 0x1040, v59
	ds_write2_b32 v2, v86, v87 offset1:1
	v_add_u32_e32 v2, 0x1048, v59
	ds_write2_b32 v2, v88, v89 offset1:1
	v_add_u32_e32 v2, 0x1450, v59
	ds_write2_b32 v2, v90, v91 offset1:1
	v_add_u32_e32 v2, 0x1458, v59
	ds_write2_b32 v2, v92, v93 offset1:1
	v_add_u32_e32 v2, 0x1860, v59
	ds_write2_b32 v2, v94, v95 offset1:1
	v_add_u32_e32 v2, 0x1868, v59
	ds_write2_b32 v2, v96, v97 offset1:1
	v_add_u32_e32 v2, 0x1c70, v59
	ds_write2_b32 v2, v98, v99 offset1:1
	v_add_u32_e32 v2, 0x1c78, v59
	ds_write2_b32 v2, v100, v101 offset1:1
	v_add_u32_e32 v2, 0x2080, v59
	ds_write2_b32 v2, v102, v103 offset1:1
	v_add_u32_e32 v2, 0x2088, v59
	ds_write2_b32 v2, v104, v105 offset1:1
	v_add_u32_e32 v2, 0x2490, v59
	ds_write2_b32 v2, v106, v107 offset1:1
	v_add_u32_e32 v2, 0x2498, v59
	ds_write2_b32 v2, v108, v109 offset1:1
	v_add_u32_e32 v2, 0x28a0, v59
	ds_write2_b32 v2, v110, v111 offset1:1
	v_add_u32_e32 v2, 0x28a8, v59
	ds_write2_b32 v2, v112, v113 offset1:1
	v_add_u32_e32 v2, 0x2cb0, v59
	ds_write2_b32 v2, v114, v115 offset1:1
	v_add_u32_e32 v2, 0x2cb8, v59
	ds_write2_b32 v2, v116, v117 offset1:1
	v_add_u32_e32 v2, 0x30c0, v59
	ds_write2_b32 v2, v118, v119 offset1:1
	v_add_u32_e32 v2, 0x30c8, v59
	ds_write2_b32 v2, v120, v121 offset1:1
	v_add_u32_e32 v2, 0x34d0, v59
	ds_write2_b32 v2, v122, v123 offset1:1
	v_add_u32_e32 v2, 0x34d8, v59
	ds_write2_b32 v2, v124, v125 offset1:1
	v_add_u32_e32 v2, 0x38e0, v59
	ds_write2_b32 v2, v126, v127 offset1:1
	v_add_u32_e32 v2, 0x38e8, v59
	ds_write2_b32 v2, v128, v129 offset1:1
	v_add_u32_e32 v2, 0x3cf0, v59
	ds_write2_b32 v2, v130, v131 offset1:1
	v_add_u32_e32 v2, 0x3cf8, v59
	ds_write2_b32 v2, v132, v133 offset1:1
	s_waitcnt vmcnt(0) expcnt(0) lgkmcnt(0)
	ds_read2_b32 v[74:75], v61 offset1:8
	ds_read2_b32 v[76:77], v61 offset0:65 offset1:73
	ds_read2_b32 v[78:79], v61 offset0:130 offset1:138
	ds_read2_b32 v[80:81], v61 offset0:195 offset1:203
	v_or_b32_e32 v90, s6, v60
	s_waitcnt lgkmcnt(3)
	v_bfe_u32 v2, v74, 16, 1
	v_add3_u32 v2, v74, v2, s27
	s_waitcnt lgkmcnt(2)
	v_bfe_u32 v53, v76, 16, 1
	v_lshrrev_b32_e32 v2, 16, v2
	v_add3_u32 v53, v76, v53, s27
	v_and_or_b32 v70, v53, s28, v2
	v_add_u32_e32 v53, 0x400, v61
	ds_read2_b32 v[82:83], v53 offset0:4 offset1:12
	ds_read2_b32 v[84:85], v53 offset0:69 offset1:77
	s_waitcnt lgkmcnt(3)
	v_bfe_u32 v2, v78, 16, 1
	v_add3_u32 v2, v78, v2, s27
	s_waitcnt lgkmcnt(2)
; DI unsigned pk2w(float lo, float hi) { return f2bfw(lo) | (f2bfw(hi) << 16); }
; DI void transpose_item(const float* W, int K, int N, bf16_t* WT, int mode, float* scr, int item, int lane) {
;     ...
;     const int c = lane & 7;
; #pragma unroll
;     for (int j = 0; j < 8; ++j) { const int n = (lane >> 3) + 8 * j; const float* sp = scr + (8 * c) * 65 + n;
;         u32x4 o; o.x = pk2w(sp[0 * 65], sp[1 * 65]); o.y = pk2w(sp[2 * 65], sp[3 * 65]); o.z = pk2w(sp[4 * 65], sp[5 * 65]); o.w = pk2w(sp[6 * 65], sp[7 * 65]);
;         *(u32x4*)(WT + (size_t)(drow0 + n) * K + k0 + 8 * c) = o; }
	v_bfe_u32 v55, v80, 16, 1
	ds_read2_b32 v[86:87], v53 offset0:134 offset1:142
	v_lshrrev_b32_e32 v2, 16, v2
	v_add3_u32 v55, v80, v55, s27
	ds_read2_b32 v[88:89], v53 offset0:199 offset1:207
	v_and_or_b32 v71, v55, s28, v2
	s_waitcnt lgkmcnt(3)
	v_bfe_u32 v2, v82, 16, 1
	v_add3_u32 v2, v82, v2, s27
	s_waitcnt lgkmcnt(2)
	v_bfe_u32 v55, v84, 16, 1
	v_lshrrev_b32_e32 v2, 16, v2
	v_add3_u32 v55, v84, v55, s27
	v_and_or_b32 v72, v55, s28, v2
	s_waitcnt lgkmcnt(1)
	v_bfe_u32 v2, v86, 16, 1
	v_add3_u32 v2, v86, v2, s27
	s_waitcnt lgkmcnt(0)
	v_bfe_u32 v55, v88, 16, 1
	v_lshrrev_b32_e32 v2, 16, v2
	v_add3_u32 v55, v88, v55, s27
	v_and_or_b32 v73, v55, s28, v2
	v_ashrrev_i32_e32 v91, 31, v90
	v_bfe_u32 v2, v75, 16, 1
	v_lshl_add_u64 v[56:57], s[8:9], 1, v[50:51]
	v_lshlrev_b64 v[90:91], 12, v[90:91]
	v_add3_u32 v2, v75, v2, s27
	v_bfe_u32 v55, v77, 16, 1
	v_lshl_add_u64 v[90:91], v[56:57], 0, v[90:91]
	v_lshrrev_b32_e32 v2, 16, v2
	v_add3_u32 v55, v77, v55, s27
	global_store_dwordx4 v[90:91], v[70:73], off
	v_or_b32_e32 v74, s6, v62
	v_ashrrev_i32_e32 v75, 31, v74
	v_and_or_b32 v70, v55, s28, v2
	v_bfe_u32 v2, v79, 16, 1
	v_add3_u32 v2, v79, v2, s27
	v_bfe_u32 v55, v81, 16, 1
	v_lshrrev_b32_e32 v2, 16, v2
	v_add3_u32 v55, v81, v55, s27
	v_and_or_b32 v71, v55, s28, v2
	v_bfe_u32 v2, v83, 16, 1
	v_add3_u32 v2, v83, v2, s27
	v_bfe_u32 v55, v85, 16, 1
	v_lshrrev_b32_e32 v2, 16, v2
	v_add3_u32 v55, v85, v55, s27
	v_and_or_b32 v72, v55, s28, v2
	v_bfe_u32 v2, v87, 16, 1
	v_add3_u32 v2, v87, v2, s27
	v_bfe_u32 v55, v89, 16, 1
	v_lshrrev_b32_e32 v2, 16, v2
	v_add3_u32 v55, v89, v55, s27
	v_lshlrev_b64 v[74:75], 12, v[74:75]
	v_and_or_b32 v73, v55, s28, v2
	ds_read2_b32 v[76:77], v61 offset0:16 offset1:24
	v_lshl_add_u64 v[74:75], v[56:57], 0, v[74:75]
	global_store_dwordx4 v[74:75], v[70:73], off
	ds_read2_b32 v[74:75], v61 offset0:81 offset1:89
	ds_read2_b32 v[78:79], v61 offset0:146 offset1:154
	ds_read2_b32 v[80:81], v61 offset0:211 offset1:219
	s_waitcnt lgkmcnt(3)
	v_bfe_u32 v2, v76, 16, 1
	v_add3_u32 v2, v76, v2, s27
	s_waitcnt lgkmcnt(2)
	v_bfe_u32 v55, v74, 16, 1
	ds_read2_b32 v[82:83], v53 offset0:20 offset1:28
	v_lshrrev_b32_e32 v2, 16, v2
	v_add3_u32 v55, v74, v55, s27
	ds_read2_b32 v[84:85], v53 offset0:85 offset1:93
	v_and_or_b32 v70, v55, s28, v2
	s_waitcnt lgkmcnt(3)
	v_bfe_u32 v2, v78, 16, 1
	v_add3_u32 v2, v78, v2, s27
	s_waitcnt lgkmcnt(2)
	v_bfe_u32 v55, v80, 16, 1
	ds_read2_b32 v[86:87], v53 offset0:150 offset1:158
	v_lshrrev_b32_e32 v2, 16, v2
	v_add3_u32 v55, v80, v55, s27
	ds_read2_b32 v[88:89], v53 offset0:215 offset1:223
	v_and_or_b32 v71, v55, s28, v2
	s_waitcnt lgkmcnt(3)
	v_bfe_u32 v2, v82, 16, 1
	v_add3_u32 v2, v82, v2, s27
	s_waitcnt lgkmcnt(2)
	v_bfe_u32 v55, v84, 16, 1
	v_lshrrev_b32_e32 v2, 16, v2
	v_add3_u32 v55, v84, v55, s27
	v_and_or_b32 v72, v55, s28, v2
	s_waitcnt lgkmcnt(1)
	v_bfe_u32 v2, v86, 16, 1
	v_add3_u32 v2, v86, v2, s27
	s_waitcnt lgkmcnt(0)
	v_bfe_u32 v55, v88, 16, 1
	v_lshrrev_b32_e32 v2, 16, v2
	v_add3_u32 v55, v88, v55, s27
	v_or_b32_e32 v90, s6, v63
	v_and_or_b32 v73, v55, s28, v2
	v_ashrrev_i32_e32 v91, 31, v90
	v_bfe_u32 v2, v77, 16, 1
	v_lshlrev_b64 v[90:91], 12, v[90:91]
	v_add3_u32 v2, v77, v2, s27
	v_bfe_u32 v55, v75, 16, 1
	v_lshl_add_u64 v[90:91], v[56:57], 0, v[90:91]
	v_lshrrev_b32_e32 v2, 16, v2
	v_add3_u32 v55, v75, v55, s27
	global_store_dwordx4 v[90:91], v[70:73], off
	v_or_b32_e32 v74, s6, v64
	v_ashrrev_i32_e32 v75, 31, v74
	v_and_or_b32 v70, v55, s28, v2
	v_bfe_u32 v2, v79, 16, 1
	v_add3_u32 v2, v79, v2, s27
	v_bfe_u32 v55, v81, 16, 1
	v_lshrrev_b32_e32 v2, 16, v2
	v_add3_u32 v55, v81, v55, s27
	v_and_or_b32 v71, v55, s28, v2
	v_bfe_u32 v2, v83, 16, 1
	v_add3_u32 v2, v83, v2, s27
	v_bfe_u32 v55, v85, 16, 1
	v_lshrrev_b32_e32 v2, 16, v2
	v_add3_u32 v55, v85, v55, s27
	v_and_or_b32 v72, v55, s28, v2
	v_bfe_u32 v2, v87, 16, 1
	v_add3_u32 v2, v87, v2, s27
	v_bfe_u32 v55, v89, 16, 1
	v_lshrrev_b32_e32 v2, 16, v2
	v_add3_u32 v55, v89, v55, s27
	v_lshlrev_b64 v[74:75], 12, v[74:75]
	v_and_or_b32 v73, v55, s28, v2
	ds_read2_b32 v[76:77], v61 offset0:32 offset1:40
	v_lshl_add_u64 v[74:75], v[56:57], 0, v[74:75]
	global_store_dwordx4 v[74:75], v[70:73], off
	ds_read2_b32 v[74:75], v61 offset0:97 offset1:105
	ds_read2_b32 v[78:79], v61 offset0:162 offset1:170
	ds_read2_b32 v[80:81], v61 offset0:227 offset1:235
	s_waitcnt lgkmcnt(3)
	v_bfe_u32 v2, v76, 16, 1
	v_add3_u32 v2, v76, v2, s27
	s_waitcnt lgkmcnt(2)
; DI unsigned pk2w(float lo, float hi) { return f2bfw(lo) | (f2bfw(hi) << 16); }
; DI void transpose_item(const float* W, int K, int N, bf16_t* WT, int mode, float* scr, int item, int lane) {
;     ...
;     const int c = lane & 7;
; #pragma unroll
;     for (int j = 0; j < 8; ++j) { const int n = (lane >> 3) + 8 * j; const float* sp = scr + (8 * c) * 65 + n;
;         u32x4 o; o.x = pk2w(sp[0 * 65], sp[1 * 65]); o.y = pk2w(sp[2 * 65], sp[3 * 65]); o.z = pk2w(sp[4 * 65], sp[5 * 65]); o.w = pk2w(sp[6 * 65], sp[7 * 65]);
;         *(u32x4*)(WT + (size_t)(drow0 + n) * K + k0 + 8 * c) = o; }
;     __builtin_amdgcn_s_waitcnt(0); __builtin_amdgcn_wave_barrier();
	v_bfe_u32 v55, v74, 16, 1
	ds_read2_b32 v[82:83], v53 offset0:36 offset1:44
	v_lshrrev_b32_e32 v2, 16, v2
	v_add3_u32 v55, v74, v55, s27
	ds_read2_b32 v[84:85], v53 offset0:101 offset1:109
	v_and_or_b32 v70, v55, s28, v2
	s_waitcnt lgkmcnt(3)
	v_bfe_u32 v2, v78, 16, 1
	v_add3_u32 v2, v78, v2, s27
	s_waitcnt lgkmcnt(2)
	v_bfe_u32 v55, v80, 16, 1
	ds_read2_b32 v[86:87], v53 offset0:166 offset1:174
	v_lshrrev_b32_e32 v2, 16, v2
	v_add3_u32 v55, v80, v55, s27
	ds_read2_b32 v[88:89], v53 offset0:231 offset1:239
	v_and_or_b32 v71, v55, s28, v2
	s_waitcnt lgkmcnt(3)
	v_bfe_u32 v2, v82, 16, 1
	v_add3_u32 v2, v82, v2, s27
	s_waitcnt lgkmcnt(2)
	v_bfe_u32 v55, v84, 16, 1
	v_lshrrev_b32_e32 v2, 16, v2
	v_add3_u32 v55, v84, v55, s27
	v_and_or_b32 v72, v55, s28, v2
	s_waitcnt lgkmcnt(1)
	v_bfe_u32 v2, v86, 16, 1
	v_add3_u32 v2, v86, v2, s27
	s_waitcnt lgkmcnt(0)
	v_bfe_u32 v55, v88, 16, 1
	v_lshrrev_b32_e32 v2, 16, v2
	v_add3_u32 v55, v88, v55, s27
	v_or_b32_e32 v90, s6, v65
	v_and_or_b32 v73, v55, s28, v2
	v_ashrrev_i32_e32 v91, 31, v90
	v_bfe_u32 v2, v77, 16, 1
	v_lshlrev_b64 v[90:91], 12, v[90:91]
	v_add3_u32 v2, v77, v2, s27
	v_bfe_u32 v55, v75, 16, 1
	v_lshl_add_u64 v[90:91], v[56:57], 0, v[90:91]
	v_lshrrev_b32_e32 v2, 16, v2
	v_add3_u32 v55, v75, v55, s27
	global_store_dwordx4 v[90:91], v[70:73], off
	v_or_b32_e32 v74, s6, v66
	v_ashrrev_i32_e32 v75, 31, v74
	v_and_or_b32 v70, v55, s28, v2
	v_bfe_u32 v2, v79, 16, 1
	v_add3_u32 v2, v79, v2, s27
	v_bfe_u32 v55, v81, 16, 1
	v_lshrrev_b32_e32 v2, 16, v2
	v_add3_u32 v55, v81, v55, s27
	v_and_or_b32 v71, v55, s28, v2
	v_bfe_u32 v2, v83, 16, 1
	v_add3_u32 v2, v83, v2, s27
	v_bfe_u32 v55, v85, 16, 1
	v_lshrrev_b32_e32 v2, 16, v2
	v_add3_u32 v55, v85, v55, s27
	v_and_or_b32 v72, v55, s28, v2
	v_bfe_u32 v2, v87, 16, 1
	v_add3_u32 v2, v87, v2, s27
	v_bfe_u32 v55, v89, 16, 1
	v_lshrrev_b32_e32 v2, 16, v2
	v_add3_u32 v55, v89, v55, s27
	v_lshlrev_b64 v[74:75], 12, v[74:75]
	v_and_or_b32 v73, v55, s28, v2
	ds_read2_b32 v[76:77], v61 offset0:48 offset1:56
	v_lshl_add_u64 v[74:75], v[56:57], 0, v[74:75]
	global_store_dwordx4 v[74:75], v[70:73], off
	ds_read2_b32 v[74:75], v61 offset0:113 offset1:121
	ds_read2_b32 v[78:79], v61 offset0:178 offset1:186
	ds_read2_b32 v[80:81], v61 offset0:243 offset1:251
	s_waitcnt lgkmcnt(3)
	v_bfe_u32 v2, v76, 16, 1
	v_add3_u32 v2, v76, v2, s27
	s_waitcnt lgkmcnt(2)
	v_bfe_u32 v55, v74, 16, 1
	ds_read2_b32 v[82:83], v53 offset0:52 offset1:60
	v_lshrrev_b32_e32 v2, 16, v2
	v_add3_u32 v55, v74, v55, s27
	ds_read2_b32 v[84:85], v53 offset0:117 offset1:125
	v_and_or_b32 v70, v55, s28, v2
	s_waitcnt lgkmcnt(3)
	v_bfe_u32 v2, v78, 16, 1
	v_add3_u32 v2, v78, v2, s27
	s_waitcnt lgkmcnt(2)
	v_bfe_u32 v55, v80, 16, 1
	ds_read2_b32 v[86:87], v53 offset0:182 offset1:190
	v_lshrrev_b32_e32 v2, 16, v2
	v_add3_u32 v55, v80, v55, s27
	ds_read2_b32 v[88:89], v53 offset0:247 offset1:255
	v_and_or_b32 v71, v55, s28, v2
	s_waitcnt lgkmcnt(3)
	v_bfe_u32 v2, v82, 16, 1
	v_add3_u32 v2, v82, v2, s27
	s_waitcnt lgkmcnt(2)
	v_bfe_u32 v55, v84, 16, 1
	v_lshrrev_b32_e32 v2, 16, v2
	v_add3_u32 v55, v84, v55, s27
	v_and_or_b32 v72, v55, s28, v2
	s_waitcnt lgkmcnt(1)
	v_bfe_u32 v2, v86, 16, 1
	v_add3_u32 v2, v86, v2, s27
	s_waitcnt lgkmcnt(0)
	v_bfe_u32 v53, v88, 16, 1
	v_lshrrev_b32_e32 v2, 16, v2
	v_add3_u32 v53, v88, v53, s27
	v_or_b32_e32 v90, s6, v67
	v_and_or_b32 v73, v53, s28, v2
	v_ashrrev_i32_e32 v91, 31, v90
	v_bfe_u32 v2, v77, 16, 1
	v_lshlrev_b64 v[90:91], 12, v[90:91]
	v_add3_u32 v2, v77, v2, s27
	v_bfe_u32 v53, v75, 16, 1
	v_lshl_add_u64 v[90:91], v[56:57], 0, v[90:91]
	v_lshrrev_b32_e32 v2, 16, v2
	v_add3_u32 v53, v75, v53, s27
	global_store_dwordx4 v[90:91], v[70:73], off
	v_or_b32_e32 v74, s6, v68
	v_ashrrev_i32_e32 v75, 31, v74
	v_and_or_b32 v70, v53, s28, v2
	v_bfe_u32 v2, v79, 16, 1
	v_add3_u32 v2, v79, v2, s27
	v_bfe_u32 v53, v81, 16, 1
	v_lshrrev_b32_e32 v2, 16, v2
	v_add3_u32 v53, v81, v53, s27
	v_and_or_b32 v71, v53, s28, v2
	v_bfe_u32 v2, v83, 16, 1
	v_add3_u32 v2, v83, v2, s27
	v_bfe_u32 v53, v85, 16, 1
	v_lshrrev_b32_e32 v2, 16, v2
	v_add3_u32 v53, v85, v53, s27
	v_and_or_b32 v72, v53, s28, v2
	v_bfe_u32 v2, v87, 16, 1
	v_add3_u32 v2, v87, v2, s27
	v_bfe_u32 v53, v89, 16, 1
	v_lshrrev_b32_e32 v2, 16, v2
	v_add3_u32 v53, v89, v53, s27
	v_lshlrev_b64 v[74:75], 12, v[74:75]
	v_and_or_b32 v73, v53, s28, v2
	v_lshl_add_u64 v[56:57], v[56:57], 0, v[74:75]
	global_store_dwordx4 v[56:57], v[70:73], off
	s_waitcnt lgkmcnt(0)
	s_branch .LBB0_252
